# second LDS-DMA load of each heavy K-loop load part (P1/P3/P5/P7) issued one phase later, counted waits vmcnt(10)/vmcnt(8) alternating
# baseline (speedup 1.0000x reference)
.LBB0_287:
	s_add_u32 s0, s22, 0xfffc0080
	s_addc_u32 s1, s23, -1
	s_add_i32 s72, 0, 0x10000
	s_cmp_eq_u32 s69, 12
	s_cselect_b32 s27, s18, s1
	s_cselect_b32 s26, s19, s0
	s_cselect_b32 s25, s45, s68
	s_cselect_b32 s24, s47, s59
	s_add_i32 m0, s53, 0xc000
	ds_read_b128 v[158:161], v165
	ds_read_b128 v[174:177], v165 offset:1024
	ds_read_b128 v[178:181], v165 offset:2048
	ds_read_b128 v[182:185], v165 offset:3072
	ds_read_b128 v[186:189], v165 offset:4096
	ds_read_b128 v[190:193], v165 offset:5120
	ds_read_b128 v[194:197], v165 offset:6144
	ds_read_b128 v[198:201], v165 offset:7168
	global_load_lds_dwordx4 v154, s[22:23]
	s_waitcnt vmcnt(10) lgkmcnt(8)
	s_setprio 1
	s_barrier
	s_waitcnt lgkmcnt(0)
	v_mfma_f32_16x16x32_bf16 v[144:147], v[68:71], v[158:161], v[144:147]
	v_mfma_f32_16x16x32_bf16 v[140:143], v[76:79], v[158:161], v[140:143]
	v_mfma_f32_16x16x32_bf16 v[128:131], v[68:71], v[178:181], v[128:131]
	v_mfma_f32_16x16x32_bf16 v[124:127], v[76:79], v[178:181], v[124:127]
	v_mfma_f32_16x16x32_bf16 v[112:115], v[68:71], v[186:189], v[112:115]
	v_mfma_f32_16x16x32_bf16 v[108:111], v[76:79], v[186:189], v[108:111]
	v_mfma_f32_16x16x32_bf16 v[96:99], v[68:71], v[194:197], v[96:99]
	v_mfma_f32_16x16x32_bf16 v[92:95], v[76:79], v[194:197], v[92:95]
	v_mfma_f32_16x16x32_bf16 v[144:147], v[72:75], v[174:177], v[144:147]
	v_mfma_f32_16x16x32_bf16 v[140:143], v[80:83], v[174:177], v[140:143]
	v_mfma_f32_16x16x32_bf16 v[128:131], v[72:75], v[182:185], v[128:131]
	v_mfma_f32_16x16x32_bf16 v[124:127], v[80:83], v[182:185], v[124:127]
	v_mfma_f32_16x16x32_bf16 v[112:115], v[72:75], v[190:193], v[112:115]
	v_mfma_f32_16x16x32_bf16 v[108:111], v[80:83], v[190:193], v[108:111]
	v_mfma_f32_16x16x32_bf16 v[96:99], v[72:75], v[198:201], v[96:99]
	v_mfma_f32_16x16x32_bf16 v[92:95], v[80:83], v[198:201], v[92:95]
	s_barrier
	s_setprio 0
	s_add_i32 s73, 0, 0x14000
	s_add_i32 s0, s72, s52
	v_add_u32_e32 v166, s73, v163
	v_lshl_add_u64 v[218:219], s[24:25], 0, v[26:27]
	s_mov_b32 m0, s0
	ds_read_b128 v[202:205], v166
	ds_read_b128 v[206:209], v166 offset:1024
	ds_read_b128 v[210:213], v166 offset:2048
	ds_read_b128 v[214:217], v166 offset:3072
	global_load_lds_dwordx4 v[218:219], off
	v_lshl_add_u64 v[220:221], s[24:25], 0, v[148:149]
	s_add_i32 m0, s0, 0x2000
	s_nop 0
	global_load_lds_dwordx4 v[220:221], off
	s_add_i32 m0, s53, 0xe000
	s_nop 0
	global_load_lds_dwordx4 v156, s[22:23]
	s_waitcnt vmcnt(8)
	s_setprio 1
	s_barrier
	s_waitcnt lgkmcnt(0)
	v_mfma_f32_16x16x32_bf16 v[136:139], v[202:205], v[158:161], v[136:139]
	v_mfma_f32_16x16x32_bf16 v[132:135], v[210:213], v[158:161], v[132:135]
	v_mfma_f32_16x16x32_bf16 v[120:123], v[202:205], v[178:181], v[120:123]
	v_mfma_f32_16x16x32_bf16 v[116:119], v[210:213], v[178:181], v[116:119]
	v_mfma_f32_16x16x32_bf16 v[104:107], v[202:205], v[186:189], v[104:107]
	v_mfma_f32_16x16x32_bf16 v[100:103], v[210:213], v[186:189], v[100:103]
	v_mfma_f32_16x16x32_bf16 v[88:91], v[202:205], v[194:197], v[88:91]
	v_mfma_f32_16x16x32_bf16 v[84:87], v[210:213], v[194:197], v[84:87]
	v_mfma_f32_16x16x32_bf16 v[136:139], v[206:209], v[174:177], v[136:139]
	v_mfma_f32_16x16x32_bf16 v[132:135], v[214:217], v[174:177], v[132:135]
	v_mfma_f32_16x16x32_bf16 v[120:123], v[206:209], v[182:185], v[120:123]
	v_mfma_f32_16x16x32_bf16 v[116:119], v[214:217], v[182:185], v[116:119]
	v_mfma_f32_16x16x32_bf16 v[104:107], v[206:209], v[190:193], v[104:107]
	v_mfma_f32_16x16x32_bf16 v[100:103], v[214:217], v[190:193], v[100:103]
	v_mfma_f32_16x16x32_bf16 v[88:91], v[206:209], v[198:201], v[88:91]
	v_mfma_f32_16x16x32_bf16 v[84:87], v[214:217], v[198:201], v[84:87]
	s_barrier
	s_setprio 0
	s_mov_b32 m0, s53
	v_lshl_add_u64 v[222:223], s[26:27], 0, v[152:153]
	ds_read_b128 v[158:161], v165 offset:16384
	ds_read_b128 v[174:177], v165 offset:17408
	ds_read_b128 v[178:181], v165 offset:18432
	ds_read_b128 v[182:185], v165 offset:19456
	ds_read_b128 v[186:189], v165 offset:20480
	ds_read_b128 v[190:193], v165 offset:21504
	ds_read_b128 v[194:197], v165 offset:22528
	ds_read_b128 v[198:201], v165 offset:23552
	global_load_lds_dwordx4 v[222:223], off
	s_waitcnt vmcnt(10)
	s_setprio 1
	s_barrier
	s_waitcnt lgkmcnt(0)
	v_mfma_f32_16x16x32_bf16 v[64:67], v[68:71], v[158:161], v[64:67]
	v_mfma_f32_16x16x32_bf16 v[60:63], v[76:79], v[158:161], v[60:63]
	v_mfma_f32_16x16x32_bf16 v[48:51], v[68:71], v[178:181], v[48:51]
	v_mfma_f32_16x16x32_bf16 v[44:47], v[76:79], v[178:181], v[44:47]
	v_mfma_f32_16x16x32_bf16 v[32:35], v[68:71], v[186:189], v[32:35]
	v_mfma_f32_16x16x32_bf16 v[28:31], v[76:79], v[186:189], v[28:31]
	v_mfma_f32_16x16x32_bf16 v[14:17], v[68:71], v[194:197], v[14:17]
	v_mfma_f32_16x16x32_bf16 v[10:13], v[76:79], v[194:197], v[10:13]
	v_mfma_f32_16x16x32_bf16 v[64:67], v[72:75], v[174:177], v[64:67]
	v_mfma_f32_16x16x32_bf16 v[60:63], v[80:83], v[174:177], v[60:63]
	v_mfma_f32_16x16x32_bf16 v[48:51], v[72:75], v[182:185], v[48:51]
	v_mfma_f32_16x16x32_bf16 v[44:47], v[80:83], v[182:185], v[44:47]
	v_mfma_f32_16x16x32_bf16 v[32:35], v[72:75], v[190:193], v[32:35]
	v_mfma_f32_16x16x32_bf16 v[28:31], v[80:83], v[190:193], v[28:31]
	v_mfma_f32_16x16x32_bf16 v[14:17], v[72:75], v[198:201], v[14:17]
	v_mfma_f32_16x16x32_bf16 v[10:13], v[80:83], v[198:201], v[10:13]
	s_barrier
	s_setprio 0
	s_add_u32 s0, s24, 0x40000
	s_addc_u32 s1, s25, 0
	s_add_i32 s72, s73, s52
	s_mov_b32 m0, s72
	s_nop 0
	global_load_lds_dwordx4 v26, s[0:1]
	s_add_i32 m0, s72, 0x2000
	s_nop 0
	global_load_lds_dwordx4 v148, s[0:1]
	v_lshl_add_u64 v[224:225], s[26:27], 0, v[150:151]
	s_mov_b32 m0, s54
	s_nop 0
	global_load_lds_dwordx4 v[224:225], off
	v_add_u32_e32 v80, 0x18000, v163
	ds_read_b128 v[68:71], v80
	ds_read_b128 v[72:75], v80 offset:1024
	ds_read_b128 v[76:79], v80 offset:2048
	ds_read_b128 v[80:83], v80 offset:3072
	s_waitcnt vmcnt(8)
	s_setprio 1
	s_barrier
	v_mfma_f32_16x16x32_bf16 v[56:59], v[202:205], v[158:161], v[56:59]
	v_mfma_f32_16x16x32_bf16 v[52:55], v[210:213], v[158:161], v[52:55]
	v_mfma_f32_16x16x32_bf16 v[40:43], v[202:205], v[178:181], v[40:43]
	v_mfma_f32_16x16x32_bf16 v[36:39], v[210:213], v[178:181], v[36:39]
	v_mfma_f32_16x16x32_bf16 v[22:25], v[202:205], v[186:189], v[22:25]
	v_mfma_f32_16x16x32_bf16 v[18:21], v[210:213], v[186:189], v[18:21]
	v_mfma_f32_16x16x32_bf16 v[6:9], v[202:205], v[194:197], v[6:9]
	v_mfma_f32_16x16x32_bf16 v[2:5], v[210:213], v[194:197], v[2:5]
	v_mfma_f32_16x16x32_bf16 v[56:59], v[206:209], v[174:177], v[56:59]
	v_mfma_f32_16x16x32_bf16 v[52:55], v[214:217], v[174:177], v[52:55]
	v_mfma_f32_16x16x32_bf16 v[40:43], v[206:209], v[182:185], v[40:43]
	v_mfma_f32_16x16x32_bf16 v[36:39], v[214:217], v[182:185], v[36:39]
	v_mfma_f32_16x16x32_bf16 v[22:25], v[206:209], v[190:193], v[22:25]
	v_mfma_f32_16x16x32_bf16 v[18:21], v[214:217], v[190:193], v[18:21]
	v_mfma_f32_16x16x32_bf16 v[6:9], v[206:209], v[198:201], v[6:9]
	v_mfma_f32_16x16x32_bf16 v[2:5], v[214:217], v[198:201], v[2:5]
	s_barrier
	s_setprio 0
	s_add_i32 s72, 0, 0x18000
	s_add_u32 s0, s26, 0x40000
	s_addc_u32 s1, s27, 0
	s_mov_b32 m0, s55
	ds_read_b128 v[158:161], v165 offset:32768
	ds_read_b128 v[174:177], v165 offset:33792
	ds_read_b128 v[178:181], v165 offset:34816
	ds_read_b128 v[182:185], v165 offset:35840
	ds_read_b128 v[186:189], v165 offset:36864
	ds_read_b128 v[190:193], v165 offset:37888
	ds_read_b128 v[194:197], v165 offset:38912
	ds_read_b128 v[198:201], v165 offset:39936
	global_load_lds_dwordx4 v152, s[0:1]
	s_mov_b64 s[100:101], s[0:1]
	s_waitcnt vmcnt(10) lgkmcnt(8)
	s_setprio 1
	s_barrier
	s_waitcnt lgkmcnt(0)
	v_mfma_f32_16x16x32_bf16 v[144:147], v[68:71], v[158:161], v[144:147]
	v_mfma_f32_16x16x32_bf16 v[140:143], v[76:79], v[158:161], v[140:143]
	v_mfma_f32_16x16x32_bf16 v[128:131], v[68:71], v[178:181], v[128:131]
	v_mfma_f32_16x16x32_bf16 v[124:127], v[76:79], v[178:181], v[124:127]
	v_mfma_f32_16x16x32_bf16 v[112:115], v[68:71], v[186:189], v[112:115]
	v_mfma_f32_16x16x32_bf16 v[108:111], v[76:79], v[186:189], v[108:111]
	v_mfma_f32_16x16x32_bf16 v[96:99], v[68:71], v[194:197], v[96:99]
	v_mfma_f32_16x16x32_bf16 v[92:95], v[76:79], v[194:197], v[92:95]
	v_mfma_f32_16x16x32_bf16 v[144:147], v[72:75], v[174:177], v[144:147]
	v_mfma_f32_16x16x32_bf16 v[140:143], v[80:83], v[174:177], v[140:143]
	v_mfma_f32_16x16x32_bf16 v[128:131], v[72:75], v[182:185], v[128:131]
	v_mfma_f32_16x16x32_bf16 v[124:127], v[80:83], v[182:185], v[124:127]
	v_mfma_f32_16x16x32_bf16 v[112:115], v[72:75], v[190:193], v[112:115]
	v_mfma_f32_16x16x32_bf16 v[108:111], v[80:83], v[190:193], v[108:111]
	v_mfma_f32_16x16x32_bf16 v[96:99], v[72:75], v[198:201], v[96:99]
	v_mfma_f32_16x16x32_bf16 v[92:95], v[80:83], v[198:201], v[92:95]
	s_barrier
	s_setprio 0
	s_add_i32 s26, 0, 0x1c000
	s_add_i32 s0, s72, s52
	v_add_u32_e32 v166, s26, v163
	v_lshl_add_u64 v[218:219], v[218:219], 0, s[12:13]
	s_mov_b32 m0, s0
	ds_read_b128 v[202:205], v166
	ds_read_b128 v[206:209], v166 offset:1024
	ds_read_b128 v[210:213], v166 offset:2048
	ds_read_b128 v[214:217], v166 offset:3072
	global_load_lds_dwordx4 v[218:219], off
	v_lshl_add_u64 v[218:219], v[220:221], 0, s[12:13]
	s_add_i32 m0, s0, 0x2000
	s_nop 0
	global_load_lds_dwordx4 v[218:219], off
	s_mov_b32 m0, s56
	s_nop 0
	global_load_lds_dwordx4 v150, s[100:101]
	s_waitcnt vmcnt(8)
	s_setprio 1
	s_barrier
	s_waitcnt lgkmcnt(0)
	v_mfma_f32_16x16x32_bf16 v[136:139], v[202:205], v[158:161], v[136:139]
	v_mfma_f32_16x16x32_bf16 v[132:135], v[210:213], v[158:161], v[132:135]
	v_mfma_f32_16x16x32_bf16 v[120:123], v[202:205], v[178:181], v[120:123]
	v_mfma_f32_16x16x32_bf16 v[116:119], v[210:213], v[178:181], v[116:119]
	v_mfma_f32_16x16x32_bf16 v[104:107], v[202:205], v[186:189], v[104:107]
	v_mfma_f32_16x16x32_bf16 v[100:103], v[210:213], v[186:189], v[100:103]
	v_mfma_f32_16x16x32_bf16 v[88:91], v[202:205], v[194:197], v[88:91]
	v_mfma_f32_16x16x32_bf16 v[84:87], v[210:213], v[194:197], v[84:87]
	v_mfma_f32_16x16x32_bf16 v[136:139], v[206:209], v[174:177], v[136:139]
	v_mfma_f32_16x16x32_bf16 v[132:135], v[214:217], v[174:177], v[132:135]
	v_mfma_f32_16x16x32_bf16 v[120:123], v[206:209], v[182:185], v[120:123]
	v_mfma_f32_16x16x32_bf16 v[116:119], v[214:217], v[182:185], v[116:119]
	v_mfma_f32_16x16x32_bf16 v[104:107], v[206:209], v[190:193], v[104:107]
	v_mfma_f32_16x16x32_bf16 v[100:103], v[214:217], v[190:193], v[100:103]
	v_mfma_f32_16x16x32_bf16 v[88:91], v[206:209], v[198:201], v[88:91]
	v_mfma_f32_16x16x32_bf16 v[84:87], v[214:217], v[198:201], v[84:87]
	s_barrier
	s_setprio 0
	s_mov_b32 m0, s30
	v_lshl_add_u64 v[218:219], v[222:223], 0, s[12:13]
	ds_read_b128 v[158:161], v165 offset:49152
	ds_read_b128 v[174:177], v165 offset:50176
	ds_read_b128 v[178:181], v165 offset:51200
	ds_read_b128 v[182:185], v165 offset:52224
	ds_read_b128 v[186:189], v165 offset:53248
	ds_read_b128 v[190:193], v165 offset:54272
	ds_read_b128 v[194:197], v165 offset:55296
	ds_read_b128 v[198:201], v165 offset:56320
	global_load_lds_dwordx4 v[218:219], off
	s_waitcnt vmcnt(10)
	s_setprio 1
	s_barrier
	s_waitcnt lgkmcnt(0)
	v_mfma_f32_16x16x32_bf16 v[64:67], v[68:71], v[158:161], v[64:67]
	v_mfma_f32_16x16x32_bf16 v[60:63], v[76:79], v[158:161], v[60:63]
	v_mfma_f32_16x16x32_bf16 v[48:51], v[68:71], v[178:181], v[48:51]
	v_mfma_f32_16x16x32_bf16 v[44:47], v[76:79], v[178:181], v[44:47]
	v_mfma_f32_16x16x32_bf16 v[32:35], v[68:71], v[186:189], v[32:35]
	v_mfma_f32_16x16x32_bf16 v[28:31], v[76:79], v[186:189], v[28:31]
	v_mfma_f32_16x16x32_bf16 v[14:17], v[68:71], v[194:197], v[14:17]
	v_mfma_f32_16x16x32_bf16 v[10:13], v[76:79], v[194:197], v[10:13]
	v_mfma_f32_16x16x32_bf16 v[64:67], v[72:75], v[174:177], v[64:67]
	v_mfma_f32_16x16x32_bf16 v[60:63], v[80:83], v[174:177], v[60:63]
	v_mfma_f32_16x16x32_bf16 v[48:51], v[72:75], v[182:185], v[48:51]
	v_mfma_f32_16x16x32_bf16 v[44:47], v[80:83], v[182:185], v[44:47]
	v_mfma_f32_16x16x32_bf16 v[32:35], v[72:75], v[190:193], v[32:35]
	v_mfma_f32_16x16x32_bf16 v[28:31], v[80:83], v[190:193], v[28:31]
	v_mfma_f32_16x16x32_bf16 v[14:17], v[72:75], v[198:201], v[14:17]
	v_mfma_f32_16x16x32_bf16 v[10:13], v[80:83], v[198:201], v[10:13]
	s_barrier
	s_setprio 0
	s_add_u32 s0, s24, 0x40080
	s_addc_u32 s1, s25, 0
	s_add_i32 s24, s26, s52
	s_mov_b32 m0, s24
	s_nop 0
	global_load_lds_dwordx4 v26, s[0:1]
	s_add_i32 m0, s24, 0x2000
	s_nop 0
	global_load_lds_dwordx4 v148, s[0:1]
	v_lshl_add_u64 v[218:219], v[224:225], 0, s[12:13]
	s_mov_b32 m0, s31
	s_nop 0
	global_load_lds_dwordx4 v[218:219], off
	v_add_u32_e32 v80, 0x10000, v163
	ds_read_b128 v[68:71], v80
	ds_read_b128 v[72:75], v80 offset:1024
	ds_read_b128 v[76:79], v80 offset:2048
	ds_read_b128 v[80:83], v80 offset:3072
	s_waitcnt vmcnt(8)
	s_setprio 1
	s_barrier
	v_mfma_f32_16x16x32_bf16 v[56:59], v[202:205], v[158:161], v[56:59]
	v_mfma_f32_16x16x32_bf16 v[52:55], v[210:213], v[158:161], v[52:55]
	v_mfma_f32_16x16x32_bf16 v[40:43], v[202:205], v[178:181], v[40:43]
	v_mfma_f32_16x16x32_bf16 v[36:39], v[210:213], v[178:181], v[36:39]
	v_mfma_f32_16x16x32_bf16 v[22:25], v[202:205], v[186:189], v[22:25]
	v_mfma_f32_16x16x32_bf16 v[18:21], v[210:213], v[186:189], v[18:21]
	v_mfma_f32_16x16x32_bf16 v[6:9], v[202:205], v[194:197], v[6:9]
	v_mfma_f32_16x16x32_bf16 v[2:5], v[210:213], v[194:197], v[2:5]
	v_mfma_f32_16x16x32_bf16 v[56:59], v[206:209], v[174:177], v[56:59]
	v_mfma_f32_16x16x32_bf16 v[52:55], v[214:217], v[174:177], v[52:55]
	v_mfma_f32_16x16x32_bf16 v[40:43], v[206:209], v[182:185], v[40:43]
	v_mfma_f32_16x16x32_bf16 v[36:39], v[214:217], v[182:185], v[36:39]
	v_mfma_f32_16x16x32_bf16 v[22:25], v[206:209], v[190:193], v[22:25]
	v_mfma_f32_16x16x32_bf16 v[18:21], v[214:217], v[190:193], v[18:21]
	v_mfma_f32_16x16x32_bf16 v[6:9], v[206:209], v[198:201], v[6:9]
	v_mfma_f32_16x16x32_bf16 v[2:5], v[214:217], v[198:201], v[2:5]
	s_barrier
	s_setprio 0
	s_add_i32 s69, s69, 2
	s_add_u32 s22, s22, 0x100
	s_addc_u32 s23, s23, 0
	s_add_u32 s59, s59, 0x100
	s_addc_u32 s68, s68, 0
	s_cmp_gt_u32 s69, 13
	s_cbranch_scc0 .LBB0_287
	s_waitcnt lgkmcnt(0)
	s_cmpk_gt_i32 s58, 0xff
	s_mov_b64 s[18:19], 0xb000
	s_cbranch_scc1 .LBB0_283
	s_ashr_i32 s0, s58, 5
	s_mul_hi_i32 s19, s0, 0x1600
	s_mul_i32 s18, s0, 0x1600
	s_branch .LBB0_283

.LBB0_361:
	s_add_u32 s28, s26, 0x100
	s_addc_u32 s29, s27, 0
	s_add_i32 s0, 0, 0x10000
	s_cmp_eq_u32 s46, 40
	s_cselect_b32 s35, s45, s29
	s_cselect_b32 s34, s44, s28
	s_cselect_b32 s31, s23, s19
	s_cselect_b32 s30, s22, s18
	s_add_i32 m0, s20, 0xc000
	ds_read_b128 v[172:175], v224
	ds_read_b128 v[176:179], v224 offset:1024
	ds_read_b128 v[180:183], v224 offset:2048
	ds_read_b128 v[184:187], v224 offset:3072
	ds_read_b128 v[188:191], v224 offset:4096
	ds_read_b128 v[192:195], v224 offset:5120
	ds_read_b128 v[196:199], v224 offset:6144
	ds_read_b128 v[200:203], v224 offset:7168
	global_load_lds_dwordx4 v152, s[26:27]
	s_mov_b64 s[100:101], s[26:27]
	s_waitcnt vmcnt(10) lgkmcnt(8)
	s_setprio 1
	s_barrier
	s_waitcnt lgkmcnt(0)
	v_mfma_f32_16x16x32_bf16 v[128:131], v[132:135], v[172:175], v[128:131]
	v_mfma_f32_16x16x32_bf16 v[124:127], v[156:159], v[172:175], v[124:127]
	v_mfma_f32_16x16x32_bf16 v[120:123], v[132:135], v[180:183], v[120:123]
	v_mfma_f32_16x16x32_bf16 v[116:119], v[156:159], v[180:183], v[116:119]
	v_mfma_f32_16x16x32_bf16 v[112:115], v[132:135], v[188:191], v[112:115]
	v_mfma_f32_16x16x32_bf16 v[108:111], v[156:159], v[188:191], v[108:111]
	v_mfma_f32_16x16x32_bf16 v[104:107], v[132:135], v[196:199], v[104:107]
	v_mfma_f32_16x16x32_bf16 v[100:103], v[156:159], v[196:199], v[100:103]
	v_mfma_f32_16x16x32_bf16 v[128:131], v[136:139], v[176:179], v[128:131]
	v_mfma_f32_16x16x32_bf16 v[124:127], v[160:163], v[176:179], v[124:127]
	v_mfma_f32_16x16x32_bf16 v[120:123], v[136:139], v[184:187], v[120:123]
	v_mfma_f32_16x16x32_bf16 v[116:119], v[160:163], v[184:187], v[116:119]
	v_mfma_f32_16x16x32_bf16 v[112:115], v[136:139], v[192:195], v[112:115]
	v_mfma_f32_16x16x32_bf16 v[108:111], v[160:163], v[192:195], v[108:111]
	v_mfma_f32_16x16x32_bf16 v[104:107], v[136:139], v[200:203], v[104:107]
	v_mfma_f32_16x16x32_bf16 v[100:103], v[160:163], v[200:203], v[100:103]
	s_barrier
	s_setprio 0
	s_add_i32 s26, 0, 0x14000
	v_add_u32_e32 v164, s26, v222
	s_add_i32 s0, s0, s17
	ds_read_b128 v[204:207], v164
	ds_read_b128 v[208:211], v164 offset:1024
	ds_read_b128 v[212:215], v164 offset:2048
	ds_read_b128 v[216:219], v164 offset:3072
	v_lshl_add_u64 v[164:165], s[30:31], 0, v[26:27]
	s_mov_b32 m0, s0
	v_lshl_add_u64 v[166:167], s[30:31], 0, v[140:141]
	global_load_lds_dwordx4 v[164:165], off
	s_add_i32 m0, s0, 0x2000
	s_nop 0
	global_load_lds_dwordx4 v[166:167], off
	v_lshl_add_u64 v[238:239], s[100:101], 0, v[154:155]
	s_add_i32 m0, s20, 0xe000
	s_nop 0
	global_load_lds_dwordx4 v[238:239], off
	s_waitcnt vmcnt(8)
	s_setprio 1
	s_barrier
	s_waitcnt lgkmcnt(0)
	v_mfma_f32_16x16x32_bf16 v[64:67], v[204:207], v[172:175], v[64:67]
	v_mfma_f32_16x16x32_bf16 v[60:63], v[212:215], v[172:175], v[60:63]
	v_mfma_f32_16x16x32_bf16 v[56:59], v[204:207], v[180:183], v[56:59]
	v_mfma_f32_16x16x32_bf16 v[52:55], v[212:215], v[180:183], v[52:55]
	v_mfma_f32_16x16x32_bf16 v[48:51], v[204:207], v[188:191], v[48:51]
	v_mfma_f32_16x16x32_bf16 v[44:47], v[212:215], v[188:191], v[44:47]
	v_mfma_f32_16x16x32_bf16 v[40:43], v[204:207], v[196:199], v[40:43]
	v_mfma_f32_16x16x32_bf16 v[36:39], v[212:215], v[196:199], v[36:39]
	v_mfma_f32_16x16x32_bf16 v[64:67], v[208:211], v[176:179], v[64:67]
	v_mfma_f32_16x16x32_bf16 v[60:63], v[216:219], v[176:179], v[60:63]
	v_mfma_f32_16x16x32_bf16 v[56:59], v[208:211], v[184:187], v[56:59]
	v_mfma_f32_16x16x32_bf16 v[52:55], v[216:219], v[184:187], v[52:55]
	v_mfma_f32_16x16x32_bf16 v[48:51], v[208:211], v[192:195], v[48:51]
	v_mfma_f32_16x16x32_bf16 v[44:47], v[216:219], v[192:195], v[44:47]
	v_mfma_f32_16x16x32_bf16 v[40:43], v[208:211], v[200:203], v[40:43]
	v_mfma_f32_16x16x32_bf16 v[36:39], v[216:219], v[200:203], v[36:39]
	s_barrier
	s_setprio 0
	s_mov_b32 m0, s20
	v_lshl_add_u64 v[168:169], s[34:35], 0, v[144:145]
	ds_read_b128 v[172:175], v224 offset:16384
	ds_read_b128 v[176:179], v224 offset:17408
	ds_read_b128 v[180:183], v224 offset:18432
	ds_read_b128 v[184:187], v224 offset:19456
	ds_read_b128 v[188:191], v224 offset:20480
	ds_read_b128 v[192:195], v224 offset:21504
	ds_read_b128 v[196:199], v224 offset:22528
	ds_read_b128 v[200:203], v224 offset:23552
	global_load_lds_dwordx4 v[168:169], off
	s_waitcnt vmcnt(10)
	s_setprio 1
	s_barrier
	s_waitcnt lgkmcnt(0)
	v_mfma_f32_16x16x32_bf16 v[96:99], v[132:135], v[172:175], v[96:99]
	v_mfma_f32_16x16x32_bf16 v[92:95], v[156:159], v[172:175], v[92:95]
	v_mfma_f32_16x16x32_bf16 v[88:91], v[132:135], v[180:183], v[88:91]
	v_mfma_f32_16x16x32_bf16 v[84:87], v[156:159], v[180:183], v[84:87]
	v_mfma_f32_16x16x32_bf16 v[80:83], v[132:135], v[188:191], v[80:83]
	v_mfma_f32_16x16x32_bf16 v[76:79], v[156:159], v[188:191], v[76:79]
	v_mfma_f32_16x16x32_bf16 v[72:75], v[132:135], v[196:199], v[72:75]
	v_mfma_f32_16x16x32_bf16 v[68:71], v[156:159], v[196:199], v[68:71]
	v_mfma_f32_16x16x32_bf16 v[96:99], v[136:139], v[176:179], v[96:99]
	v_mfma_f32_16x16x32_bf16 v[92:95], v[160:163], v[176:179], v[92:95]
	v_mfma_f32_16x16x32_bf16 v[88:91], v[136:139], v[184:187], v[88:91]
	v_mfma_f32_16x16x32_bf16 v[84:87], v[160:163], v[184:187], v[84:87]
	v_mfma_f32_16x16x32_bf16 v[80:83], v[136:139], v[192:195], v[80:83]
	v_mfma_f32_16x16x32_bf16 v[76:79], v[160:163], v[192:195], v[76:79]
	v_mfma_f32_16x16x32_bf16 v[72:75], v[136:139], v[200:203], v[72:75]
	v_mfma_f32_16x16x32_bf16 v[68:71], v[160:163], v[200:203], v[68:71]
	s_barrier
	s_setprio 0
	s_add_u32 s0, s30, 0xb0000
	s_addc_u32 s1, s31, 0
	s_add_i32 s26, s26, s17
	s_mov_b32 m0, s26
	s_nop 0
	global_load_lds_dwordx4 v26, s[0:1]
	s_add_i32 m0, s26, 0x2000
	s_nop 0
	global_load_lds_dwordx4 v140, s[0:1]
	v_lshl_add_u64 v[220:221], s[34:35], 0, v[142:143]
	s_mov_b32 m0, s21
	s_nop 0
	global_load_lds_dwordx4 v[220:221], off
	v_add_u32_e32 v160, 0x18000, v222
	ds_read_b128 v[132:135], v160
	ds_read_b128 v[136:139], v160 offset:1024
	ds_read_b128 v[156:159], v160 offset:2048
	ds_read_b128 v[160:163], v160 offset:3072
	s_waitcnt vmcnt(8)
	s_setprio 1
	s_barrier
	v_mfma_f32_16x16x32_bf16 v[32:35], v[204:207], v[172:175], v[32:35]
	v_mfma_f32_16x16x32_bf16 v[28:31], v[212:215], v[172:175], v[28:31]
	v_mfma_f32_16x16x32_bf16 v[22:25], v[204:207], v[180:183], v[22:25]
	v_mfma_f32_16x16x32_bf16 v[18:21], v[212:215], v[180:183], v[18:21]
	v_mfma_f32_16x16x32_bf16 v[14:17], v[204:207], v[188:191], v[14:17]
	v_mfma_f32_16x16x32_bf16 v[10:13], v[212:215], v[188:191], v[10:13]
	v_mfma_f32_16x16x32_bf16 v[6:9], v[204:207], v[196:199], v[6:9]
	v_mfma_f32_16x16x32_bf16 v[2:5], v[212:215], v[196:199], v[2:5]
	v_mfma_f32_16x16x32_bf16 v[32:35], v[208:211], v[176:179], v[32:35]
	v_mfma_f32_16x16x32_bf16 v[28:31], v[216:219], v[176:179], v[28:31]
	v_mfma_f32_16x16x32_bf16 v[22:25], v[208:211], v[184:187], v[22:25]
	v_mfma_f32_16x16x32_bf16 v[18:21], v[216:219], v[184:187], v[18:21]
	v_mfma_f32_16x16x32_bf16 v[14:17], v[208:211], v[192:195], v[14:17]
	v_mfma_f32_16x16x32_bf16 v[10:13], v[216:219], v[192:195], v[10:13]
	v_mfma_f32_16x16x32_bf16 v[6:9], v[208:211], v[200:203], v[6:9]
	v_mfma_f32_16x16x32_bf16 v[2:5], v[216:219], v[200:203], v[2:5]
	s_barrier
	s_setprio 0
	s_add_i32 s26, 0, 0x18000
	s_add_u32 s0, s34, 0xb0000
	s_addc_u32 s1, s35, 0
	s_mov_b32 m0, s36
	ds_read_b128 v[172:175], v224 offset:32768
	ds_read_b128 v[176:179], v224 offset:33792
	ds_read_b128 v[180:183], v224 offset:34816
	ds_read_b128 v[184:187], v224 offset:35840
	ds_read_b128 v[188:191], v224 offset:36864
	ds_read_b128 v[192:195], v224 offset:37888
	ds_read_b128 v[196:199], v224 offset:38912
	ds_read_b128 v[200:203], v224 offset:39936
	global_load_lds_dwordx4 v144, s[0:1]
	s_mov_b64 s[100:101], s[0:1]
	s_waitcnt vmcnt(10) lgkmcnt(8)
	s_setprio 1
	s_barrier
	s_waitcnt lgkmcnt(0)
	v_mfma_f32_16x16x32_bf16 v[128:131], v[132:135], v[172:175], v[128:131]
	v_mfma_f32_16x16x32_bf16 v[124:127], v[156:159], v[172:175], v[124:127]
	v_mfma_f32_16x16x32_bf16 v[120:123], v[132:135], v[180:183], v[120:123]
	v_mfma_f32_16x16x32_bf16 v[116:119], v[156:159], v[180:183], v[116:119]
	v_mfma_f32_16x16x32_bf16 v[112:115], v[132:135], v[188:191], v[112:115]
	v_mfma_f32_16x16x32_bf16 v[108:111], v[156:159], v[188:191], v[108:111]
	v_mfma_f32_16x16x32_bf16 v[104:107], v[132:135], v[196:199], v[104:107]
	v_mfma_f32_16x16x32_bf16 v[100:103], v[156:159], v[196:199], v[100:103]
	v_mfma_f32_16x16x32_bf16 v[128:131], v[136:139], v[176:179], v[128:131]
	v_mfma_f32_16x16x32_bf16 v[124:127], v[160:163], v[176:179], v[124:127]
	v_mfma_f32_16x16x32_bf16 v[120:123], v[136:139], v[184:187], v[120:123]
	v_mfma_f32_16x16x32_bf16 v[116:119], v[160:163], v[184:187], v[116:119]
	v_mfma_f32_16x16x32_bf16 v[112:115], v[136:139], v[192:195], v[112:115]
	v_mfma_f32_16x16x32_bf16 v[108:111], v[160:163], v[192:195], v[108:111]
	v_mfma_f32_16x16x32_bf16 v[104:107], v[136:139], v[200:203], v[104:107]
	v_mfma_f32_16x16x32_bf16 v[100:103], v[160:163], v[200:203], v[100:103]
	s_barrier
	s_setprio 0
	s_add_i32 s27, 0, 0x1c000
	s_add_i32 s0, s26, s17
	v_add_u32_e32 v216, s27, v222
	v_lshl_add_u64 v[164:165], v[164:165], 0, s[12:13]
	s_mov_b32 m0, s0
	ds_read_b128 v[204:207], v216
	ds_read_b128 v[208:211], v216 offset:1024
	ds_read_b128 v[212:215], v216 offset:2048
	ds_read_b128 v[216:219], v216 offset:3072
	global_load_lds_dwordx4 v[164:165], off
	v_lshl_add_u64 v[164:165], v[166:167], 0, s[12:13]
	s_add_i32 m0, s0, 0x2000
	s_nop 0
	global_load_lds_dwordx4 v[164:165], off
	s_mov_b32 m0, s37
	s_nop 0
	global_load_lds_dwordx4 v142, s[100:101]
	s_waitcnt vmcnt(8)
	s_setprio 1
	s_barrier
	s_waitcnt lgkmcnt(0)
	v_mfma_f32_16x16x32_bf16 v[64:67], v[204:207], v[172:175], v[64:67]
	v_mfma_f32_16x16x32_bf16 v[60:63], v[212:215], v[172:175], v[60:63]
	v_mfma_f32_16x16x32_bf16 v[56:59], v[204:207], v[180:183], v[56:59]
	v_mfma_f32_16x16x32_bf16 v[52:55], v[212:215], v[180:183], v[52:55]
	v_mfma_f32_16x16x32_bf16 v[48:51], v[204:207], v[188:191], v[48:51]
	v_mfma_f32_16x16x32_bf16 v[44:47], v[212:215], v[188:191], v[44:47]
	v_mfma_f32_16x16x32_bf16 v[40:43], v[204:207], v[196:199], v[40:43]
	v_mfma_f32_16x16x32_bf16 v[36:39], v[212:215], v[196:199], v[36:39]
	v_mfma_f32_16x16x32_bf16 v[64:67], v[208:211], v[176:179], v[64:67]
	v_mfma_f32_16x16x32_bf16 v[60:63], v[216:219], v[176:179], v[60:63]
	v_mfma_f32_16x16x32_bf16 v[56:59], v[208:211], v[184:187], v[56:59]
	v_mfma_f32_16x16x32_bf16 v[52:55], v[216:219], v[184:187], v[52:55]
	v_mfma_f32_16x16x32_bf16 v[48:51], v[208:211], v[192:195], v[48:51]
	v_mfma_f32_16x16x32_bf16 v[44:47], v[216:219], v[192:195], v[44:47]
	v_mfma_f32_16x16x32_bf16 v[40:43], v[208:211], v[200:203], v[40:43]
	v_mfma_f32_16x16x32_bf16 v[36:39], v[216:219], v[200:203], v[36:39]
	s_barrier
	s_setprio 0
	s_mov_b32 m0, s59
	v_lshl_add_u64 v[164:165], v[168:169], 0, s[12:13]
	ds_read_b128 v[172:175], v224 offset:49152
	ds_read_b128 v[176:179], v224 offset:50176
	ds_read_b128 v[180:183], v224 offset:51200
	ds_read_b128 v[184:187], v224 offset:52224
	ds_read_b128 v[188:191], v224 offset:53248
	ds_read_b128 v[192:195], v224 offset:54272
	ds_read_b128 v[196:199], v224 offset:55296
	ds_read_b128 v[200:203], v224 offset:56320
	global_load_lds_dwordx4 v[164:165], off
	s_waitcnt vmcnt(10)
	s_setprio 1
	s_barrier
	s_waitcnt lgkmcnt(0)
	v_mfma_f32_16x16x32_bf16 v[96:99], v[132:135], v[172:175], v[96:99]
	v_mfma_f32_16x16x32_bf16 v[92:95], v[156:159], v[172:175], v[92:95]
	v_mfma_f32_16x16x32_bf16 v[88:91], v[132:135], v[180:183], v[88:91]
	v_mfma_f32_16x16x32_bf16 v[84:87], v[156:159], v[180:183], v[84:87]
	v_mfma_f32_16x16x32_bf16 v[80:83], v[132:135], v[188:191], v[80:83]
	v_mfma_f32_16x16x32_bf16 v[76:79], v[156:159], v[188:191], v[76:79]
	v_mfma_f32_16x16x32_bf16 v[72:75], v[132:135], v[196:199], v[72:75]
	v_mfma_f32_16x16x32_bf16 v[68:71], v[156:159], v[196:199], v[68:71]
	v_mfma_f32_16x16x32_bf16 v[96:99], v[136:139], v[176:179], v[96:99]
	v_mfma_f32_16x16x32_bf16 v[92:95], v[160:163], v[176:179], v[92:95]
	v_mfma_f32_16x16x32_bf16 v[88:91], v[136:139], v[184:187], v[88:91]
	v_mfma_f32_16x16x32_bf16 v[84:87], v[160:163], v[184:187], v[84:87]
	v_mfma_f32_16x16x32_bf16 v[80:83], v[136:139], v[192:195], v[80:83]
	v_mfma_f32_16x16x32_bf16 v[76:79], v[160:163], v[192:195], v[76:79]
	v_mfma_f32_16x16x32_bf16 v[72:75], v[136:139], v[200:203], v[72:75]
	v_mfma_f32_16x16x32_bf16 v[68:71], v[160:163], v[200:203], v[68:71]
	s_barrier
	s_setprio 0
	s_add_u32 s0, s30, 0xb0080
	s_addc_u32 s1, s31, 0
	s_add_i32 s26, s27, s17
	s_mov_b32 m0, s26
	s_nop 0
	global_load_lds_dwordx4 v26, s[0:1]
	s_add_i32 m0, s26, 0x2000
	s_nop 0
	global_load_lds_dwordx4 v140, s[0:1]
	v_lshl_add_u64 v[164:165], v[220:221], 0, s[12:13]
	s_mov_b32 m0, s68
	s_nop 0
	global_load_lds_dwordx4 v[164:165], off
	v_add_u32_e32 v160, 0x10000, v222
	ds_read_b128 v[132:135], v160
	ds_read_b128 v[136:139], v160 offset:1024
	ds_read_b128 v[156:159], v160 offset:2048
	ds_read_b128 v[160:163], v160 offset:3072
	s_waitcnt vmcnt(8)
	s_setprio 1
	s_barrier
	v_mfma_f32_16x16x32_bf16 v[32:35], v[204:207], v[172:175], v[32:35]
	v_mfma_f32_16x16x32_bf16 v[28:31], v[212:215], v[172:175], v[28:31]
	v_mfma_f32_16x16x32_bf16 v[22:25], v[204:207], v[180:183], v[22:25]
	v_mfma_f32_16x16x32_bf16 v[18:21], v[212:215], v[180:183], v[18:21]
	v_mfma_f32_16x16x32_bf16 v[14:17], v[204:207], v[188:191], v[14:17]
	v_mfma_f32_16x16x32_bf16 v[10:13], v[212:215], v[188:191], v[10:13]
	v_mfma_f32_16x16x32_bf16 v[6:9], v[204:207], v[196:199], v[6:9]
	v_mfma_f32_16x16x32_bf16 v[2:5], v[212:215], v[196:199], v[2:5]
	v_mfma_f32_16x16x32_bf16 v[32:35], v[208:211], v[176:179], v[32:35]
	v_mfma_f32_16x16x32_bf16 v[28:31], v[216:219], v[176:179], v[28:31]
	v_mfma_f32_16x16x32_bf16 v[22:25], v[208:211], v[184:187], v[22:25]
	v_mfma_f32_16x16x32_bf16 v[18:21], v[216:219], v[184:187], v[18:21]
	v_mfma_f32_16x16x32_bf16 v[14:17], v[208:211], v[192:195], v[14:17]
	v_mfma_f32_16x16x32_bf16 v[10:13], v[216:219], v[192:195], v[10:13]
	v_mfma_f32_16x16x32_bf16 v[6:9], v[208:211], v[200:203], v[6:9]
	v_mfma_f32_16x16x32_bf16 v[2:5], v[216:219], v[200:203], v[2:5]
	s_barrier
	s_setprio 0
	s_add_i32 s46, s46, 2
	s_add_u32 s18, s18, 0x100
	s_addc_u32 s19, s19, 0
	s_cmp_gt_u32 s46, 41
	s_mov_b64 s[26:27], s[28:29]
	s_cbranch_scc0 .LBB0_361
	s_waitcnt lgkmcnt(0)
	s_min_i32 s0, s24, 0x100
	s_ashr_i32 s0, s0, 5
	s_ashr_i32 s1, s0, 31
	s_add_i32 s18, s24, 0xffffff00
	s_cmpk_lt_i32 s24, 0x100
	s_cselect_b32 s18, s24, s18
	s_cselect_b32 s27, 0, s58
	s_cselect_b32 s26, 0, s57
	s_ashr_i32 s19, s18, 31
	s_lshl_b64 s[18:19], s[18:19], 19
	s_add_u32 s26, s50, s26
	v_lshl_or_b32 v178, s25, 8, v223
	s_addc_u32 s27, s51, s27
	s_ashr_i32 s25, s24, 31
	v_lshl_add_u64 v[132:133], s[18:19], 0, v[146:147]
	s_lshl_b64 s[18:19], s[24:25], 19
	v_lshl_add_u64 v[184:185], v[148:149], 0, s[18:19]
	s_lshl_b64 s[24:25], s[24:25], 10
	s_mul_i32 s18, s0, 0x9000
	v_ashrrev_i32_e32 v179, 31, v178
	s_mul_hi_i32 s19, s0, 0x9000
	s_add_u32 s18, s48, s18
	s_addc_u32 s19, s49, s19
	v_lshlrev_b64 v[186:187], 2, v[178:179]
	v_lshl_add_u64 v[156:157], s[18:19], 0, v[186:187]
	v_lshl_add_u64 v[180:181], v[132:133], 0, v[178:179]
	v_lshl_add_u64 v[182:183], v[132:133], 1, s[26:27]
	global_load_dwordx4 v[132:135], v[156:157], off offset:16
	global_load_dwordx4 v[136:139], v[156:157], off
	s_lshl_b64 s[0:1], s[0:1], 12
	s_add_u32 s28, s52, s0
	s_addc_u32 s29, s53, s1
	v_lshl_add_u64 v[196:197], v[180:181], 1, s[26:27]
	v_lshl_add_u64 v[180:181], s[28:29], 0, v[186:187]
	v_add_co_u32_e32 v210, vcc, s65, v196
	v_lshlrev_b64 v[188:189], 1, v[178:179]
	s_nop 0
	v_addc_co_u32_e32 v211, vcc, 0, v197, vcc
	s_mov_b32 s1, 0x20000
	v_lshl_add_u64 v[178:179], v[184:185], 0, v[188:189]
	v_add_co_u32_e32 v184, vcc, s1, v196
	s_mov_b32 s18, 0x30000
	s_nop 0
	v_addc_co_u32_e32 v185, vcc, 0, v197, vcc
	v_lshl_add_u64 v[182:183], v[182:183], 0, v[188:189]
	v_add_co_u32_e32 v188, vcc, s18, v196
	s_mov_b32 s0, 0x8000
	s_nop 0
	v_addc_co_u32_e32 v189, vcc, 0, v197, vcc
	s_mov_b32 s19, 0x80000
	s_mov_b32 s26, 0x90000
	s_waitcnt vmcnt(0)
	v_pk_mul_f32 v[172:173], v[134:135], 0.5 op_sel_hi:[1,0]
	v_pk_mul_f32 v[176:177], v[138:139], 0.5 op_sel_hi:[1,0]
	v_pk_mul_f32 v[174:175], v[136:137], 0.5 op_sel_hi:[1,0]
	v_pk_mul_f32 v[164:165], v[132:133], 0.5 op_sel_hi:[1,0]
	global_load_dwordx4 v[132:135], v[156:157], off offset:528
	global_load_dwordx4 v[136:139], v[156:157], off offset:512
	s_waitcnt vmcnt(0)
	v_pk_mul_f32 v[158:159], v[134:135], 0.5 op_sel_hi:[1,0]
	v_pk_mul_f32 v[162:163], v[138:139], 0.5 op_sel_hi:[1,0]
	v_pk_mul_f32 v[160:161], v[136:137], 0.5 op_sel_hi:[1,0]
	v_pk_mul_f32 v[156:157], v[132:133], 0.5 op_sel_hi:[1,0]
	global_load_dwordx4 v[132:135], v[180:181], off offset:16
	global_load_dwordx4 v[136:139], v[180:181], off
	global_load_dwordx4 v[190:193], v[196:197], off offset:2048
	global_load_dwordx4 v[198:201], v[210:211], off offset:2048
	global_load_dwordx4 v[202:205], v[184:185], off offset:2048
	global_load_dwordx4 v[206:209], v[188:189], off offset:2048
	s_waitcnt vmcnt(0)
	v_lshlrev_b32_e32 v186, 16, v190
	v_and_b32_e32 v187, 0xffff0000, v190
	v_lshlrev_b32_e32 v190, 16, v191
	v_and_b32_e32 v191, 0xffff0000, v191
	v_lshlrev_b32_e32 v194, 16, v192
	v_and_b32_e32 v195, 0xffff0000, v192
	v_lshlrev_b32_e32 v192, 16, v193
	v_and_b32_e32 v193, 0xffff0000, v193
	v_pk_fma_f32 v[130:131], v[130:131], v[176:177], v[190:191]
	v_pk_fma_f32 v[128:129], v[128:129], v[174:175], v[186:187]
	v_pk_fma_f32 v[126:127], v[126:127], v[172:173], v[192:193]
	v_pk_fma_f32 v[124:125], v[124:125], v[164:165], v[194:195]
	v_cvt_pk_bf16_f32 v190, v128, v129
	v_cvt_pk_bf16_f32 v191, v130, v131
	v_cvt_pk_bf16_f32 v192, v124, v125
	v_cvt_pk_bf16_f32 v193, v126, v127
	v_lshlrev_b32_e32 v130, 16, v190
	v_and_b32_e32 v131, 0xffff0000, v190
	v_lshlrev_b32_e32 v128, 16, v191
	v_and_b32_e32 v129, 0xffff0000, v191
	v_lshlrev_b32_e32 v126, 16, v192
	v_and_b32_e32 v127, 0xffff0000, v192
	v_lshlrev_b32_e32 v124, 16, v193
	v_and_b32_e32 v125, 0xffff0000, v193
	v_lshlrev_b32_e32 v212, 16, v198
	v_and_b32_e32 v213, 0xffff0000, v198
	v_lshlrev_b32_e32 v198, 16, v199
	v_and_b32_e32 v199, 0xffff0000, v199
	global_store_dwordx4 v[182:183], v[190:193], off offset:2048
	v_pk_mul_f32 v[186:187], v[138:139], v[128:129]
	v_pk_mul_f32 v[194:195], v[134:135], v[124:125]
	v_pk_mul_f32 v[190:191], v[136:137], v[130:131]
	v_pk_mul_f32 v[192:193], v[132:133], v[126:127]
	v_lshlrev_b32_e32 v214, 16, v200
	v_and_b32_e32 v215, 0xffff0000, v200
	v_lshlrev_b32_e32 v200, 16, v201
	v_and_b32_e32 v201, 0xffff0000, v201
	v_cvt_pk_bf16_f32 v190, v190, v191
	v_cvt_pk_bf16_f32 v191, v186, v187
	v_cvt_pk_bf16_f32 v192, v192, v193
	v_cvt_pk_bf16_f32 v193, v194, v195
	v_pk_fma_f32 v[122:123], v[122:123], v[176:177], v[198:199]
	v_pk_fma_f32 v[120:121], v[120:121], v[174:175], v[212:213]
	global_store_dwordx4 v[178:179], v[190:193], off
	v_pk_fma_f32 v[118:119], v[118:119], v[172:173], v[200:201]
	v_pk_fma_f32 v[116:117], v[116:117], v[164:165], v[214:215]
	v_cvt_pk_bf16_f32 v190, v120, v121
	v_cvt_pk_bf16_f32 v191, v122, v123
	v_add_co_u32_e32 v186, vcc, s65, v182
	v_cvt_pk_bf16_f32 v192, v116, v117
	v_cvt_pk_bf16_f32 v193, v118, v119
	v_addc_co_u32_e32 v187, vcc, 0, v183, vcc
	v_lshlrev_b32_e32 v122, 16, v190
	v_and_b32_e32 v123, 0xffff0000, v190
	v_lshlrev_b32_e32 v120, 16, v191
	v_and_b32_e32 v121, 0xffff0000, v191
	global_store_dwordx4 v[186:187], v[190:193], off offset:2048
	v_lshlrev_b32_e32 v118, 16, v192
	v_and_b32_e32 v119, 0xffff0000, v192
	v_lshlrev_b32_e32 v116, 16, v193
	v_and_b32_e32 v117, 0xffff0000, v193
	v_pk_mul_f32 v[190:191], v[138:139], v[120:121]
	v_pk_mul_f32 v[192:193], v[136:137], v[122:123]
	v_pk_mul_f32 v[198:199], v[134:135], v[116:117]
	v_pk_mul_f32 v[194:195], v[132:133], v[118:119]
	v_cvt_pk_bf16_f32 v192, v192, v193
	v_cvt_pk_bf16_f32 v193, v190, v191
	v_add_co_u32_e32 v190, vcc, s0, v178
	v_cvt_pk_bf16_f32 v194, v194, v195
	v_cvt_pk_bf16_f32 v195, v198, v199
	v_addc_co_u32_e32 v191, vcc, 0, v179, vcc
	global_store_dwordx4 v[190:191], v[192:195], off
	v_lshlrev_b32_e32 v198, 16, v202
	v_and_b32_e32 v199, 0xffff0000, v202
	v_add_co_u32_e32 v192, vcc, s19, v196
	v_lshlrev_b32_e32 v200, 16, v203
	s_nop 0
	v_addc_co_u32_e32 v193, vcc, 0, v197, vcc
	v_add_co_u32_e32 v194, vcc, s26, v196
	v_and_b32_e32 v201, 0xffff0000, v203
	global_load_dwordx4 v[212:215], v[192:193], off offset:2048
	v_addc_co_u32_e32 v195, vcc, 0, v197, vcc
	v_lshlrev_b32_e32 v202, 16, v204
	v_and_b32_e32 v203, 0xffff0000, v204
	v_lshlrev_b32_e32 v204, 16, v205
	v_and_b32_e32 v205, 0xffff0000, v205
	v_pk_fma_f32 v[114:115], v[114:115], v[176:177], v[200:201]
	v_pk_fma_f32 v[112:113], v[112:113], v[174:175], v[198:199]
	v_pk_fma_f32 v[110:111], v[110:111], v[172:173], v[204:205]
	v_pk_fma_f32 v[108:109], v[108:109], v[164:165], v[202:203]
	v_cvt_pk_bf16_f32 v200, v112, v113
	v_cvt_pk_bf16_f32 v201, v114, v115
	v_add_co_u32_e32 v198, vcc, s1, v182
	v_cvt_pk_bf16_f32 v202, v108, v109
	v_cvt_pk_bf16_f32 v203, v110, v111
	v_addc_co_u32_e32 v199, vcc, 0, v183, vcc
	v_lshlrev_b32_e32 v114, 16, v200
	v_and_b32_e32 v115, 0xffff0000, v200
	v_lshlrev_b32_e32 v112, 16, v201
	v_and_b32_e32 v113, 0xffff0000, v201
	global_load_dwordx4 v[216:219], v[194:195], off offset:2048
	v_lshlrev_b32_e32 v110, 16, v202
	global_store_dwordx4 v[198:199], v[200:203], off offset:2048
	v_and_b32_e32 v111, 0xffff0000, v202
	v_lshlrev_b32_e32 v108, 16, v203
	v_and_b32_e32 v109, 0xffff0000, v203
	v_pk_mul_f32 v[200:201], v[138:139], v[112:113]
	v_pk_mul_f32 v[202:203], v[136:137], v[114:115]
	v_lshlrev_b32_e32 v220, 16, v206
	v_and_b32_e32 v221, 0xffff0000, v206
	v_lshlrev_b32_e32 v206, 16, v207
	v_and_b32_e32 v207, 0xffff0000, v207
	v_pk_mul_f32 v[238:239], v[134:135], v[108:109]
	v_pk_mul_f32 v[204:205], v[132:133], v[110:111]
	v_cvt_pk_bf16_f32 v202, v202, v203
	v_cvt_pk_bf16_f32 v203, v200, v201
	v_add_co_u32_e32 v200, vcc, s65, v178
	v_lshlrev_b32_e32 v234, 16, v208
	v_and_b32_e32 v235, 0xffff0000, v208
	v_lshlrev_b32_e32 v208, 16, v209
	v_and_b32_e32 v209, 0xffff0000, v209
	v_cvt_pk_bf16_f32 v204, v204, v205
	v_cvt_pk_bf16_f32 v205, v238, v239
	v_addc_co_u32_e32 v201, vcc, 0, v179, vcc
	v_pk_fma_f32 v[106:107], v[106:107], v[176:177], v[206:207]
	v_pk_fma_f32 v[104:105], v[104:105], v[174:175], v[220:221]
	global_store_dwordx4 v[200:201], v[202:205], off
	v_pk_fma_f32 v[102:103], v[102:103], v[172:173], v[208:209]
	v_pk_fma_f32 v[100:101], v[100:101], v[164:165], v[234:235]
	v_cvt_pk_bf16_f32 v204, v104, v105
	v_cvt_pk_bf16_f32 v205, v106, v107
	v_add_co_u32_e32 v202, vcc, s18, v182
	v_cvt_pk_bf16_f32 v206, v100, v101
	v_cvt_pk_bf16_f32 v207, v102, v103
	v_addc_co_u32_e32 v203, vcc, 0, v183, vcc
	v_lshlrev_b32_e32 v106, 16, v204
	v_and_b32_e32 v107, 0xffff0000, v204
	v_lshlrev_b32_e32 v104, 16, v205
	v_and_b32_e32 v105, 0xffff0000, v205
	global_store_dwordx4 v[202:203], v[204:207], off offset:2048
	v_lshlrev_b32_e32 v102, 16, v206
	v_and_b32_e32 v103, 0xffff0000, v206
	v_lshlrev_b32_e32 v100, 16, v207
	v_and_b32_e32 v101, 0xffff0000, v207
	v_pk_mul_f32 v[204:205], v[138:139], v[104:105]
	v_pk_mul_f32 v[206:207], v[136:137], v[106:107]
	s_mov_b32 s0, 0x18000
	v_pk_mul_f32 v[220:221], v[134:135], v[100:101]
	v_pk_mul_f32 v[208:209], v[132:133], v[102:103]
	v_cvt_pk_bf16_f32 v206, v206, v207
	v_cvt_pk_bf16_f32 v207, v204, v205
	v_add_co_u32_e32 v204, vcc, s0, v178
	v_cvt_pk_bf16_f32 v208, v208, v209
	v_cvt_pk_bf16_f32 v209, v220, v221
	v_addc_co_u32_e32 v205, vcc, 0, v179, vcc
	global_store_dwordx4 v[204:205], v[206:209], off
	s_mov_b32 s0, 0xb0000
	s_waitcnt vmcnt(0)
	v_lshlrev_b32_e32 v220, 16, v212
	v_add_co_u32_e32 v206, vcc, s76, v196
	v_and_b32_e32 v221, 0xffff0000, v212
	s_nop 0
	v_addc_co_u32_e32 v207, vcc, 0, v197, vcc
	global_load_dwordx4 v[238:241], v[206:207], off offset:2048
	v_add_co_u32_e32 v208, vcc, s0, v196
	v_lshlrev_b32_e32 v212, 16, v213
	s_nop 0
	v_addc_co_u32_e32 v209, vcc, 0, v197, vcc
	global_load_dwordx4 v[242:245], v[208:209], off offset:2048
	v_and_b32_e32 v213, 0xffff0000, v213
	v_lshlrev_b32_e32 v234, 16, v214
	v_and_b32_e32 v235, 0xffff0000, v214
	v_lshlrev_b32_e32 v214, 16, v215
	v_and_b32_e32 v215, 0xffff0000, v215
	v_pk_fma_f32 v[98:99], v[98:99], v[176:177], v[212:213]
	v_pk_fma_f32 v[96:97], v[96:97], v[174:175], v[220:221]
	v_pk_fma_f32 v[94:95], v[94:95], v[172:173], v[214:215]
	v_pk_fma_f32 v[92:93], v[92:93], v[164:165], v[234:235]
	v_cvt_pk_bf16_f32 v214, v96, v97
	v_cvt_pk_bf16_f32 v215, v98, v99
	v_add_co_u32_e32 v212, vcc, s19, v182
	v_lshlrev_b32_e32 v246, 16, v216
	v_and_b32_e32 v247, 0xffff0000, v216
	v_lshlrev_b32_e32 v248, 16, v217
	v_and_b32_e32 v249, 0xffff0000, v217
	v_cvt_pk_bf16_f32 v216, v92, v93
	v_cvt_pk_bf16_f32 v217, v94, v95
	v_addc_co_u32_e32 v213, vcc, 0, v183, vcc
	v_lshlrev_b32_e32 v98, 16, v214
	v_and_b32_e32 v99, 0xffff0000, v214
	v_lshlrev_b32_e32 v96, 16, v215
	v_and_b32_e32 v97, 0xffff0000, v215
	global_store_dwordx4 v[212:213], v[214:217], off offset:2048
	v_lshlrev_b32_e32 v94, 16, v216
	v_and_b32_e32 v95, 0xffff0000, v216
	v_lshlrev_b32_e32 v92, 16, v217
	v_and_b32_e32 v93, 0xffff0000, v217
	v_pk_mul_f32 v[214:215], v[138:139], v[96:97]
	v_pk_mul_f32 v[216:217], v[136:137], v[98:99]
	s_mov_b32 s1, 0x40000
	v_lshlrev_b32_e32 v250, 16, v218
	v_and_b32_e32 v251, 0xffff0000, v218
	v_lshlrev_b32_e32 v252, 16, v219
	v_and_b32_e32 v253, 0xffff0000, v219
	v_pk_mul_f32 v[220:221], v[134:135], v[92:93]
	v_pk_mul_f32 v[218:219], v[132:133], v[94:95]
	v_cvt_pk_bf16_f32 v216, v216, v217
	v_cvt_pk_bf16_f32 v217, v214, v215
	v_add_co_u32_e32 v214, vcc, s1, v178
	v_cvt_pk_bf16_f32 v218, v218, v219
	v_cvt_pk_bf16_f32 v219, v220, v221
	v_addc_co_u32_e32 v215, vcc, 0, v179, vcc
	v_pk_fma_f32 v[90:91], v[90:91], v[176:177], v[248:249]
	global_store_dwordx4 v[214:215], v[216:219], off
	v_pk_fma_f32 v[88:89], v[88:89], v[174:175], v[246:247]
	v_pk_fma_f32 v[86:87], v[86:87], v[172:173], v[252:253]
	v_pk_fma_f32 v[84:85], v[84:85], v[164:165], v[250:251]
	v_cvt_pk_bf16_f32 v219, v90, v91
	v_add_co_u32_e32 v216, vcc, s26, v182
	v_cvt_pk_bf16_f32 v218, v88, v89
	v_cvt_pk_bf16_f32 v220, v84, v85
	v_cvt_pk_bf16_f32 v221, v86, v87
	v_addc_co_u32_e32 v217, vcc, 0, v183, vcc
	v_lshlrev_b32_e32 v88, 16, v219
	v_and_b32_e32 v89, 0xffff0000, v219
	global_store_dwordx4 v[216:217], v[218:221], off offset:2048
	v_lshlrev_b32_e32 v90, 16, v218
	v_and_b32_e32 v91, 0xffff0000, v218
	v_lshlrev_b32_e32 v86, 16, v220
	v_and_b32_e32 v87, 0xffff0000, v220
	v_lshlrev_b32_e32 v84, 16, v221
	v_and_b32_e32 v85, 0xffff0000, v221
	v_pk_mul_f32 v[218:219], v[138:139], v[88:89]
	s_mov_b32 s1, 0x48000
	v_pk_mul_f32 v[220:221], v[136:137], v[90:91]
	v_pk_mul_f32 v[234:235], v[134:135], v[84:85]
	v_pk_mul_f32 v[248:249], v[132:133], v[86:87]
	v_cvt_pk_bf16_f32 v247, v218, v219
	v_add_co_u32_e32 v218, vcc, s1, v178
	v_cvt_pk_bf16_f32 v246, v220, v221
	v_cvt_pk_bf16_f32 v248, v248, v249
	v_cvt_pk_bf16_f32 v249, v234, v235
	v_addc_co_u32_e32 v219, vcc, 0, v179, vcc
	global_store_dwordx4 v[218:219], v[246:249], off
	global_load_dwordx4 v[246:249], v[196:197], off offset:2304
	s_nop 0
	global_load_dwordx4 v[250:253], v[210:211], off offset:2304
	s_waitcnt vmcnt(0)
	v_lshlrev_b32_e32 v210, 16, v239
	v_and_b32_e32 v211, 0xffff0000, v239
	v_lshlrev_b32_e32 v196, 16, v238
	v_and_b32_e32 v197, 0xffff0000, v238
	v_pk_fma_f32 v[82:83], v[82:83], v[176:177], v[210:211]
	v_lshlrev_b32_e32 v220, 16, v240
	v_and_b32_e32 v221, 0xffff0000, v240
	v_lshlrev_b32_e32 v234, 16, v241
	v_and_b32_e32 v235, 0xffff0000, v241
	v_pk_fma_f32 v[80:81], v[80:81], v[174:175], v[196:197]
	v_cvt_pk_bf16_f32 v239, v82, v83
	v_pk_fma_f32 v[78:79], v[78:79], v[172:173], v[234:235]
	v_pk_fma_f32 v[76:77], v[76:77], v[164:165], v[220:221]
	v_cvt_pk_bf16_f32 v238, v80, v81
	v_add_co_u32_e32 v196, vcc, s76, v182
	v_lshlrev_b32_e32 v80, 16, v239
	v_and_b32_e32 v81, 0xffff0000, v239
	v_cvt_pk_bf16_f32 v240, v76, v77
	v_cvt_pk_bf16_f32 v241, v78, v79
	v_addc_co_u32_e32 v197, vcc, 0, v183, vcc
	v_pk_mul_f32 v[210:211], v[138:139], v[80:81]
	v_lshlrev_b32_e32 v166, 16, v242
	v_and_b32_e32 v167, 0xffff0000, v242
	v_lshlrev_b32_e32 v242, 16, v243
	v_and_b32_e32 v243, 0xffff0000, v243
	v_lshlrev_b32_e32 v168, 16, v244
	v_and_b32_e32 v169, 0xffff0000, v244
	v_lshlrev_b32_e32 v244, 16, v245
	v_and_b32_e32 v245, 0xffff0000, v245
	global_store_dwordx4 v[196:197], v[238:241], off offset:2048
	v_lshlrev_b32_e32 v82, 16, v238
	v_and_b32_e32 v83, 0xffff0000, v238
	v_cvt_pk_bf16_f32 v239, v210, v211
	v_add_co_u32_e32 v210, vcc, s77, v178
	v_lshlrev_b32_e32 v78, 16, v240
	v_and_b32_e32 v79, 0xffff0000, v240
	v_lshlrev_b32_e32 v76, 16, v241
	v_and_b32_e32 v77, 0xffff0000, v241
	v_pk_mul_f32 v[220:221], v[136:137], v[82:83]
	v_addc_co_u32_e32 v211, vcc, 0, v179, vcc
	v_pk_fma_f32 v[74:75], v[74:75], v[176:177], v[242:243]
	v_pk_fma_f32 v[72:73], v[72:73], v[174:175], v[166:167]
	v_pk_fma_f32 v[166:167], v[70:71], v[172:173], v[244:245]
	v_pk_fma_f32 v[70:71], v[68:69], v[164:165], v[168:169]
	v_pk_mul_f32 v[234:235], v[134:135], v[76:77]
	v_pk_mul_f32 v[240:241], v[132:133], v[78:79]
	v_cvt_pk_bf16_f32 v238, v220, v221
	v_cvt_pk_bf16_f32 v68, v72, v73
	v_cvt_pk_bf16_f32 v69, v74, v75
	v_cvt_pk_bf16_f32 v70, v70, v71
	v_cvt_pk_bf16_f32 v71, v166, v167
	v_add_co_u32_e32 v220, vcc, s0, v182
	v_cvt_pk_bf16_f32 v240, v240, v241
	v_cvt_pk_bf16_f32 v241, v234, v235
	v_addc_co_u32_e32 v221, vcc, 0, v183, vcc
	v_lshlrev_b32_e32 v176, 16, v68
	v_and_b32_e32 v177, 0xffff0000, v68
	v_lshlrev_b32_e32 v174, 16, v69
	v_and_b32_e32 v175, 0xffff0000, v69
	v_lshlrev_b32_e32 v172, 16, v70
	v_and_b32_e32 v173, 0xffff0000, v70
	v_lshlrev_b32_e32 v164, 16, v71
	v_and_b32_e32 v165, 0xffff0000, v71
	s_mov_b32 s0, 0x58000
	global_store_dwordx4 v[210:211], v[238:241], off
	global_store_dwordx4 v[220:221], v[68:71], off offset:2048
	v_pk_mul_f32 v[72:73], v[134:135], v[164:165]
	v_pk_mul_f32 v[74:75], v[132:133], v[172:173]
	v_pk_mul_f32 v[70:71], v[138:139], v[174:175]
	v_pk_mul_f32 v[68:69], v[136:137], v[176:177]
	v_add_co_u32_e32 v132, vcc, s0, v178
	v_cvt_pk_bf16_f32 v68, v68, v69
	v_cvt_pk_bf16_f32 v69, v70, v71
	v_cvt_pk_bf16_f32 v70, v74, v75
	v_cvt_pk_bf16_f32 v71, v72, v73
	v_addc_co_u32_e32 v133, vcc, 0, v179, vcc
	global_store_dwordx4 v[132:133], v[68:71], off
	global_load_dwordx4 v[134:137], v[184:185], off offset:2304
	global_load_dwordx4 v[238:241], v[188:189], off offset:2304
	s_nop 0
	global_load_dwordx4 v[68:71], v[180:181], off offset:528
	global_load_dwordx4 v[72:75], v[180:181], off offset:512
	v_lshlrev_b32_e32 v138, 16, v246
	v_and_b32_e32 v139, 0xffff0000, v246
	v_lshlrev_b32_e32 v166, 16, v247
	v_and_b32_e32 v167, 0xffff0000, v247
	v_lshlrev_b32_e32 v168, 16, v248
	v_and_b32_e32 v169, 0xffff0000, v248
	v_lshlrev_b32_e32 v180, 16, v249
	v_and_b32_e32 v181, 0xffff0000, v249
	v_pk_fma_f32 v[66:67], v[66:67], v[162:163], v[166:167]
	v_pk_fma_f32 v[64:65], v[64:65], v[160:161], v[138:139]
	v_pk_fma_f32 v[62:63], v[62:63], v[158:159], v[180:181]
	v_pk_fma_f32 v[60:61], v[60:61], v[156:157], v[168:169]
	v_cvt_pk_bf16_f32 v242, v64, v65
	v_cvt_pk_bf16_f32 v243, v66, v67
	v_cvt_pk_bf16_f32 v244, v60, v61
	v_cvt_pk_bf16_f32 v245, v62, v63
	v_lshlrev_b32_e32 v66, 16, v242
	v_and_b32_e32 v67, 0xffff0000, v242
	v_lshlrev_b32_e32 v64, 16, v243
	v_and_b32_e32 v65, 0xffff0000, v243
	v_lshlrev_b32_e32 v62, 16, v244
	v_and_b32_e32 v63, 0xffff0000, v244
	v_lshlrev_b32_e32 v60, 16, v245
	v_and_b32_e32 v61, 0xffff0000, v245
	v_lshlrev_b32_e32 v184, 16, v250
	v_and_b32_e32 v185, 0xffff0000, v250
	v_lshlrev_b32_e32 v188, 16, v251
	v_and_b32_e32 v189, 0xffff0000, v251
	v_lshlrev_b32_e32 v234, 16, v252
	v_and_b32_e32 v235, 0xffff0000, v252
	v_lshlrev_b32_e32 v246, 16, v253
	v_and_b32_e32 v247, 0xffff0000, v253
	global_store_dwordx4 v[182:183], v[242:245], off offset:2304
	v_pk_fma_f32 v[58:59], v[58:59], v[162:163], v[188:189]
	v_pk_fma_f32 v[56:57], v[56:57], v[160:161], v[184:185]
	v_pk_fma_f32 v[54:55], v[54:55], v[158:159], v[246:247]
	v_pk_fma_f32 v[52:53], v[52:53], v[156:157], v[234:235]
	s_waitcnt vmcnt(0)
	v_lshlrev_b32_e32 v188, 16, v240
	v_pk_mul_f32 v[168:169], v[70:71], v[60:61]
	v_pk_mul_f32 v[138:139], v[74:75], v[64:65]
	v_pk_mul_f32 v[166:167], v[72:73], v[66:67]
	v_pk_mul_f32 v[182:183], v[68:69], v[62:63]
	v_cvt_pk_bf16_f32 v180, v166, v167
	v_cvt_pk_bf16_f32 v181, v138, v139
	v_cvt_pk_bf16_f32 v182, v182, v183
	v_cvt_pk_bf16_f32 v183, v168, v169
	global_store_dwordx4 v[178:179], v[180:183], off offset:256
	v_cvt_pk_bf16_f32 v178, v56, v57
	v_cvt_pk_bf16_f32 v179, v58, v59
	v_cvt_pk_bf16_f32 v180, v52, v53
	v_cvt_pk_bf16_f32 v181, v54, v55
	v_lshlrev_b32_e32 v58, 16, v178
	v_and_b32_e32 v59, 0xffff0000, v178
	v_lshlrev_b32_e32 v56, 16, v179
	v_and_b32_e32 v57, 0xffff0000, v179
	v_lshlrev_b32_e32 v54, 16, v180
	v_and_b32_e32 v55, 0xffff0000, v180
	v_lshlrev_b32_e32 v52, 16, v181
	v_and_b32_e32 v53, 0xffff0000, v181
	global_store_dwordx4 v[186:187], v[178:181], off offset:2304
	v_pk_mul_f32 v[138:139], v[74:75], v[56:57]
	v_pk_mul_f32 v[166:167], v[72:73], v[58:59]
	v_pk_mul_f32 v[168:169], v[70:71], v[52:53]
	v_pk_mul_f32 v[180:181], v[68:69], v[54:55]
	v_cvt_pk_bf16_f32 v178, v166, v167
	v_cvt_pk_bf16_f32 v179, v138, v139
	v_cvt_pk_bf16_f32 v180, v180, v181
	v_cvt_pk_bf16_f32 v181, v168, v169
	v_lshlrev_b32_e32 v138, 16, v134
	v_and_b32_e32 v139, 0xffff0000, v134
	v_lshlrev_b32_e32 v134, 16, v135
	v_and_b32_e32 v135, 0xffff0000, v135
	v_lshlrev_b32_e32 v166, 16, v136
	v_and_b32_e32 v167, 0xffff0000, v136
	v_lshlrev_b32_e32 v136, 16, v137
	v_and_b32_e32 v137, 0xffff0000, v137
	global_store_dwordx4 v[190:191], v[178:181], off offset:256
	v_pk_fma_f32 v[50:51], v[50:51], v[162:163], v[134:135]
	v_pk_fma_f32 v[48:49], v[48:49], v[160:161], v[138:139]
	v_pk_fma_f32 v[46:47], v[46:47], v[158:159], v[136:137]
	v_pk_fma_f32 v[44:45], v[44:45], v[156:157], v[166:167]
	global_load_dwordx4 v[178:181], v[192:193], off offset:2304
	global_load_dwordx4 v[182:185], v[194:195], off offset:2304
	v_cvt_pk_bf16_f32 v134, v48, v49
	v_cvt_pk_bf16_f32 v135, v50, v51
	v_cvt_pk_bf16_f32 v136, v44, v45
	v_cvt_pk_bf16_f32 v137, v46, v47
	v_lshlrev_b32_e32 v50, 16, v134
	v_and_b32_e32 v51, 0xffff0000, v134
	v_lshlrev_b32_e32 v48, 16, v135
	v_and_b32_e32 v49, 0xffff0000, v135
	v_lshlrev_b32_e32 v46, 16, v136
	v_and_b32_e32 v47, 0xffff0000, v136
	v_lshlrev_b32_e32 v44, 16, v137
	v_and_b32_e32 v45, 0xffff0000, v137
	v_lshlrev_b32_e32 v168, 16, v238
	v_and_b32_e32 v169, 0xffff0000, v238
	v_lshlrev_b32_e32 v186, 16, v239
	v_and_b32_e32 v187, 0xffff0000, v239
	v_and_b32_e32 v189, 0xffff0000, v240
	v_lshlrev_b32_e32 v190, 16, v241
	v_and_b32_e32 v191, 0xffff0000, v241
	global_store_dwordx4 v[198:199], v[134:137], off offset:2304
	v_pk_mul_f32 v[138:139], v[70:71], v[44:45]
	v_pk_mul_f32 v[166:167], v[68:69], v[46:47]
	v_pk_mul_f32 v[136:137], v[74:75], v[48:49]
	v_pk_mul_f32 v[134:135], v[72:73], v[50:51]
	v_pk_fma_f32 v[42:43], v[42:43], v[162:163], v[186:187]
	v_cvt_pk_bf16_f32 v134, v134, v135
	v_cvt_pk_bf16_f32 v135, v136, v137
	v_cvt_pk_bf16_f32 v136, v166, v167
	v_cvt_pk_bf16_f32 v137, v138, v139
	v_pk_fma_f32 v[40:41], v[40:41], v[160:161], v[168:169]
	v_pk_fma_f32 v[38:39], v[38:39], v[158:159], v[190:191]
	v_pk_fma_f32 v[36:37], v[36:37], v[156:157], v[188:189]
	global_store_dwordx4 v[200:201], v[134:137], off offset:256
	v_mul_f32_e32 v67, v67, v67
	v_mul_f32_e32 v65, v65, v65
	v_cvt_pk_bf16_f32 v134, v40, v41
	v_cvt_pk_bf16_f32 v135, v42, v43
	v_cvt_pk_bf16_f32 v136, v36, v37
	v_cvt_pk_bf16_f32 v137, v38, v39
	v_lshlrev_b32_e32 v42, 16, v134
	v_and_b32_e32 v43, 0xffff0000, v134
	v_lshlrev_b32_e32 v40, 16, v135
	v_and_b32_e32 v41, 0xffff0000, v135
	v_lshlrev_b32_e32 v38, 16, v136
	v_and_b32_e32 v39, 0xffff0000, v136
	v_lshlrev_b32_e32 v36, 16, v137
	v_and_b32_e32 v37, 0xffff0000, v137
	global_store_dwordx4 v[202:203], v[134:137], off offset:2304
	v_pk_mul_f32 v[138:139], v[70:71], v[36:37]
	v_pk_mul_f32 v[166:167], v[68:69], v[38:39]
	v_pk_mul_f32 v[136:137], v[74:75], v[40:41]
	v_pk_mul_f32 v[134:135], v[72:73], v[42:43]
	v_fmac_f32_e32 v67, v66, v66
	v_cvt_pk_bf16_f32 v134, v134, v135
	v_cvt_pk_bf16_f32 v135, v136, v137
	v_cvt_pk_bf16_f32 v136, v166, v167
	v_cvt_pk_bf16_f32 v137, v138, v139
	global_store_dwordx4 v[204:205], v[134:137], off offset:256
	global_load_dwordx4 v[134:137], v[206:207], off offset:2304
	s_nop 0
	global_load_dwordx4 v[186:189], v[208:209], off offset:2304
	v_fmac_f32_e32 v65, v64, v64
	v_mul_f32_e32 v63, v63, v63
	v_mul_f32_e32 v61, v61, v61
	v_add_f32_e32 v64, v67, v65
	v_fmac_f32_e32 v63, v62, v62
	v_fmac_f32_e32 v61, v60, v60
	v_add_f32_e32 v60, v63, v61
	s_waitcnt vmcnt(0)
	v_lshlrev_b32_e32 v138, 16, v178
	v_and_b32_e32 v139, 0xffff0000, v178
	v_lshlrev_b32_e32 v166, 16, v179
	v_and_b32_e32 v167, 0xffff0000, v179
	v_lshlrev_b32_e32 v168, 16, v180
	v_and_b32_e32 v169, 0xffff0000, v180
	v_lshlrev_b32_e32 v178, 16, v181
	v_and_b32_e32 v179, 0xffff0000, v181
	v_pk_fma_f32 v[34:35], v[34:35], v[162:163], v[166:167]
	v_pk_fma_f32 v[32:33], v[32:33], v[160:161], v[138:139]
	v_pk_fma_f32 v[30:31], v[30:31], v[158:159], v[178:179]
	v_pk_fma_f32 v[28:29], v[28:29], v[156:157], v[168:169]
	v_cvt_pk_bf16_f32 v178, v32, v33
	v_cvt_pk_bf16_f32 v179, v34, v35
	v_cvt_pk_bf16_f32 v180, v28, v29
	v_cvt_pk_bf16_f32 v181, v30, v31
	v_lshlrev_b32_e32 v34, 16, v178
	v_and_b32_e32 v35, 0xffff0000, v178
	v_lshlrev_b32_e32 v32, 16, v179
	v_and_b32_e32 v33, 0xffff0000, v179
	v_lshlrev_b32_e32 v30, 16, v180
	v_and_b32_e32 v31, 0xffff0000, v180
	v_lshlrev_b32_e32 v28, 16, v181
	v_and_b32_e32 v29, 0xffff0000, v181
	v_lshlrev_b32_e32 v190, 16, v182
	v_and_b32_e32 v191, 0xffff0000, v182
	v_lshlrev_b32_e32 v182, 16, v183
	v_and_b32_e32 v183, 0xffff0000, v183
	global_store_dwordx4 v[212:213], v[178:181], off offset:2304
	v_pk_mul_f32 v[138:139], v[74:75], v[32:33]
	v_pk_mul_f32 v[166:167], v[72:73], v[34:35]
	v_pk_mul_f32 v[168:169], v[70:71], v[28:29]
	v_pk_mul_f32 v[180:181], v[68:69], v[30:31]
	v_cvt_pk_bf16_f32 v178, v166, v167
	v_cvt_pk_bf16_f32 v179, v138, v139
	v_cvt_pk_bf16_f32 v180, v180, v181
	v_cvt_pk_bf16_f32 v181, v168, v169
	v_pk_fma_f32 v[24:25], v[24:25], v[162:163], v[182:183]
	v_pk_fma_f32 v[22:23], v[22:23], v[160:161], v[190:191]
	v_lshlrev_b32_e32 v192, 16, v184
	v_and_b32_e32 v193, 0xffff0000, v184
	v_lshlrev_b32_e32 v184, 16, v185
	v_and_b32_e32 v185, 0xffff0000, v185
	global_store_dwordx4 v[214:215], v[178:181], off offset:256
	v_pk_fma_f32 v[20:21], v[20:21], v[158:159], v[184:185]
	v_pk_fma_f32 v[18:19], v[18:19], v[156:157], v[192:193]
	v_cvt_pk_bf16_f32 v178, v22, v23
	v_cvt_pk_bf16_f32 v179, v24, v25
	v_lshlrev_b32_e32 v24, 16, v178
	v_and_b32_e32 v25, 0xffff0000, v178
	v_lshlrev_b32_e32 v22, 16, v179
	v_and_b32_e32 v23, 0xffff0000, v179
	v_cvt_pk_bf16_f32 v180, v18, v19
	v_cvt_pk_bf16_f32 v181, v20, v21
	v_pk_mul_f32 v[138:139], v[74:75], v[22:23]
	v_pk_mul_f32 v[166:167], v[72:73], v[24:25]
	global_store_dwordx4 v[216:217], v[178:181], off offset:2304
	v_lshlrev_b32_e32 v20, 16, v180
	v_and_b32_e32 v21, 0xffff0000, v180
	v_cvt_pk_bf16_f32 v178, v166, v167
	v_cvt_pk_bf16_f32 v179, v138, v139
	v_lshlrev_b32_e32 v138, 16, v134
	v_and_b32_e32 v139, 0xffff0000, v134
	v_lshlrev_b32_e32 v134, 16, v135
	v_and_b32_e32 v135, 0xffff0000, v135
	v_lshlrev_b32_e32 v166, 16, v136
	v_and_b32_e32 v167, 0xffff0000, v136
	v_lshlrev_b32_e32 v136, 16, v137
	v_and_b32_e32 v137, 0xffff0000, v137
	v_lshlrev_b32_e32 v18, 16, v181
	v_and_b32_e32 v19, 0xffff0000, v181
	v_pk_fma_f32 v[16:17], v[16:17], v[162:163], v[134:135]
	v_pk_fma_f32 v[14:15], v[14:15], v[160:161], v[138:139]
	v_pk_fma_f32 v[12:13], v[12:13], v[158:159], v[136:137]
	v_pk_fma_f32 v[10:11], v[10:11], v[156:157], v[166:167]
	v_pk_mul_f32 v[168:169], v[70:71], v[18:19]
	v_pk_mul_f32 v[180:181], v[68:69], v[20:21]
	v_cvt_pk_bf16_f32 v134, v14, v15
	v_cvt_pk_bf16_f32 v135, v16, v17
	v_cvt_pk_bf16_f32 v136, v10, v11
	v_cvt_pk_bf16_f32 v137, v12, v13
	v_cvt_pk_bf16_f32 v180, v180, v181
	v_cvt_pk_bf16_f32 v181, v168, v169
	v_lshlrev_b32_e32 v16, 16, v134
	v_and_b32_e32 v17, 0xffff0000, v134
	v_lshlrev_b32_e32 v14, 16, v135
	v_and_b32_e32 v15, 0xffff0000, v135
	v_lshlrev_b32_e32 v12, 16, v136
	v_and_b32_e32 v13, 0xffff0000, v136
	v_lshlrev_b32_e32 v10, 16, v137
	v_and_b32_e32 v11, 0xffff0000, v137
	global_store_dwordx4 v[218:219], v[178:181], off offset:256
	v_lshlrev_b32_e32 v168, 16, v186
	v_and_b32_e32 v169, 0xffff0000, v186
	v_lshlrev_b32_e32 v178, 16, v187
	v_and_b32_e32 v179, 0xffff0000, v187
	v_lshlrev_b32_e32 v180, 16, v188
	v_and_b32_e32 v181, 0xffff0000, v188
	v_lshlrev_b32_e32 v182, 16, v189
	v_and_b32_e32 v183, 0xffff0000, v189
	global_store_dwordx4 v[196:197], v[134:137], off offset:2304
	v_pk_mul_f32 v[138:139], v[70:71], v[10:11]
	v_pk_mul_f32 v[166:167], v[68:69], v[12:13]
	v_pk_mul_f32 v[136:137], v[74:75], v[14:15]
	v_pk_mul_f32 v[134:135], v[72:73], v[16:17]
	v_pk_fma_f32 v[8:9], v[8:9], v[162:163], v[178:179]
	v_cvt_pk_bf16_f32 v134, v134, v135
	v_cvt_pk_bf16_f32 v135, v136, v137
	v_cvt_pk_bf16_f32 v136, v166, v167
	v_cvt_pk_bf16_f32 v137, v138, v139
	v_pk_fma_f32 v[6:7], v[6:7], v[160:161], v[168:169]
	v_pk_fma_f32 v[4:5], v[4:5], v[158:159], v[182:183]
	v_pk_fma_f32 v[2:3], v[2:3], v[156:157], v[180:181]
	global_store_dwordx4 v[210:211], v[134:137], off offset:256
	s_nop 1
	v_cvt_pk_bf16_f32 v134, v6, v7
	v_cvt_pk_bf16_f32 v135, v8, v9
	v_cvt_pk_bf16_f32 v136, v2, v3
	v_cvt_pk_bf16_f32 v137, v4, v5
	v_lshlrev_b32_e32 v8, 16, v134
	v_and_b32_e32 v9, 0xffff0000, v134
	v_lshlrev_b32_e32 v6, 16, v135
	v_and_b32_e32 v7, 0xffff0000, v135
	v_lshlrev_b32_e32 v4, 16, v136
	v_and_b32_e32 v5, 0xffff0000, v136
	v_lshlrev_b32_e32 v2, 16, v137
	v_and_b32_e32 v3, 0xffff0000, v137
	global_store_dwordx4 v[220:221], v[134:137], off offset:2304
	v_pk_mul_f32 v[74:75], v[74:75], v[6:7]
	v_pk_mul_f32 v[72:73], v[72:73], v[8:9]
	v_pk_mul_f32 v[134:135], v[70:71], v[2:3]
	v_pk_mul_f32 v[70:71], v[68:69], v[4:5]
	v_cvt_pk_bf16_f32 v68, v72, v73
	v_cvt_pk_bf16_f32 v69, v74, v75
	v_cvt_pk_bf16_f32 v70, v70, v71
	v_cvt_pk_bf16_f32 v71, v134, v135
	global_store_dwordx4 v[132:133], v[68:71], off offset:256
	v_xor_b32_e32 v72, 32, v227
	v_mul_f32_e32 v73, v129, v129
	v_and_b32_e32 v71, 64, v227
	v_xor_b32_e32 v70, 16, v227
	v_add_u32_e32 v71, 64, v71
	v_cmp_lt_i32_e32 vcc, v70, v71
	v_fmac_f32_e32 v73, v128, v128
	v_mul_f32_e32 v74, v125, v125
	v_cndmask_b32_e32 v70, v227, v70, vcc
	v_cmp_lt_i32_e32 vcc, v72, v71
	v_fmac_f32_e32 v74, v124, v124
	v_lshlrev_b32_e32 v70, 2, v70
	v_cndmask_b32_e32 v71, v227, v72, vcc
	v_mul_f32_e32 v72, v131, v131
	v_fmac_f32_e32 v72, v130, v130
	v_add_f32_e32 v72, v72, v73
	v_mul_f32_e32 v73, v127, v127
	v_fmac_f32_e32 v73, v126, v126
	v_add_f32_e32 v73, v73, v74
	v_add_f32_e32 v72, v72, v73
	v_add_f32_e32 v64, v72, v64
	v_add_f32_e32 v60, v60, v64
	ds_bpermute_b32 v61, v70, v60
	v_lshlrev_b32_e32 v71, 2, v71
	v_lshl_add_u64 v[68:69], v[150:151], 0, s[24:25]
	s_waitcnt lgkmcnt(0)
	v_add_f32_e32 v60, v60, v61
	ds_bpermute_b32 v61, v71, v60
	s_and_saveexec_b64 s[18:19], s[40:41]
	s_cbranch_execz .LBB0_364
	s_waitcnt lgkmcnt(0)
	v_add_f32_e32 v60, v60, v61
	global_atomic_add_f32 v[68:69], v60, off

.LBB0_395:
	s_add_u32 s26, s24, 0x100
	s_addc_u32 s27, s25, 0
	s_add_i32 s0, 0, 0x10000
	s_cmp_eq_u32 s52, 40
	s_cselect_b32 s31, s43, s27
	s_cselect_b32 s30, s42, s26
	s_cselect_b32 s29, s45, s19
	s_cselect_b32 s28, s44, s18
	s_add_i32 m0, s69, 0xc000
	ds_read_b128 v[172:175], v235
	ds_read_b128 v[176:179], v235 offset:1024
	ds_read_b128 v[180:183], v235 offset:2048
	ds_read_b128 v[184:187], v235 offset:3072
	ds_read_b128 v[188:191], v235 offset:4096
	ds_read_b128 v[192:195], v235 offset:5120
	ds_read_b128 v[196:199], v235 offset:6144
	ds_read_b128 v[200:203], v235 offset:7168
	global_load_lds_dwordx4 v152, s[24:25]
	s_mov_b64 s[100:101], s[24:25]
	s_waitcnt vmcnt(10) lgkmcnt(8)
	s_setprio 1
	s_barrier
	s_waitcnt lgkmcnt(0)
	v_mfma_f32_16x16x32_bf16 v[136:139], v[100:103], v[172:175], v[136:139]
	v_mfma_f32_16x16x32_bf16 v[132:135], v[156:159], v[172:175], v[132:135]
	v_mfma_f32_16x16x32_bf16 v[128:131], v[100:103], v[180:183], v[128:131]
	v_mfma_f32_16x16x32_bf16 v[124:127], v[156:159], v[180:183], v[124:127]
	v_mfma_f32_16x16x32_bf16 v[120:123], v[100:103], v[188:191], v[120:123]
	v_mfma_f32_16x16x32_bf16 v[116:119], v[156:159], v[188:191], v[116:119]
	v_mfma_f32_16x16x32_bf16 v[112:115], v[100:103], v[196:199], v[112:115]
	v_mfma_f32_16x16x32_bf16 v[108:111], v[156:159], v[196:199], v[108:111]
	v_mfma_f32_16x16x32_bf16 v[136:139], v[104:107], v[176:179], v[136:139]
	v_mfma_f32_16x16x32_bf16 v[132:135], v[160:163], v[176:179], v[132:135]
	v_mfma_f32_16x16x32_bf16 v[128:131], v[104:107], v[184:187], v[128:131]
	v_mfma_f32_16x16x32_bf16 v[124:127], v[160:163], v[184:187], v[124:127]
	v_mfma_f32_16x16x32_bf16 v[120:123], v[104:107], v[192:195], v[120:123]
	v_mfma_f32_16x16x32_bf16 v[116:119], v[160:163], v[192:195], v[116:119]
	v_mfma_f32_16x16x32_bf16 v[112:115], v[104:107], v[200:203], v[112:115]
	v_mfma_f32_16x16x32_bf16 v[108:111], v[160:163], v[200:203], v[108:111]
	s_barrier
	s_setprio 0
	s_add_i32 s24, 0, 0x14000
	v_add_u32_e32 v164, s24, v233
	s_add_i32 s0, s0, s68
	ds_read_b128 v[204:207], v164
	ds_read_b128 v[208:211], v164 offset:1024
	ds_read_b128 v[212:215], v164 offset:2048
	ds_read_b128 v[216:219], v164 offset:3072
	v_lshl_add_u64 v[164:165], s[28:29], 0, v[26:27]
	s_mov_b32 m0, s0
	v_lshl_add_u64 v[220:221], s[28:29], 0, v[140:141]
	global_load_lds_dwordx4 v[164:165], off
	s_add_i32 m0, s0, 0x2000
	s_nop 0
	global_load_lds_dwordx4 v[220:221], off
	v_lshl_add_u64 v[238:239], s[100:101], 0, v[154:155]
	s_add_i32 m0, s69, 0xe000
	s_nop 0
	global_load_lds_dwordx4 v[238:239], off
	s_waitcnt vmcnt(8)
	s_setprio 1
	s_barrier
	s_waitcnt lgkmcnt(0)
	v_mfma_f32_16x16x32_bf16 v[64:67], v[204:207], v[172:175], v[64:67]
	v_mfma_f32_16x16x32_bf16 v[60:63], v[212:215], v[172:175], v[60:63]
	v_mfma_f32_16x16x32_bf16 v[56:59], v[204:207], v[180:183], v[56:59]
	v_mfma_f32_16x16x32_bf16 v[52:55], v[212:215], v[180:183], v[52:55]
	v_mfma_f32_16x16x32_bf16 v[48:51], v[204:207], v[188:191], v[48:51]
	v_mfma_f32_16x16x32_bf16 v[44:47], v[212:215], v[188:191], v[44:47]
	v_mfma_f32_16x16x32_bf16 v[40:43], v[204:207], v[196:199], v[40:43]
	v_mfma_f32_16x16x32_bf16 v[36:39], v[212:215], v[196:199], v[36:39]
	v_mfma_f32_16x16x32_bf16 v[64:67], v[208:211], v[176:179], v[64:67]
	v_mfma_f32_16x16x32_bf16 v[60:63], v[216:219], v[176:179], v[60:63]
	v_mfma_f32_16x16x32_bf16 v[56:59], v[208:211], v[184:187], v[56:59]
	v_mfma_f32_16x16x32_bf16 v[52:55], v[216:219], v[184:187], v[52:55]
	v_mfma_f32_16x16x32_bf16 v[48:51], v[208:211], v[192:195], v[48:51]
	v_mfma_f32_16x16x32_bf16 v[44:47], v[216:219], v[192:195], v[44:47]
	v_mfma_f32_16x16x32_bf16 v[40:43], v[208:211], v[200:203], v[40:43]
	v_mfma_f32_16x16x32_bf16 v[36:39], v[216:219], v[200:203], v[36:39]
	s_barrier
	s_setprio 0
	s_mov_b32 m0, s69
	v_lshl_add_u64 v[222:223], s[30:31], 0, v[144:145]
	ds_read_b128 v[172:175], v235 offset:16384
	ds_read_b128 v[176:179], v235 offset:17408
	ds_read_b128 v[180:183], v235 offset:18432
	ds_read_b128 v[184:187], v235 offset:19456
	ds_read_b128 v[188:191], v235 offset:20480
	ds_read_b128 v[192:195], v235 offset:21504
	ds_read_b128 v[196:199], v235 offset:22528
	ds_read_b128 v[200:203], v235 offset:23552
	global_load_lds_dwordx4 v[222:223], off
	s_waitcnt vmcnt(10)
	s_setprio 1
	s_barrier
	s_waitcnt lgkmcnt(0)
	v_mfma_f32_16x16x32_bf16 v[96:99], v[100:103], v[172:175], v[96:99]
	v_mfma_f32_16x16x32_bf16 v[92:95], v[156:159], v[172:175], v[92:95]
	v_mfma_f32_16x16x32_bf16 v[88:91], v[100:103], v[180:183], v[88:91]
	v_mfma_f32_16x16x32_bf16 v[84:87], v[156:159], v[180:183], v[84:87]
	v_mfma_f32_16x16x32_bf16 v[80:83], v[100:103], v[188:191], v[80:83]
	v_mfma_f32_16x16x32_bf16 v[76:79], v[156:159], v[188:191], v[76:79]
	v_mfma_f32_16x16x32_bf16 v[72:75], v[100:103], v[196:199], v[72:75]
	v_mfma_f32_16x16x32_bf16 v[68:71], v[156:159], v[196:199], v[68:71]
	v_mfma_f32_16x16x32_bf16 v[96:99], v[104:107], v[176:179], v[96:99]
	v_mfma_f32_16x16x32_bf16 v[92:95], v[160:163], v[176:179], v[92:95]
	v_mfma_f32_16x16x32_bf16 v[88:91], v[104:107], v[184:187], v[88:91]
	v_mfma_f32_16x16x32_bf16 v[84:87], v[160:163], v[184:187], v[84:87]
	v_mfma_f32_16x16x32_bf16 v[80:83], v[104:107], v[192:195], v[80:83]
	v_mfma_f32_16x16x32_bf16 v[76:79], v[160:163], v[192:195], v[76:79]
	v_mfma_f32_16x16x32_bf16 v[72:75], v[104:107], v[200:203], v[72:75]
	v_mfma_f32_16x16x32_bf16 v[68:71], v[160:163], v[200:203], v[68:71]
	s_barrier
	s_setprio 0
	s_add_u32 s0, s28, 0xb0000
	s_addc_u32 s1, s29, 0
	s_add_i32 s24, s24, s68
	s_mov_b32 m0, s24
	s_nop 0
	global_load_lds_dwordx4 v26, s[0:1]
	s_add_i32 m0, s24, 0x2000
	s_nop 0
	global_load_lds_dwordx4 v140, s[0:1]
	v_lshl_add_u64 v[224:225], s[30:31], 0, v[142:143]
	s_mov_b32 m0, s72
	s_nop 0
	global_load_lds_dwordx4 v[224:225], off
	v_add_u32_e32 v160, 0x18000, v233
	ds_read_b128 v[100:103], v160
	ds_read_b128 v[104:107], v160 offset:1024
	ds_read_b128 v[156:159], v160 offset:2048
	ds_read_b128 v[160:163], v160 offset:3072
	s_waitcnt vmcnt(8)
	s_setprio 1
	s_barrier
	v_mfma_f32_16x16x32_bf16 v[32:35], v[204:207], v[172:175], v[32:35]
	v_mfma_f32_16x16x32_bf16 v[28:31], v[212:215], v[172:175], v[28:31]
	v_mfma_f32_16x16x32_bf16 v[22:25], v[204:207], v[180:183], v[22:25]
	v_mfma_f32_16x16x32_bf16 v[18:21], v[212:215], v[180:183], v[18:21]
	v_mfma_f32_16x16x32_bf16 v[14:17], v[204:207], v[188:191], v[14:17]
	v_mfma_f32_16x16x32_bf16 v[10:13], v[212:215], v[188:191], v[10:13]
	v_mfma_f32_16x16x32_bf16 v[6:9], v[204:207], v[196:199], v[6:9]
	v_mfma_f32_16x16x32_bf16 v[2:5], v[212:215], v[196:199], v[2:5]
	v_mfma_f32_16x16x32_bf16 v[32:35], v[208:211], v[176:179], v[32:35]
	v_mfma_f32_16x16x32_bf16 v[28:31], v[216:219], v[176:179], v[28:31]
	v_mfma_f32_16x16x32_bf16 v[22:25], v[208:211], v[184:187], v[22:25]
	v_mfma_f32_16x16x32_bf16 v[18:21], v[216:219], v[184:187], v[18:21]
	v_mfma_f32_16x16x32_bf16 v[14:17], v[208:211], v[192:195], v[14:17]
	v_mfma_f32_16x16x32_bf16 v[10:13], v[216:219], v[192:195], v[10:13]
	v_mfma_f32_16x16x32_bf16 v[6:9], v[208:211], v[200:203], v[6:9]
	v_mfma_f32_16x16x32_bf16 v[2:5], v[216:219], v[200:203], v[2:5]
	s_barrier
	s_setprio 0
	s_add_i32 s24, 0, 0x18000
	s_add_u32 s0, s30, 0xb0000
	s_addc_u32 s1, s31, 0
	s_mov_b32 m0, s73
	ds_read_b128 v[172:175], v235 offset:32768
	ds_read_b128 v[176:179], v235 offset:33792
	ds_read_b128 v[180:183], v235 offset:34816
	ds_read_b128 v[184:187], v235 offset:35840
	ds_read_b128 v[188:191], v235 offset:36864
	ds_read_b128 v[192:195], v235 offset:37888
	ds_read_b128 v[196:199], v235 offset:38912
	ds_read_b128 v[200:203], v235 offset:39936
	global_load_lds_dwordx4 v144, s[0:1]
	s_mov_b64 s[100:101], s[0:1]
	s_waitcnt vmcnt(10) lgkmcnt(8)
	s_setprio 1
	s_barrier
	s_waitcnt lgkmcnt(0)
	v_mfma_f32_16x16x32_bf16 v[136:139], v[100:103], v[172:175], v[136:139]
	v_mfma_f32_16x16x32_bf16 v[132:135], v[156:159], v[172:175], v[132:135]
	v_mfma_f32_16x16x32_bf16 v[128:131], v[100:103], v[180:183], v[128:131]
	v_mfma_f32_16x16x32_bf16 v[124:127], v[156:159], v[180:183], v[124:127]
	v_mfma_f32_16x16x32_bf16 v[120:123], v[100:103], v[188:191], v[120:123]
	v_mfma_f32_16x16x32_bf16 v[116:119], v[156:159], v[188:191], v[116:119]
	v_mfma_f32_16x16x32_bf16 v[112:115], v[100:103], v[196:199], v[112:115]
	v_mfma_f32_16x16x32_bf16 v[108:111], v[156:159], v[196:199], v[108:111]
	v_mfma_f32_16x16x32_bf16 v[136:139], v[104:107], v[176:179], v[136:139]
	v_mfma_f32_16x16x32_bf16 v[132:135], v[160:163], v[176:179], v[132:135]
	v_mfma_f32_16x16x32_bf16 v[128:131], v[104:107], v[184:187], v[128:131]
	v_mfma_f32_16x16x32_bf16 v[124:127], v[160:163], v[184:187], v[124:127]
	v_mfma_f32_16x16x32_bf16 v[120:123], v[104:107], v[192:195], v[120:123]
	v_mfma_f32_16x16x32_bf16 v[116:119], v[160:163], v[192:195], v[116:119]
	v_mfma_f32_16x16x32_bf16 v[112:115], v[104:107], v[200:203], v[112:115]
	v_mfma_f32_16x16x32_bf16 v[108:111], v[160:163], v[200:203], v[108:111]
	s_barrier
	s_setprio 0
	s_add_i32 s25, 0, 0x1c000
	s_add_i32 s0, s24, s68
	v_add_u32_e32 v166, s25, v233
	v_lshl_add_u64 v[164:165], v[164:165], 0, s[12:13]
	s_mov_b32 m0, s0
	ds_read_b128 v[204:207], v166
	ds_read_b128 v[208:211], v166 offset:1024
	ds_read_b128 v[212:215], v166 offset:2048
	ds_read_b128 v[216:219], v166 offset:3072
	global_load_lds_dwordx4 v[164:165], off
	v_lshl_add_u64 v[164:165], v[220:221], 0, s[12:13]
	s_add_i32 m0, s0, 0x2000
	s_nop 0
	global_load_lds_dwordx4 v[164:165], off
	s_mov_b32 m0, s81
	s_nop 0
	global_load_lds_dwordx4 v142, s[100:101]
	s_waitcnt vmcnt(8)
	s_setprio 1
	s_barrier
	s_waitcnt lgkmcnt(0)
	v_mfma_f32_16x16x32_bf16 v[64:67], v[204:207], v[172:175], v[64:67]
	v_mfma_f32_16x16x32_bf16 v[60:63], v[212:215], v[172:175], v[60:63]
	v_mfma_f32_16x16x32_bf16 v[56:59], v[204:207], v[180:183], v[56:59]
	v_mfma_f32_16x16x32_bf16 v[52:55], v[212:215], v[180:183], v[52:55]
	v_mfma_f32_16x16x32_bf16 v[48:51], v[204:207], v[188:191], v[48:51]
	v_mfma_f32_16x16x32_bf16 v[44:47], v[212:215], v[188:191], v[44:47]
	v_mfma_f32_16x16x32_bf16 v[40:43], v[204:207], v[196:199], v[40:43]
	v_mfma_f32_16x16x32_bf16 v[36:39], v[212:215], v[196:199], v[36:39]
	v_mfma_f32_16x16x32_bf16 v[64:67], v[208:211], v[176:179], v[64:67]
	v_mfma_f32_16x16x32_bf16 v[60:63], v[216:219], v[176:179], v[60:63]
	v_mfma_f32_16x16x32_bf16 v[56:59], v[208:211], v[184:187], v[56:59]
	v_mfma_f32_16x16x32_bf16 v[52:55], v[216:219], v[184:187], v[52:55]
	v_mfma_f32_16x16x32_bf16 v[48:51], v[208:211], v[192:195], v[48:51]
	v_mfma_f32_16x16x32_bf16 v[44:47], v[216:219], v[192:195], v[44:47]
	v_mfma_f32_16x16x32_bf16 v[40:43], v[208:211], v[200:203], v[40:43]
	v_mfma_f32_16x16x32_bf16 v[36:39], v[216:219], v[200:203], v[36:39]
	s_barrier
	s_setprio 0
	s_mov_b32 m0, s21
	v_lshl_add_u64 v[164:165], v[222:223], 0, s[12:13]
	ds_read_b128 v[172:175], v235 offset:49152
	ds_read_b128 v[176:179], v235 offset:50176
	ds_read_b128 v[180:183], v235 offset:51200
	ds_read_b128 v[184:187], v235 offset:52224
	ds_read_b128 v[188:191], v235 offset:53248
	ds_read_b128 v[192:195], v235 offset:54272
	ds_read_b128 v[196:199], v235 offset:55296
	ds_read_b128 v[200:203], v235 offset:56320
	global_load_lds_dwordx4 v[164:165], off
	s_waitcnt vmcnt(10)
	s_setprio 1
	s_barrier
	s_waitcnt lgkmcnt(0)
	v_mfma_f32_16x16x32_bf16 v[96:99], v[100:103], v[172:175], v[96:99]
	v_mfma_f32_16x16x32_bf16 v[92:95], v[156:159], v[172:175], v[92:95]
	v_mfma_f32_16x16x32_bf16 v[88:91], v[100:103], v[180:183], v[88:91]
	v_mfma_f32_16x16x32_bf16 v[84:87], v[156:159], v[180:183], v[84:87]
	v_mfma_f32_16x16x32_bf16 v[80:83], v[100:103], v[188:191], v[80:83]
	v_mfma_f32_16x16x32_bf16 v[76:79], v[156:159], v[188:191], v[76:79]
	v_mfma_f32_16x16x32_bf16 v[72:75], v[100:103], v[196:199], v[72:75]
	v_mfma_f32_16x16x32_bf16 v[68:71], v[156:159], v[196:199], v[68:71]
	v_mfma_f32_16x16x32_bf16 v[96:99], v[104:107], v[176:179], v[96:99]
	v_mfma_f32_16x16x32_bf16 v[92:95], v[160:163], v[176:179], v[92:95]
	v_mfma_f32_16x16x32_bf16 v[88:91], v[104:107], v[184:187], v[88:91]
	v_mfma_f32_16x16x32_bf16 v[84:87], v[160:163], v[184:187], v[84:87]
	v_mfma_f32_16x16x32_bf16 v[80:83], v[104:107], v[192:195], v[80:83]
	v_mfma_f32_16x16x32_bf16 v[76:79], v[160:163], v[192:195], v[76:79]
	v_mfma_f32_16x16x32_bf16 v[72:75], v[104:107], v[200:203], v[72:75]
	v_mfma_f32_16x16x32_bf16 v[68:71], v[160:163], v[200:203], v[68:71]
	s_barrier
	s_setprio 0
	s_add_u32 s0, s28, 0xb0080
	s_addc_u32 s1, s29, 0
	s_add_i32 s24, s25, s68
	s_mov_b32 m0, s24
	s_nop 0
	global_load_lds_dwordx4 v26, s[0:1]
	s_add_i32 m0, s24, 0x2000
	s_nop 0
	global_load_lds_dwordx4 v140, s[0:1]
	v_lshl_add_u64 v[164:165], v[224:225], 0, s[12:13]
	s_mov_b32 m0, s48
	s_nop 0
	global_load_lds_dwordx4 v[164:165], off
	v_add_u32_e32 v160, 0x10000, v233
	ds_read_b128 v[100:103], v160
	ds_read_b128 v[104:107], v160 offset:1024
	ds_read_b128 v[156:159], v160 offset:2048
	ds_read_b128 v[160:163], v160 offset:3072
	s_waitcnt vmcnt(8)
	s_setprio 1
	s_barrier
	v_mfma_f32_16x16x32_bf16 v[32:35], v[204:207], v[172:175], v[32:35]
	v_mfma_f32_16x16x32_bf16 v[28:31], v[212:215], v[172:175], v[28:31]
	v_mfma_f32_16x16x32_bf16 v[22:25], v[204:207], v[180:183], v[22:25]
	v_mfma_f32_16x16x32_bf16 v[18:21], v[212:215], v[180:183], v[18:21]
	v_mfma_f32_16x16x32_bf16 v[14:17], v[204:207], v[188:191], v[14:17]
	v_mfma_f32_16x16x32_bf16 v[10:13], v[212:215], v[188:191], v[10:13]
	v_mfma_f32_16x16x32_bf16 v[6:9], v[204:207], v[196:199], v[6:9]
	v_mfma_f32_16x16x32_bf16 v[2:5], v[212:215], v[196:199], v[2:5]
	v_mfma_f32_16x16x32_bf16 v[32:35], v[208:211], v[176:179], v[32:35]
	v_mfma_f32_16x16x32_bf16 v[28:31], v[216:219], v[176:179], v[28:31]
	v_mfma_f32_16x16x32_bf16 v[22:25], v[208:211], v[184:187], v[22:25]
	v_mfma_f32_16x16x32_bf16 v[18:21], v[216:219], v[184:187], v[18:21]
	v_mfma_f32_16x16x32_bf16 v[14:17], v[208:211], v[192:195], v[14:17]
	v_mfma_f32_16x16x32_bf16 v[10:13], v[216:219], v[192:195], v[10:13]
	v_mfma_f32_16x16x32_bf16 v[6:9], v[208:211], v[200:203], v[6:9]
	v_mfma_f32_16x16x32_bf16 v[2:5], v[216:219], v[200:203], v[2:5]
	s_barrier
	s_setprio 0
	s_add_i32 s52, s52, 2
	s_add_u32 s18, s18, 0x100
	s_addc_u32 s19, s19, 0
	s_cmp_gt_u32 s52, 41
	s_mov_b64 s[24:25], s[26:27]
	s_cbranch_scc0 .LBB0_395
	s_waitcnt lgkmcnt(0)
	s_min_i32 s0, s22, 0x100
	s_ashr_i32 s0, s0, 5
	s_ashr_i32 s1, s0, 31
	s_add_i32 s18, s22, 0xffffff00
	s_cmpk_lt_i32 s22, 0x100
	s_cselect_b32 s18, s22, s18
	s_cselect_b32 s25, 0, s35
	s_cselect_b32 s24, 0, s34
	s_cselect_b32 s26, 0, s57
	s_cselect_b32 s27, 0, s58
	s_ashr_i32 s19, s18, 31
	s_add_u32 s24, s46, s24
	s_addc_u32 s25, s47, s25
	s_lshl_b64 s[18:19], s[18:19], 20
	v_lshl_add_u64 v[100:101], s[18:19], 0, v[146:147]
	s_add_u32 s18, s50, s26
	v_lshl_or_b32 v172, s23, 8, v234
	s_addc_u32 s19, s51, s27
	s_ashr_i32 s23, s22, 31
	v_lshl_add_u64 v[180:181], s[18:19], 0, v[100:101]
	s_lshl_b64 s[18:19], s[22:23], 19
	v_lshl_add_u64 v[184:185], v[148:149], 0, s[18:19]
	s_lshl_b64 s[52:53], s[22:23], 10
	s_mul_i32 s18, s0, 0x9000
	v_ashrrev_i32_e32 v173, 31, v172
	s_mul_hi_i32 s19, s0, 0x9000
	s_add_u32 s18, s36, s18
	s_addc_u32 s19, s37, s19
	v_lshlrev_b64 v[186:187], 2, v[172:173]
	v_lshl_add_u64 v[156:157], s[18:19], 0, v[186:187]
	v_lshl_add_u64 v[164:165], s[24:25], 0, v[100:101]
	global_load_dwordx4 v[100:103], v[156:157], off offset:16
	global_load_dwordx4 v[104:107], v[156:157], off
	s_lshl_b64 s[0:1], s[0:1], 12
	s_add_u32 s0, s59, s0
	s_addc_u32 s1, s20, s1
	v_lshl_add_u64 v[164:165], v[164:165], 0, v[186:187]
	s_mov_b32 s18, 0x20000
	s_waitcnt vmcnt(0)
	v_pk_mul_f32 v[178:179], v[102:103], 0.5 op_sel_hi:[1,0]
	v_pk_mul_f32 v[174:175], v[106:107], 0.5 op_sel_hi:[1,0]
	v_pk_mul_f32 v[176:177], v[104:105], 0.5 op_sel_hi:[1,0]
	v_pk_mul_f32 v[210:211], v[100:101], 0.5 op_sel_hi:[1,0]
	global_load_dwordx4 v[100:103], v[156:157], off offset:528
	global_load_dwordx4 v[104:107], v[156:157], off offset:512
	s_waitcnt vmcnt(0)
	v_pk_mul_f32 v[162:163], v[100:101], 0.5 op_sel_hi:[1,0]
	v_lshlrev_b64 v[100:101], 1, v[172:173]
	v_lshl_add_u64 v[182:183], v[180:181], 0, v[100:101]
	v_lshl_add_u64 v[180:181], v[184:185], 0, v[100:101]
	v_lshl_add_u64 v[184:185], s[0:1], 0, v[186:187]
	v_pk_mul_f32 v[156:157], v[106:107], 0.5 op_sel_hi:[1,0]
	v_pk_mul_f32 v[158:159], v[104:105], 0.5 op_sel_hi:[1,0]
	v_pk_mul_f32 v[160:161], v[102:103], 0.5 op_sel_hi:[1,0]
	global_load_dwordx4 v[100:103], v[184:185], off offset:16
	global_load_dwordx4 v[104:107], v[184:185], off
	global_load_dwordx4 v[188:191], v[164:165], off offset:16
	global_load_dwordx4 v[192:195], v[164:165], off
	v_add_co_u32_e32 v186, vcc, s65, v164
	s_mov_b64 s[0:1], 0x10000
	s_nop 0
	v_addc_co_u32_e32 v187, vcc, 0, v165, vcc
	v_lshl_add_u64 v[172:173], v[164:165], 0, s[0:1]
	global_load_dwordx4 v[196:199], v[186:187], off
	global_load_dwordx4 v[200:203], v[172:173], off offset:16
	s_mov_b32 s0, 0x8000
	s_waitcnt vmcnt(0)
	v_pk_fma_f32 v[134:135], v[134:135], v[178:179], v[190:191]
	v_pk_fma_f32 v[138:139], v[138:139], v[174:175], v[194:195]
	v_pk_fma_f32 v[136:137], v[136:137], v[176:177], v[192:193]
	v_pk_fma_f32 v[132:133], v[132:133], v[210:211], v[188:189]
	v_cvt_pk_bf16_f32 v188, v136, v137
	v_cvt_pk_bf16_f32 v189, v138, v139
	v_cvt_pk_bf16_f32 v190, v132, v133
	v_cvt_pk_bf16_f32 v191, v134, v135
	v_lshlrev_b32_e32 v138, 16, v188
	v_and_b32_e32 v139, 0xffff0000, v188
	v_lshlrev_b32_e32 v136, 16, v189
	v_and_b32_e32 v137, 0xffff0000, v189
	global_store_dwordx4 v[182:183], v[188:191], off offset:2048
	v_lshlrev_b32_e32 v134, 16, v190
	v_and_b32_e32 v135, 0xffff0000, v190
	v_lshlrev_b32_e32 v132, 16, v191
	v_and_b32_e32 v133, 0xffff0000, v191
	v_pk_mul_f32 v[172:173], v[106:107], v[136:137]
	v_pk_mul_f32 v[188:189], v[104:105], v[138:139]
	v_pk_mul_f32 v[192:193], v[102:103], v[132:133]
	v_pk_mul_f32 v[190:191], v[100:101], v[134:135]
	v_cvt_pk_bf16_f32 v188, v188, v189
	v_cvt_pk_bf16_f32 v189, v172, v173
	v_pk_fma_f32 v[130:131], v[130:131], v[174:175], v[198:199]
	v_pk_fma_f32 v[128:129], v[128:129], v[176:177], v[196:197]
	v_pk_fma_f32 v[172:173], v[126:127], v[178:179], v[202:203]
	v_pk_fma_f32 v[126:127], v[124:125], v[210:211], v[200:201]
	v_add_co_u32_e32 v202, vcc, s65, v182
	v_cvt_pk_bf16_f32 v190, v190, v191
	v_cvt_pk_bf16_f32 v191, v192, v193
	v_cvt_pk_bf16_f32 v124, v128, v129
	v_cvt_pk_bf16_f32 v125, v130, v131
	v_cvt_pk_bf16_f32 v126, v126, v127
	v_cvt_pk_bf16_f32 v127, v172, v173
	v_addc_co_u32_e32 v203, vcc, 0, v183, vcc
	global_store_dwordx4 v[180:181], v[188:191], off
	global_store_dwordx4 v[202:203], v[124:127], off offset:2048
	v_lshlrev_b32_e32 v128, 16, v124
	v_and_b32_e32 v129, 0xffff0000, v124
	v_lshlrev_b32_e32 v124, 16, v125
	v_and_b32_e32 v125, 0xffff0000, v125
	v_lshlrev_b32_e32 v130, 16, v126
	v_and_b32_e32 v131, 0xffff0000, v126
	v_lshlrev_b32_e32 v126, 16, v127
	v_and_b32_e32 v127, 0xffff0000, v127
	v_pk_mul_f32 v[172:173], v[106:107], v[124:125]
	v_pk_mul_f32 v[188:189], v[104:105], v[128:129]
	v_pk_mul_f32 v[192:193], v[102:103], v[126:127]
	v_pk_mul_f32 v[190:191], v[100:101], v[130:131]
	v_add_co_u32_e32 v220, vcc, s0, v180
	v_cvt_pk_bf16_f32 v188, v188, v189
	v_cvt_pk_bf16_f32 v189, v172, v173
	v_cvt_pk_bf16_f32 v190, v190, v191
	v_cvt_pk_bf16_f32 v191, v192, v193
	v_addc_co_u32_e32 v221, vcc, 0, v181, vcc
	global_store_dwordx4 v[220:221], v[188:191], off
	s_mov_b64 s[0:1], 0x20000
	v_lshl_add_u64 v[172:173], v[164:165], 0, s[0:1]
	v_add_co_u32_e32 v188, vcc, s18, v164
	s_mov_b64 s[0:1], 0x30000
	s_nop 0
	v_addc_co_u32_e32 v189, vcc, 0, v165, vcc
	global_load_dwordx4 v[192:195], v[188:189], off
	global_load_dwordx4 v[196:199], v[172:173], off offset:16
	v_lshl_add_u64 v[172:173], v[164:165], 0, s[0:1]
	s_mov_b32 s0, 0x30000
	v_add_co_u32_e32 v190, vcc, s0, v164
	s_waitcnt vmcnt(0)
	v_pk_fma_f32 v[120:121], v[120:121], v[176:177], v[192:193]
	v_addc_co_u32_e32 v191, vcc, 0, v165, vcc
	global_load_dwordx4 v[204:207], v[190:191], off
	global_load_dwordx4 v[212:215], v[172:173], off offset:16
	v_pk_fma_f32 v[122:123], v[122:123], v[174:175], v[194:195]
	v_pk_fma_f32 v[118:119], v[118:119], v[178:179], v[198:199]
	v_pk_fma_f32 v[116:117], v[116:117], v[210:211], v[196:197]
	v_cvt_pk_bf16_f32 v194, v120, v121
	v_add_co_u32_e32 v192, vcc, s18, v182
	v_cvt_pk_bf16_f32 v195, v122, v123
	v_cvt_pk_bf16_f32 v196, v116, v117
	v_cvt_pk_bf16_f32 v197, v118, v119
	v_addc_co_u32_e32 v193, vcc, 0, v183, vcc
	v_lshlrev_b32_e32 v122, 16, v194
	v_and_b32_e32 v123, 0xffff0000, v194
	global_store_dwordx4 v[192:193], v[194:197], off offset:2048
	v_lshlrev_b32_e32 v120, 16, v195
	v_and_b32_e32 v121, 0xffff0000, v195
	v_pk_mul_f32 v[194:195], v[104:105], v[122:123]
	v_lshlrev_b32_e32 v118, 16, v196
	v_and_b32_e32 v119, 0xffff0000, v196
	v_cvt_pk_bf16_f32 v196, v194, v195
	v_add_co_u32_e32 v194, vcc, s65, v180
	v_lshlrev_b32_e32 v116, 16, v197
	v_and_b32_e32 v117, 0xffff0000, v197
	v_pk_mul_f32 v[172:173], v[106:107], v[120:121]
	v_addc_co_u32_e32 v195, vcc, 0, v181, vcc
	v_pk_mul_f32 v[200:201], v[102:103], v[116:117]
	v_pk_mul_f32 v[198:199], v[100:101], v[118:119]
	v_cvt_pk_bf16_f32 v197, v172, v173
	v_cvt_pk_bf16_f32 v198, v198, v199
	v_cvt_pk_bf16_f32 v199, v200, v201
	global_store_dwordx4 v[194:195], v[196:199], off
	s_mov_b32 s18, 0x80000
	s_waitcnt vmcnt(0)
	v_pk_fma_f32 v[114:115], v[114:115], v[174:175], v[206:207]
	v_pk_fma_f32 v[112:113], v[112:113], v[176:177], v[204:205]
	v_pk_fma_f32 v[172:173], v[110:111], v[178:179], v[214:215]
	v_pk_fma_f32 v[110:111], v[108:109], v[210:211], v[212:213]
	v_add_co_u32_e32 v212, vcc, s0, v182
	v_cvt_pk_bf16_f32 v108, v112, v113
	v_cvt_pk_bf16_f32 v109, v114, v115
	v_cvt_pk_bf16_f32 v110, v110, v111
	v_cvt_pk_bf16_f32 v111, v172, v173
	v_addc_co_u32_e32 v213, vcc, 0, v183, vcc
	global_store_dwordx4 v[212:213], v[108:111], off offset:2048
	v_lshlrev_b32_e32 v112, 16, v108
	v_and_b32_e32 v113, 0xffff0000, v108
	v_lshlrev_b32_e32 v172, 16, v109
	v_and_b32_e32 v173, 0xffff0000, v109
	v_lshlrev_b32_e32 v114, 16, v110
	v_and_b32_e32 v115, 0xffff0000, v110
	v_lshlrev_b32_e32 v108, 16, v111
	v_and_b32_e32 v109, 0xffff0000, v111
	s_mov_b32 s0, 0x18000
	v_pk_mul_f32 v[110:111], v[106:107], v[172:173]
	v_pk_mul_f32 v[196:197], v[104:105], v[112:113]
	v_pk_mul_f32 v[200:201], v[102:103], v[108:109]
	v_pk_mul_f32 v[198:199], v[100:101], v[114:115]
	v_add_co_u32_e32 v222, vcc, s0, v180
	v_cvt_pk_bf16_f32 v196, v196, v197
	v_cvt_pk_bf16_f32 v197, v110, v111
	v_cvt_pk_bf16_f32 v198, v198, v199
	v_cvt_pk_bf16_f32 v199, v200, v201
	v_addc_co_u32_e32 v223, vcc, 0, v181, vcc
	global_store_dwordx4 v[222:223], v[196:199], off
	s_mov_b64 s[0:1], 0x80000
	v_lshl_add_u64 v[110:111], v[164:165], 0, s[0:1]
	v_add_co_u32_e32 v196, vcc, s18, v164
	s_mov_b64 s[0:1], 0x90000
	s_nop 0
	v_addc_co_u32_e32 v197, vcc, 0, v165, vcc
	global_load_dwordx4 v[204:207], v[196:197], off
	global_load_dwordx4 v[214:217], v[110:111], off offset:16
	v_lshl_add_u64 v[110:111], v[164:165], 0, s[0:1]
	s_mov_b32 s0, 0x90000
	v_add_co_u32_e32 v198, vcc, s0, v164
	s_mov_b32 s1, 0x40000
	s_nop 0
	v_addc_co_u32_e32 v199, vcc, 0, v165, vcc
	global_load_dwordx4 v[238:241], v[198:199], off
	global_load_dwordx4 v[242:245], v[110:111], off offset:16
	v_add_co_u32_e32 v200, vcc, s18, v182
	s_waitcnt vmcnt(0)
	v_pk_fma_f32 v[96:97], v[96:97], v[176:177], v[204:205]
	v_pk_fma_f32 v[98:99], v[98:99], v[174:175], v[206:207]
	v_pk_fma_f32 v[94:95], v[94:95], v[178:179], v[216:217]
	v_pk_fma_f32 v[92:93], v[92:93], v[210:211], v[214:215]
	v_cvt_pk_bf16_f32 v204, v96, v97
	v_cvt_pk_bf16_f32 v205, v98, v99
	v_cvt_pk_bf16_f32 v206, v92, v93
	v_cvt_pk_bf16_f32 v207, v94, v95
	v_addc_co_u32_e32 v201, vcc, 0, v183, vcc
	v_lshlrev_b32_e32 v98, 16, v204
	v_and_b32_e32 v99, 0xffff0000, v204
	global_store_dwordx4 v[200:201], v[204:207], off offset:2048
	v_lshlrev_b32_e32 v96, 16, v205
	v_and_b32_e32 v97, 0xffff0000, v205
	v_pk_mul_f32 v[204:205], v[104:105], v[98:99]
	v_lshlrev_b32_e32 v94, 16, v206
	v_and_b32_e32 v95, 0xffff0000, v206
	v_cvt_pk_bf16_f32 v206, v204, v205
	v_add_co_u32_e32 v204, vcc, s1, v180
	v_lshlrev_b32_e32 v92, 16, v207
	v_and_b32_e32 v93, 0xffff0000, v207
	v_pk_mul_f32 v[110:111], v[106:107], v[96:97]
	v_addc_co_u32_e32 v205, vcc, 0, v181, vcc
	v_pk_mul_f32 v[214:215], v[102:103], v[92:93]
	v_pk_mul_f32 v[208:209], v[100:101], v[94:95]
	v_cvt_pk_bf16_f32 v207, v110, v111
	v_pk_fma_f32 v[90:91], v[90:91], v[174:175], v[240:241]
	v_pk_fma_f32 v[88:89], v[88:89], v[176:177], v[238:239]
	v_pk_fma_f32 v[110:111], v[86:87], v[178:179], v[244:245]
	v_pk_fma_f32 v[86:87], v[84:85], v[210:211], v[242:243]
	v_add_co_u32_e32 v218, vcc, s0, v182
	v_cvt_pk_bf16_f32 v208, v208, v209
	v_cvt_pk_bf16_f32 v209, v214, v215
	v_cvt_pk_bf16_f32 v84, v88, v89
	v_cvt_pk_bf16_f32 v85, v90, v91
	v_cvt_pk_bf16_f32 v86, v86, v87
	v_cvt_pk_bf16_f32 v87, v110, v111
	v_addc_co_u32_e32 v219, vcc, 0, v183, vcc
	global_store_dwordx4 v[204:205], v[206:209], off
	global_store_dwordx4 v[218:219], v[84:87], off offset:2048
	v_lshlrev_b32_e32 v88, 16, v84
	v_and_b32_e32 v89, 0xffff0000, v84
	v_lshlrev_b32_e32 v110, 16, v85
	v_and_b32_e32 v111, 0xffff0000, v85
	v_lshlrev_b32_e32 v90, 16, v86
	v_and_b32_e32 v91, 0xffff0000, v86
	v_lshlrev_b32_e32 v84, 16, v87
	v_and_b32_e32 v85, 0xffff0000, v87
	s_mov_b32 s0, 0x48000
	v_pk_mul_f32 v[86:87], v[106:107], v[110:111]
	v_pk_mul_f32 v[206:207], v[104:105], v[88:89]
	v_pk_mul_f32 v[214:215], v[102:103], v[84:85]
	v_pk_mul_f32 v[208:209], v[100:101], v[90:91]
	v_add_co_u32_e32 v224, vcc, s0, v180
	v_cvt_pk_bf16_f32 v206, v206, v207
	v_cvt_pk_bf16_f32 v207, v86, v87
	v_cvt_pk_bf16_f32 v208, v208, v209
	v_cvt_pk_bf16_f32 v209, v214, v215
	v_addc_co_u32_e32 v225, vcc, 0, v181, vcc
	global_store_dwordx4 v[224:225], v[206:209], off
	s_mov_b64 s[0:1], 0xa0000
	v_lshl_add_u64 v[86:87], v[164:165], 0, s[0:1]
	v_add_co_u32_e32 v206, vcc, s76, v164
	s_mov_b64 s[0:1], 0xb0000
	s_nop 0
	v_addc_co_u32_e32 v207, vcc, 0, v165, vcc
	global_load_dwordx4 v[214:217], v[206:207], off
	global_load_dwordx4 v[238:241], v[86:87], off offset:16
	v_lshl_add_u64 v[86:87], v[164:165], 0, s[0:1]
	s_mov_b32 s0, 0xb0000
	v_add_co_u32_e32 v208, vcc, s0, v164
	s_waitcnt vmcnt(0)
	v_pk_fma_f32 v[80:81], v[80:81], v[176:177], v[214:215]
	v_addc_co_u32_e32 v209, vcc, 0, v165, vcc
	global_load_dwordx4 v[242:245], v[208:209], off
	global_load_dwordx4 v[246:249], v[86:87], off offset:16
	v_pk_fma_f32 v[82:83], v[82:83], v[174:175], v[216:217]
	v_pk_fma_f32 v[76:77], v[76:77], v[210:211], v[238:239]
	v_cvt_pk_bf16_f32 v238, v80, v81
	v_pk_fma_f32 v[78:79], v[78:79], v[178:179], v[240:241]
	v_cvt_pk_bf16_f32 v239, v82, v83
	v_add_co_u32_e32 v214, vcc, s76, v182
	v_lshlrev_b32_e32 v82, 16, v238
	v_and_b32_e32 v83, 0xffff0000, v238
	v_cvt_pk_bf16_f32 v240, v76, v77
	v_cvt_pk_bf16_f32 v241, v78, v79
	v_addc_co_u32_e32 v215, vcc, 0, v183, vcc
	v_lshlrev_b32_e32 v80, 16, v239
	v_and_b32_e32 v81, 0xffff0000, v239
	v_pk_mul_f32 v[216:217], v[104:105], v[82:83]
	global_store_dwordx4 v[214:215], v[238:241], off offset:2048
	v_pk_mul_f32 v[86:87], v[106:107], v[80:81]
	v_lshlrev_b32_e32 v78, 16, v240
	v_cvt_pk_bf16_f32 v238, v216, v217
	v_add_co_u32_e32 v216, vcc, s77, v180
	v_and_b32_e32 v79, 0xffff0000, v240
	v_lshlrev_b32_e32 v76, 16, v241
	v_and_b32_e32 v77, 0xffff0000, v241
	v_cvt_pk_bf16_f32 v239, v86, v87
	v_addc_co_u32_e32 v217, vcc, 0, v181, vcc
	v_pk_mul_f32 v[250:251], v[102:103], v[76:77]
	v_pk_mul_f32 v[240:241], v[100:101], v[78:79]
	s_waitcnt vmcnt(0)
	v_pk_fma_f32 v[74:75], v[74:75], v[174:175], v[244:245]
	v_pk_fma_f32 v[72:73], v[72:73], v[176:177], v[242:243]
	v_pk_fma_f32 v[86:87], v[70:71], v[178:179], v[248:249]
	v_pk_fma_f32 v[70:71], v[68:69], v[210:211], v[246:247]
	v_cvt_pk_bf16_f32 v68, v72, v73
	v_cvt_pk_bf16_f32 v69, v74, v75
	v_cvt_pk_bf16_f32 v70, v70, v71
	v_cvt_pk_bf16_f32 v71, v86, v87
	v_add_co_u32_e32 v210, vcc, s0, v182
	v_cvt_pk_bf16_f32 v240, v240, v241
	v_cvt_pk_bf16_f32 v241, v250, v251
	v_addc_co_u32_e32 v211, vcc, 0, v183, vcc
	v_lshlrev_b32_e32 v86, 16, v68
	v_and_b32_e32 v87, 0xffff0000, v68
	v_lshlrev_b32_e32 v178, 16, v69
	v_and_b32_e32 v179, 0xffff0000, v69
	v_lshlrev_b32_e32 v176, 16, v70
	v_and_b32_e32 v177, 0xffff0000, v70
	v_lshlrev_b32_e32 v174, 16, v71
	v_and_b32_e32 v175, 0xffff0000, v71
	s_mov_b32 s0, 0x58000
	global_store_dwordx4 v[216:217], v[238:241], off
	global_store_dwordx4 v[210:211], v[68:71], off offset:2048
	v_pk_mul_f32 v[72:73], v[102:103], v[174:175]
	v_pk_mul_f32 v[74:75], v[100:101], v[176:177]
	v_pk_mul_f32 v[70:71], v[106:107], v[178:179]
	v_pk_mul_f32 v[68:69], v[104:105], v[86:87]
	v_add_co_u32_e32 v100, vcc, s0, v180
	v_cvt_pk_bf16_f32 v68, v68, v69
	v_cvt_pk_bf16_f32 v69, v70, v71
	v_cvt_pk_bf16_f32 v70, v74, v75
	v_cvt_pk_bf16_f32 v71, v72, v73
	v_addc_co_u32_e32 v101, vcc, 0, v181, vcc
	global_store_dwordx4 v[100:101], v[68:71], off
	global_load_dwordx4 v[68:71], v[184:185], off offset:528
	s_nop 0
	global_load_dwordx4 v[72:75], v[184:185], off offset:512
	global_load_dwordx4 v[102:105], v[164:165], off offset:528
	global_load_dwordx4 v[238:241], v[164:165], off offset:512
	s_mov_b64 s[0:1], 0x10200
	v_lshl_add_u64 v[106:107], v[164:165], 0, s[0:1]
	global_load_dwordx4 v[184:187], v[186:187], off offset:512
	s_nop 0
	global_load_dwordx4 v[242:245], v[106:107], off offset:16
	s_mov_b64 s[0:1], 0x20200
	s_waitcnt vmcnt(0)
	v_pk_fma_f32 v[62:63], v[62:63], v[160:161], v[104:105]
	v_pk_fma_f32 v[66:67], v[66:67], v[156:157], v[240:241]
	v_pk_fma_f32 v[64:65], v[64:65], v[158:159], v[238:239]
	v_pk_fma_f32 v[60:61], v[60:61], v[162:163], v[102:103]
	v_cvt_pk_bf16_f32 v102, v64, v65
	v_cvt_pk_bf16_f32 v103, v66, v67
	v_cvt_pk_bf16_f32 v104, v60, v61
	v_cvt_pk_bf16_f32 v105, v62, v63
	v_lshlrev_b32_e32 v66, 16, v102
	v_and_b32_e32 v67, 0xffff0000, v102
	v_lshlrev_b32_e32 v64, 16, v103
	v_and_b32_e32 v65, 0xffff0000, v103
	v_lshlrev_b32_e32 v62, 16, v104
	v_and_b32_e32 v63, 0xffff0000, v104
	v_lshlrev_b32_e32 v60, 16, v105
	v_and_b32_e32 v61, 0xffff0000, v105
	global_store_dwordx4 v[182:183], v[102:105], off offset:2304
	v_pk_mul_f32 v[106:107], v[70:71], v[60:61]
	v_pk_mul_f32 v[182:183], v[68:69], v[62:63]
	v_pk_mul_f32 v[104:105], v[74:75], v[64:65]
	v_pk_mul_f32 v[102:103], v[72:73], v[66:67]
	v_pk_fma_f32 v[58:59], v[58:59], v[156:157], v[186:187]
	v_cvt_pk_bf16_f32 v102, v102, v103
	v_cvt_pk_bf16_f32 v103, v104, v105
	v_cvt_pk_bf16_f32 v104, v182, v183
	v_cvt_pk_bf16_f32 v105, v106, v107
	v_pk_fma_f32 v[56:57], v[56:57], v[158:159], v[184:185]
	v_pk_fma_f32 v[54:55], v[54:55], v[160:161], v[244:245]
	v_pk_fma_f32 v[52:53], v[52:53], v[162:163], v[242:243]
	global_store_dwordx4 v[180:181], v[102:105], off offset:256
	v_mul_f32_e32 v67, v67, v67
	v_mul_f32_e32 v65, v65, v65
	v_cvt_pk_bf16_f32 v102, v56, v57
	v_cvt_pk_bf16_f32 v103, v58, v59
	v_cvt_pk_bf16_f32 v104, v52, v53
	v_cvt_pk_bf16_f32 v105, v54, v55
	v_lshlrev_b32_e32 v58, 16, v102
	v_and_b32_e32 v59, 0xffff0000, v102
	v_lshlrev_b32_e32 v56, 16, v103
	v_and_b32_e32 v57, 0xffff0000, v103
	v_lshlrev_b32_e32 v54, 16, v104
	v_and_b32_e32 v55, 0xffff0000, v104
	v_lshlrev_b32_e32 v52, 16, v105
	v_and_b32_e32 v53, 0xffff0000, v105
	global_store_dwordx4 v[202:203], v[102:105], off offset:2304
	v_pk_mul_f32 v[106:107], v[70:71], v[52:53]
	v_pk_mul_f32 v[180:181], v[68:69], v[54:55]
	v_pk_mul_f32 v[104:105], v[74:75], v[56:57]
	v_pk_mul_f32 v[102:103], v[72:73], v[58:59]
	v_fmac_f32_e32 v67, v66, v66
	v_cvt_pk_bf16_f32 v102, v102, v103
	v_cvt_pk_bf16_f32 v103, v104, v105
	v_cvt_pk_bf16_f32 v104, v180, v181
	v_cvt_pk_bf16_f32 v105, v106, v107
	global_store_dwordx4 v[220:221], v[102:105], off offset:256
	v_lshl_add_u64 v[106:107], v[164:165], 0, s[0:1]
	global_load_dwordx4 v[102:105], v[188:189], off offset:512
	global_load_dwordx4 v[180:183], v[106:107], off offset:16
	s_mov_b64 s[0:1], 0x30200
	v_lshl_add_u64 v[106:107], v[164:165], 0, s[0:1]
	global_load_dwordx4 v[184:187], v[190:191], off offset:512
	s_nop 0
	global_load_dwordx4 v[188:191], v[106:107], off offset:16
	s_mov_b64 s[0:1], 0x80200
	v_fmac_f32_e32 v65, v64, v64
	v_mul_f32_e32 v63, v63, v63
	v_mul_f32_e32 v61, v61, v61
	v_add_f32_e32 v64, v67, v65
	v_fmac_f32_e32 v63, v62, v62
	v_fmac_f32_e32 v61, v60, v60
	v_add_f32_e32 v60, v63, v61
	s_waitcnt vmcnt(0)
	v_pk_fma_f32 v[50:51], v[50:51], v[156:157], v[104:105]
	v_pk_fma_f32 v[48:49], v[48:49], v[158:159], v[102:103]
	v_pk_fma_f32 v[46:47], v[46:47], v[160:161], v[182:183]
	v_pk_fma_f32 v[44:45], v[44:45], v[162:163], v[180:181]
	v_cvt_pk_bf16_f32 v102, v48, v49
	v_cvt_pk_bf16_f32 v103, v50, v51
	v_cvt_pk_bf16_f32 v104, v44, v45
	v_cvt_pk_bf16_f32 v105, v46, v47
	v_lshlrev_b32_e32 v50, 16, v102
	v_and_b32_e32 v51, 0xffff0000, v102
	v_lshlrev_b32_e32 v48, 16, v103
	v_and_b32_e32 v49, 0xffff0000, v103
	v_lshlrev_b32_e32 v46, 16, v104
	v_and_b32_e32 v47, 0xffff0000, v104
	v_lshlrev_b32_e32 v44, 16, v105
	v_and_b32_e32 v45, 0xffff0000, v105
	global_store_dwordx4 v[192:193], v[102:105], off offset:2304
	v_pk_mul_f32 v[106:107], v[70:71], v[44:45]
	v_pk_mul_f32 v[180:181], v[68:69], v[46:47]
	v_pk_mul_f32 v[104:105], v[74:75], v[48:49]
	v_pk_mul_f32 v[102:103], v[72:73], v[50:51]
	v_pk_fma_f32 v[42:43], v[42:43], v[156:157], v[186:187]
	v_cvt_pk_bf16_f32 v102, v102, v103
	v_cvt_pk_bf16_f32 v103, v104, v105
	v_cvt_pk_bf16_f32 v104, v180, v181
	v_cvt_pk_bf16_f32 v105, v106, v107
	v_pk_fma_f32 v[40:41], v[40:41], v[158:159], v[184:185]
	v_pk_fma_f32 v[38:39], v[38:39], v[160:161], v[190:191]
	v_pk_fma_f32 v[36:37], v[36:37], v[162:163], v[188:189]
	global_store_dwordx4 v[194:195], v[102:105], off offset:256
	s_nop 1
	v_cvt_pk_bf16_f32 v102, v40, v41
	v_cvt_pk_bf16_f32 v103, v42, v43
	v_cvt_pk_bf16_f32 v104, v36, v37
	v_cvt_pk_bf16_f32 v105, v38, v39
	v_lshlrev_b32_e32 v42, 16, v102
	v_and_b32_e32 v43, 0xffff0000, v102
	v_lshlrev_b32_e32 v40, 16, v103
	v_and_b32_e32 v41, 0xffff0000, v103
	v_lshlrev_b32_e32 v38, 16, v104
	v_and_b32_e32 v39, 0xffff0000, v104
	v_lshlrev_b32_e32 v36, 16, v105
	v_and_b32_e32 v37, 0xffff0000, v105
	global_store_dwordx4 v[212:213], v[102:105], off offset:2304
	v_pk_mul_f32 v[106:107], v[70:71], v[36:37]
	v_pk_mul_f32 v[180:181], v[68:69], v[38:39]
	v_pk_mul_f32 v[104:105], v[74:75], v[40:41]
	v_pk_mul_f32 v[102:103], v[72:73], v[42:43]
	s_nop 0
	v_cvt_pk_bf16_f32 v102, v102, v103
	v_cvt_pk_bf16_f32 v103, v104, v105
	v_cvt_pk_bf16_f32 v104, v180, v181
	v_cvt_pk_bf16_f32 v105, v106, v107
	global_store_dwordx4 v[222:223], v[102:105], off offset:256
	v_lshl_add_u64 v[106:107], v[164:165], 0, s[0:1]
	global_load_dwordx4 v[102:105], v[196:197], off offset:512
	global_load_dwordx4 v[180:183], v[106:107], off offset:16
	s_mov_b64 s[0:1], 0x90200
	v_lshl_add_u64 v[106:107], v[164:165], 0, s[0:1]
	global_load_dwordx4 v[184:187], v[198:199], off offset:512
	global_load_dwordx4 v[188:191], v[106:107], off offset:16
	s_mov_b64 s[0:1], 0xa0200
	s_waitcnt vmcnt(0)
	v_pk_fma_f32 v[34:35], v[34:35], v[156:157], v[104:105]
	v_pk_fma_f32 v[32:33], v[32:33], v[158:159], v[102:103]
	v_pk_fma_f32 v[30:31], v[30:31], v[160:161], v[182:183]
	v_pk_fma_f32 v[28:29], v[28:29], v[162:163], v[180:181]
	v_cvt_pk_bf16_f32 v102, v32, v33
	v_cvt_pk_bf16_f32 v103, v34, v35
	v_cvt_pk_bf16_f32 v104, v28, v29
	v_cvt_pk_bf16_f32 v105, v30, v31
	v_lshlrev_b32_e32 v34, 16, v102
	v_and_b32_e32 v35, 0xffff0000, v102
	v_lshlrev_b32_e32 v32, 16, v103
	v_and_b32_e32 v33, 0xffff0000, v103
	v_lshlrev_b32_e32 v30, 16, v104
	v_and_b32_e32 v31, 0xffff0000, v104
	v_lshlrev_b32_e32 v28, 16, v105
	v_and_b32_e32 v29, 0xffff0000, v105
	global_store_dwordx4 v[200:201], v[102:105], off offset:2304
	v_pk_mul_f32 v[106:107], v[70:71], v[28:29]
	v_pk_mul_f32 v[180:181], v[68:69], v[30:31]
	v_pk_mul_f32 v[104:105], v[74:75], v[32:33]
	v_pk_mul_f32 v[102:103], v[72:73], v[34:35]
	v_pk_fma_f32 v[24:25], v[24:25], v[156:157], v[186:187]
	v_cvt_pk_bf16_f32 v102, v102, v103
	v_cvt_pk_bf16_f32 v103, v104, v105
	v_cvt_pk_bf16_f32 v104, v180, v181
	v_cvt_pk_bf16_f32 v105, v106, v107
	v_pk_fma_f32 v[22:23], v[22:23], v[158:159], v[184:185]
	v_pk_fma_f32 v[20:21], v[20:21], v[160:161], v[190:191]
	v_pk_fma_f32 v[18:19], v[18:19], v[162:163], v[188:189]
	global_store_dwordx4 v[204:205], v[102:105], off offset:256
	s_nop 1
	v_cvt_pk_bf16_f32 v102, v22, v23
	v_cvt_pk_bf16_f32 v103, v24, v25
	v_cvt_pk_bf16_f32 v104, v18, v19
	v_cvt_pk_bf16_f32 v105, v20, v21
	v_lshlrev_b32_e32 v24, 16, v102
	v_and_b32_e32 v25, 0xffff0000, v102
	v_lshlrev_b32_e32 v22, 16, v103
	v_and_b32_e32 v23, 0xffff0000, v103
	v_lshlrev_b32_e32 v20, 16, v104
	v_and_b32_e32 v21, 0xffff0000, v104
	v_lshlrev_b32_e32 v18, 16, v105
	v_and_b32_e32 v19, 0xffff0000, v105
	global_store_dwordx4 v[218:219], v[102:105], off offset:2304
	v_pk_mul_f32 v[106:107], v[70:71], v[18:19]
	v_pk_mul_f32 v[180:181], v[68:69], v[20:21]
	v_pk_mul_f32 v[104:105], v[74:75], v[22:23]
	v_pk_mul_f32 v[102:103], v[72:73], v[24:25]
	s_nop 0
	v_cvt_pk_bf16_f32 v102, v102, v103
	v_cvt_pk_bf16_f32 v103, v104, v105
	v_cvt_pk_bf16_f32 v104, v180, v181
	v_cvt_pk_bf16_f32 v105, v106, v107
	global_store_dwordx4 v[224:225], v[102:105], off offset:256
	v_lshl_add_u64 v[106:107], v[164:165], 0, s[0:1]
	global_load_dwordx4 v[102:105], v[206:207], off offset:512
	global_load_dwordx4 v[180:183], v[106:107], off offset:16
	s_mov_b64 s[0:1], 0xb0200
	v_lshl_add_u64 v[106:107], v[164:165], 0, s[0:1]
	global_load_dwordx4 v[184:187], v[208:209], off offset:512
	global_load_dwordx4 v[188:191], v[106:107], off offset:16
	s_waitcnt vmcnt(0)
	v_pk_fma_f32 v[16:17], v[16:17], v[156:157], v[104:105]
	v_pk_fma_f32 v[14:15], v[14:15], v[158:159], v[102:103]
	v_pk_fma_f32 v[102:103], v[12:13], v[160:161], v[182:183]
	v_pk_fma_f32 v[12:13], v[10:11], v[162:163], v[180:181]
	v_cvt_pk_bf16_f32 v10, v14, v15
	v_cvt_pk_bf16_f32 v11, v16, v17
	v_cvt_pk_bf16_f32 v12, v12, v13
	v_cvt_pk_bf16_f32 v13, v102, v103
	v_lshlrev_b32_e32 v102, 16, v10
	v_and_b32_e32 v103, 0xffff0000, v10
	v_lshlrev_b32_e32 v16, 16, v11
	v_and_b32_e32 v17, 0xffff0000, v11
	global_store_dwordx4 v[214:215], v[10:13], off offset:2304
	v_lshlrev_b32_e32 v14, 16, v12
	v_and_b32_e32 v15, 0xffff0000, v12
	v_lshlrev_b32_e32 v12, 16, v13
	v_and_b32_e32 v13, 0xffff0000, v13
	v_pk_mul_f32 v[10:11], v[74:75], v[16:17]
	v_pk_mul_f32 v[104:105], v[72:73], v[102:103]
	v_pk_mul_f32 v[164:165], v[70:71], v[12:13]
	v_pk_mul_f32 v[106:107], v[68:69], v[14:15]
	v_cvt_pk_bf16_f32 v104, v104, v105
	v_cvt_pk_bf16_f32 v105, v10, v11
	v_pk_fma_f32 v[8:9], v[8:9], v[156:157], v[186:187]
	v_pk_fma_f32 v[6:7], v[6:7], v[158:159], v[184:185]
	v_pk_fma_f32 v[10:11], v[4:5], v[160:161], v[190:191]
	v_pk_fma_f32 v[4:5], v[2:3], v[162:163], v[188:189]
	v_cvt_pk_bf16_f32 v106, v106, v107
	v_cvt_pk_bf16_f32 v107, v164, v165
	v_cvt_pk_bf16_f32 v2, v6, v7
	v_cvt_pk_bf16_f32 v3, v8, v9
	v_cvt_pk_bf16_f32 v4, v4, v5
	v_cvt_pk_bf16_f32 v5, v10, v11
	global_store_dwordx4 v[216:217], v[104:107], off offset:256
	global_store_dwordx4 v[210:211], v[2:5], off offset:2304
	v_lshlrev_b32_e32 v10, 16, v2
	v_and_b32_e32 v11, 0xffff0000, v2
	v_lshlrev_b32_e32 v8, 16, v3
	v_and_b32_e32 v9, 0xffff0000, v3
	v_lshlrev_b32_e32 v6, 16, v4
	v_and_b32_e32 v7, 0xffff0000, v4
	v_lshlrev_b32_e32 v4, 16, v5
	v_and_b32_e32 v5, 0xffff0000, v5
	v_pk_mul_f32 v[2:3], v[74:75], v[8:9]
	v_pk_mul_f32 v[72:73], v[72:73], v[10:11]
	v_pk_mul_f32 v[74:75], v[70:71], v[4:5]
	v_pk_mul_f32 v[70:71], v[68:69], v[6:7]
	v_cvt_pk_bf16_f32 v68, v72, v73
	v_cvt_pk_bf16_f32 v69, v2, v3
	v_cvt_pk_bf16_f32 v70, v70, v71
	v_cvt_pk_bf16_f32 v71, v74, v75
	global_store_dwordx4 v[100:101], v[68:71], off offset:256
	v_mul_f32_e32 v72, v133, v133
	v_fmac_f32_e32 v72, v132, v132
	v_and_b32_e32 v69, 64, v227
	v_xor_b32_e32 v68, 16, v227
	v_add_u32_e32 v69, 64, v69
	v_cmp_lt_i32_e32 vcc, v68, v69
	v_xor_b32_e32 v70, 32, v227
	v_mul_f32_e32 v71, v137, v137
	v_cndmask_b32_e32 v68, v227, v68, vcc
	v_cmp_lt_i32_e32 vcc, v70, v69
	v_fmac_f32_e32 v71, v136, v136
	v_lshlrev_b32_e32 v68, 2, v68
	v_cndmask_b32_e32 v69, v227, v70, vcc
	v_mul_f32_e32 v70, v139, v139
	v_fmac_f32_e32 v70, v138, v138
	v_add_f32_e32 v70, v70, v71
	v_mul_f32_e32 v71, v135, v135
	v_fmac_f32_e32 v71, v134, v134
	v_add_f32_e32 v71, v71, v72
	v_add_f32_e32 v70, v70, v71
	v_add_f32_e32 v64, v70, v64
	v_add_f32_e32 v60, v64, v60
	ds_bpermute_b32 v61, v68, v60
	v_lshlrev_b32_e32 v69, 2, v69
	v_lshl_add_u64 v[2:3], v[150:151], 0, s[52:53]
	s_waitcnt lgkmcnt(0)
	v_add_f32_e32 v60, v60, v61
	ds_bpermute_b32 v61, v69, v60
	s_and_saveexec_b64 s[18:19], s[38:39]
	s_cbranch_execz .LBB0_398
	s_waitcnt lgkmcnt(0)
	v_add_f32_e32 v60, v60, v61
	global_atomic_add_f32 v[2:3], v60, off

.LBB0_479:
	s_add_u32 s0, s22, 0xfffc0080
	s_addc_u32 s1, s23, -1
	s_add_i32 s69, 0, 0x10000
	s_cmp_eq_u32 s68, 12
	s_cselect_b32 s27, s35, s1
	s_cselect_b32 s26, s40, s0
	s_cselect_b32 s25, s41, s59
	s_cselect_b32 s24, s49, s51
	s_add_i32 m0, s37, 0xc000
	ds_read_b128 v[158:161], v165
	ds_read_b128 v[172:175], v165 offset:1024
	ds_read_b128 v[176:179], v165 offset:2048
	ds_read_b128 v[180:183], v165 offset:3072
	ds_read_b128 v[184:187], v165 offset:4096
	ds_read_b128 v[188:191], v165 offset:5120
	ds_read_b128 v[192:195], v165 offset:6144
	ds_read_b128 v[196:199], v165 offset:7168
	global_load_lds_dwordx4 v146, s[22:23]
	s_waitcnt vmcnt(10) lgkmcnt(8)
	s_setprio 1
	s_barrier
	s_waitcnt lgkmcnt(0)
	v_mfma_f32_16x16x32_bf16 v[136:139], v[100:103], v[158:161], v[136:139]
	v_mfma_f32_16x16x32_bf16 v[132:135], v[150:153], v[158:161], v[132:135]
	v_mfma_f32_16x16x32_bf16 v[128:131], v[100:103], v[176:179], v[128:131]
	v_mfma_f32_16x16x32_bf16 v[124:127], v[150:153], v[176:179], v[124:127]
	v_mfma_f32_16x16x32_bf16 v[120:123], v[100:103], v[184:187], v[120:123]
	v_mfma_f32_16x16x32_bf16 v[116:119], v[150:153], v[184:187], v[116:119]
	v_mfma_f32_16x16x32_bf16 v[112:115], v[100:103], v[192:195], v[112:115]
	v_mfma_f32_16x16x32_bf16 v[108:111], v[150:153], v[192:195], v[108:111]
	v_mfma_f32_16x16x32_bf16 v[136:139], v[104:107], v[172:175], v[136:139]
	v_mfma_f32_16x16x32_bf16 v[132:135], v[154:157], v[172:175], v[132:135]
	v_mfma_f32_16x16x32_bf16 v[128:131], v[104:107], v[180:183], v[128:131]
	v_mfma_f32_16x16x32_bf16 v[124:127], v[154:157], v[180:183], v[124:127]
	v_mfma_f32_16x16x32_bf16 v[120:123], v[104:107], v[188:191], v[120:123]
	v_mfma_f32_16x16x32_bf16 v[116:119], v[154:157], v[188:191], v[116:119]
	v_mfma_f32_16x16x32_bf16 v[112:115], v[104:107], v[196:199], v[112:115]
	v_mfma_f32_16x16x32_bf16 v[108:111], v[154:157], v[196:199], v[108:111]
	s_barrier
	s_setprio 0
	s_add_i32 s72, 0, 0x14000
	v_add_u32_e32 v166, s72, v163
	s_add_i32 s0, s69, s36
	ds_read_b128 v[200:203], v166
	ds_read_b128 v[204:207], v166 offset:1024
	ds_read_b128 v[208:211], v166 offset:2048
	ds_read_b128 v[212:215], v166 offset:3072
	v_lshl_add_u64 v[166:167], s[24:25], 0, v[26:27]
	s_mov_b32 m0, s0
	v_lshl_add_u64 v[168:169], s[24:25], 0, v[140:141]
	global_load_lds_dwordx4 v[166:167], off
	s_add_i32 m0, s0, 0x2000
	s_nop 0
	global_load_lds_dwordx4 v[168:169], off
	v_lshl_add_u64 v[238:239], s[22:23], 0, v[148:149]
	s_add_i32 m0, s37, 0xe000
	s_nop 0
	global_load_lds_dwordx4 v[238:239], off
	s_waitcnt vmcnt(8)
	s_setprio 1
	s_barrier
	s_waitcnt lgkmcnt(0)
	v_mfma_f32_16x16x32_bf16 v[64:67], v[200:203], v[158:161], v[64:67]
	v_mfma_f32_16x16x32_bf16 v[60:63], v[208:211], v[158:161], v[60:63]
	v_mfma_f32_16x16x32_bf16 v[56:59], v[200:203], v[176:179], v[56:59]
	v_mfma_f32_16x16x32_bf16 v[52:55], v[208:211], v[176:179], v[52:55]
	v_mfma_f32_16x16x32_bf16 v[48:51], v[200:203], v[184:187], v[48:51]
	v_mfma_f32_16x16x32_bf16 v[44:47], v[208:211], v[184:187], v[44:47]
	v_mfma_f32_16x16x32_bf16 v[40:43], v[200:203], v[192:195], v[40:43]
	v_mfma_f32_16x16x32_bf16 v[36:39], v[208:211], v[192:195], v[36:39]
	v_mfma_f32_16x16x32_bf16 v[64:67], v[204:207], v[172:175], v[64:67]
	v_mfma_f32_16x16x32_bf16 v[60:63], v[212:215], v[172:175], v[60:63]
	v_mfma_f32_16x16x32_bf16 v[56:59], v[204:207], v[180:183], v[56:59]
	v_mfma_f32_16x16x32_bf16 v[52:55], v[212:215], v[180:183], v[52:55]
	v_mfma_f32_16x16x32_bf16 v[48:51], v[204:207], v[188:191], v[48:51]
	v_mfma_f32_16x16x32_bf16 v[44:47], v[212:215], v[188:191], v[44:47]
	v_mfma_f32_16x16x32_bf16 v[40:43], v[204:207], v[196:199], v[40:43]
	v_mfma_f32_16x16x32_bf16 v[36:39], v[212:215], v[196:199], v[36:39]
	s_barrier
	s_setprio 0
	s_mov_b32 m0, s37
	v_lshl_add_u64 v[216:217], s[26:27], 0, v[144:145]
	ds_read_b128 v[158:161], v165 offset:16384
	ds_read_b128 v[172:175], v165 offset:17408
	ds_read_b128 v[176:179], v165 offset:18432
	ds_read_b128 v[180:183], v165 offset:19456
	ds_read_b128 v[184:187], v165 offset:20480
	ds_read_b128 v[188:191], v165 offset:21504
	ds_read_b128 v[192:195], v165 offset:22528
	ds_read_b128 v[196:199], v165 offset:23552
	global_load_lds_dwordx4 v[216:217], off
	s_waitcnt vmcnt(10)
	s_setprio 1
	s_barrier
	s_waitcnt lgkmcnt(0)
	v_mfma_f32_16x16x32_bf16 v[96:99], v[100:103], v[158:161], v[96:99]
	v_mfma_f32_16x16x32_bf16 v[92:95], v[150:153], v[158:161], v[92:95]
	v_mfma_f32_16x16x32_bf16 v[88:91], v[100:103], v[176:179], v[88:91]
	v_mfma_f32_16x16x32_bf16 v[84:87], v[150:153], v[176:179], v[84:87]
	v_mfma_f32_16x16x32_bf16 v[80:83], v[100:103], v[184:187], v[80:83]
	v_mfma_f32_16x16x32_bf16 v[76:79], v[150:153], v[184:187], v[76:79]
	v_mfma_f32_16x16x32_bf16 v[72:75], v[100:103], v[192:195], v[72:75]
	v_mfma_f32_16x16x32_bf16 v[68:71], v[150:153], v[192:195], v[68:71]
	v_mfma_f32_16x16x32_bf16 v[96:99], v[104:107], v[172:175], v[96:99]
	v_mfma_f32_16x16x32_bf16 v[92:95], v[154:157], v[172:175], v[92:95]
	v_mfma_f32_16x16x32_bf16 v[88:91], v[104:107], v[180:183], v[88:91]
	v_mfma_f32_16x16x32_bf16 v[84:87], v[154:157], v[180:183], v[84:87]
	v_mfma_f32_16x16x32_bf16 v[80:83], v[104:107], v[188:191], v[80:83]
	v_mfma_f32_16x16x32_bf16 v[76:79], v[154:157], v[188:191], v[76:79]
	v_mfma_f32_16x16x32_bf16 v[72:75], v[104:107], v[196:199], v[72:75]
	v_mfma_f32_16x16x32_bf16 v[68:71], v[154:157], v[196:199], v[68:71]
	s_barrier
	s_setprio 0
	s_add_u32 s0, s24, 0x40000
	s_addc_u32 s1, s25, 0
	s_add_i32 s69, s72, s36
	s_mov_b32 m0, s69
	s_nop 0
	global_load_lds_dwordx4 v26, s[0:1]
	s_add_i32 m0, s69, 0x2000
	s_nop 0
	global_load_lds_dwordx4 v140, s[0:1]
	v_lshl_add_u64 v[218:219], s[26:27], 0, v[142:143]
	s_mov_b32 m0, s56
	s_nop 0
	global_load_lds_dwordx4 v[218:219], off
	v_add_u32_e32 v154, 0x18000, v163
	ds_read_b128 v[100:103], v154
	ds_read_b128 v[104:107], v154 offset:1024
	ds_read_b128 v[150:153], v154 offset:2048
	ds_read_b128 v[154:157], v154 offset:3072
	s_waitcnt vmcnt(8)
	s_setprio 1
	s_barrier
	v_mfma_f32_16x16x32_bf16 v[32:35], v[200:203], v[158:161], v[32:35]
	v_mfma_f32_16x16x32_bf16 v[28:31], v[208:211], v[158:161], v[28:31]
	v_mfma_f32_16x16x32_bf16 v[22:25], v[200:203], v[176:179], v[22:25]
	v_mfma_f32_16x16x32_bf16 v[18:21], v[208:211], v[176:179], v[18:21]
	v_mfma_f32_16x16x32_bf16 v[14:17], v[200:203], v[184:187], v[14:17]
	v_mfma_f32_16x16x32_bf16 v[10:13], v[208:211], v[184:187], v[10:13]
	v_mfma_f32_16x16x32_bf16 v[6:9], v[200:203], v[192:195], v[6:9]
	v_mfma_f32_16x16x32_bf16 v[2:5], v[208:211], v[192:195], v[2:5]
	v_mfma_f32_16x16x32_bf16 v[32:35], v[204:207], v[172:175], v[32:35]
	v_mfma_f32_16x16x32_bf16 v[28:31], v[212:215], v[172:175], v[28:31]
	v_mfma_f32_16x16x32_bf16 v[22:25], v[204:207], v[180:183], v[22:25]
	v_mfma_f32_16x16x32_bf16 v[18:21], v[212:215], v[180:183], v[18:21]
	v_mfma_f32_16x16x32_bf16 v[14:17], v[204:207], v[188:191], v[14:17]
	v_mfma_f32_16x16x32_bf16 v[10:13], v[212:215], v[188:191], v[10:13]
	v_mfma_f32_16x16x32_bf16 v[6:9], v[204:207], v[196:199], v[6:9]
	v_mfma_f32_16x16x32_bf16 v[2:5], v[212:215], v[196:199], v[2:5]
	s_barrier
	s_setprio 0
	s_add_i32 s69, 0, 0x18000
	s_add_u32 s0, s26, 0x40000
	s_addc_u32 s1, s27, 0
	s_mov_b32 m0, s57
	ds_read_b128 v[158:161], v165 offset:32768
	ds_read_b128 v[172:175], v165 offset:33792
	ds_read_b128 v[176:179], v165 offset:34816
	ds_read_b128 v[180:183], v165 offset:35840
	ds_read_b128 v[184:187], v165 offset:36864
	ds_read_b128 v[188:191], v165 offset:37888
	ds_read_b128 v[192:195], v165 offset:38912
	ds_read_b128 v[196:199], v165 offset:39936
	global_load_lds_dwordx4 v144, s[0:1]
	s_mov_b64 s[100:101], s[0:1]
	s_waitcnt vmcnt(10) lgkmcnt(8)
	s_setprio 1
	s_barrier
	s_waitcnt lgkmcnt(0)
	v_mfma_f32_16x16x32_bf16 v[136:139], v[100:103], v[158:161], v[136:139]
	v_mfma_f32_16x16x32_bf16 v[132:135], v[150:153], v[158:161], v[132:135]
	v_mfma_f32_16x16x32_bf16 v[128:131], v[100:103], v[176:179], v[128:131]
	v_mfma_f32_16x16x32_bf16 v[124:127], v[150:153], v[176:179], v[124:127]
	v_mfma_f32_16x16x32_bf16 v[120:123], v[100:103], v[184:187], v[120:123]
	v_mfma_f32_16x16x32_bf16 v[116:119], v[150:153], v[184:187], v[116:119]
	v_mfma_f32_16x16x32_bf16 v[112:115], v[100:103], v[192:195], v[112:115]
	v_mfma_f32_16x16x32_bf16 v[108:111], v[150:153], v[192:195], v[108:111]
	v_mfma_f32_16x16x32_bf16 v[136:139], v[104:107], v[172:175], v[136:139]
	v_mfma_f32_16x16x32_bf16 v[132:135], v[154:157], v[172:175], v[132:135]
	v_mfma_f32_16x16x32_bf16 v[128:131], v[104:107], v[180:183], v[128:131]
	v_mfma_f32_16x16x32_bf16 v[124:127], v[154:157], v[180:183], v[124:127]
	v_mfma_f32_16x16x32_bf16 v[120:123], v[104:107], v[188:191], v[120:123]
	v_mfma_f32_16x16x32_bf16 v[116:119], v[154:157], v[188:191], v[116:119]
	v_mfma_f32_16x16x32_bf16 v[112:115], v[104:107], v[196:199], v[112:115]
	v_mfma_f32_16x16x32_bf16 v[108:111], v[154:157], v[196:199], v[108:111]
	s_barrier
	s_setprio 0
	s_add_i32 s26, 0, 0x1c000
	s_add_i32 s0, s69, s36
	v_add_u32_e32 v212, s26, v163
	v_lshl_add_u64 v[166:167], v[166:167], 0, s[12:13]
	s_mov_b32 m0, s0
	ds_read_b128 v[200:203], v212
	ds_read_b128 v[204:207], v212 offset:1024
	ds_read_b128 v[208:211], v212 offset:2048
	ds_read_b128 v[212:215], v212 offset:3072
	global_load_lds_dwordx4 v[166:167], off
	v_lshl_add_u64 v[166:167], v[168:169], 0, s[12:13]
	s_add_i32 m0, s0, 0x2000
	s_nop 0
	global_load_lds_dwordx4 v[166:167], off
	s_mov_b32 m0, s58
	s_nop 0
	global_load_lds_dwordx4 v142, s[100:101]
	s_waitcnt vmcnt(8)
	s_setprio 1
	s_barrier
	s_waitcnt lgkmcnt(0)
	v_mfma_f32_16x16x32_bf16 v[64:67], v[200:203], v[158:161], v[64:67]
	v_mfma_f32_16x16x32_bf16 v[60:63], v[208:211], v[158:161], v[60:63]
	v_mfma_f32_16x16x32_bf16 v[56:59], v[200:203], v[176:179], v[56:59]
	v_mfma_f32_16x16x32_bf16 v[52:55], v[208:211], v[176:179], v[52:55]
	v_mfma_f32_16x16x32_bf16 v[48:51], v[200:203], v[184:187], v[48:51]
	v_mfma_f32_16x16x32_bf16 v[44:47], v[208:211], v[184:187], v[44:47]
	v_mfma_f32_16x16x32_bf16 v[40:43], v[200:203], v[192:195], v[40:43]
	v_mfma_f32_16x16x32_bf16 v[36:39], v[208:211], v[192:195], v[36:39]
	v_mfma_f32_16x16x32_bf16 v[64:67], v[204:207], v[172:175], v[64:67]
	v_mfma_f32_16x16x32_bf16 v[60:63], v[212:215], v[172:175], v[60:63]
	v_mfma_f32_16x16x32_bf16 v[56:59], v[204:207], v[180:183], v[56:59]
	v_mfma_f32_16x16x32_bf16 v[52:55], v[212:215], v[180:183], v[52:55]
	v_mfma_f32_16x16x32_bf16 v[48:51], v[204:207], v[188:191], v[48:51]
	v_mfma_f32_16x16x32_bf16 v[44:47], v[212:215], v[188:191], v[44:47]
	v_mfma_f32_16x16x32_bf16 v[40:43], v[204:207], v[196:199], v[40:43]
	v_mfma_f32_16x16x32_bf16 v[36:39], v[212:215], v[196:199], v[36:39]
	s_barrier
	s_setprio 0
	s_mov_b32 m0, s28
	v_lshl_add_u64 v[166:167], v[216:217], 0, s[12:13]
	ds_read_b128 v[158:161], v165 offset:49152
	ds_read_b128 v[172:175], v165 offset:50176
	ds_read_b128 v[176:179], v165 offset:51200
	ds_read_b128 v[180:183], v165 offset:52224
	ds_read_b128 v[184:187], v165 offset:53248
	ds_read_b128 v[188:191], v165 offset:54272
	ds_read_b128 v[192:195], v165 offset:55296
	ds_read_b128 v[196:199], v165 offset:56320
	global_load_lds_dwordx4 v[166:167], off
	s_waitcnt vmcnt(10)
	s_setprio 1
	s_barrier
	s_waitcnt lgkmcnt(0)
	v_mfma_f32_16x16x32_bf16 v[96:99], v[100:103], v[158:161], v[96:99]
	v_mfma_f32_16x16x32_bf16 v[92:95], v[150:153], v[158:161], v[92:95]
	v_mfma_f32_16x16x32_bf16 v[88:91], v[100:103], v[176:179], v[88:91]
	v_mfma_f32_16x16x32_bf16 v[84:87], v[150:153], v[176:179], v[84:87]
	v_mfma_f32_16x16x32_bf16 v[80:83], v[100:103], v[184:187], v[80:83]
	v_mfma_f32_16x16x32_bf16 v[76:79], v[150:153], v[184:187], v[76:79]
	v_mfma_f32_16x16x32_bf16 v[72:75], v[100:103], v[192:195], v[72:75]
	v_mfma_f32_16x16x32_bf16 v[68:71], v[150:153], v[192:195], v[68:71]
	v_mfma_f32_16x16x32_bf16 v[96:99], v[104:107], v[172:175], v[96:99]
	v_mfma_f32_16x16x32_bf16 v[92:95], v[154:157], v[172:175], v[92:95]
	v_mfma_f32_16x16x32_bf16 v[88:91], v[104:107], v[180:183], v[88:91]
	v_mfma_f32_16x16x32_bf16 v[84:87], v[154:157], v[180:183], v[84:87]
	v_mfma_f32_16x16x32_bf16 v[80:83], v[104:107], v[188:191], v[80:83]
	v_mfma_f32_16x16x32_bf16 v[76:79], v[154:157], v[188:191], v[76:79]
	v_mfma_f32_16x16x32_bf16 v[72:75], v[104:107], v[196:199], v[72:75]
	v_mfma_f32_16x16x32_bf16 v[68:71], v[154:157], v[196:199], v[68:71]
	s_barrier
	s_setprio 0
	s_add_u32 s0, s24, 0x40080
	s_addc_u32 s1, s25, 0
	s_add_i32 s24, s26, s36
	s_mov_b32 m0, s24
	s_nop 0
	global_load_lds_dwordx4 v26, s[0:1]
	s_add_i32 m0, s24, 0x2000
	s_nop 0
	global_load_lds_dwordx4 v140, s[0:1]
	v_lshl_add_u64 v[166:167], v[218:219], 0, s[12:13]
	s_mov_b32 m0, s29
	s_nop 0
	global_load_lds_dwordx4 v[166:167], off
	v_add_u32_e32 v154, 0x10000, v163
	ds_read_b128 v[100:103], v154
	ds_read_b128 v[104:107], v154 offset:1024
	ds_read_b128 v[150:153], v154 offset:2048
	ds_read_b128 v[154:157], v154 offset:3072
	s_waitcnt vmcnt(8)
	s_setprio 1
	s_barrier
	v_mfma_f32_16x16x32_bf16 v[32:35], v[200:203], v[158:161], v[32:35]
	v_mfma_f32_16x16x32_bf16 v[28:31], v[208:211], v[158:161], v[28:31]
	v_mfma_f32_16x16x32_bf16 v[22:25], v[200:203], v[176:179], v[22:25]
	v_mfma_f32_16x16x32_bf16 v[18:21], v[208:211], v[176:179], v[18:21]
	v_mfma_f32_16x16x32_bf16 v[14:17], v[200:203], v[184:187], v[14:17]
	v_mfma_f32_16x16x32_bf16 v[10:13], v[208:211], v[184:187], v[10:13]
	v_mfma_f32_16x16x32_bf16 v[6:9], v[200:203], v[192:195], v[6:9]
	v_mfma_f32_16x16x32_bf16 v[2:5], v[208:211], v[192:195], v[2:5]
	v_mfma_f32_16x16x32_bf16 v[32:35], v[204:207], v[172:175], v[32:35]
	v_mfma_f32_16x16x32_bf16 v[28:31], v[212:215], v[172:175], v[28:31]
	v_mfma_f32_16x16x32_bf16 v[22:25], v[204:207], v[180:183], v[22:25]
	v_mfma_f32_16x16x32_bf16 v[18:21], v[212:215], v[180:183], v[18:21]
	v_mfma_f32_16x16x32_bf16 v[14:17], v[204:207], v[188:191], v[14:17]
	v_mfma_f32_16x16x32_bf16 v[10:13], v[212:215], v[188:191], v[10:13]
	v_mfma_f32_16x16x32_bf16 v[6:9], v[204:207], v[196:199], v[6:9]
	v_mfma_f32_16x16x32_bf16 v[2:5], v[212:215], v[196:199], v[2:5]
	s_barrier
	s_setprio 0
	s_add_i32 s68, s68, 2
	s_add_u32 s22, s22, 0x100
	s_addc_u32 s23, s23, 0
	s_add_u32 s51, s51, 0x100
	s_addc_u32 s59, s59, 0
	s_cmp_gt_u32 s68, 13
	s_cbranch_scc0 .LBB0_479
	s_waitcnt lgkmcnt(0)
	s_cmpk_gt_i32 s34, 0xff
	s_mov_b64 s[22:23], 0xb000
	s_cbranch_scc1 .LBB0_482
	s_ashr_i32 s0, s34, 5
	s_mul_hi_i32 s23, s0, 0x1600
	s_mul_i32 s22, s0, 0x1600

.LBB0_887:
	s_add_u32 s24, s22, 0x100
	s_addc_u32 s25, s23, 0
	s_add_i32 s0, 0, 0x10000
	s_cmp_eq_u32 s51, 4
	s_cselect_b32 s29, s47, s25
	s_cselect_b32 s28, s46, s24
	s_cselect_b32 s27, s18, s50
	s_cselect_b32 s26, s19, s45
	s_add_i32 m0, s58, 0xc000
	ds_read_b128 v[150:153], v193
	ds_read_b128 v[154:157], v193 offset:1024
	ds_read_b128 v[158:161], v193 offset:2048
	ds_read_b128 v[162:165], v193 offset:3072
	ds_read_b128 v[184:187], v193 offset:4096
	ds_read_b128 v[194:197], v193 offset:5120
	ds_read_b128 v[198:201], v193 offset:6144
	ds_read_b128 v[202:205], v193 offset:7168
	global_load_lds_dwordx4 v180, s[22:23]
	s_mov_b64 s[100:101], s[22:23]
	s_waitcnt vmcnt(10) lgkmcnt(8)
	s_setprio 1
	s_barrier
	s_waitcnt lgkmcnt(0)
	v_mfma_f32_16x16x32_bf16 v[130:133], v[134:137], v[150:153], v[130:133]
	v_mfma_f32_16x16x32_bf16 v[126:129], v[142:145], v[150:153], v[126:129]
	v_mfma_f32_16x16x32_bf16 v[122:125], v[134:137], v[158:161], v[122:125]
	v_mfma_f32_16x16x32_bf16 v[118:121], v[142:145], v[158:161], v[118:121]
	v_mfma_f32_16x16x32_bf16 v[114:117], v[134:137], v[184:187], v[114:117]
	v_mfma_f32_16x16x32_bf16 v[110:113], v[142:145], v[184:187], v[110:113]
	v_mfma_f32_16x16x32_bf16 v[106:109], v[134:137], v[198:201], v[106:109]
	v_mfma_f32_16x16x32_bf16 v[102:105], v[142:145], v[198:201], v[102:105]
	v_mfma_f32_16x16x32_bf16 v[130:133], v[138:141], v[154:157], v[130:133]
	v_mfma_f32_16x16x32_bf16 v[126:129], v[146:149], v[154:157], v[126:129]
	v_mfma_f32_16x16x32_bf16 v[122:125], v[138:141], v[162:165], v[122:125]
	v_mfma_f32_16x16x32_bf16 v[118:121], v[146:149], v[162:165], v[118:121]
	v_mfma_f32_16x16x32_bf16 v[114:117], v[138:141], v[194:197], v[114:117]
	v_mfma_f32_16x16x32_bf16 v[110:113], v[146:149], v[194:197], v[110:113]
	v_mfma_f32_16x16x32_bf16 v[106:109], v[138:141], v[202:205], v[106:109]
	v_mfma_f32_16x16x32_bf16 v[102:105], v[146:149], v[202:205], v[102:105]
	s_barrier
	s_setprio 0
	s_add_i32 s22, 0, 0x14000
	s_add_i32 s0, s0, s55
	v_add_u32_e32 v26, s22, v191
	v_lshl_add_u64 v[166:167], s[26:27], 0, v[176:177]
	s_mov_b32 m0, s0
	ds_read_b128 v[206:209], v26
	ds_read_b128 v[210:213], v26 offset:1024
	ds_read_b128 v[214:217], v26 offset:2048
	ds_read_b128 v[218:221], v26 offset:3072
	global_load_lds_dwordx4 v[166:167], off
	v_lshl_add_u64 v[168:169], s[26:27], 0, v[172:173]
	s_add_i32 m0, s0, 0x2000
	s_nop 0
	global_load_lds_dwordx4 v[168:169], off
	s_add_i32 m0, s58, 0xe000
	s_nop 0
	global_load_lds_dwordx4 v182, s[100:101]
	s_waitcnt vmcnt(8)
	s_setprio 1
	s_barrier
	s_waitcnt lgkmcnt(0)
	v_mfma_f32_16x16x32_bf16 v[98:101], v[206:209], v[150:153], v[98:101]
	v_mfma_f32_16x16x32_bf16 v[94:97], v[214:217], v[150:153], v[94:97]
	v_mfma_f32_16x16x32_bf16 v[90:93], v[206:209], v[158:161], v[90:93]
	v_mfma_f32_16x16x32_bf16 v[86:89], v[214:217], v[158:161], v[86:89]
	v_mfma_f32_16x16x32_bf16 v[82:85], v[206:209], v[184:187], v[82:85]
	v_mfma_f32_16x16x32_bf16 v[78:81], v[214:217], v[184:187], v[78:81]
	v_mfma_f32_16x16x32_bf16 v[74:77], v[206:209], v[198:201], v[74:77]
	v_mfma_f32_16x16x32_bf16 v[70:73], v[214:217], v[198:201], v[70:73]
	v_mfma_f32_16x16x32_bf16 v[98:101], v[210:213], v[154:157], v[98:101]
	v_mfma_f32_16x16x32_bf16 v[94:97], v[218:221], v[154:157], v[94:97]
	v_mfma_f32_16x16x32_bf16 v[90:93], v[210:213], v[162:165], v[90:93]
	v_mfma_f32_16x16x32_bf16 v[86:89], v[218:221], v[162:165], v[86:89]
	v_mfma_f32_16x16x32_bf16 v[82:85], v[210:213], v[194:197], v[82:85]
	v_mfma_f32_16x16x32_bf16 v[78:81], v[218:221], v[194:197], v[78:81]
	v_mfma_f32_16x16x32_bf16 v[74:77], v[210:213], v[202:205], v[74:77]
	v_mfma_f32_16x16x32_bf16 v[70:73], v[218:221], v[202:205], v[70:73]
	s_barrier
	s_setprio 0
	s_mov_b32 m0, s58
	v_lshl_add_u64 v[188:189], s[28:29], 0, v[178:179]
	ds_read_b128 v[150:153], v193 offset:16384
	ds_read_b128 v[154:157], v193 offset:17408
	ds_read_b128 v[158:161], v193 offset:18432
	ds_read_b128 v[162:165], v193 offset:19456
	ds_read_b128 v[184:187], v193 offset:20480
	ds_read_b128 v[194:197], v193 offset:21504
	ds_read_b128 v[198:201], v193 offset:22528
	ds_read_b128 v[202:205], v193 offset:23552
	global_load_lds_dwordx4 v[188:189], off
	s_waitcnt vmcnt(10)
	s_setprio 1
	s_barrier
	s_waitcnt lgkmcnt(0)
	v_mfma_f32_16x16x32_bf16 v[66:69], v[134:137], v[150:153], v[66:69]
	v_mfma_f32_16x16x32_bf16 v[62:65], v[142:145], v[150:153], v[62:65]
	v_mfma_f32_16x16x32_bf16 v[58:61], v[134:137], v[158:161], v[58:61]
	v_mfma_f32_16x16x32_bf16 v[54:57], v[142:145], v[158:161], v[54:57]
	v_mfma_f32_16x16x32_bf16 v[50:53], v[134:137], v[184:187], v[50:53]
	v_mfma_f32_16x16x32_bf16 v[46:49], v[142:145], v[184:187], v[46:49]
	v_mfma_f32_16x16x32_bf16 v[42:45], v[134:137], v[198:201], v[42:45]
	v_mfma_f32_16x16x32_bf16 v[38:41], v[142:145], v[198:201], v[38:41]
	v_mfma_f32_16x16x32_bf16 v[66:69], v[138:141], v[154:157], v[66:69]
	v_mfma_f32_16x16x32_bf16 v[62:65], v[146:149], v[154:157], v[62:65]
	v_mfma_f32_16x16x32_bf16 v[58:61], v[138:141], v[162:165], v[58:61]
	v_mfma_f32_16x16x32_bf16 v[54:57], v[146:149], v[162:165], v[54:57]
	v_mfma_f32_16x16x32_bf16 v[50:53], v[138:141], v[194:197], v[50:53]
	v_mfma_f32_16x16x32_bf16 v[46:49], v[146:149], v[194:197], v[46:49]
	v_mfma_f32_16x16x32_bf16 v[42:45], v[138:141], v[202:205], v[42:45]
	v_mfma_f32_16x16x32_bf16 v[38:41], v[146:149], v[202:205], v[38:41]
	s_barrier
	s_setprio 0
	s_add_u32 s0, s26, 0x20000
	s_addc_u32 s1, s27, 0
	s_add_i32 s22, s22, s55
	s_mov_b32 m0, s22
	s_nop 0
	global_load_lds_dwordx4 v176, s[0:1]
	s_add_i32 m0, s22, 0x2000
	s_nop 0
	global_load_lds_dwordx4 v172, s[0:1]
	v_lshl_add_u64 v[222:223], s[28:29], 0, v[174:175]
	s_mov_b32 m0, s59
	s_nop 0
	global_load_lds_dwordx4 v[222:223], off
	v_add_u32_e32 v26, 0x18000, v191
	ds_read_b128 v[134:137], v26
	ds_read_b128 v[138:141], v26 offset:1024
	ds_read_b128 v[142:145], v26 offset:2048
	ds_read_b128 v[146:149], v26 offset:3072
	s_waitcnt vmcnt(8)
	s_setprio 1
	s_barrier
	v_mfma_f32_16x16x32_bf16 v[34:37], v[206:209], v[150:153], v[34:37]
	v_mfma_f32_16x16x32_bf16 v[28:31], v[214:217], v[150:153], v[30:33]
	v_mfma_f32_16x16x32_bf16 v[22:25], v[206:209], v[158:161], v[22:25]
	v_mfma_f32_16x16x32_bf16 v[18:21], v[214:217], v[158:161], v[18:21]
	v_mfma_f32_16x16x32_bf16 v[14:17], v[206:209], v[184:187], v[14:17]
	v_mfma_f32_16x16x32_bf16 v[10:13], v[214:217], v[184:187], v[10:13]
	v_mfma_f32_16x16x32_bf16 v[6:9], v[206:209], v[198:201], v[6:9]
	v_mfma_f32_16x16x32_bf16 v[2:5], v[214:217], v[198:201], v[2:5]
	v_mfma_f32_16x16x32_bf16 v[34:37], v[210:213], v[154:157], v[34:37]
	v_mfma_f32_16x16x32_bf16 v[28:31], v[218:221], v[154:157], v[28:31]
	v_mfma_f32_16x16x32_bf16 v[22:25], v[210:213], v[162:165], v[22:25]
	v_mfma_f32_16x16x32_bf16 v[18:21], v[218:221], v[162:165], v[18:21]
	v_mfma_f32_16x16x32_bf16 v[14:17], v[210:213], v[194:197], v[14:17]
	v_mfma_f32_16x16x32_bf16 v[10:13], v[218:221], v[194:197], v[10:13]
	v_mfma_f32_16x16x32_bf16 v[6:9], v[210:213], v[202:205], v[6:9]
	v_mfma_f32_16x16x32_bf16 v[2:5], v[218:221], v[202:205], v[2:5]
	s_barrier
	s_setprio 0
	s_add_i32 s22, 0, 0x18000
	s_add_u32 s0, s28, 0x140000
	s_addc_u32 s1, s29, 0
	s_mov_b32 m0, s68
	ds_read_b128 v[150:153], v193 offset:32768
	ds_read_b128 v[154:157], v193 offset:33792
	ds_read_b128 v[158:161], v193 offset:34816
	ds_read_b128 v[162:165], v193 offset:35840
	ds_read_b128 v[184:187], v193 offset:36864
	ds_read_b128 v[194:197], v193 offset:37888
	ds_read_b128 v[198:201], v193 offset:38912
	ds_read_b128 v[202:205], v193 offset:39936
	global_load_lds_dwordx4 v178, s[0:1]
	s_mov_b64 s[100:101], s[0:1]
	s_waitcnt vmcnt(10) lgkmcnt(8)
	s_setprio 1
	s_barrier
	s_waitcnt lgkmcnt(0)
	v_mfma_f32_16x16x32_bf16 v[130:133], v[134:137], v[150:153], v[130:133]
	v_mfma_f32_16x16x32_bf16 v[126:129], v[142:145], v[150:153], v[126:129]
	v_mfma_f32_16x16x32_bf16 v[122:125], v[134:137], v[158:161], v[122:125]
	v_mfma_f32_16x16x32_bf16 v[118:121], v[142:145], v[158:161], v[118:121]
	v_mfma_f32_16x16x32_bf16 v[114:117], v[134:137], v[184:187], v[114:117]
	v_mfma_f32_16x16x32_bf16 v[110:113], v[142:145], v[184:187], v[110:113]
	v_mfma_f32_16x16x32_bf16 v[106:109], v[134:137], v[198:201], v[106:109]
	v_mfma_f32_16x16x32_bf16 v[102:105], v[142:145], v[198:201], v[102:105]
	v_mfma_f32_16x16x32_bf16 v[130:133], v[138:141], v[154:157], v[130:133]
	v_mfma_f32_16x16x32_bf16 v[126:129], v[146:149], v[154:157], v[126:129]
	v_mfma_f32_16x16x32_bf16 v[122:125], v[138:141], v[162:165], v[122:125]
	v_mfma_f32_16x16x32_bf16 v[118:121], v[146:149], v[162:165], v[118:121]
	v_mfma_f32_16x16x32_bf16 v[114:117], v[138:141], v[194:197], v[114:117]
	v_mfma_f32_16x16x32_bf16 v[110:113], v[146:149], v[194:197], v[110:113]
	v_mfma_f32_16x16x32_bf16 v[106:109], v[138:141], v[202:205], v[106:109]
	v_mfma_f32_16x16x32_bf16 v[102:105], v[146:149], v[202:205], v[102:105]
	s_barrier
	s_setprio 0
	s_add_i32 s23, 0, 0x1c000
	s_add_i32 s0, s22, s55
	v_add_u32_e32 v26, s23, v191
	v_lshl_add_u64 v[32:33], v[166:167], 0, s[12:13]
	s_mov_b32 m0, s0
	ds_read_b128 v[206:209], v26
	ds_read_b128 v[210:213], v26 offset:1024
	ds_read_b128 v[214:217], v26 offset:2048
	ds_read_b128 v[218:221], v26 offset:3072
	global_load_lds_dwordx4 v[32:33], off
	v_lshl_add_u64 v[32:33], v[168:169], 0, s[12:13]
	s_add_i32 m0, s0, 0x2000
	s_nop 0
	global_load_lds_dwordx4 v[32:33], off
	s_mov_b32 m0, s69
	s_nop 0
	global_load_lds_dwordx4 v174, s[100:101]
	s_waitcnt vmcnt(8)
	s_setprio 1
	s_barrier
	s_waitcnt lgkmcnt(0)
	v_mfma_f32_16x16x32_bf16 v[98:101], v[206:209], v[150:153], v[98:101]
	v_mfma_f32_16x16x32_bf16 v[94:97], v[214:217], v[150:153], v[94:97]
	v_mfma_f32_16x16x32_bf16 v[90:93], v[206:209], v[158:161], v[90:93]
	v_mfma_f32_16x16x32_bf16 v[86:89], v[214:217], v[158:161], v[86:89]
	v_mfma_f32_16x16x32_bf16 v[82:85], v[206:209], v[184:187], v[82:85]
	v_mfma_f32_16x16x32_bf16 v[78:81], v[214:217], v[184:187], v[78:81]
	v_mfma_f32_16x16x32_bf16 v[74:77], v[206:209], v[198:201], v[74:77]
	v_mfma_f32_16x16x32_bf16 v[70:73], v[214:217], v[198:201], v[70:73]
	v_mfma_f32_16x16x32_bf16 v[98:101], v[210:213], v[154:157], v[98:101]
	v_mfma_f32_16x16x32_bf16 v[94:97], v[218:221], v[154:157], v[94:97]
	v_mfma_f32_16x16x32_bf16 v[90:93], v[210:213], v[162:165], v[90:93]
	v_mfma_f32_16x16x32_bf16 v[86:89], v[218:221], v[162:165], v[86:89]
	v_mfma_f32_16x16x32_bf16 v[82:85], v[210:213], v[194:197], v[82:85]
	v_mfma_f32_16x16x32_bf16 v[78:81], v[218:221], v[194:197], v[78:81]
	v_mfma_f32_16x16x32_bf16 v[74:77], v[210:213], v[202:205], v[74:77]
	v_mfma_f32_16x16x32_bf16 v[70:73], v[218:221], v[202:205], v[70:73]
	s_barrier
	s_setprio 0
	s_mov_b32 m0, s30
	v_lshl_add_u64 v[32:33], v[188:189], 0, s[12:13]
	ds_read_b128 v[150:153], v193 offset:49152
	ds_read_b128 v[154:157], v193 offset:50176
	ds_read_b128 v[158:161], v193 offset:51200
	ds_read_b128 v[162:165], v193 offset:52224
	ds_read_b128 v[184:187], v193 offset:53248
	ds_read_b128 v[194:197], v193 offset:54272
	ds_read_b128 v[198:201], v193 offset:55296
	ds_read_b128 v[202:205], v193 offset:56320
	global_load_lds_dwordx4 v[32:33], off
	s_waitcnt vmcnt(10)
	s_setprio 1
	s_barrier
	s_waitcnt lgkmcnt(0)
	v_mfma_f32_16x16x32_bf16 v[66:69], v[134:137], v[150:153], v[66:69]
	v_mfma_f32_16x16x32_bf16 v[62:65], v[142:145], v[150:153], v[62:65]
	v_mfma_f32_16x16x32_bf16 v[58:61], v[134:137], v[158:161], v[58:61]
	v_mfma_f32_16x16x32_bf16 v[54:57], v[142:145], v[158:161], v[54:57]
	v_mfma_f32_16x16x32_bf16 v[50:53], v[134:137], v[184:187], v[50:53]
	v_mfma_f32_16x16x32_bf16 v[46:49], v[142:145], v[184:187], v[46:49]
	v_mfma_f32_16x16x32_bf16 v[42:45], v[134:137], v[198:201], v[42:45]
	v_mfma_f32_16x16x32_bf16 v[38:41], v[142:145], v[198:201], v[38:41]
	v_mfma_f32_16x16x32_bf16 v[66:69], v[138:141], v[154:157], v[66:69]
	v_mfma_f32_16x16x32_bf16 v[62:65], v[146:149], v[154:157], v[62:65]
	v_mfma_f32_16x16x32_bf16 v[58:61], v[138:141], v[162:165], v[58:61]
	v_mfma_f32_16x16x32_bf16 v[54:57], v[146:149], v[162:165], v[54:57]
	v_mfma_f32_16x16x32_bf16 v[50:53], v[138:141], v[194:197], v[50:53]
	v_mfma_f32_16x16x32_bf16 v[46:49], v[146:149], v[194:197], v[46:49]
	v_mfma_f32_16x16x32_bf16 v[42:45], v[138:141], v[202:205], v[42:45]
	v_mfma_f32_16x16x32_bf16 v[38:41], v[146:149], v[202:205], v[38:41]
	s_barrier
	s_setprio 0
	s_add_u32 s0, s26, 0x20080
	s_addc_u32 s1, s27, 0
	s_add_i32 s22, s23, s55
	s_mov_b32 m0, s22
	s_nop 0
	global_load_lds_dwordx4 v176, s[0:1]
	s_add_i32 m0, s22, 0x2000
	s_nop 0
	global_load_lds_dwordx4 v172, s[0:1]
	v_lshl_add_u64 v[32:33], v[222:223], 0, s[12:13]
	s_mov_b32 m0, s34
	s_nop 0
	global_load_lds_dwordx4 v[32:33], off
	v_add_u32_e32 v26, 0x10000, v191
	ds_read_b128 v[134:137], v26
	ds_read_b128 v[138:141], v26 offset:1024
	ds_read_b128 v[142:145], v26 offset:2048
	ds_read_b128 v[146:149], v26 offset:3072
	s_waitcnt vmcnt(8)
	s_setprio 1
	s_barrier
	v_mfma_f32_16x16x32_bf16 v[32:35], v[206:209], v[150:153], v[34:37]
	v_mfma_f32_16x16x32_bf16 v[28:31], v[214:217], v[150:153], v[28:31]
	v_mfma_f32_16x16x32_bf16 v[22:25], v[206:209], v[158:161], v[22:25]
	v_mfma_f32_16x16x32_bf16 v[18:21], v[214:217], v[158:161], v[18:21]
	v_mfma_f32_16x16x32_bf16 v[14:17], v[206:209], v[184:187], v[14:17]
	v_mfma_f32_16x16x32_bf16 v[10:13], v[214:217], v[184:187], v[10:13]
	v_mfma_f32_16x16x32_bf16 v[6:9], v[206:209], v[198:201], v[6:9]
	v_mfma_f32_16x16x32_bf16 v[2:5], v[214:217], v[198:201], v[2:5]
	v_mfma_f32_16x16x32_bf16 v[34:37], v[210:213], v[154:157], v[32:35]
	v_mfma_f32_16x16x32_bf16 v[30:33], v[218:221], v[154:157], v[28:31]
	v_mfma_f32_16x16x32_bf16 v[22:25], v[210:213], v[162:165], v[22:25]
	v_mfma_f32_16x16x32_bf16 v[18:21], v[218:221], v[162:165], v[18:21]
	v_mfma_f32_16x16x32_bf16 v[14:17], v[210:213], v[194:197], v[14:17]
	v_mfma_f32_16x16x32_bf16 v[10:13], v[218:221], v[194:197], v[10:13]
	v_mfma_f32_16x16x32_bf16 v[6:9], v[210:213], v[202:205], v[6:9]
	v_mfma_f32_16x16x32_bf16 v[2:5], v[218:221], v[202:205], v[2:5]
	s_barrier
	s_setprio 0
	s_add_i32 s51, s51, 2
	s_add_u32 s45, s45, 0x100
	s_addc_u32 s50, s50, 0
	s_cmp_gt_u32 s51, 5
	s_mov_b64 s[22:23], s[24:25]
	s_cbranch_scc0 .LBB0_887
	s_waitcnt lgkmcnt(0)
	v_lshl_or_b32 v186, s17, 8, v192
	v_ashrrev_i32_e32 v187, 31, v186
	v_lshl_add_u32 v26, s16, 8, v190
	s_cmp_lg_u32 s81, 0
	v_lshl_add_u64 v[28:29], v[186:187], 1, s[40:41]
	s_cselect_b64 s[50:51], -1, 0
	s_cmp_eq_u32 s81, 0
	v_mad_i64_i32 v[184:185], s[0:1], v26, s78, v[28:29]
	v_or_b32_e32 v198, 16, v26
	v_or_b32_e32 v197, 32, v26
	v_or_b32_e32 v196, 48, v26
	v_add_u32_e32 v195, 0x80, v26
	v_add_u32_e32 v194, 0x90, v26
	s_cbranch_scc1 .LBB0_894
	v_add_co_u32_e32 v134, vcc, 0x2000, v184
	v_mad_i64_i32 v[166:167], s[0:1], v26, s78, 0
	s_nop 0
	v_addc_co_u32_e32 v135, vcc, 0, v185, vcc
	global_load_dwordx4 v[162:165], v[134:135], off
	global_load_dwordx4 v[158:161], v[134:135], off offset:256
	v_mad_i64_i32 v[134:135], s[0:1], v198, s78, v[28:29]
	v_add_co_u32_e32 v134, vcc, 0x2000, v134
	v_lshlrev_b64 v[186:187], 1, v[186:187]
	s_nop 0
	v_addc_co_u32_e32 v135, vcc, 0, v135, vcc
	global_load_dwordx4 v[154:157], v[134:135], off
	global_load_dwordx4 v[150:153], v[134:135], off offset:256
	v_mad_i64_i32 v[134:135], s[0:1], v197, s78, v[28:29]
	v_add_co_u32_e32 v134, vcc, 0x2000, v134
	s_movk_i32 s16, 0x2000
	s_nop 0
	v_addc_co_u32_e32 v135, vcc, 0, v135, vcc
	global_load_dwordx4 v[146:149], v[134:135], off
	global_load_dwordx4 v[142:145], v[134:135], off offset:256
	v_mad_i64_i32 v[134:135], s[0:1], v196, s78, v[28:29]
	v_add_co_u32_e32 v134, vcc, 0x2000, v134
	s_nop 1
	v_addc_co_u32_e32 v135, vcc, 0, v135, vcc
	global_load_dwordx4 v[138:141], v[134:135], off
	s_nop 0
	global_load_dwordx4 v[134:137], v[134:135], off offset:256
	s_waitcnt vmcnt(0)
	v_lshlrev_b32_e32 v168, 16, v162
	v_and_b32_e32 v162, 0xffff0000, v162
	v_mul_f32_e32 v162, 0xbfb8aa3b, v162
	v_exp_f32_e32 v162, v162
	v_mul_f32_e32 v168, 0xbfb8aa3b, v168
	v_exp_f32_e32 v168, v168
	v_add_f32_e32 v162, 1.0, v162
	v_rcp_f32_e32 v169, v162
	v_lshlrev_b32_e32 v162, 16, v163
	v_and_b32_e32 v163, 0xffff0000, v163
	v_mul_f32_e32 v162, 0xbfb8aa3b, v162
	v_mul_f32_e32 v163, 0xbfb8aa3b, v163
	v_exp_f32_e32 v162, v162
	v_exp_f32_e32 v163, v163
	v_add_f32_e32 v168, 1.0, v168
	v_rcp_f32_e32 v168, v168
	v_add_f32_e32 v162, 1.0, v162
	v_add_f32_e32 v163, 1.0, v163
	v_rcp_f32_e32 v162, v162
	v_rcp_f32_e32 v163, v163
	v_pk_mul_f32 v[168:169], v[130:131], v[168:169]
	v_pk_mul_f32 v[188:189], v[132:133], v[162:163]
	v_lshlrev_b32_e32 v162, 16, v164
	v_and_b32_e32 v163, 0xffff0000, v164
	v_mul_f32_e32 v162, 0xbfb8aa3b, v162
	v_mul_f32_e32 v163, 0xbfb8aa3b, v163
	v_exp_f32_e32 v162, v162
	v_exp_f32_e32 v163, v163
	v_add_f32_e32 v162, 1.0, v162
	v_add_f32_e32 v163, 1.0, v163
	v_rcp_f32_e32 v162, v162
	v_rcp_f32_e32 v163, v163
	s_nop 0
	v_pk_mul_f32 v[200:201], v[126:127], v[162:163]
	v_lshlrev_b32_e32 v162, 16, v165
	v_and_b32_e32 v163, 0xffff0000, v165
	v_mul_f32_e32 v162, 0xbfb8aa3b, v162
	v_mul_f32_e32 v163, 0xbfb8aa3b, v163
	v_exp_f32_e32 v162, v162
	v_exp_f32_e32 v163, v163
	v_cvt_pk_bf16_f32 v164, v200, v201
	v_add_f32_e32 v162, 1.0, v162
	v_add_f32_e32 v163, 1.0, v163
	v_rcp_f32_e32 v162, v162
	v_rcp_f32_e32 v163, v163
	s_nop 0
	v_pk_mul_f32 v[202:203], v[128:129], v[162:163]
	v_cvt_pk_bf16_f32 v163, v188, v189
	v_lshl_add_u64 v[188:189], s[42:43], 0, v[166:167]
	v_cvt_pk_bf16_f32 v162, v168, v169
	v_cvt_pk_bf16_f32 v165, v202, v203
	v_lshl_add_u64 v[188:189], v[188:189], 0, v[186:187]
	global_store_dwordx4 v[188:189], v[162:165], off
	s_nop 1
	v_lshlrev_b32_e32 v162, 16, v158
	v_and_b32_e32 v158, 0xffff0000, v158
	v_mul_f32_e32 v158, 0xbfb8aa3b, v158
	v_exp_f32_e32 v158, v158
	v_mul_f32_e32 v162, 0xbfb8aa3b, v162
	v_exp_f32_e32 v162, v162
	v_add_f32_e32 v158, 1.0, v158
	v_rcp_f32_e32 v163, v158
	v_lshlrev_b32_e32 v158, 16, v159
	v_and_b32_e32 v159, 0xffff0000, v159
	v_mul_f32_e32 v158, 0xbfb8aa3b, v158
	v_mul_f32_e32 v159, 0xbfb8aa3b, v159
	v_exp_f32_e32 v158, v158
	v_exp_f32_e32 v159, v159
	v_add_f32_e32 v162, 1.0, v162
	v_rcp_f32_e32 v162, v162
	v_add_f32_e32 v158, 1.0, v158
	v_add_f32_e32 v159, 1.0, v159
	v_rcp_f32_e32 v158, v158
	v_rcp_f32_e32 v159, v159
	v_pk_mul_f32 v[162:163], v[98:99], v[162:163]
	v_pk_mul_f32 v[164:165], v[100:101], v[158:159]
	v_lshlrev_b32_e32 v158, 16, v160
	v_and_b32_e32 v159, 0xffff0000, v160
	v_mul_f32_e32 v158, 0xbfb8aa3b, v158
	v_mul_f32_e32 v159, 0xbfb8aa3b, v159
	v_exp_f32_e32 v158, v158
	v_exp_f32_e32 v159, v159
	v_add_f32_e32 v158, 1.0, v158
	v_add_f32_e32 v159, 1.0, v159
	v_rcp_f32_e32 v158, v158
	v_rcp_f32_e32 v159, v159
	s_nop 0
	v_pk_mul_f32 v[166:167], v[94:95], v[158:159]
	v_lshlrev_b32_e32 v158, 16, v161
	v_and_b32_e32 v159, 0xffff0000, v161
	v_mul_f32_e32 v158, 0xbfb8aa3b, v158
	v_mul_f32_e32 v159, 0xbfb8aa3b, v159
	v_exp_f32_e32 v158, v158
	v_exp_f32_e32 v159, v159
	v_cvt_pk_bf16_f32 v160, v166, v167
	v_add_f32_e32 v158, 1.0, v158
	v_add_f32_e32 v159, 1.0, v159
	v_rcp_f32_e32 v158, v158
	v_rcp_f32_e32 v159, v159
	s_nop 0
	v_pk_mul_f32 v[168:169], v[96:97], v[158:159]
	v_cvt_pk_bf16_f32 v158, v162, v163
	v_cvt_pk_bf16_f32 v159, v164, v165
	v_cvt_pk_bf16_f32 v161, v168, v169
	global_store_dwordx4 v[188:189], v[158:161], off offset:256
	s_nop 1
	v_lshlrev_b32_e32 v158, 16, v154
	v_and_b32_e32 v154, 0xffff0000, v154
	v_mul_f32_e32 v154, 0xbfb8aa3b, v154
	v_exp_f32_e32 v154, v154
	v_mul_f32_e32 v158, 0xbfb8aa3b, v158
	v_exp_f32_e32 v158, v158
	v_add_f32_e32 v154, 1.0, v154
	v_rcp_f32_e32 v159, v154
	v_lshlrev_b32_e32 v154, 16, v155
	v_and_b32_e32 v155, 0xffff0000, v155
	v_mul_f32_e32 v154, 0xbfb8aa3b, v154
	v_mul_f32_e32 v155, 0xbfb8aa3b, v155
	v_exp_f32_e32 v154, v154
	v_exp_f32_e32 v155, v155
	v_add_f32_e32 v158, 1.0, v158
	v_rcp_f32_e32 v158, v158
	v_add_f32_e32 v154, 1.0, v154
	v_add_f32_e32 v155, 1.0, v155
	v_rcp_f32_e32 v154, v154
	v_rcp_f32_e32 v155, v155
	v_pk_mul_f32 v[158:159], v[122:123], v[158:159]
	v_pk_mul_f32 v[160:161], v[124:125], v[154:155]
	v_lshlrev_b32_e32 v154, 16, v156
	v_and_b32_e32 v155, 0xffff0000, v156
	v_mul_f32_e32 v154, 0xbfb8aa3b, v154
	v_mul_f32_e32 v155, 0xbfb8aa3b, v155
	v_exp_f32_e32 v154, v154
	v_exp_f32_e32 v155, v155
	v_add_f32_e32 v154, 1.0, v154
	v_add_f32_e32 v155, 1.0, v155
	v_rcp_f32_e32 v154, v154
	v_rcp_f32_e32 v155, v155
	s_nop 0
	v_pk_mul_f32 v[162:163], v[118:119], v[154:155]
	v_lshlrev_b32_e32 v154, 16, v157
	v_and_b32_e32 v155, 0xffff0000, v157
	v_mul_f32_e32 v154, 0xbfb8aa3b, v154
	v_mul_f32_e32 v155, 0xbfb8aa3b, v155
	v_exp_f32_e32 v154, v154
	v_exp_f32_e32 v155, v155
	v_cvt_pk_bf16_f32 v156, v162, v163
	v_mov_b64_e32 v[162:163], s[42:43]
	v_add_f32_e32 v154, 1.0, v154
	v_add_f32_e32 v155, 1.0, v155
	v_rcp_f32_e32 v154, v154
	v_rcp_f32_e32 v155, v155
	s_nop 0
	v_pk_mul_f32 v[164:165], v[120:121], v[154:155]
	v_cvt_pk_bf16_f32 v154, v158, v159
	v_mad_i64_i32 v[158:159], s[0:1], v198, s78, v[162:163]
	v_cvt_pk_bf16_f32 v155, v160, v161
	v_cvt_pk_bf16_f32 v157, v164, v165
	v_lshl_add_u64 v[158:159], v[158:159], 0, v[186:187]
	global_store_dwordx4 v[158:159], v[154:157], off
	s_nop 1
	v_lshlrev_b32_e32 v154, 16, v150
	v_and_b32_e32 v150, 0xffff0000, v150
	v_mul_f32_e32 v150, 0xbfb8aa3b, v150
	v_exp_f32_e32 v150, v150
	v_mul_f32_e32 v154, 0xbfb8aa3b, v154
	v_exp_f32_e32 v154, v154
	v_add_f32_e32 v150, 1.0, v150
	v_rcp_f32_e32 v155, v150
	v_lshlrev_b32_e32 v150, 16, v151
	v_and_b32_e32 v151, 0xffff0000, v151
	v_mul_f32_e32 v150, 0xbfb8aa3b, v150
	v_mul_f32_e32 v151, 0xbfb8aa3b, v151
	v_exp_f32_e32 v150, v150
	v_exp_f32_e32 v151, v151
	v_add_f32_e32 v154, 1.0, v154
	v_rcp_f32_e32 v154, v154
	v_add_f32_e32 v150, 1.0, v150
	v_add_f32_e32 v151, 1.0, v151
	v_rcp_f32_e32 v150, v150
	v_rcp_f32_e32 v151, v151
	v_pk_mul_f32 v[154:155], v[90:91], v[154:155]
	v_pk_mul_f32 v[156:157], v[92:93], v[150:151]
	v_lshlrev_b32_e32 v150, 16, v152
	v_and_b32_e32 v151, 0xffff0000, v152
	v_mul_f32_e32 v150, 0xbfb8aa3b, v150
	v_mul_f32_e32 v151, 0xbfb8aa3b, v151
	v_exp_f32_e32 v150, v150
	v_exp_f32_e32 v151, v151
	v_add_f32_e32 v150, 1.0, v150
	v_add_f32_e32 v151, 1.0, v151
	v_rcp_f32_e32 v150, v150
	v_rcp_f32_e32 v151, v151
	s_nop 0
	v_pk_mul_f32 v[160:161], v[86:87], v[150:151]
	v_lshlrev_b32_e32 v150, 16, v153
	v_and_b32_e32 v151, 0xffff0000, v153
	v_mul_f32_e32 v150, 0xbfb8aa3b, v150
	v_mul_f32_e32 v151, 0xbfb8aa3b, v151
	v_exp_f32_e32 v150, v150
	v_exp_f32_e32 v151, v151
	v_cvt_pk_bf16_f32 v152, v160, v161
	v_add_f32_e32 v150, 1.0, v150
	v_add_f32_e32 v151, 1.0, v151
	v_rcp_f32_e32 v150, v150
	v_rcp_f32_e32 v151, v151
	s_nop 0
	v_pk_mul_f32 v[164:165], v[88:89], v[150:151]
	v_cvt_pk_bf16_f32 v150, v154, v155
	v_cvt_pk_bf16_f32 v151, v156, v157
	v_cvt_pk_bf16_f32 v153, v164, v165
	global_store_dwordx4 v[158:159], v[150:153], off offset:256
	v_add_u32_e32 v165, 0xa0, v26
	v_add_u32_e32 v164, 0xb0, v26
	v_lshlrev_b32_e32 v150, 16, v146
	v_and_b32_e32 v146, 0xffff0000, v146
	v_mul_f32_e32 v146, 0xbfb8aa3b, v146
	v_exp_f32_e32 v146, v146
	v_mul_f32_e32 v150, 0xbfb8aa3b, v150
	v_exp_f32_e32 v150, v150
	v_add_f32_e32 v146, 1.0, v146
	v_rcp_f32_e32 v151, v146
	v_lshlrev_b32_e32 v146, 16, v147
	v_and_b32_e32 v147, 0xffff0000, v147
	v_mul_f32_e32 v146, 0xbfb8aa3b, v146
	v_mul_f32_e32 v147, 0xbfb8aa3b, v147
	v_exp_f32_e32 v146, v146
	v_exp_f32_e32 v147, v147
	v_add_f32_e32 v150, 1.0, v150
	v_rcp_f32_e32 v150, v150
	v_add_f32_e32 v146, 1.0, v146
	v_add_f32_e32 v147, 1.0, v147
	v_rcp_f32_e32 v146, v146
	v_rcp_f32_e32 v147, v147
	v_pk_mul_f32 v[150:151], v[114:115], v[150:151]
	v_pk_mul_f32 v[152:153], v[116:117], v[146:147]
	v_lshlrev_b32_e32 v146, 16, v148
	v_and_b32_e32 v147, 0xffff0000, v148
	v_mul_f32_e32 v146, 0xbfb8aa3b, v146
	v_mul_f32_e32 v147, 0xbfb8aa3b, v147
	v_exp_f32_e32 v146, v146
	v_exp_f32_e32 v147, v147
	v_add_f32_e32 v146, 1.0, v146
	v_add_f32_e32 v147, 1.0, v147
	v_rcp_f32_e32 v146, v146
	v_rcp_f32_e32 v147, v147
	s_nop 0
	v_pk_mul_f32 v[154:155], v[110:111], v[146:147]
	v_lshlrev_b32_e32 v146, 16, v149
	v_and_b32_e32 v147, 0xffff0000, v149
	v_mul_f32_e32 v146, 0xbfb8aa3b, v146
	v_mul_f32_e32 v147, 0xbfb8aa3b, v147
	v_exp_f32_e32 v146, v146
	v_exp_f32_e32 v147, v147
	v_cvt_pk_bf16_f32 v148, v154, v155
	v_add_f32_e32 v146, 1.0, v146
	v_add_f32_e32 v147, 1.0, v147
	v_rcp_f32_e32 v146, v146
	v_rcp_f32_e32 v147, v147
	s_nop 0
	v_pk_mul_f32 v[156:157], v[112:113], v[146:147]
	v_cvt_pk_bf16_f32 v146, v150, v151
	v_mad_i64_i32 v[150:151], s[0:1], v197, s78, v[162:163]
	v_cvt_pk_bf16_f32 v147, v152, v153
	v_cvt_pk_bf16_f32 v149, v156, v157
	v_lshl_add_u64 v[150:151], v[150:151], 0, v[186:187]
	global_store_dwordx4 v[150:151], v[146:149], off
	s_nop 1
	v_lshlrev_b32_e32 v146, 16, v142
	v_and_b32_e32 v142, 0xffff0000, v142
	v_mul_f32_e32 v142, 0xbfb8aa3b, v142
	v_exp_f32_e32 v142, v142
	v_mul_f32_e32 v146, 0xbfb8aa3b, v146
	v_exp_f32_e32 v146, v146
	v_add_f32_e32 v142, 1.0, v142
	v_rcp_f32_e32 v147, v142
	v_lshlrev_b32_e32 v142, 16, v143
	v_and_b32_e32 v143, 0xffff0000, v143
	v_mul_f32_e32 v142, 0xbfb8aa3b, v142
	v_mul_f32_e32 v143, 0xbfb8aa3b, v143
	v_exp_f32_e32 v142, v142
	v_exp_f32_e32 v143, v143
	v_add_f32_e32 v146, 1.0, v146
	v_rcp_f32_e32 v146, v146
	v_add_f32_e32 v142, 1.0, v142
	v_add_f32_e32 v143, 1.0, v143
	v_rcp_f32_e32 v142, v142
	v_rcp_f32_e32 v143, v143
	v_pk_mul_f32 v[146:147], v[82:83], v[146:147]
	v_pk_mul_f32 v[148:149], v[84:85], v[142:143]
	v_lshlrev_b32_e32 v142, 16, v144
	v_and_b32_e32 v143, 0xffff0000, v144
	v_mul_f32_e32 v142, 0xbfb8aa3b, v142
	v_mul_f32_e32 v143, 0xbfb8aa3b, v143
	v_exp_f32_e32 v142, v142
	v_exp_f32_e32 v143, v143
	v_add_f32_e32 v142, 1.0, v142
	v_add_f32_e32 v143, 1.0, v143
	v_rcp_f32_e32 v142, v142
	v_rcp_f32_e32 v143, v143
	s_nop 0
	v_pk_mul_f32 v[152:153], v[78:79], v[142:143]
	v_lshlrev_b32_e32 v142, 16, v145
	v_and_b32_e32 v143, 0xffff0000, v145
	v_mul_f32_e32 v142, 0xbfb8aa3b, v142
	v_mul_f32_e32 v143, 0xbfb8aa3b, v143
	v_exp_f32_e32 v142, v142
	v_exp_f32_e32 v143, v143
	v_cvt_pk_bf16_f32 v144, v152, v153
	v_add_f32_e32 v142, 1.0, v142
	v_add_f32_e32 v143, 1.0, v143
	v_rcp_f32_e32 v142, v142
	v_rcp_f32_e32 v143, v143
	s_nop 0
	v_pk_mul_f32 v[154:155], v[80:81], v[142:143]
	v_cvt_pk_bf16_f32 v142, v146, v147
	v_cvt_pk_bf16_f32 v143, v148, v149
	v_cvt_pk_bf16_f32 v145, v154, v155
	global_store_dwordx4 v[150:151], v[142:145], off offset:256
	s_nop 1
	v_lshlrev_b32_e32 v142, 16, v138
	v_and_b32_e32 v138, 0xffff0000, v138
	v_mul_f32_e32 v138, 0xbfb8aa3b, v138
	v_exp_f32_e32 v138, v138
	v_mul_f32_e32 v142, 0xbfb8aa3b, v142
	v_exp_f32_e32 v142, v142
	v_add_f32_e32 v138, 1.0, v138
	v_rcp_f32_e32 v143, v138
	v_lshlrev_b32_e32 v138, 16, v139
	v_and_b32_e32 v139, 0xffff0000, v139
	v_mul_f32_e32 v138, 0xbfb8aa3b, v138
	v_mul_f32_e32 v139, 0xbfb8aa3b, v139
	v_exp_f32_e32 v138, v138
	v_exp_f32_e32 v139, v139
	v_add_f32_e32 v142, 1.0, v142
	v_rcp_f32_e32 v142, v142
	v_add_f32_e32 v138, 1.0, v138
	v_add_f32_e32 v139, 1.0, v139
	v_rcp_f32_e32 v138, v138
	v_rcp_f32_e32 v139, v139
	v_pk_mul_f32 v[142:143], v[106:107], v[142:143]
	v_pk_mul_f32 v[144:145], v[108:109], v[138:139]
	v_lshlrev_b32_e32 v138, 16, v140
	v_and_b32_e32 v139, 0xffff0000, v140
	v_mul_f32_e32 v138, 0xbfb8aa3b, v138
	v_mul_f32_e32 v139, 0xbfb8aa3b, v139
	v_exp_f32_e32 v138, v138
	v_exp_f32_e32 v139, v139
	v_add_f32_e32 v138, 1.0, v138
	v_add_f32_e32 v139, 1.0, v139
	v_rcp_f32_e32 v138, v138
	v_rcp_f32_e32 v139, v139
	s_nop 0
	v_pk_mul_f32 v[146:147], v[102:103], v[138:139]
	v_lshlrev_b32_e32 v138, 16, v141
	v_and_b32_e32 v139, 0xffff0000, v141
	v_mul_f32_e32 v138, 0xbfb8aa3b, v138
	v_mul_f32_e32 v139, 0xbfb8aa3b, v139
	v_exp_f32_e32 v138, v138
	v_exp_f32_e32 v139, v139
	v_cvt_pk_bf16_f32 v140, v146, v147
	v_add_f32_e32 v138, 1.0, v138
	v_add_f32_e32 v139, 1.0, v139
	v_rcp_f32_e32 v138, v138
	v_rcp_f32_e32 v139, v139
	s_nop 0
	v_pk_mul_f32 v[148:149], v[104:105], v[138:139]
	v_cvt_pk_bf16_f32 v138, v142, v143
	v_mad_i64_i32 v[142:143], s[0:1], v196, s78, v[162:163]
	v_cvt_pk_bf16_f32 v139, v144, v145
	v_cvt_pk_bf16_f32 v141, v148, v149
	v_lshl_add_u64 v[142:143], v[142:143], 0, v[186:187]
	global_store_dwordx4 v[142:143], v[138:141], off
	s_nop 1
	v_lshlrev_b32_e32 v138, 16, v134
	v_and_b32_e32 v134, 0xffff0000, v134
	v_mul_f32_e32 v134, 0xbfb8aa3b, v134
	v_exp_f32_e32 v134, v134
	v_mul_f32_e32 v138, 0xbfb8aa3b, v138
	v_exp_f32_e32 v138, v138
	v_add_f32_e32 v134, 1.0, v134
	v_rcp_f32_e32 v139, v134
	v_lshlrev_b32_e32 v134, 16, v135
	v_and_b32_e32 v135, 0xffff0000, v135
	v_mul_f32_e32 v134, 0xbfb8aa3b, v134
	v_mul_f32_e32 v135, 0xbfb8aa3b, v135
	v_exp_f32_e32 v134, v134
	v_exp_f32_e32 v135, v135
	v_add_f32_e32 v138, 1.0, v138
	v_rcp_f32_e32 v138, v138
	v_add_f32_e32 v134, 1.0, v134
	v_add_f32_e32 v135, 1.0, v135
	v_rcp_f32_e32 v134, v134
	v_rcp_f32_e32 v135, v135
	v_pk_mul_f32 v[138:139], v[74:75], v[138:139]
	v_pk_mul_f32 v[140:141], v[76:77], v[134:135]
	v_lshlrev_b32_e32 v134, 16, v136
	v_and_b32_e32 v135, 0xffff0000, v136
	v_mul_f32_e32 v134, 0xbfb8aa3b, v134
	v_mul_f32_e32 v135, 0xbfb8aa3b, v135
	v_exp_f32_e32 v134, v134
	v_exp_f32_e32 v135, v135
	v_add_f32_e32 v134, 1.0, v134
	v_add_f32_e32 v135, 1.0, v135
	v_rcp_f32_e32 v134, v134
	v_rcp_f32_e32 v135, v135
	s_nop 0
	v_pk_mul_f32 v[144:145], v[70:71], v[134:135]
	v_lshlrev_b32_e32 v134, 16, v137
	v_and_b32_e32 v135, 0xffff0000, v137
	v_mul_f32_e32 v134, 0xbfb8aa3b, v134
	v_mul_f32_e32 v135, 0xbfb8aa3b, v135
	v_exp_f32_e32 v134, v134
	v_exp_f32_e32 v135, v135
	v_cvt_pk_bf16_f32 v136, v144, v145
	v_add_f32_e32 v134, 1.0, v134
	v_add_f32_e32 v135, 1.0, v135
	v_rcp_f32_e32 v134, v134
	v_rcp_f32_e32 v135, v135
	s_nop 0
	v_pk_mul_f32 v[146:147], v[72:73], v[134:135]
	v_cvt_pk_bf16_f32 v134, v138, v139
	v_cvt_pk_bf16_f32 v135, v140, v141
	v_cvt_pk_bf16_f32 v137, v146, v147
	global_store_dwordx4 v[142:143], v[134:137], off offset:256
	s_nop 1
	v_mad_i64_i32 v[134:135], s[0:1], v195, s78, v[28:29]
	v_add_co_u32_e32 v134, vcc, s16, v134
	s_nop 1
	v_addc_co_u32_e32 v135, vcc, 0, v135, vcc
	global_load_dwordx4 v[200:203], v[134:135], off
	global_load_dwordx4 v[158:161], v[134:135], off offset:256
	v_mad_i64_i32 v[134:135], s[0:1], v194, s78, v[28:29]
	v_add_co_u32_e32 v134, vcc, s16, v134
	s_waitcnt vmcnt(0)
	v_lshlrev_b32_e32 v199, 16, v203
	v_addc_co_u32_e32 v135, vcc, 0, v135, vcc
	global_load_dwordx4 v[154:157], v[134:135], off
	global_load_dwordx4 v[150:153], v[134:135], off offset:256
	v_mul_f32_e32 v199, 0xbfb8aa3b, v199
	v_exp_f32_e32 v199, v199
	v_lshlrev_b32_e32 v168, 16, v201
	v_and_b32_e32 v169, 0xffff0000, v201
	v_lshlrev_b32_e32 v166, 16, v200
	v_add_f32_e32 v199, 1.0, v199
	v_and_b32_e32 v167, 0xffff0000, v200
	v_mul_f32_e32 v168, 0xbfb8aa3b, v168
	v_mul_f32_e32 v169, 0xbfb8aa3b, v169
	v_rcp_f32_e32 v200, v199
	v_and_b32_e32 v199, 0xffff0000, v203
	v_exp_f32_e32 v168, v168
	v_exp_f32_e32 v169, v169
	v_mul_f32_e32 v199, 0xbfb8aa3b, v199
	v_exp_f32_e32 v199, v199
	v_add_f32_e32 v168, 1.0, v168
	v_add_f32_e32 v169, 1.0, v169
	v_rcp_f32_e32 v168, v168
	v_rcp_f32_e32 v169, v169
	v_add_f32_e32 v199, 1.0, v199
	v_rcp_f32_e32 v201, v199
	v_lshlrev_b32_e32 v188, 16, v202
	v_pk_mul_f32 v[168:169], v[68:69], v[168:169]
	v_and_b32_e32 v189, 0xffff0000, v202
	v_pk_mul_f32 v[204:205], v[64:65], v[200:201]
	v_cvt_pk_bf16_f32 v201, v168, v169
	v_lshlrev_b32_e32 v168, 16, v158
	v_and_b32_e32 v158, 0xffff0000, v158
	v_mul_f32_e32 v158, 0xbfb8aa3b, v158
	v_exp_f32_e32 v158, v158
	v_mul_f32_e32 v188, 0xbfb8aa3b, v188
	v_mul_f32_e32 v189, 0xbfb8aa3b, v189
	v_exp_f32_e32 v188, v188
	v_add_f32_e32 v158, 1.0, v158
	v_rcp_f32_e32 v169, v158
	v_lshlrev_b32_e32 v158, 16, v159
	v_and_b32_e32 v159, 0xffff0000, v159
	v_exp_f32_e32 v189, v189
	v_mul_f32_e32 v158, 0xbfb8aa3b, v158
	v_mul_f32_e32 v159, 0xbfb8aa3b, v159
	v_exp_f32_e32 v158, v158
	v_exp_f32_e32 v159, v159
	v_add_f32_e32 v188, 1.0, v188
	v_add_f32_e32 v189, 1.0, v189
	v_rcp_f32_e32 v188, v188
	v_rcp_f32_e32 v189, v189
	v_add_f32_e32 v158, 1.0, v158
	v_add_f32_e32 v159, 1.0, v159
	v_rcp_f32_e32 v158, v158
	v_rcp_f32_e32 v159, v159
	v_mul_f32_e32 v166, 0xbfb8aa3b, v166
	v_mul_f32_e32 v167, 0xbfb8aa3b, v167
	v_exp_f32_e32 v166, v166
	v_exp_f32_e32 v167, v167
	v_pk_mul_f32 v[188:189], v[62:63], v[188:189]
	v_mad_i64_i32 v[134:135], s[0:1], v165, s78, v[28:29]
	v_cvt_pk_bf16_f32 v202, v188, v189
	v_pk_mul_f32 v[188:189], v[36:37], v[158:159]
	v_lshlrev_b32_e32 v158, 16, v160
	v_and_b32_e32 v159, 0xffff0000, v160
	v_mul_f32_e32 v158, 0xbfb8aa3b, v158
	v_mul_f32_e32 v159, 0xbfb8aa3b, v159
	v_exp_f32_e32 v158, v158
	v_exp_f32_e32 v159, v159
	v_add_f32_e32 v166, 1.0, v166
	v_add_f32_e32 v167, 1.0, v167
	v_rcp_f32_e32 v166, v166
	v_rcp_f32_e32 v167, v167
	v_add_co_u32_e32 v134, vcc, s16, v134
	v_add_f32_e32 v158, 1.0, v158
	v_add_f32_e32 v159, 1.0, v159
	v_addc_co_u32_e32 v135, vcc, 0, v135, vcc
	v_rcp_f32_e32 v158, v158
	v_rcp_f32_e32 v159, v159
	global_load_dwordx4 v[146:149], v[134:135], off
	global_load_dwordx4 v[142:145], v[134:135], off offset:256
	v_mad_i64_i32 v[134:135], s[0:1], v164, s78, v[28:29]
	v_pk_mul_f32 v[166:167], v[66:67], v[166:167]
	v_add_co_u32_e32 v134, vcc, s16, v134
	v_cvt_pk_bf16_f32 v200, v166, v167
	v_mad_i64_i32 v[166:167], s[0:1], v195, s78, v[162:163]
	v_addc_co_u32_e32 v135, vcc, 0, v135, vcc
	v_cvt_pk_bf16_f32 v203, v204, v205
	v_lshl_add_u64 v[166:167], v[166:167], 0, v[186:187]
	global_load_dwordx4 v[138:141], v[134:135], off
	s_nop 0
	global_load_dwordx4 v[134:137], v[134:135], off offset:256
	v_mul_f32_e32 v168, 0xbfb8aa3b, v168
	global_store_dwordx4 v[166:167], v[200:203], off
	v_exp_f32_e32 v168, v168
	s_nop 0
	v_pk_mul_f32 v[200:201], v[30:31], v[158:159]
	v_lshlrev_b32_e32 v158, 16, v161
	v_and_b32_e32 v159, 0xffff0000, v161
	v_mul_f32_e32 v158, 0xbfb8aa3b, v158
	v_mul_f32_e32 v159, 0xbfb8aa3b, v159
	v_exp_f32_e32 v158, v158
	v_exp_f32_e32 v159, v159
	v_add_f32_e32 v168, 1.0, v168
	v_rcp_f32_e32 v168, v168
	v_add_f32_e32 v158, 1.0, v158
	v_add_f32_e32 v159, 1.0, v159
	v_rcp_f32_e32 v158, v158
	v_rcp_f32_e32 v159, v159
	v_pk_mul_f32 v[168:169], v[34:35], v[168:169]
	v_cvt_pk_bf16_f32 v160, v200, v201
	v_pk_mul_f32 v[202:203], v[32:33], v[158:159]
	v_cvt_pk_bf16_f32 v158, v168, v169
	v_cvt_pk_bf16_f32 v159, v188, v189
	v_cvt_pk_bf16_f32 v161, v202, v203
	global_store_dwordx4 v[166:167], v[158:161], off offset:256
	s_waitcnt vmcnt(0)
	s_nop 0
	v_lshlrev_b32_e32 v158, 16, v154
	v_and_b32_e32 v154, 0xffff0000, v154
	v_mul_f32_e32 v154, 0xbfb8aa3b, v154
	v_exp_f32_e32 v154, v154
	v_mul_f32_e32 v158, 0xbfb8aa3b, v158
	v_exp_f32_e32 v158, v158
	v_add_f32_e32 v154, 1.0, v154
	v_rcp_f32_e32 v159, v154
	v_lshlrev_b32_e32 v154, 16, v155
	v_and_b32_e32 v155, 0xffff0000, v155
	v_mul_f32_e32 v154, 0xbfb8aa3b, v154
	v_mul_f32_e32 v155, 0xbfb8aa3b, v155
	v_exp_f32_e32 v154, v154
	v_exp_f32_e32 v155, v155
	v_add_f32_e32 v158, 1.0, v158
	v_rcp_f32_e32 v158, v158
	v_add_f32_e32 v154, 1.0, v154
	v_add_f32_e32 v155, 1.0, v155
	v_rcp_f32_e32 v154, v154
	v_rcp_f32_e32 v155, v155
	v_pk_mul_f32 v[158:159], v[58:59], v[158:159]
	v_pk_mul_f32 v[160:161], v[60:61], v[154:155]
	v_lshlrev_b32_e32 v154, 16, v156
	v_and_b32_e32 v155, 0xffff0000, v156
	v_mul_f32_e32 v154, 0xbfb8aa3b, v154
	v_mul_f32_e32 v155, 0xbfb8aa3b, v155
	v_exp_f32_e32 v154, v154
	v_exp_f32_e32 v155, v155
	v_add_f32_e32 v154, 1.0, v154
	v_add_f32_e32 v155, 1.0, v155
	v_rcp_f32_e32 v154, v154
	v_rcp_f32_e32 v155, v155
	s_nop 0
	v_pk_mul_f32 v[166:167], v[54:55], v[154:155]
	v_lshlrev_b32_e32 v154, 16, v157
	v_and_b32_e32 v155, 0xffff0000, v157
	v_mul_f32_e32 v154, 0xbfb8aa3b, v154
	v_mul_f32_e32 v155, 0xbfb8aa3b, v155
	v_exp_f32_e32 v154, v154
	v_exp_f32_e32 v155, v155
	v_cvt_pk_bf16_f32 v156, v166, v167
	v_add_f32_e32 v154, 1.0, v154
	v_add_f32_e32 v155, 1.0, v155
	v_rcp_f32_e32 v154, v154
	v_rcp_f32_e32 v155, v155
	s_nop 0
	v_pk_mul_f32 v[168:169], v[56:57], v[154:155]
	v_cvt_pk_bf16_f32 v154, v158, v159
	v_mad_i64_i32 v[158:159], s[0:1], v194, s78, v[162:163]
	v_cvt_pk_bf16_f32 v155, v160, v161
	v_cvt_pk_bf16_f32 v157, v168, v169
	v_lshl_add_u64 v[158:159], v[158:159], 0, v[186:187]
	global_store_dwordx4 v[158:159], v[154:157], off
	s_nop 1
	v_lshlrev_b32_e32 v154, 16, v150
	v_and_b32_e32 v150, 0xffff0000, v150
	v_mul_f32_e32 v150, 0xbfb8aa3b, v150
	v_exp_f32_e32 v150, v150
	v_mul_f32_e32 v154, 0xbfb8aa3b, v154
	v_exp_f32_e32 v154, v154
	v_add_f32_e32 v150, 1.0, v150
	v_rcp_f32_e32 v155, v150
	v_lshlrev_b32_e32 v150, 16, v151
	v_and_b32_e32 v151, 0xffff0000, v151
	v_mul_f32_e32 v150, 0xbfb8aa3b, v150
	v_mul_f32_e32 v151, 0xbfb8aa3b, v151
	v_exp_f32_e32 v150, v150
	v_exp_f32_e32 v151, v151
	v_add_f32_e32 v154, 1.0, v154
	v_rcp_f32_e32 v154, v154
	v_add_f32_e32 v150, 1.0, v150
	v_add_f32_e32 v151, 1.0, v151
	v_rcp_f32_e32 v150, v150
	v_rcp_f32_e32 v151, v151
	v_pk_mul_f32 v[154:155], v[22:23], v[154:155]
	v_pk_mul_f32 v[156:157], v[24:25], v[150:151]
	v_lshlrev_b32_e32 v150, 16, v152
	v_and_b32_e32 v151, 0xffff0000, v152
	v_mul_f32_e32 v150, 0xbfb8aa3b, v150
	v_mul_f32_e32 v151, 0xbfb8aa3b, v151
	v_exp_f32_e32 v150, v150
	v_exp_f32_e32 v151, v151
	v_add_f32_e32 v150, 1.0, v150
	v_add_f32_e32 v151, 1.0, v151
	v_rcp_f32_e32 v150, v150
	v_rcp_f32_e32 v151, v151
	s_nop 0
	v_pk_mul_f32 v[160:161], v[18:19], v[150:151]
	v_lshlrev_b32_e32 v150, 16, v153
	v_and_b32_e32 v151, 0xffff0000, v153
	v_mul_f32_e32 v150, 0xbfb8aa3b, v150
	v_mul_f32_e32 v151, 0xbfb8aa3b, v151
	v_exp_f32_e32 v150, v150
	v_exp_f32_e32 v151, v151
	v_cvt_pk_bf16_f32 v152, v160, v161
	v_add_f32_e32 v150, 1.0, v150
	v_add_f32_e32 v151, 1.0, v151
	v_rcp_f32_e32 v150, v150
	v_rcp_f32_e32 v151, v151
	s_nop 0
	v_pk_mul_f32 v[166:167], v[20:21], v[150:151]
	v_cvt_pk_bf16_f32 v150, v154, v155
	v_cvt_pk_bf16_f32 v151, v156, v157
	v_cvt_pk_bf16_f32 v153, v166, v167
	global_store_dwordx4 v[158:159], v[150:153], off offset:256
	s_nop 1
	v_lshlrev_b32_e32 v150, 16, v146
	v_and_b32_e32 v146, 0xffff0000, v146
	v_mul_f32_e32 v146, 0xbfb8aa3b, v146
	v_exp_f32_e32 v146, v146
	v_mul_f32_e32 v150, 0xbfb8aa3b, v150
	v_exp_f32_e32 v150, v150
	v_add_f32_e32 v146, 1.0, v146
	v_rcp_f32_e32 v151, v146
	v_lshlrev_b32_e32 v146, 16, v147
	v_and_b32_e32 v147, 0xffff0000, v147
	v_mul_f32_e32 v146, 0xbfb8aa3b, v146
	v_mul_f32_e32 v147, 0xbfb8aa3b, v147
	v_exp_f32_e32 v146, v146
	v_exp_f32_e32 v147, v147
	v_add_f32_e32 v150, 1.0, v150
	v_rcp_f32_e32 v150, v150
	v_add_f32_e32 v146, 1.0, v146
	v_add_f32_e32 v147, 1.0, v147
	v_rcp_f32_e32 v146, v146
	v_rcp_f32_e32 v147, v147
	v_pk_mul_f32 v[150:151], v[50:51], v[150:151]
	v_pk_mul_f32 v[152:153], v[52:53], v[146:147]
	v_lshlrev_b32_e32 v146, 16, v148
	v_and_b32_e32 v147, 0xffff0000, v148
	v_mul_f32_e32 v146, 0xbfb8aa3b, v146
	v_mul_f32_e32 v147, 0xbfb8aa3b, v147
	v_exp_f32_e32 v146, v146
	v_exp_f32_e32 v147, v147
	v_add_f32_e32 v146, 1.0, v146
	v_add_f32_e32 v147, 1.0, v147
	v_rcp_f32_e32 v146, v146
	v_rcp_f32_e32 v147, v147
	s_nop 0
	v_pk_mul_f32 v[154:155], v[46:47], v[146:147]
	v_lshlrev_b32_e32 v146, 16, v149
	v_and_b32_e32 v147, 0xffff0000, v149
	v_mul_f32_e32 v146, 0xbfb8aa3b, v146
	v_mul_f32_e32 v147, 0xbfb8aa3b, v147
	v_exp_f32_e32 v146, v146
	v_exp_f32_e32 v147, v147
	v_cvt_pk_bf16_f32 v148, v154, v155
	v_add_f32_e32 v146, 1.0, v146
	v_add_f32_e32 v147, 1.0, v147
	v_rcp_f32_e32 v146, v146
	v_rcp_f32_e32 v147, v147
	s_nop 0
	v_pk_mul_f32 v[156:157], v[48:49], v[146:147]
	v_cvt_pk_bf16_f32 v146, v150, v151
	v_mad_i64_i32 v[150:151], s[0:1], v165, s78, v[162:163]
	v_cvt_pk_bf16_f32 v147, v152, v153
	v_cvt_pk_bf16_f32 v149, v156, v157
	v_lshl_add_u64 v[150:151], v[150:151], 0, v[186:187]
	global_store_dwordx4 v[150:151], v[146:149], off
	s_nop 1
	v_lshlrev_b32_e32 v146, 16, v142
	v_and_b32_e32 v142, 0xffff0000, v142
	v_mul_f32_e32 v142, 0xbfb8aa3b, v142
	v_exp_f32_e32 v142, v142
	v_mul_f32_e32 v146, 0xbfb8aa3b, v146
	v_exp_f32_e32 v146, v146
	v_add_f32_e32 v142, 1.0, v142
	v_rcp_f32_e32 v147, v142
	v_lshlrev_b32_e32 v142, 16, v143
	v_and_b32_e32 v143, 0xffff0000, v143
	v_mul_f32_e32 v142, 0xbfb8aa3b, v142
	v_mul_f32_e32 v143, 0xbfb8aa3b, v143
	v_exp_f32_e32 v142, v142
	v_exp_f32_e32 v143, v143
	v_add_f32_e32 v146, 1.0, v146
	v_rcp_f32_e32 v146, v146
	v_add_f32_e32 v142, 1.0, v142
	v_add_f32_e32 v143, 1.0, v143
	v_rcp_f32_e32 v142, v142
	v_rcp_f32_e32 v143, v143
	v_pk_mul_f32 v[146:147], v[14:15], v[146:147]
	v_pk_mul_f32 v[148:149], v[16:17], v[142:143]
	v_lshlrev_b32_e32 v142, 16, v144
	v_and_b32_e32 v143, 0xffff0000, v144
	v_mul_f32_e32 v142, 0xbfb8aa3b, v142
	v_mul_f32_e32 v143, 0xbfb8aa3b, v143
	v_exp_f32_e32 v142, v142
	v_exp_f32_e32 v143, v143
	v_add_f32_e32 v142, 1.0, v142
	v_add_f32_e32 v143, 1.0, v143
	v_rcp_f32_e32 v142, v142
	v_rcp_f32_e32 v143, v143
	s_nop 0
	v_pk_mul_f32 v[152:153], v[10:11], v[142:143]
	v_lshlrev_b32_e32 v142, 16, v145
	v_and_b32_e32 v143, 0xffff0000, v145
	v_mul_f32_e32 v142, 0xbfb8aa3b, v142
	v_mul_f32_e32 v143, 0xbfb8aa3b, v143
	v_exp_f32_e32 v142, v142
	v_exp_f32_e32 v143, v143
	v_cvt_pk_bf16_f32 v144, v152, v153
	v_add_f32_e32 v142, 1.0, v142
	v_add_f32_e32 v143, 1.0, v143
	v_rcp_f32_e32 v142, v142
	v_rcp_f32_e32 v143, v143
	s_nop 0
	v_pk_mul_f32 v[154:155], v[12:13], v[142:143]
	v_cvt_pk_bf16_f32 v142, v146, v147
	v_cvt_pk_bf16_f32 v143, v148, v149
	v_cvt_pk_bf16_f32 v145, v154, v155
	global_store_dwordx4 v[150:151], v[142:145], off offset:256
	s_nop 1
	v_lshlrev_b32_e32 v142, 16, v138
	v_and_b32_e32 v138, 0xffff0000, v138
	v_mul_f32_e32 v138, 0xbfb8aa3b, v138
	v_exp_f32_e32 v138, v138
	v_mul_f32_e32 v142, 0xbfb8aa3b, v142
	v_exp_f32_e32 v142, v142
	v_add_f32_e32 v138, 1.0, v138
	v_rcp_f32_e32 v143, v138
	v_lshlrev_b32_e32 v138, 16, v139
	v_and_b32_e32 v139, 0xffff0000, v139
	v_mul_f32_e32 v138, 0xbfb8aa3b, v138
	v_mul_f32_e32 v139, 0xbfb8aa3b, v139
	v_exp_f32_e32 v138, v138
	v_exp_f32_e32 v139, v139
	v_add_f32_e32 v142, 1.0, v142
	v_rcp_f32_e32 v142, v142
	v_add_f32_e32 v138, 1.0, v138
	v_add_f32_e32 v139, 1.0, v139
	v_rcp_f32_e32 v138, v138
	v_rcp_f32_e32 v139, v139
	v_pk_mul_f32 v[142:143], v[42:43], v[142:143]
	v_pk_mul_f32 v[144:145], v[44:45], v[138:139]
	v_lshlrev_b32_e32 v138, 16, v140
	v_and_b32_e32 v139, 0xffff0000, v140
	v_mul_f32_e32 v138, 0xbfb8aa3b, v138
	v_mul_f32_e32 v139, 0xbfb8aa3b, v139
	v_exp_f32_e32 v138, v138
	v_exp_f32_e32 v139, v139
	v_add_f32_e32 v138, 1.0, v138
	v_add_f32_e32 v139, 1.0, v139
	v_rcp_f32_e32 v138, v138
	v_rcp_f32_e32 v139, v139
	s_nop 0
	v_pk_mul_f32 v[146:147], v[38:39], v[138:139]
	v_lshlrev_b32_e32 v138, 16, v141
	v_and_b32_e32 v139, 0xffff0000, v141
	v_mul_f32_e32 v138, 0xbfb8aa3b, v138
	v_mul_f32_e32 v139, 0xbfb8aa3b, v139
	v_exp_f32_e32 v138, v138
	v_exp_f32_e32 v139, v139
	v_cvt_pk_bf16_f32 v140, v146, v147
	v_add_f32_e32 v138, 1.0, v138
	v_add_f32_e32 v139, 1.0, v139
	v_rcp_f32_e32 v138, v138
	v_rcp_f32_e32 v139, v139
	s_nop 0
	v_pk_mul_f32 v[148:149], v[40:41], v[138:139]
	v_cvt_pk_bf16_f32 v138, v142, v143
	v_mad_i64_i32 v[142:143], s[0:1], v164, s78, v[162:163]
	v_cvt_pk_bf16_f32 v139, v144, v145
	v_cvt_pk_bf16_f32 v141, v148, v149
	v_lshl_add_u64 v[142:143], v[142:143], 0, v[186:187]
	global_store_dwordx4 v[142:143], v[138:141], off
	s_nop 1
	v_lshlrev_b32_e32 v138, 16, v134
	v_and_b32_e32 v134, 0xffff0000, v134
	v_mul_f32_e32 v134, 0xbfb8aa3b, v134
	v_exp_f32_e32 v134, v134
	v_mul_f32_e32 v138, 0xbfb8aa3b, v138
	v_exp_f32_e32 v138, v138
	v_add_f32_e32 v134, 1.0, v134
	v_rcp_f32_e32 v139, v134
	v_lshlrev_b32_e32 v134, 16, v135
	v_and_b32_e32 v135, 0xffff0000, v135
	v_mul_f32_e32 v134, 0xbfb8aa3b, v134
	v_mul_f32_e32 v135, 0xbfb8aa3b, v135
	v_exp_f32_e32 v134, v134
	v_exp_f32_e32 v135, v135
	v_add_f32_e32 v138, 1.0, v138
	v_rcp_f32_e32 v138, v138
	v_add_f32_e32 v134, 1.0, v134
	v_add_f32_e32 v135, 1.0, v135
	v_rcp_f32_e32 v134, v134
	v_rcp_f32_e32 v135, v135
	v_pk_mul_f32 v[138:139], v[6:7], v[138:139]
	v_pk_mul_f32 v[140:141], v[8:9], v[134:135]
	v_lshlrev_b32_e32 v134, 16, v136
	v_and_b32_e32 v135, 0xffff0000, v136
	v_mul_f32_e32 v134, 0xbfb8aa3b, v134
	v_mul_f32_e32 v135, 0xbfb8aa3b, v135
	v_exp_f32_e32 v134, v134
	v_exp_f32_e32 v135, v135
	v_add_f32_e32 v134, 1.0, v134
	v_add_f32_e32 v135, 1.0, v135
	v_rcp_f32_e32 v134, v134
	v_rcp_f32_e32 v135, v135
	s_nop 0
	v_pk_mul_f32 v[144:145], v[2:3], v[134:135]
	v_lshlrev_b32_e32 v134, 16, v137
	v_and_b32_e32 v135, 0xffff0000, v137
	v_mul_f32_e32 v134, 0xbfb8aa3b, v134
	v_mul_f32_e32 v135, 0xbfb8aa3b, v135
	v_exp_f32_e32 v134, v134
	v_exp_f32_e32 v135, v135
	v_cvt_pk_bf16_f32 v136, v144, v145
	v_add_f32_e32 v134, 1.0, v134
	v_add_f32_e32 v135, 1.0, v135
	v_rcp_f32_e32 v134, v134
	v_rcp_f32_e32 v135, v135
	s_nop 0
	v_pk_mul_f32 v[146:147], v[4:5], v[134:135]
	v_cvt_pk_bf16_f32 v134, v138, v139
	v_cvt_pk_bf16_f32 v135, v140, v141
	v_cvt_pk_bf16_f32 v137, v146, v147
	global_store_dwordx4 v[142:143], v[134:137], off offset:256
	s_cbranch_execnz .LBB0_891

.LBB0_965:
	s_add_u32 s36, s34, 0x100
	s_addc_u32 s37, s35, 0
	s_add_i32 s0, 0, 0x10000
	s_cmp_eq_u32 s31, 12
	s_cselect_b32 s47, s25, s37
	s_cselect_b32 s46, s24, s36
	s_cselect_b32 s43, s18, s29
	s_cselect_b32 s42, s19, s23
	s_add_i32 m0, s54, 0xc000
	ds_read_b128 v[148:151], v224
	ds_read_b128 v[152:155], v224 offset:1024
	ds_read_b128 v[178:181], v224 offset:2048
	ds_read_b128 v[182:185], v224 offset:3072
	ds_read_b128 v[186:189], v224 offset:4096
	ds_read_b128 v[190:193], v224 offset:5120
	ds_read_b128 v[194:197], v224 offset:6144
	ds_read_b128 v[198:201], v224 offset:7168
	global_load_lds_dwordx4 v174, s[34:35]
	s_mov_b64 s[100:101], s[34:35]
	s_waitcnt vmcnt(10) lgkmcnt(8)
	s_setprio 1
	s_barrier
	s_waitcnt lgkmcnt(0)
	v_mfma_f32_16x16x32_bf16 v[136:139], v[100:103], v[148:151], v[136:139]
	v_mfma_f32_16x16x32_bf16 v[132:135], v[140:143], v[148:151], v[132:135]
	v_mfma_f32_16x16x32_bf16 v[128:131], v[100:103], v[178:181], v[128:131]
	v_mfma_f32_16x16x32_bf16 v[124:127], v[140:143], v[178:181], v[124:127]
	v_mfma_f32_16x16x32_bf16 v[120:123], v[100:103], v[186:189], v[120:123]
	v_mfma_f32_16x16x32_bf16 v[116:119], v[140:143], v[186:189], v[116:119]
	v_mfma_f32_16x16x32_bf16 v[112:115], v[100:103], v[194:197], v[112:115]
	v_mfma_f32_16x16x32_bf16 v[108:111], v[140:143], v[194:197], v[108:111]
	v_mfma_f32_16x16x32_bf16 v[136:139], v[104:107], v[152:155], v[136:139]
	v_mfma_f32_16x16x32_bf16 v[132:135], v[144:147], v[152:155], v[132:135]
	v_mfma_f32_16x16x32_bf16 v[128:131], v[104:107], v[182:185], v[128:131]
	v_mfma_f32_16x16x32_bf16 v[124:127], v[144:147], v[182:185], v[124:127]
	v_mfma_f32_16x16x32_bf16 v[120:123], v[104:107], v[190:193], v[120:123]
	v_mfma_f32_16x16x32_bf16 v[116:119], v[144:147], v[190:193], v[116:119]
	v_mfma_f32_16x16x32_bf16 v[112:115], v[104:107], v[198:201], v[112:115]
	v_mfma_f32_16x16x32_bf16 v[108:111], v[144:147], v[198:201], v[108:111]
	s_barrier
	s_setprio 0
	s_add_i32 s34, 0, 0x14000
	v_add_u32_e32 v166, s34, v222
	s_add_i32 s0, s0, s53
	ds_read_b128 v[202:205], v166
	ds_read_b128 v[206:209], v166 offset:1024
	ds_read_b128 v[210:213], v166 offset:2048
	ds_read_b128 v[214:217], v166 offset:3072
	v_lshl_add_u64 v[166:167], s[42:43], 0, v[26:27]
	s_mov_b32 m0, s0
	v_lshl_add_u64 v[168:169], s[42:43], 0, v[160:161]
	global_load_lds_dwordx4 v[166:167], off
	s_add_i32 m0, s0, 0x2000
	s_nop 0
	global_load_lds_dwordx4 v[168:169], off
	v_lshl_add_u64 v[238:239], s[100:101], 0, v[176:177]
	s_add_i32 m0, s54, 0xe000
	s_nop 0
	global_load_lds_dwordx4 v[238:239], off
	s_waitcnt vmcnt(8)
	s_setprio 1
	s_barrier
	s_waitcnt lgkmcnt(0)
	v_mfma_f32_16x16x32_bf16 v[64:67], v[202:205], v[148:151], v[64:67]
	v_mfma_f32_16x16x32_bf16 v[60:63], v[210:213], v[148:151], v[60:63]
	v_mfma_f32_16x16x32_bf16 v[56:59], v[202:205], v[178:181], v[56:59]
	v_mfma_f32_16x16x32_bf16 v[52:55], v[210:213], v[178:181], v[52:55]
	v_mfma_f32_16x16x32_bf16 v[48:51], v[202:205], v[186:189], v[48:51]
	v_mfma_f32_16x16x32_bf16 v[44:47], v[210:213], v[186:189], v[44:47]
	v_mfma_f32_16x16x32_bf16 v[40:43], v[202:205], v[194:197], v[40:43]
	v_mfma_f32_16x16x32_bf16 v[36:39], v[210:213], v[194:197], v[36:39]
	v_mfma_f32_16x16x32_bf16 v[64:67], v[206:209], v[152:155], v[64:67]
	v_mfma_f32_16x16x32_bf16 v[60:63], v[214:217], v[152:155], v[60:63]
	v_mfma_f32_16x16x32_bf16 v[56:59], v[206:209], v[182:185], v[56:59]
	v_mfma_f32_16x16x32_bf16 v[52:55], v[214:217], v[182:185], v[52:55]
	v_mfma_f32_16x16x32_bf16 v[48:51], v[206:209], v[190:193], v[48:51]
	v_mfma_f32_16x16x32_bf16 v[44:47], v[214:217], v[190:193], v[44:47]
	v_mfma_f32_16x16x32_bf16 v[40:43], v[206:209], v[198:201], v[40:43]
	v_mfma_f32_16x16x32_bf16 v[36:39], v[214:217], v[198:201], v[36:39]
	s_barrier
	s_setprio 0
	s_mov_b32 m0, s54
	v_lshl_add_u64 v[218:219], s[46:47], 0, v[156:157]
	ds_read_b128 v[148:151], v224 offset:16384
	ds_read_b128 v[152:155], v224 offset:17408
	ds_read_b128 v[178:181], v224 offset:18432
	ds_read_b128 v[182:185], v224 offset:19456
	ds_read_b128 v[186:189], v224 offset:20480
	ds_read_b128 v[190:193], v224 offset:21504
	ds_read_b128 v[194:197], v224 offset:22528
	ds_read_b128 v[198:201], v224 offset:23552
	global_load_lds_dwordx4 v[218:219], off
	s_waitcnt vmcnt(10)
	s_setprio 1
	s_barrier
	s_waitcnt lgkmcnt(0)
	v_mfma_f32_16x16x32_bf16 v[96:99], v[100:103], v[148:151], v[96:99]
	v_mfma_f32_16x16x32_bf16 v[92:95], v[140:143], v[148:151], v[92:95]
	v_mfma_f32_16x16x32_bf16 v[88:91], v[100:103], v[178:181], v[88:91]
	v_mfma_f32_16x16x32_bf16 v[84:87], v[140:143], v[178:181], v[84:87]
	v_mfma_f32_16x16x32_bf16 v[80:83], v[100:103], v[186:189], v[80:83]
	v_mfma_f32_16x16x32_bf16 v[76:79], v[140:143], v[186:189], v[76:79]
	v_mfma_f32_16x16x32_bf16 v[72:75], v[100:103], v[194:197], v[72:75]
	v_mfma_f32_16x16x32_bf16 v[68:71], v[140:143], v[194:197], v[68:71]
	v_mfma_f32_16x16x32_bf16 v[96:99], v[104:107], v[152:155], v[96:99]
	v_mfma_f32_16x16x32_bf16 v[92:95], v[144:147], v[152:155], v[92:95]
	v_mfma_f32_16x16x32_bf16 v[88:91], v[104:107], v[182:185], v[88:91]
	v_mfma_f32_16x16x32_bf16 v[84:87], v[144:147], v[182:185], v[84:87]
	v_mfma_f32_16x16x32_bf16 v[80:83], v[104:107], v[190:193], v[80:83]
	v_mfma_f32_16x16x32_bf16 v[76:79], v[144:147], v[190:193], v[76:79]
	v_mfma_f32_16x16x32_bf16 v[72:75], v[104:107], v[198:201], v[72:75]
	v_mfma_f32_16x16x32_bf16 v[68:71], v[144:147], v[198:201], v[68:71]
	s_barrier
	s_setprio 0
	s_add_u32 s0, s42, 0x40000
	s_addc_u32 s1, s43, 0
	s_add_i32 s34, s34, s53
	s_mov_b32 m0, s34
	s_nop 0
	global_load_lds_dwordx4 v26, s[0:1]
	s_add_i32 m0, s34, 0x2000
	s_nop 0
	global_load_lds_dwordx4 v160, s[0:1]
	v_lshl_add_u64 v[220:221], s[46:47], 0, v[158:159]
	s_mov_b32 m0, s55
	s_nop 0
	global_load_lds_dwordx4 v[220:221], off
	v_add_u32_e32 v144, 0x18000, v222
	ds_read_b128 v[100:103], v144
	ds_read_b128 v[104:107], v144 offset:1024
	ds_read_b128 v[140:143], v144 offset:2048
	ds_read_b128 v[144:147], v144 offset:3072
	s_waitcnt vmcnt(8)
	s_setprio 1
	s_barrier
	v_mfma_f32_16x16x32_bf16 v[32:35], v[202:205], v[148:151], v[32:35]
	v_mfma_f32_16x16x32_bf16 v[28:31], v[210:213], v[148:151], v[28:31]
	v_mfma_f32_16x16x32_bf16 v[22:25], v[202:205], v[178:181], v[22:25]
	v_mfma_f32_16x16x32_bf16 v[18:21], v[210:213], v[178:181], v[18:21]
	v_mfma_f32_16x16x32_bf16 v[14:17], v[202:205], v[186:189], v[14:17]
	v_mfma_f32_16x16x32_bf16 v[10:13], v[210:213], v[186:189], v[10:13]
	v_mfma_f32_16x16x32_bf16 v[6:9], v[202:205], v[194:197], v[6:9]
	v_mfma_f32_16x16x32_bf16 v[2:5], v[210:213], v[194:197], v[2:5]
	v_mfma_f32_16x16x32_bf16 v[32:35], v[206:209], v[152:155], v[32:35]
	v_mfma_f32_16x16x32_bf16 v[28:31], v[214:217], v[152:155], v[28:31]
	v_mfma_f32_16x16x32_bf16 v[22:25], v[206:209], v[182:185], v[22:25]
	v_mfma_f32_16x16x32_bf16 v[18:21], v[214:217], v[182:185], v[18:21]
	v_mfma_f32_16x16x32_bf16 v[14:17], v[206:209], v[190:193], v[14:17]
	v_mfma_f32_16x16x32_bf16 v[10:13], v[214:217], v[190:193], v[10:13]
	v_mfma_f32_16x16x32_bf16 v[6:9], v[206:209], v[198:201], v[6:9]
	v_mfma_f32_16x16x32_bf16 v[2:5], v[214:217], v[198:201], v[2:5]
	s_barrier
	s_setprio 0
	s_add_i32 s34, 0, 0x18000
	s_add_u32 s0, s46, 0x140000
	s_addc_u32 s1, s47, 0
	s_mov_b32 m0, s56
	ds_read_b128 v[148:151], v224 offset:32768
	ds_read_b128 v[152:155], v224 offset:33792
	ds_read_b128 v[178:181], v224 offset:34816
	ds_read_b128 v[182:185], v224 offset:35840
	ds_read_b128 v[186:189], v224 offset:36864
	ds_read_b128 v[190:193], v224 offset:37888
	ds_read_b128 v[194:197], v224 offset:38912
	ds_read_b128 v[198:201], v224 offset:39936
	global_load_lds_dwordx4 v156, s[0:1]
	s_mov_b64 s[100:101], s[0:1]
	s_waitcnt vmcnt(10) lgkmcnt(8)
	s_setprio 1
	s_barrier
	s_waitcnt lgkmcnt(0)
	v_mfma_f32_16x16x32_bf16 v[136:139], v[100:103], v[148:151], v[136:139]
	v_mfma_f32_16x16x32_bf16 v[132:135], v[140:143], v[148:151], v[132:135]
	v_mfma_f32_16x16x32_bf16 v[128:131], v[100:103], v[178:181], v[128:131]
	v_mfma_f32_16x16x32_bf16 v[124:127], v[140:143], v[178:181], v[124:127]
	v_mfma_f32_16x16x32_bf16 v[120:123], v[100:103], v[186:189], v[120:123]
	v_mfma_f32_16x16x32_bf16 v[116:119], v[140:143], v[186:189], v[116:119]
	v_mfma_f32_16x16x32_bf16 v[112:115], v[100:103], v[194:197], v[112:115]
	v_mfma_f32_16x16x32_bf16 v[108:111], v[140:143], v[194:197], v[108:111]
	v_mfma_f32_16x16x32_bf16 v[136:139], v[104:107], v[152:155], v[136:139]
	v_mfma_f32_16x16x32_bf16 v[132:135], v[144:147], v[152:155], v[132:135]
	v_mfma_f32_16x16x32_bf16 v[128:131], v[104:107], v[182:185], v[128:131]
	v_mfma_f32_16x16x32_bf16 v[124:127], v[144:147], v[182:185], v[124:127]
	v_mfma_f32_16x16x32_bf16 v[120:123], v[104:107], v[190:193], v[120:123]
	v_mfma_f32_16x16x32_bf16 v[116:119], v[144:147], v[190:193], v[116:119]
	v_mfma_f32_16x16x32_bf16 v[112:115], v[104:107], v[198:201], v[112:115]
	v_mfma_f32_16x16x32_bf16 v[108:111], v[144:147], v[198:201], v[108:111]
	s_barrier
	s_setprio 0
	s_add_i32 s35, 0, 0x1c000
	s_add_i32 s0, s34, s53
	v_add_u32_e32 v214, s35, v222
	v_lshl_add_u64 v[166:167], v[166:167], 0, s[12:13]
	s_mov_b32 m0, s0
	ds_read_b128 v[202:205], v214
	ds_read_b128 v[206:209], v214 offset:1024
	ds_read_b128 v[210:213], v214 offset:2048
	ds_read_b128 v[214:217], v214 offset:3072
	global_load_lds_dwordx4 v[166:167], off
	v_lshl_add_u64 v[166:167], v[168:169], 0, s[12:13]
	s_add_i32 m0, s0, 0x2000
	s_nop 0
	global_load_lds_dwordx4 v[166:167], off
	s_mov_b32 m0, s57
	s_nop 0
	global_load_lds_dwordx4 v158, s[100:101]
	s_waitcnt vmcnt(8)
	s_setprio 1
	s_barrier
	s_waitcnt lgkmcnt(0)
	v_mfma_f32_16x16x32_bf16 v[64:67], v[202:205], v[148:151], v[64:67]
	v_mfma_f32_16x16x32_bf16 v[60:63], v[210:213], v[148:151], v[60:63]
	v_mfma_f32_16x16x32_bf16 v[56:59], v[202:205], v[178:181], v[56:59]
	v_mfma_f32_16x16x32_bf16 v[52:55], v[210:213], v[178:181], v[52:55]
	v_mfma_f32_16x16x32_bf16 v[48:51], v[202:205], v[186:189], v[48:51]
	v_mfma_f32_16x16x32_bf16 v[44:47], v[210:213], v[186:189], v[44:47]
	v_mfma_f32_16x16x32_bf16 v[40:43], v[202:205], v[194:197], v[40:43]
	v_mfma_f32_16x16x32_bf16 v[36:39], v[210:213], v[194:197], v[36:39]
	v_mfma_f32_16x16x32_bf16 v[64:67], v[206:209], v[152:155], v[64:67]
	v_mfma_f32_16x16x32_bf16 v[60:63], v[214:217], v[152:155], v[60:63]
	v_mfma_f32_16x16x32_bf16 v[56:59], v[206:209], v[182:185], v[56:59]
	v_mfma_f32_16x16x32_bf16 v[52:55], v[214:217], v[182:185], v[52:55]
	v_mfma_f32_16x16x32_bf16 v[48:51], v[206:209], v[190:193], v[48:51]
	v_mfma_f32_16x16x32_bf16 v[44:47], v[214:217], v[190:193], v[44:47]
	v_mfma_f32_16x16x32_bf16 v[40:43], v[206:209], v[198:201], v[40:43]
	v_mfma_f32_16x16x32_bf16 v[36:39], v[214:217], v[198:201], v[36:39]
	s_barrier
	s_setprio 0
	s_mov_b32 m0, s81
	v_lshl_add_u64 v[166:167], v[218:219], 0, s[12:13]
	ds_read_b128 v[148:151], v224 offset:49152
	ds_read_b128 v[152:155], v224 offset:50176
	ds_read_b128 v[178:181], v224 offset:51200
	ds_read_b128 v[182:185], v224 offset:52224
	ds_read_b128 v[186:189], v224 offset:53248
	ds_read_b128 v[190:193], v224 offset:54272
	ds_read_b128 v[194:197], v224 offset:55296
	ds_read_b128 v[198:201], v224 offset:56320
	global_load_lds_dwordx4 v[166:167], off
	s_waitcnt vmcnt(10)
	s_setprio 1
	s_barrier
	s_waitcnt lgkmcnt(0)
	v_mfma_f32_16x16x32_bf16 v[96:99], v[100:103], v[148:151], v[96:99]
	v_mfma_f32_16x16x32_bf16 v[92:95], v[140:143], v[148:151], v[92:95]
	v_mfma_f32_16x16x32_bf16 v[88:91], v[100:103], v[178:181], v[88:91]
	v_mfma_f32_16x16x32_bf16 v[84:87], v[140:143], v[178:181], v[84:87]
	v_mfma_f32_16x16x32_bf16 v[80:83], v[100:103], v[186:189], v[80:83]
	v_mfma_f32_16x16x32_bf16 v[76:79], v[140:143], v[186:189], v[76:79]
	v_mfma_f32_16x16x32_bf16 v[72:75], v[100:103], v[194:197], v[72:75]
	v_mfma_f32_16x16x32_bf16 v[68:71], v[140:143], v[194:197], v[68:71]
	v_mfma_f32_16x16x32_bf16 v[96:99], v[104:107], v[152:155], v[96:99]
	v_mfma_f32_16x16x32_bf16 v[92:95], v[144:147], v[152:155], v[92:95]
	v_mfma_f32_16x16x32_bf16 v[88:91], v[104:107], v[182:185], v[88:91]
	v_mfma_f32_16x16x32_bf16 v[84:87], v[144:147], v[182:185], v[84:87]
	v_mfma_f32_16x16x32_bf16 v[80:83], v[104:107], v[190:193], v[80:83]
	v_mfma_f32_16x16x32_bf16 v[76:79], v[144:147], v[190:193], v[76:79]
	v_mfma_f32_16x16x32_bf16 v[72:75], v[104:107], v[198:201], v[72:75]
	v_mfma_f32_16x16x32_bf16 v[68:71], v[144:147], v[198:201], v[68:71]
	s_barrier
	s_setprio 0
	s_add_u32 s0, s42, 0x40080
	s_addc_u32 s1, s43, 0
	s_add_i32 s34, s35, s53
	s_mov_b32 m0, s34
	s_nop 0
	global_load_lds_dwordx4 v26, s[0:1]
	s_add_i32 m0, s34, 0x2000
	s_nop 0
	global_load_lds_dwordx4 v160, s[0:1]
	v_lshl_add_u64 v[166:167], v[220:221], 0, s[12:13]
	s_mov_b32 m0, s17
	s_nop 0
	global_load_lds_dwordx4 v[166:167], off
	v_add_u32_e32 v144, 0x10000, v222
	ds_read_b128 v[100:103], v144
	ds_read_b128 v[104:107], v144 offset:1024
	ds_read_b128 v[140:143], v144 offset:2048
	ds_read_b128 v[144:147], v144 offset:3072
	s_waitcnt vmcnt(8)
	s_setprio 1
	s_barrier
	v_mfma_f32_16x16x32_bf16 v[32:35], v[202:205], v[148:151], v[32:35]
	v_mfma_f32_16x16x32_bf16 v[28:31], v[210:213], v[148:151], v[28:31]
	v_mfma_f32_16x16x32_bf16 v[22:25], v[202:205], v[178:181], v[22:25]
	v_mfma_f32_16x16x32_bf16 v[18:21], v[210:213], v[178:181], v[18:21]
	v_mfma_f32_16x16x32_bf16 v[14:17], v[202:205], v[186:189], v[14:17]
	v_mfma_f32_16x16x32_bf16 v[10:13], v[210:213], v[186:189], v[10:13]
	v_mfma_f32_16x16x32_bf16 v[6:9], v[202:205], v[194:197], v[6:9]
	v_mfma_f32_16x16x32_bf16 v[2:5], v[210:213], v[194:197], v[2:5]
	v_mfma_f32_16x16x32_bf16 v[32:35], v[206:209], v[152:155], v[32:35]
	v_mfma_f32_16x16x32_bf16 v[28:31], v[214:217], v[152:155], v[28:31]
	v_mfma_f32_16x16x32_bf16 v[22:25], v[206:209], v[182:185], v[22:25]
	v_mfma_f32_16x16x32_bf16 v[18:21], v[214:217], v[182:185], v[18:21]
	v_mfma_f32_16x16x32_bf16 v[14:17], v[206:209], v[190:193], v[14:17]
	v_mfma_f32_16x16x32_bf16 v[10:13], v[214:217], v[190:193], v[10:13]
	v_mfma_f32_16x16x32_bf16 v[6:9], v[206:209], v[198:201], v[6:9]
	v_mfma_f32_16x16x32_bf16 v[2:5], v[214:217], v[198:201], v[2:5]
	s_barrier
	s_setprio 0
	s_add_i32 s31, s31, 2
	s_add_u32 s23, s23, 0x100
	s_addc_u32 s29, s29, 0
	s_cmp_gt_u32 s31, 13
	s_mov_b64 s[34:35], s[36:37]
	s_cbranch_scc0 .LBB0_965
	s_waitcnt lgkmcnt(0)
	s_min_i32 s0, s28, 0x100
	s_ashr_i32 s0, s0, 5
	s_ashr_i32 s1, s0, 31
	s_add_i32 s18, s28, 0xffffff00
	s_cmpk_lt_i32 s28, 0x100
	s_cselect_b32 s18, s28, s18
	s_cselect_b32 s23, 0, s59
	s_cselect_b32 s29, 0, s58
	s_ashr_i32 s19, s18, 31
	s_lshl_b64 s[18:19], s[18:19], 19
	v_lshl_or_b32 v148, s30, 8, v223
	s_add_u32 s30, s44, s29
	s_addc_u32 s31, s45, s23
	s_ashr_i32 s29, s28, 31
	v_lshl_add_u64 v[100:101], s[18:19], 0, v[162:163]
	s_lshl_b64 s[18:19], s[28:29], 19
	v_lshl_add_u64 v[152:153], v[164:165], 0, s[18:19]
	s_lshl_b64 s[28:29], s[28:29], 10
	s_mul_i32 s18, s0, 0x9000
	s_mul_hi_i32 s19, s0, 0x9000
	s_add_u32 s18, s68, s18
	s_addc_u32 s19, s69, s19
	s_lshl_b64 s[0:1], s[0:1], 12
	v_ashrrev_i32_e32 v149, 31, v148
	s_add_u32 s0, s72, s0
	v_lshlrev_b64 v[154:155], 2, v[148:149]
	s_addc_u32 s1, s73, s1
	v_lshl_add_u64 v[150:151], v[100:101], 0, v[148:149]
	v_lshl_add_u64 v[104:105], s[18:19], 0, v[154:155]
	v_lshlrev_b64 v[168:169], 1, v[148:149]
	v_lshl_add_u64 v[180:181], s[0:1], 0, v[154:155]
	v_lshl_add_u64 v[166:167], v[100:101], 1, s[30:31]
	global_load_dwordx4 v[140:143], v[104:105], off offset:16
	global_load_dwordx4 v[144:147], v[104:105], off
	global_load_dwordx4 v[100:103], v[104:105], off offset:528
	s_nop 0
	global_load_dwordx4 v[104:107], v[104:105], off offset:512
	v_lshl_add_u64 v[196:197], v[150:151], 1, s[30:31]
	v_lshl_add_u64 v[178:179], v[152:153], 0, v[168:169]
	global_load_dwordx4 v[148:151], v[180:181], off offset:16
	global_load_dwordx4 v[152:155], v[180:181], off
	global_load_dwordx4 v[190:193], v[196:197], off offset:2048
	v_add_co_u32_e32 v210, vcc, s65, v196
	s_mov_b32 s1, 0x20000
	s_nop 0
	v_addc_co_u32_e32 v211, vcc, 0, v197, vcc
	global_load_dwordx4 v[198:201], v[210:211], off offset:2048
	v_add_co_u32_e32 v184, vcc, s1, v196
	s_mov_b32 s18, 0x30000
	s_nop 0
	v_addc_co_u32_e32 v185, vcc, 0, v197, vcc
	global_load_dwordx4 v[202:205], v[184:185], off offset:2048
	v_add_co_u32_e32 v188, vcc, s18, v196
	v_lshl_add_u64 v[182:183], v[166:167], 0, v[168:169]
	s_nop 0
	v_addc_co_u32_e32 v189, vcc, 0, v197, vcc
	global_load_dwordx4 v[206:209], v[188:189], off offset:2048
	s_mov_b32 s0, 0x8000
	s_mov_b32 s19, 0x80000
	s_mov_b32 s23, 0x90000
	s_waitcnt vmcnt(0)
	v_lshlrev_b32_e32 v166, 16, v190
	v_and_b32_e32 v167, 0xffff0000, v190
	v_lshlrev_b32_e32 v168, 16, v191
	v_and_b32_e32 v169, 0xffff0000, v191
	v_lshlrev_b32_e32 v186, 16, v192
	v_and_b32_e32 v187, 0xffff0000, v192
	v_lshlrev_b32_e32 v190, 16, v193
	v_and_b32_e32 v191, 0xffff0000, v193
	v_pk_fma_f32 v[138:139], v[138:139], v[146:147], v[168:169]
	v_pk_fma_f32 v[136:137], v[136:137], v[144:145], v[166:167]
	v_pk_fma_f32 v[134:135], v[134:135], v[142:143], v[190:191]
	v_pk_fma_f32 v[132:133], v[132:133], v[140:141], v[186:187]
	v_cvt_pk_bf16_f32 v190, v136, v137
	v_cvt_pk_bf16_f32 v191, v138, v139
	v_cvt_pk_bf16_f32 v192, v132, v133
	v_cvt_pk_bf16_f32 v193, v134, v135
	v_lshlrev_b32_e32 v138, 16, v190
	v_and_b32_e32 v139, 0xffff0000, v190
	v_lshlrev_b32_e32 v136, 16, v191
	v_and_b32_e32 v137, 0xffff0000, v191
	v_lshlrev_b32_e32 v134, 16, v192
	v_and_b32_e32 v135, 0xffff0000, v192
	v_lshlrev_b32_e32 v132, 16, v193
	v_and_b32_e32 v133, 0xffff0000, v193
	v_lshlrev_b32_e32 v212, 16, v200
	v_and_b32_e32 v213, 0xffff0000, v200
	v_lshlrev_b32_e32 v200, 16, v201
	v_and_b32_e32 v201, 0xffff0000, v201
	global_store_dwordx4 v[182:183], v[190:193], off offset:2048
	v_pk_mul_f32 v[166:167], v[154:155], v[136:137]
	v_pk_mul_f32 v[168:169], v[152:153], v[138:139]
	v_pk_mul_f32 v[186:187], v[150:151], v[132:133]
	v_pk_mul_f32 v[192:193], v[148:149], v[134:135]
	v_lshlrev_b32_e32 v194, 16, v198
	v_and_b32_e32 v195, 0xffff0000, v198
	v_lshlrev_b32_e32 v198, 16, v199
	v_and_b32_e32 v199, 0xffff0000, v199
	v_cvt_pk_bf16_f32 v190, v168, v169
	v_cvt_pk_bf16_f32 v191, v166, v167
	v_cvt_pk_bf16_f32 v192, v192, v193
	v_cvt_pk_bf16_f32 v193, v186, v187
	v_pk_fma_f32 v[126:127], v[126:127], v[142:143], v[200:201]
	v_pk_fma_f32 v[124:125], v[124:125], v[140:141], v[212:213]
	global_store_dwordx4 v[178:179], v[190:193], off
	v_pk_fma_f32 v[130:131], v[130:131], v[146:147], v[198:199]
	v_pk_fma_f32 v[128:129], v[128:129], v[144:145], v[194:195]
	v_cvt_pk_bf16_f32 v192, v124, v125
	v_cvt_pk_bf16_f32 v193, v126, v127
	v_add_co_u32_e32 v186, vcc, s65, v182
	v_cvt_pk_bf16_f32 v190, v128, v129
	v_cvt_pk_bf16_f32 v191, v130, v131
	v_addc_co_u32_e32 v187, vcc, 0, v183, vcc
	v_lshlrev_b32_e32 v126, 16, v192
	v_and_b32_e32 v127, 0xffff0000, v192
	v_lshlrev_b32_e32 v124, 16, v193
	v_and_b32_e32 v125, 0xffff0000, v193
	global_store_dwordx4 v[186:187], v[190:193], off offset:2048
	v_lshlrev_b32_e32 v130, 16, v190
	v_and_b32_e32 v131, 0xffff0000, v190
	v_lshlrev_b32_e32 v128, 16, v191
	v_and_b32_e32 v129, 0xffff0000, v191
	v_pk_mul_f32 v[190:191], v[150:151], v[124:125]
	v_pk_mul_f32 v[194:195], v[148:149], v[126:127]
	v_pk_mul_f32 v[166:167], v[154:155], v[128:129]
	v_pk_mul_f32 v[168:169], v[152:153], v[130:131]
	v_cvt_pk_bf16_f32 v194, v194, v195
	v_cvt_pk_bf16_f32 v195, v190, v191
	v_add_co_u32_e32 v190, vcc, s0, v178
	v_cvt_pk_bf16_f32 v192, v168, v169
	v_cvt_pk_bf16_f32 v193, v166, v167
	v_addc_co_u32_e32 v191, vcc, 0, v179, vcc
	global_store_dwordx4 v[190:191], v[192:195], off
	v_lshlrev_b32_e32 v198, 16, v204
	v_and_b32_e32 v199, 0xffff0000, v204
	v_add_co_u32_e32 v192, vcc, s19, v196
	v_lshlrev_b32_e32 v200, 16, v205
	s_nop 0
	v_addc_co_u32_e32 v193, vcc, 0, v197, vcc
	v_add_co_u32_e32 v194, vcc, s23, v196
	v_and_b32_e32 v201, 0xffff0000, v205
	global_load_dwordx4 v[212:215], v[192:193], off offset:2048
	v_addc_co_u32_e32 v195, vcc, 0, v197, vcc
	v_lshlrev_b32_e32 v166, 16, v202
	v_and_b32_e32 v167, 0xffff0000, v202
	v_lshlrev_b32_e32 v168, 16, v203
	v_and_b32_e32 v169, 0xffff0000, v203
	v_pk_fma_f32 v[118:119], v[118:119], v[142:143], v[200:201]
	v_pk_fma_f32 v[116:117], v[116:117], v[140:141], v[198:199]
	v_pk_fma_f32 v[122:123], v[122:123], v[146:147], v[168:169]
	v_pk_fma_f32 v[120:121], v[120:121], v[144:145], v[166:167]
	v_cvt_pk_bf16_f32 v202, v116, v117
	v_cvt_pk_bf16_f32 v203, v118, v119
	v_add_co_u32_e32 v198, vcc, s1, v182
	global_load_dwordx4 v[216:219], v[194:195], off offset:2048
	v_cvt_pk_bf16_f32 v200, v120, v121
	v_cvt_pk_bf16_f32 v201, v122, v123
	v_addc_co_u32_e32 v199, vcc, 0, v183, vcc
	v_lshlrev_b32_e32 v118, 16, v202
	v_and_b32_e32 v119, 0xffff0000, v202
	v_lshlrev_b32_e32 v116, 16, v203
	v_and_b32_e32 v117, 0xffff0000, v203
	global_store_dwordx4 v[198:199], v[200:203], off offset:2048
	v_lshlrev_b32_e32 v122, 16, v200
	v_and_b32_e32 v123, 0xffff0000, v200
	v_lshlrev_b32_e32 v120, 16, v201
	v_and_b32_e32 v121, 0xffff0000, v201
	v_pk_mul_f32 v[200:201], v[150:151], v[116:117]
	v_pk_mul_f32 v[204:205], v[148:149], v[118:119]
	v_lshlrev_b32_e32 v234, 16, v208
	v_and_b32_e32 v235, 0xffff0000, v208
	v_lshlrev_b32_e32 v208, 16, v209
	v_and_b32_e32 v209, 0xffff0000, v209
	v_pk_mul_f32 v[166:167], v[154:155], v[120:121]
	v_pk_mul_f32 v[168:169], v[152:153], v[122:123]
	v_cvt_pk_bf16_f32 v204, v204, v205
	v_cvt_pk_bf16_f32 v205, v200, v201
	v_add_co_u32_e32 v200, vcc, s65, v178
	v_lshlrev_b32_e32 v220, 16, v206
	v_and_b32_e32 v221, 0xffff0000, v206
	v_lshlrev_b32_e32 v206, 16, v207
	v_and_b32_e32 v207, 0xffff0000, v207
	v_cvt_pk_bf16_f32 v202, v168, v169
	v_cvt_pk_bf16_f32 v203, v166, v167
	v_addc_co_u32_e32 v201, vcc, 0, v179, vcc
	v_pk_fma_f32 v[110:111], v[110:111], v[142:143], v[208:209]
	v_pk_fma_f32 v[108:109], v[108:109], v[140:141], v[234:235]
	global_store_dwordx4 v[200:201], v[202:205], off
	v_pk_fma_f32 v[114:115], v[114:115], v[146:147], v[206:207]
	v_pk_fma_f32 v[112:113], v[112:113], v[144:145], v[220:221]
	v_cvt_pk_bf16_f32 v206, v108, v109
	v_cvt_pk_bf16_f32 v207, v110, v111
	v_add_co_u32_e32 v202, vcc, s18, v182
	v_cvt_pk_bf16_f32 v204, v112, v113
	v_cvt_pk_bf16_f32 v205, v114, v115
	v_addc_co_u32_e32 v203, vcc, 0, v183, vcc
	v_lshlrev_b32_e32 v110, 16, v206
	v_and_b32_e32 v111, 0xffff0000, v206
	v_lshlrev_b32_e32 v108, 16, v207
	v_and_b32_e32 v109, 0xffff0000, v207
	global_store_dwordx4 v[202:203], v[204:207], off offset:2048
	v_lshlrev_b32_e32 v114, 16, v204
	v_and_b32_e32 v115, 0xffff0000, v204
	v_lshlrev_b32_e32 v112, 16, v205
	v_and_b32_e32 v113, 0xffff0000, v205
	v_pk_mul_f32 v[204:205], v[150:151], v[108:109]
	v_pk_mul_f32 v[208:209], v[148:149], v[110:111]
	s_mov_b32 s0, 0x18000
	v_pk_mul_f32 v[166:167], v[154:155], v[112:113]
	v_pk_mul_f32 v[168:169], v[152:153], v[114:115]
	v_cvt_pk_bf16_f32 v208, v208, v209
	v_cvt_pk_bf16_f32 v209, v204, v205
	v_add_co_u32_e32 v204, vcc, s0, v178
	v_cvt_pk_bf16_f32 v206, v168, v169
	v_cvt_pk_bf16_f32 v207, v166, v167
	v_addc_co_u32_e32 v205, vcc, 0, v179, vcc
	global_store_dwordx4 v[204:205], v[206:209], off
	s_mov_b32 s0, 0xb0000
	s_waitcnt vmcnt(0)
	v_lshlrev_b32_e32 v166, 16, v212
	v_add_co_u32_e32 v206, vcc, s76, v196
	v_and_b32_e32 v167, 0xffff0000, v212
	s_nop 0
	v_addc_co_u32_e32 v207, vcc, 0, v197, vcc
	global_load_dwordx4 v[238:241], v[206:207], off offset:2048
	v_add_co_u32_e32 v208, vcc, s0, v196
	v_lshlrev_b32_e32 v168, 16, v213
	s_nop 0
	v_addc_co_u32_e32 v209, vcc, 0, v197, vcc
	global_load_dwordx4 v[242:245], v[208:209], off offset:2048
	v_and_b32_e32 v169, 0xffff0000, v213
	v_lshlrev_b32_e32 v212, 16, v214
	v_and_b32_e32 v213, 0xffff0000, v214
	v_lshlrev_b32_e32 v214, 16, v215
	v_and_b32_e32 v215, 0xffff0000, v215
	v_pk_fma_f32 v[94:95], v[94:95], v[142:143], v[214:215]
	v_pk_fma_f32 v[92:93], v[92:93], v[140:141], v[212:213]
	v_lshlrev_b32_e32 v220, 16, v216
	v_and_b32_e32 v221, 0xffff0000, v216
	v_lshlrev_b32_e32 v234, 16, v217
	v_and_b32_e32 v235, 0xffff0000, v217
	v_pk_fma_f32 v[98:99], v[98:99], v[146:147], v[168:169]
	v_pk_fma_f32 v[96:97], v[96:97], v[144:145], v[166:167]
	v_cvt_pk_bf16_f32 v216, v92, v93
	v_cvt_pk_bf16_f32 v217, v94, v95
	v_add_co_u32_e32 v212, vcc, s19, v182
	v_cvt_pk_bf16_f32 v214, v96, v97
	v_cvt_pk_bf16_f32 v215, v98, v99
	v_addc_co_u32_e32 v213, vcc, 0, v183, vcc
	v_lshlrev_b32_e32 v94, 16, v216
	v_and_b32_e32 v95, 0xffff0000, v216
	v_lshlrev_b32_e32 v92, 16, v217
	v_and_b32_e32 v93, 0xffff0000, v217
	v_lshlrev_b32_e32 v246, 16, v218
	v_and_b32_e32 v247, 0xffff0000, v218
	v_lshlrev_b32_e32 v248, 16, v219
	v_and_b32_e32 v249, 0xffff0000, v219
	global_store_dwordx4 v[212:213], v[214:217], off offset:2048
	v_lshlrev_b32_e32 v98, 16, v214
	v_and_b32_e32 v99, 0xffff0000, v214
	v_lshlrev_b32_e32 v96, 16, v215
	v_and_b32_e32 v97, 0xffff0000, v215
	v_pk_mul_f32 v[214:215], v[150:151], v[92:93]
	v_pk_mul_f32 v[218:219], v[148:149], v[94:95]
	s_mov_b32 s1, 0x40000
	v_pk_mul_f32 v[166:167], v[154:155], v[96:97]
	v_pk_mul_f32 v[168:169], v[152:153], v[98:99]
	v_cvt_pk_bf16_f32 v218, v218, v219
	v_cvt_pk_bf16_f32 v219, v214, v215
	v_add_co_u32_e32 v214, vcc, s1, v178
	v_cvt_pk_bf16_f32 v216, v168, v169
	v_cvt_pk_bf16_f32 v217, v166, v167
	v_addc_co_u32_e32 v215, vcc, 0, v179, vcc
	v_pk_fma_f32 v[86:87], v[86:87], v[142:143], v[248:249]
	global_store_dwordx4 v[214:215], v[216:219], off
	v_pk_fma_f32 v[90:91], v[90:91], v[146:147], v[234:235]
	v_pk_fma_f32 v[88:89], v[88:89], v[144:145], v[220:221]
	v_pk_fma_f32 v[84:85], v[84:85], v[140:141], v[246:247]
	v_cvt_pk_bf16_f32 v221, v86, v87
	v_add_co_u32_e32 v216, vcc, s23, v182
	v_cvt_pk_bf16_f32 v218, v88, v89
	v_cvt_pk_bf16_f32 v219, v90, v91
	v_cvt_pk_bf16_f32 v220, v84, v85
	v_addc_co_u32_e32 v217, vcc, 0, v183, vcc
	v_lshlrev_b32_e32 v84, 16, v221
	v_and_b32_e32 v85, 0xffff0000, v221
	global_store_dwordx4 v[216:217], v[218:221], off offset:2048
	v_lshlrev_b32_e32 v90, 16, v218
	v_and_b32_e32 v91, 0xffff0000, v218
	v_lshlrev_b32_e32 v88, 16, v219
	v_and_b32_e32 v89, 0xffff0000, v219
	v_lshlrev_b32_e32 v86, 16, v220
	v_and_b32_e32 v87, 0xffff0000, v220
	v_pk_mul_f32 v[218:219], v[150:151], v[84:85]
	s_mov_b32 s1, 0x48000
	v_pk_mul_f32 v[166:167], v[154:155], v[88:89]
	v_pk_mul_f32 v[168:169], v[152:153], v[90:91]
	v_pk_mul_f32 v[220:221], v[148:149], v[86:87]
	v_cvt_pk_bf16_f32 v249, v218, v219
	v_add_co_u32_e32 v218, vcc, s1, v178
	v_cvt_pk_bf16_f32 v246, v168, v169
	v_cvt_pk_bf16_f32 v247, v166, v167
	v_cvt_pk_bf16_f32 v248, v220, v221
	v_addc_co_u32_e32 v219, vcc, 0, v179, vcc
	global_store_dwordx4 v[218:219], v[246:249], off
	global_load_dwordx4 v[246:249], v[196:197], off offset:2304
	s_nop 0
	global_load_dwordx4 v[250:253], v[210:211], off offset:2304
	s_waitcnt vmcnt(0)
	v_lshlrev_b32_e32 v196, 16, v240
	v_and_b32_e32 v197, 0xffff0000, v240
	v_lshlrev_b32_e32 v210, 16, v241
	v_and_b32_e32 v211, 0xffff0000, v241
	v_lshlrev_b32_e32 v166, 16, v238
	v_and_b32_e32 v167, 0xffff0000, v238
	v_lshlrev_b32_e32 v168, 16, v239
	v_and_b32_e32 v169, 0xffff0000, v239
	v_pk_fma_f32 v[78:79], v[78:79], v[142:143], v[210:211]
	v_pk_fma_f32 v[76:77], v[76:77], v[140:141], v[196:197]
	v_pk_fma_f32 v[82:83], v[82:83], v[146:147], v[168:169]
	v_pk_fma_f32 v[80:81], v[80:81], v[144:145], v[166:167]
	v_cvt_pk_bf16_f32 v240, v76, v77
	v_cvt_pk_bf16_f32 v241, v78, v79
	v_add_co_u32_e32 v196, vcc, s76, v182
	v_cvt_pk_bf16_f32 v238, v80, v81
	v_cvt_pk_bf16_f32 v239, v82, v83
	v_addc_co_u32_e32 v197, vcc, 0, v183, vcc
	v_lshlrev_b32_e32 v78, 16, v240
	v_and_b32_e32 v79, 0xffff0000, v240
	v_lshlrev_b32_e32 v76, 16, v241
	v_and_b32_e32 v77, 0xffff0000, v241
	global_store_dwordx4 v[196:197], v[238:241], off offset:2048
	v_pk_mul_f32 v[210:211], v[150:151], v[76:77]
	v_lshlrev_b32_e32 v220, 16, v242
	v_pk_mul_f32 v[240:241], v[148:149], v[78:79]
	v_and_b32_e32 v221, 0xffff0000, v242
	v_lshlrev_b32_e32 v234, 16, v243
	v_and_b32_e32 v235, 0xffff0000, v243
	v_lshlrev_b32_e32 v242, 16, v244
	v_and_b32_e32 v243, 0xffff0000, v244
	v_lshlrev_b32_e32 v244, 16, v245
	v_and_b32_e32 v245, 0xffff0000, v245
	v_cvt_pk_bf16_f32 v240, v240, v241
	v_cvt_pk_bf16_f32 v241, v210, v211
	v_add_co_u32_e32 v210, vcc, s77, v178
	v_lshlrev_b32_e32 v82, 16, v238
	v_and_b32_e32 v83, 0xffff0000, v238
	v_lshlrev_b32_e32 v80, 16, v239
	v_and_b32_e32 v81, 0xffff0000, v239
	v_addc_co_u32_e32 v211, vcc, 0, v179, vcc
	v_pk_fma_f32 v[74:75], v[74:75], v[146:147], v[234:235]
	v_pk_fma_f32 v[72:73], v[72:73], v[144:145], v[220:221]
	v_pk_fma_f32 v[142:143], v[70:71], v[142:143], v[244:245]
	v_pk_fma_f32 v[70:71], v[68:69], v[140:141], v[242:243]
	v_pk_mul_f32 v[166:167], v[154:155], v[80:81]
	v_pk_mul_f32 v[168:169], v[152:153], v[82:83]
	v_cvt_pk_bf16_f32 v68, v72, v73
	v_cvt_pk_bf16_f32 v69, v74, v75
	v_cvt_pk_bf16_f32 v70, v70, v71
	v_cvt_pk_bf16_f32 v71, v142, v143
	v_add_co_u32_e32 v220, vcc, s0, v182
	v_cvt_pk_bf16_f32 v238, v168, v169
	v_cvt_pk_bf16_f32 v239, v166, v167
	v_addc_co_u32_e32 v221, vcc, 0, v183, vcc
	v_lshlrev_b32_e32 v146, 16, v68
	v_and_b32_e32 v147, 0xffff0000, v68
	v_lshlrev_b32_e32 v144, 16, v69
	v_and_b32_e32 v145, 0xffff0000, v69
	v_lshlrev_b32_e32 v142, 16, v70
	v_and_b32_e32 v143, 0xffff0000, v70
	v_lshlrev_b32_e32 v140, 16, v71
	v_and_b32_e32 v141, 0xffff0000, v71
	s_mov_b32 s0, 0x58000
	global_store_dwordx4 v[210:211], v[238:241], off
	global_store_dwordx4 v[220:221], v[68:71], off offset:2048
	v_pk_mul_f32 v[72:73], v[150:151], v[140:141]
	v_pk_mul_f32 v[74:75], v[148:149], v[142:143]
	v_pk_mul_f32 v[70:71], v[154:155], v[144:145]
	v_pk_mul_f32 v[68:69], v[152:153], v[146:147]
	v_add_co_u32_e32 v148, vcc, s0, v178
	v_cvt_pk_bf16_f32 v68, v68, v69
	v_cvt_pk_bf16_f32 v69, v70, v71
	v_cvt_pk_bf16_f32 v70, v74, v75
	v_cvt_pk_bf16_f32 v71, v72, v73
	v_addc_co_u32_e32 v149, vcc, 0, v179, vcc
	global_store_dwordx4 v[148:149], v[68:71], off
	global_load_dwordx4 v[150:153], v[184:185], off offset:2304
	global_load_dwordx4 v[238:241], v[188:189], off offset:2304
	s_nop 0
	global_load_dwordx4 v[68:71], v[180:181], off offset:528
	global_load_dwordx4 v[72:75], v[180:181], off offset:512
	v_lshlrev_b32_e32 v154, 16, v246
	v_and_b32_e32 v155, 0xffff0000, v246
	v_lshlrev_b32_e32 v166, 16, v247
	v_and_b32_e32 v167, 0xffff0000, v247
	v_lshlrev_b32_e32 v168, 16, v248
	v_and_b32_e32 v169, 0xffff0000, v248
	v_lshlrev_b32_e32 v180, 16, v249
	v_and_b32_e32 v181, 0xffff0000, v249
	v_pk_fma_f32 v[66:67], v[66:67], v[106:107], v[166:167]
	v_pk_fma_f32 v[64:65], v[64:65], v[104:105], v[154:155]
	v_pk_fma_f32 v[62:63], v[62:63], v[102:103], v[180:181]
	v_pk_fma_f32 v[60:61], v[60:61], v[100:101], v[168:169]
	v_cvt_pk_bf16_f32 v242, v64, v65
	v_cvt_pk_bf16_f32 v243, v66, v67
	v_cvt_pk_bf16_f32 v244, v60, v61
	v_cvt_pk_bf16_f32 v245, v62, v63
	v_lshlrev_b32_e32 v66, 16, v242
	v_and_b32_e32 v67, 0xffff0000, v242
	v_lshlrev_b32_e32 v64, 16, v243
	v_and_b32_e32 v65, 0xffff0000, v243
	v_lshlrev_b32_e32 v62, 16, v244
	v_and_b32_e32 v63, 0xffff0000, v244
	v_lshlrev_b32_e32 v60, 16, v245
	v_and_b32_e32 v61, 0xffff0000, v245
	v_lshlrev_b32_e32 v184, 16, v250
	v_and_b32_e32 v185, 0xffff0000, v250
	v_lshlrev_b32_e32 v188, 16, v251
	v_and_b32_e32 v189, 0xffff0000, v251
	v_lshlrev_b32_e32 v234, 16, v252
	v_and_b32_e32 v235, 0xffff0000, v252
	v_lshlrev_b32_e32 v246, 16, v253
	v_and_b32_e32 v247, 0xffff0000, v253
	global_store_dwordx4 v[182:183], v[242:245], off offset:2304
	v_pk_fma_f32 v[58:59], v[58:59], v[106:107], v[188:189]
	v_pk_fma_f32 v[56:57], v[56:57], v[104:105], v[184:185]
	v_pk_fma_f32 v[54:55], v[54:55], v[102:103], v[246:247]
	v_pk_fma_f32 v[52:53], v[52:53], v[100:101], v[234:235]
	s_waitcnt vmcnt(0)
	v_lshlrev_b32_e32 v188, 16, v240
	v_pk_mul_f32 v[168:169], v[70:71], v[60:61]
	v_pk_mul_f32 v[154:155], v[74:75], v[64:65]
	v_pk_mul_f32 v[166:167], v[72:73], v[66:67]
	v_pk_mul_f32 v[182:183], v[68:69], v[62:63]
	v_cvt_pk_bf16_f32 v180, v166, v167
	v_cvt_pk_bf16_f32 v181, v154, v155
	v_cvt_pk_bf16_f32 v182, v182, v183
	v_cvt_pk_bf16_f32 v183, v168, v169
	global_store_dwordx4 v[178:179], v[180:183], off offset:256
	v_cvt_pk_bf16_f32 v178, v56, v57
	v_cvt_pk_bf16_f32 v179, v58, v59
	v_cvt_pk_bf16_f32 v180, v52, v53
	v_cvt_pk_bf16_f32 v181, v54, v55
	v_lshlrev_b32_e32 v58, 16, v178
	v_and_b32_e32 v59, 0xffff0000, v178
	v_lshlrev_b32_e32 v56, 16, v179
	v_and_b32_e32 v57, 0xffff0000, v179
	v_lshlrev_b32_e32 v54, 16, v180
	v_and_b32_e32 v55, 0xffff0000, v180
	v_lshlrev_b32_e32 v52, 16, v181
	v_and_b32_e32 v53, 0xffff0000, v181
	global_store_dwordx4 v[186:187], v[178:181], off offset:2304
	v_pk_mul_f32 v[154:155], v[74:75], v[56:57]
	v_pk_mul_f32 v[166:167], v[72:73], v[58:59]
	v_pk_mul_f32 v[168:169], v[70:71], v[52:53]
	v_pk_mul_f32 v[180:181], v[68:69], v[54:55]
	v_cvt_pk_bf16_f32 v178, v166, v167
	v_cvt_pk_bf16_f32 v179, v154, v155
	v_cvt_pk_bf16_f32 v180, v180, v181
	v_cvt_pk_bf16_f32 v181, v168, v169
	v_lshlrev_b32_e32 v154, 16, v150
	v_and_b32_e32 v155, 0xffff0000, v150
	v_lshlrev_b32_e32 v150, 16, v151
	v_and_b32_e32 v151, 0xffff0000, v151
	v_lshlrev_b32_e32 v166, 16, v152
	v_and_b32_e32 v167, 0xffff0000, v152
	v_lshlrev_b32_e32 v152, 16, v153
	v_and_b32_e32 v153, 0xffff0000, v153
	global_store_dwordx4 v[190:191], v[178:181], off offset:256
	v_pk_fma_f32 v[50:51], v[50:51], v[106:107], v[150:151]
	v_pk_fma_f32 v[48:49], v[48:49], v[104:105], v[154:155]
	v_pk_fma_f32 v[46:47], v[46:47], v[102:103], v[152:153]
	v_pk_fma_f32 v[44:45], v[44:45], v[100:101], v[166:167]
	global_load_dwordx4 v[178:181], v[192:193], off offset:2304
	global_load_dwordx4 v[182:185], v[194:195], off offset:2304
	v_cvt_pk_bf16_f32 v150, v48, v49
	v_cvt_pk_bf16_f32 v151, v50, v51
	v_cvt_pk_bf16_f32 v152, v44, v45
	v_cvt_pk_bf16_f32 v153, v46, v47
	v_lshlrev_b32_e32 v50, 16, v150
	v_and_b32_e32 v51, 0xffff0000, v150
	v_lshlrev_b32_e32 v48, 16, v151
	v_and_b32_e32 v49, 0xffff0000, v151
	v_lshlrev_b32_e32 v46, 16, v152
	v_and_b32_e32 v47, 0xffff0000, v152
	v_lshlrev_b32_e32 v44, 16, v153
	v_and_b32_e32 v45, 0xffff0000, v153
	v_lshlrev_b32_e32 v168, 16, v238
	v_and_b32_e32 v169, 0xffff0000, v238
	v_lshlrev_b32_e32 v186, 16, v239
	v_and_b32_e32 v187, 0xffff0000, v239
	v_and_b32_e32 v189, 0xffff0000, v240
	v_lshlrev_b32_e32 v190, 16, v241
	v_and_b32_e32 v191, 0xffff0000, v241
	global_store_dwordx4 v[198:199], v[150:153], off offset:2304
	v_pk_mul_f32 v[154:155], v[70:71], v[44:45]
	v_pk_mul_f32 v[166:167], v[68:69], v[46:47]
	v_pk_mul_f32 v[152:153], v[74:75], v[48:49]
	v_pk_mul_f32 v[150:151], v[72:73], v[50:51]
	v_pk_fma_f32 v[42:43], v[42:43], v[106:107], v[186:187]
	v_cvt_pk_bf16_f32 v150, v150, v151
	v_cvt_pk_bf16_f32 v151, v152, v153
	v_cvt_pk_bf16_f32 v152, v166, v167
	v_cvt_pk_bf16_f32 v153, v154, v155
	v_pk_fma_f32 v[40:41], v[40:41], v[104:105], v[168:169]
	v_pk_fma_f32 v[38:39], v[38:39], v[102:103], v[190:191]
	v_pk_fma_f32 v[36:37], v[36:37], v[100:101], v[188:189]
	global_store_dwordx4 v[200:201], v[150:153], off offset:256
	v_mul_f32_e32 v67, v67, v67
	v_mul_f32_e32 v65, v65, v65
	v_cvt_pk_bf16_f32 v150, v40, v41
	v_cvt_pk_bf16_f32 v151, v42, v43
	v_cvt_pk_bf16_f32 v152, v36, v37
	v_cvt_pk_bf16_f32 v153, v38, v39
	v_lshlrev_b32_e32 v42, 16, v150
	v_and_b32_e32 v43, 0xffff0000, v150
	v_lshlrev_b32_e32 v40, 16, v151
	v_and_b32_e32 v41, 0xffff0000, v151
	v_lshlrev_b32_e32 v38, 16, v152
	v_and_b32_e32 v39, 0xffff0000, v152
	v_lshlrev_b32_e32 v36, 16, v153
	v_and_b32_e32 v37, 0xffff0000, v153
	global_store_dwordx4 v[202:203], v[150:153], off offset:2304
	v_pk_mul_f32 v[154:155], v[70:71], v[36:37]
	v_pk_mul_f32 v[166:167], v[68:69], v[38:39]
	v_pk_mul_f32 v[152:153], v[74:75], v[40:41]
	v_pk_mul_f32 v[150:151], v[72:73], v[42:43]
	v_fmac_f32_e32 v67, v66, v66
	v_cvt_pk_bf16_f32 v150, v150, v151
	v_cvt_pk_bf16_f32 v151, v152, v153
	v_cvt_pk_bf16_f32 v152, v166, v167
	v_cvt_pk_bf16_f32 v153, v154, v155
	global_store_dwordx4 v[204:205], v[150:153], off offset:256
	global_load_dwordx4 v[150:153], v[206:207], off offset:2304
	s_nop 0
	global_load_dwordx4 v[186:189], v[208:209], off offset:2304
	v_fmac_f32_e32 v65, v64, v64
	v_mul_f32_e32 v63, v63, v63
	v_mul_f32_e32 v61, v61, v61
	v_add_f32_e32 v64, v67, v65
	v_fmac_f32_e32 v63, v62, v62
	v_fmac_f32_e32 v61, v60, v60
	v_add_f32_e32 v60, v63, v61
	s_waitcnt vmcnt(0)
	v_lshlrev_b32_e32 v154, 16, v178
	v_and_b32_e32 v155, 0xffff0000, v178
	v_lshlrev_b32_e32 v166, 16, v179
	v_and_b32_e32 v167, 0xffff0000, v179
	v_lshlrev_b32_e32 v168, 16, v180
	v_and_b32_e32 v169, 0xffff0000, v180
	v_lshlrev_b32_e32 v178, 16, v181
	v_and_b32_e32 v179, 0xffff0000, v181
	v_pk_fma_f32 v[34:35], v[34:35], v[106:107], v[166:167]
	v_pk_fma_f32 v[32:33], v[32:33], v[104:105], v[154:155]
	v_pk_fma_f32 v[30:31], v[30:31], v[102:103], v[178:179]
	v_pk_fma_f32 v[28:29], v[28:29], v[100:101], v[168:169]
	v_cvt_pk_bf16_f32 v178, v32, v33
	v_cvt_pk_bf16_f32 v179, v34, v35
	v_cvt_pk_bf16_f32 v180, v28, v29
	v_cvt_pk_bf16_f32 v181, v30, v31
	v_lshlrev_b32_e32 v34, 16, v178
	v_and_b32_e32 v35, 0xffff0000, v178
	v_lshlrev_b32_e32 v32, 16, v179
	v_and_b32_e32 v33, 0xffff0000, v179
	v_lshlrev_b32_e32 v30, 16, v180
	v_and_b32_e32 v31, 0xffff0000, v180
	v_lshlrev_b32_e32 v28, 16, v181
	v_and_b32_e32 v29, 0xffff0000, v181
	v_lshlrev_b32_e32 v190, 16, v182
	v_and_b32_e32 v191, 0xffff0000, v182
	v_lshlrev_b32_e32 v182, 16, v183
	v_and_b32_e32 v183, 0xffff0000, v183
	global_store_dwordx4 v[212:213], v[178:181], off offset:2304
	v_pk_mul_f32 v[154:155], v[74:75], v[32:33]
	v_pk_mul_f32 v[166:167], v[72:73], v[34:35]
	v_pk_mul_f32 v[168:169], v[70:71], v[28:29]
	v_pk_mul_f32 v[180:181], v[68:69], v[30:31]
	v_lshlrev_b32_e32 v192, 16, v184
	v_and_b32_e32 v193, 0xffff0000, v184
	v_lshlrev_b32_e32 v184, 16, v185
	v_and_b32_e32 v185, 0xffff0000, v185
	v_cvt_pk_bf16_f32 v178, v166, v167
	v_cvt_pk_bf16_f32 v179, v154, v155
	v_cvt_pk_bf16_f32 v180, v180, v181
	v_cvt_pk_bf16_f32 v181, v168, v169
	v_pk_fma_f32 v[24:25], v[24:25], v[106:107], v[182:183]
	v_pk_fma_f32 v[22:23], v[22:23], v[104:105], v[190:191]
	global_store_dwordx4 v[214:215], v[178:181], off offset:256
	v_pk_fma_f32 v[20:21], v[20:21], v[102:103], v[184:185]
	v_pk_fma_f32 v[18:19], v[18:19], v[100:101], v[192:193]
	v_cvt_pk_bf16_f32 v178, v22, v23
	v_cvt_pk_bf16_f32 v179, v24, v25
	v_cvt_pk_bf16_f32 v180, v18, v19
	v_cvt_pk_bf16_f32 v181, v20, v21
	v_lshlrev_b32_e32 v24, 16, v178
	v_and_b32_e32 v25, 0xffff0000, v178
	v_lshlrev_b32_e32 v22, 16, v179
	v_and_b32_e32 v23, 0xffff0000, v179
	v_lshlrev_b32_e32 v20, 16, v180
	v_and_b32_e32 v21, 0xffff0000, v180
	v_lshlrev_b32_e32 v18, 16, v181
	v_and_b32_e32 v19, 0xffff0000, v181
	v_pk_mul_f32 v[154:155], v[74:75], v[22:23]
	v_pk_mul_f32 v[166:167], v[72:73], v[24:25]
	global_store_dwordx4 v[216:217], v[178:181], off offset:2304
	v_pk_mul_f32 v[168:169], v[70:71], v[18:19]
	v_lshlrev_b32_e32 v182, 16, v189
	v_pk_mul_f32 v[180:181], v[68:69], v[20:21]
	v_cvt_pk_bf16_f32 v178, v166, v167
	v_cvt_pk_bf16_f32 v179, v154, v155
	v_lshlrev_b32_e32 v154, 16, v150
	v_and_b32_e32 v155, 0xffff0000, v150
	v_lshlrev_b32_e32 v150, 16, v151
	v_and_b32_e32 v151, 0xffff0000, v151
	v_lshlrev_b32_e32 v166, 16, v152
	v_and_b32_e32 v167, 0xffff0000, v152
	v_lshlrev_b32_e32 v152, 16, v153
	v_and_b32_e32 v153, 0xffff0000, v153
	v_cvt_pk_bf16_f32 v180, v180, v181
	v_cvt_pk_bf16_f32 v181, v168, v169
	v_pk_fma_f32 v[16:17], v[16:17], v[106:107], v[150:151]
	v_pk_fma_f32 v[14:15], v[14:15], v[104:105], v[154:155]
	v_pk_fma_f32 v[12:13], v[12:13], v[102:103], v[152:153]
	v_pk_fma_f32 v[10:11], v[10:11], v[100:101], v[166:167]
	global_store_dwordx4 v[218:219], v[178:181], off offset:256
	v_lshlrev_b32_e32 v168, 16, v186
	v_and_b32_e32 v169, 0xffff0000, v186
	v_lshlrev_b32_e32 v178, 16, v187
	v_and_b32_e32 v179, 0xffff0000, v187
	v_lshlrev_b32_e32 v180, 16, v188
	v_and_b32_e32 v181, 0xffff0000, v188
	v_and_b32_e32 v183, 0xffff0000, v189
	v_cvt_pk_bf16_f32 v150, v14, v15
	v_cvt_pk_bf16_f32 v151, v16, v17
	v_cvt_pk_bf16_f32 v152, v10, v11
	v_cvt_pk_bf16_f32 v153, v12, v13
	v_lshlrev_b32_e32 v16, 16, v150
	v_and_b32_e32 v17, 0xffff0000, v150
	v_lshlrev_b32_e32 v14, 16, v151
	v_and_b32_e32 v15, 0xffff0000, v151
	v_lshlrev_b32_e32 v12, 16, v152
	v_and_b32_e32 v13, 0xffff0000, v152
	v_lshlrev_b32_e32 v10, 16, v153
	v_and_b32_e32 v11, 0xffff0000, v153
	v_pk_fma_f32 v[8:9], v[8:9], v[106:107], v[178:179]
	v_pk_fma_f32 v[6:7], v[6:7], v[104:105], v[168:169]
	v_pk_fma_f32 v[4:5], v[4:5], v[102:103], v[182:183]
	v_pk_fma_f32 v[2:3], v[2:3], v[100:101], v[180:181]
	global_store_dwordx4 v[196:197], v[150:153], off offset:2304
	v_pk_mul_f32 v[154:155], v[70:71], v[10:11]
	v_pk_mul_f32 v[166:167], v[68:69], v[12:13]
	v_pk_mul_f32 v[152:153], v[74:75], v[14:15]
	v_pk_mul_f32 v[150:151], v[72:73], v[16:17]
	v_cvt_pk_bf16_f32 v100, v6, v7
	v_cvt_pk_bf16_f32 v101, v8, v9
	v_cvt_pk_bf16_f32 v102, v2, v3
	v_cvt_pk_bf16_f32 v103, v4, v5
	v_cvt_pk_bf16_f32 v150, v150, v151
	v_cvt_pk_bf16_f32 v151, v152, v153
	v_cvt_pk_bf16_f32 v152, v166, v167
	v_cvt_pk_bf16_f32 v153, v154, v155
	v_lshlrev_b32_e32 v8, 16, v100
	v_and_b32_e32 v9, 0xffff0000, v100
	v_lshlrev_b32_e32 v6, 16, v101
	v_and_b32_e32 v7, 0xffff0000, v101
	v_lshlrev_b32_e32 v4, 16, v102
	v_and_b32_e32 v5, 0xffff0000, v102
	v_lshlrev_b32_e32 v2, 16, v103
	v_and_b32_e32 v3, 0xffff0000, v103
	global_store_dwordx4 v[210:211], v[150:153], off offset:256
	global_store_dwordx4 v[220:221], v[100:103], off offset:2304
	v_pk_mul_f32 v[74:75], v[74:75], v[6:7]
	v_pk_mul_f32 v[72:73], v[72:73], v[8:9]
	v_pk_mul_f32 v[100:101], v[70:71], v[2:3]
	v_pk_mul_f32 v[70:71], v[68:69], v[4:5]
	v_cvt_pk_bf16_f32 v68, v72, v73
	v_cvt_pk_bf16_f32 v69, v74, v75
	v_cvt_pk_bf16_f32 v70, v70, v71
	v_cvt_pk_bf16_f32 v71, v100, v101
	global_store_dwordx4 v[148:149], v[68:71], off offset:256
	v_xor_b32_e32 v72, 32, v227
	v_mul_f32_e32 v73, v137, v137
	v_and_b32_e32 v71, 64, v227
	v_xor_b32_e32 v70, 16, v227
	v_add_u32_e32 v71, 64, v71
	v_cmp_lt_i32_e32 vcc, v70, v71
	v_fmac_f32_e32 v73, v136, v136
	v_mul_f32_e32 v74, v133, v133
	v_cndmask_b32_e32 v70, v227, v70, vcc
	v_cmp_lt_i32_e32 vcc, v72, v71
	v_fmac_f32_e32 v74, v132, v132
	v_lshlrev_b32_e32 v70, 2, v70
	v_cndmask_b32_e32 v71, v227, v72, vcc
	v_mul_f32_e32 v72, v139, v139
	v_fmac_f32_e32 v72, v138, v138
	v_add_f32_e32 v72, v72, v73
	v_mul_f32_e32 v73, v135, v135
	v_fmac_f32_e32 v73, v134, v134
	v_add_f32_e32 v73, v73, v74
	v_add_f32_e32 v72, v72, v73
	v_add_f32_e32 v64, v72, v64
	v_add_f32_e32 v60, v60, v64
	ds_bpermute_b32 v61, v70, v60
	v_lshlrev_b32_e32 v71, 2, v71
	v_lshl_add_u64 v[68:69], v[172:173], 0, s[28:29]
	s_waitcnt lgkmcnt(0)
	v_add_f32_e32 v60, v60, v61
	ds_bpermute_b32 v61, v71, v60
	s_and_saveexec_b64 s[18:19], s[38:39]
	s_cbranch_execz .LBB0_968
	s_waitcnt lgkmcnt(0)
	v_add_f32_e32 v60, v60, v61
	global_atomic_add_f32 v[68:69], v60, off

.LBB0_1048:
	s_add_u32 s0, s24, 0xfffc0080
	s_addc_u32 s1, s25, -1
	s_add_i32 s83, 0, 0x10000
	s_cmp_eq_u32 s82, 12
	s_cselect_b32 s29, s43, s1
	s_cselect_b32 s28, s69, s0
	s_cselect_b32 s27, s45, s81
	s_cselect_b32 s26, s72, s73
	s_add_i32 m0, s23, 0xc000
	ds_read_b128 v[158:161], v165
	ds_read_b128 v[174:177], v165 offset:1024
	ds_read_b128 v[178:181], v165 offset:2048
	ds_read_b128 v[182:185], v165 offset:3072
	ds_read_b128 v[186:189], v165 offset:4096
	ds_read_b128 v[190:193], v165 offset:5120
	ds_read_b128 v[194:197], v165 offset:6144
	ds_read_b128 v[198:201], v165 offset:7168
	global_load_lds_dwordx4 v154, s[24:25]
	s_waitcnt vmcnt(10) lgkmcnt(8)
	s_setprio 1
	s_barrier
	s_waitcnt lgkmcnt(0)
	v_mfma_f32_16x16x32_bf16 v[144:147], v[68:71], v[158:161], v[144:147]
	v_mfma_f32_16x16x32_bf16 v[140:143], v[76:79], v[158:161], v[140:143]
	v_mfma_f32_16x16x32_bf16 v[128:131], v[68:71], v[178:181], v[128:131]
	v_mfma_f32_16x16x32_bf16 v[124:127], v[76:79], v[178:181], v[124:127]
	v_mfma_f32_16x16x32_bf16 v[112:115], v[68:71], v[186:189], v[112:115]
	v_mfma_f32_16x16x32_bf16 v[108:111], v[76:79], v[186:189], v[108:111]
	v_mfma_f32_16x16x32_bf16 v[96:99], v[68:71], v[194:197], v[96:99]
	v_mfma_f32_16x16x32_bf16 v[92:95], v[76:79], v[194:197], v[92:95]
	v_mfma_f32_16x16x32_bf16 v[144:147], v[72:75], v[174:177], v[144:147]
	v_mfma_f32_16x16x32_bf16 v[140:143], v[80:83], v[174:177], v[140:143]
	v_mfma_f32_16x16x32_bf16 v[128:131], v[72:75], v[182:185], v[128:131]
	v_mfma_f32_16x16x32_bf16 v[124:127], v[80:83], v[182:185], v[124:127]
	v_mfma_f32_16x16x32_bf16 v[112:115], v[72:75], v[190:193], v[112:115]
	v_mfma_f32_16x16x32_bf16 v[108:111], v[80:83], v[190:193], v[108:111]
	v_mfma_f32_16x16x32_bf16 v[96:99], v[72:75], v[198:201], v[96:99]
	v_mfma_f32_16x16x32_bf16 v[92:95], v[80:83], v[198:201], v[92:95]
	s_barrier
	s_setprio 0
	s_add_i32 s84, 0, 0x14000
	v_add_u32_e32 v166, s84, v163
	s_add_i32 s0, s83, s54
	ds_read_b128 v[202:205], v166
	ds_read_b128 v[206:209], v166 offset:1024
	ds_read_b128 v[210:213], v166 offset:2048
	ds_read_b128 v[214:217], v166 offset:3072
	v_lshl_add_u64 v[166:167], s[26:27], 0, v[26:27]
	s_mov_b32 m0, s0
	v_lshl_add_u64 v[168:169], s[26:27], 0, v[148:149]
	global_load_lds_dwordx4 v[166:167], off
	s_add_i32 m0, s0, 0x2000
	s_nop 0
	global_load_lds_dwordx4 v[168:169], off
	v_lshl_add_u64 v[238:239], s[24:25], 0, v[156:157]
	s_add_i32 m0, s23, 0xe000
	s_nop 0
	global_load_lds_dwordx4 v[238:239], off
	s_waitcnt vmcnt(8)
	s_setprio 1
	s_barrier
	s_waitcnt lgkmcnt(0)
	v_mfma_f32_16x16x32_bf16 v[136:139], v[202:205], v[158:161], v[136:139]
	v_mfma_f32_16x16x32_bf16 v[132:135], v[210:213], v[158:161], v[132:135]
	v_mfma_f32_16x16x32_bf16 v[120:123], v[202:205], v[178:181], v[120:123]
	v_mfma_f32_16x16x32_bf16 v[116:119], v[210:213], v[178:181], v[116:119]
	v_mfma_f32_16x16x32_bf16 v[104:107], v[202:205], v[186:189], v[104:107]
	v_mfma_f32_16x16x32_bf16 v[100:103], v[210:213], v[186:189], v[100:103]
	v_mfma_f32_16x16x32_bf16 v[88:91], v[202:205], v[194:197], v[88:91]
	v_mfma_f32_16x16x32_bf16 v[84:87], v[210:213], v[194:197], v[84:87]
	v_mfma_f32_16x16x32_bf16 v[136:139], v[206:209], v[174:177], v[136:139]
	v_mfma_f32_16x16x32_bf16 v[132:135], v[214:217], v[174:177], v[132:135]
	v_mfma_f32_16x16x32_bf16 v[120:123], v[206:209], v[182:185], v[120:123]
	v_mfma_f32_16x16x32_bf16 v[116:119], v[214:217], v[182:185], v[116:119]
	v_mfma_f32_16x16x32_bf16 v[104:107], v[206:209], v[190:193], v[104:107]
	v_mfma_f32_16x16x32_bf16 v[100:103], v[214:217], v[190:193], v[100:103]
	v_mfma_f32_16x16x32_bf16 v[88:91], v[206:209], v[198:201], v[88:91]
	v_mfma_f32_16x16x32_bf16 v[84:87], v[214:217], v[198:201], v[84:87]
	s_barrier
	s_setprio 0
	s_mov_b32 m0, s23
	v_lshl_add_u64 v[218:219], s[28:29], 0, v[152:153]
	ds_read_b128 v[158:161], v165 offset:16384
	ds_read_b128 v[174:177], v165 offset:17408
	ds_read_b128 v[178:181], v165 offset:18432
	ds_read_b128 v[182:185], v165 offset:19456
	ds_read_b128 v[186:189], v165 offset:20480
	ds_read_b128 v[190:193], v165 offset:21504
	ds_read_b128 v[194:197], v165 offset:22528
	ds_read_b128 v[198:201], v165 offset:23552
	global_load_lds_dwordx4 v[218:219], off
	s_waitcnt vmcnt(10)
	s_setprio 1
	s_barrier
	s_waitcnt lgkmcnt(0)
	v_mfma_f32_16x16x32_bf16 v[64:67], v[68:71], v[158:161], v[64:67]
	v_mfma_f32_16x16x32_bf16 v[60:63], v[76:79], v[158:161], v[60:63]
	v_mfma_f32_16x16x32_bf16 v[48:51], v[68:71], v[178:181], v[48:51]
	v_mfma_f32_16x16x32_bf16 v[44:47], v[76:79], v[178:181], v[44:47]
	v_mfma_f32_16x16x32_bf16 v[32:35], v[68:71], v[186:189], v[32:35]
	v_mfma_f32_16x16x32_bf16 v[28:31], v[76:79], v[186:189], v[28:31]
	v_mfma_f32_16x16x32_bf16 v[14:17], v[68:71], v[194:197], v[14:17]
	v_mfma_f32_16x16x32_bf16 v[10:13], v[76:79], v[194:197], v[10:13]
	v_mfma_f32_16x16x32_bf16 v[64:67], v[72:75], v[174:177], v[64:67]
	v_mfma_f32_16x16x32_bf16 v[60:63], v[80:83], v[174:177], v[60:63]
	v_mfma_f32_16x16x32_bf16 v[48:51], v[72:75], v[182:185], v[48:51]
	v_mfma_f32_16x16x32_bf16 v[44:47], v[80:83], v[182:185], v[44:47]
	v_mfma_f32_16x16x32_bf16 v[32:35], v[72:75], v[190:193], v[32:35]
	v_mfma_f32_16x16x32_bf16 v[28:31], v[80:83], v[190:193], v[28:31]
	v_mfma_f32_16x16x32_bf16 v[14:17], v[72:75], v[198:201], v[14:17]
	v_mfma_f32_16x16x32_bf16 v[10:13], v[80:83], v[198:201], v[10:13]
	s_barrier
	s_setprio 0
	s_add_u32 s0, s26, 0x40000
	s_addc_u32 s1, s27, 0
	s_add_i32 s83, s84, s54
	s_mov_b32 m0, s83
	s_nop 0
	global_load_lds_dwordx4 v26, s[0:1]
	s_add_i32 m0, s83, 0x2000
	s_nop 0
	global_load_lds_dwordx4 v148, s[0:1]
	v_lshl_add_u64 v[220:221], s[28:29], 0, v[150:151]
	s_mov_b32 m0, s57
	s_nop 0
	global_load_lds_dwordx4 v[220:221], off
	v_add_u32_e32 v80, 0x18000, v163
	ds_read_b128 v[68:71], v80
	ds_read_b128 v[72:75], v80 offset:1024
	ds_read_b128 v[76:79], v80 offset:2048
	ds_read_b128 v[80:83], v80 offset:3072
	s_waitcnt vmcnt(8)
	s_setprio 1
	s_barrier
	v_mfma_f32_16x16x32_bf16 v[56:59], v[202:205], v[158:161], v[56:59]
	v_mfma_f32_16x16x32_bf16 v[52:55], v[210:213], v[158:161], v[52:55]
	v_mfma_f32_16x16x32_bf16 v[40:43], v[202:205], v[178:181], v[40:43]
	v_mfma_f32_16x16x32_bf16 v[36:39], v[210:213], v[178:181], v[36:39]
	v_mfma_f32_16x16x32_bf16 v[22:25], v[202:205], v[186:189], v[22:25]
	v_mfma_f32_16x16x32_bf16 v[18:21], v[210:213], v[186:189], v[18:21]
	v_mfma_f32_16x16x32_bf16 v[6:9], v[202:205], v[194:197], v[6:9]
	v_mfma_f32_16x16x32_bf16 v[2:5], v[210:213], v[194:197], v[2:5]
	v_mfma_f32_16x16x32_bf16 v[56:59], v[206:209], v[174:177], v[56:59]
	v_mfma_f32_16x16x32_bf16 v[52:55], v[214:217], v[174:177], v[52:55]
	v_mfma_f32_16x16x32_bf16 v[40:43], v[206:209], v[182:185], v[40:43]
	v_mfma_f32_16x16x32_bf16 v[36:39], v[214:217], v[182:185], v[36:39]
	v_mfma_f32_16x16x32_bf16 v[22:25], v[206:209], v[190:193], v[22:25]
	v_mfma_f32_16x16x32_bf16 v[18:21], v[214:217], v[190:193], v[18:21]
	v_mfma_f32_16x16x32_bf16 v[6:9], v[206:209], v[198:201], v[6:9]
	v_mfma_f32_16x16x32_bf16 v[2:5], v[214:217], v[198:201], v[2:5]
	s_barrier
	s_setprio 0
	s_add_i32 s83, 0, 0x18000
	s_add_u32 s0, s28, 0x40000
	s_addc_u32 s1, s29, 0
	s_mov_b32 m0, s58
	ds_read_b128 v[158:161], v165 offset:32768
	ds_read_b128 v[174:177], v165 offset:33792
	ds_read_b128 v[178:181], v165 offset:34816
	ds_read_b128 v[182:185], v165 offset:35840
	ds_read_b128 v[186:189], v165 offset:36864
	ds_read_b128 v[190:193], v165 offset:37888
	ds_read_b128 v[194:197], v165 offset:38912
	ds_read_b128 v[198:201], v165 offset:39936
	global_load_lds_dwordx4 v152, s[0:1]
	s_mov_b64 s[100:101], s[0:1]
	s_waitcnt vmcnt(10) lgkmcnt(8)
	s_setprio 1
	s_barrier
	s_waitcnt lgkmcnt(0)
	v_mfma_f32_16x16x32_bf16 v[144:147], v[68:71], v[158:161], v[144:147]
	v_mfma_f32_16x16x32_bf16 v[140:143], v[76:79], v[158:161], v[140:143]
	v_mfma_f32_16x16x32_bf16 v[128:131], v[68:71], v[178:181], v[128:131]
	v_mfma_f32_16x16x32_bf16 v[124:127], v[76:79], v[178:181], v[124:127]
	v_mfma_f32_16x16x32_bf16 v[112:115], v[68:71], v[186:189], v[112:115]
	v_mfma_f32_16x16x32_bf16 v[108:111], v[76:79], v[186:189], v[108:111]
	v_mfma_f32_16x16x32_bf16 v[96:99], v[68:71], v[194:197], v[96:99]
	v_mfma_f32_16x16x32_bf16 v[92:95], v[76:79], v[194:197], v[92:95]
	v_mfma_f32_16x16x32_bf16 v[144:147], v[72:75], v[174:177], v[144:147]
	v_mfma_f32_16x16x32_bf16 v[140:143], v[80:83], v[174:177], v[140:143]
	v_mfma_f32_16x16x32_bf16 v[128:131], v[72:75], v[182:185], v[128:131]
	v_mfma_f32_16x16x32_bf16 v[124:127], v[80:83], v[182:185], v[124:127]
	v_mfma_f32_16x16x32_bf16 v[112:115], v[72:75], v[190:193], v[112:115]
	v_mfma_f32_16x16x32_bf16 v[108:111], v[80:83], v[190:193], v[108:111]
	v_mfma_f32_16x16x32_bf16 v[96:99], v[72:75], v[198:201], v[96:99]
	v_mfma_f32_16x16x32_bf16 v[92:95], v[80:83], v[198:201], v[92:95]
	s_barrier
	s_setprio 0
	s_add_i32 s28, 0, 0x1c000
	s_add_i32 s0, s83, s54
	v_add_u32_e32 v173, s28, v163
	v_lshl_add_u64 v[166:167], v[166:167], 0, s[12:13]
	s_mov_b32 m0, s0
	ds_read_b128 v[202:205], v173
	ds_read_b128 v[206:209], v173 offset:1024
	ds_read_b128 v[210:213], v173 offset:2048
	ds_read_b128 v[214:217], v173 offset:3072
	global_load_lds_dwordx4 v[166:167], off
	v_lshl_add_u64 v[166:167], v[168:169], 0, s[12:13]
	s_add_i32 m0, s0, 0x2000
	s_nop 0
	global_load_lds_dwordx4 v[166:167], off
	s_mov_b32 m0, s59
	s_nop 0
	global_load_lds_dwordx4 v150, s[100:101]
	s_waitcnt vmcnt(8)
	s_setprio 1
	s_barrier
	s_waitcnt lgkmcnt(0)
	v_mfma_f32_16x16x32_bf16 v[136:139], v[202:205], v[158:161], v[136:139]
	v_mfma_f32_16x16x32_bf16 v[132:135], v[210:213], v[158:161], v[132:135]
	v_mfma_f32_16x16x32_bf16 v[120:123], v[202:205], v[178:181], v[120:123]
	v_mfma_f32_16x16x32_bf16 v[116:119], v[210:213], v[178:181], v[116:119]
	v_mfma_f32_16x16x32_bf16 v[104:107], v[202:205], v[186:189], v[104:107]
	v_mfma_f32_16x16x32_bf16 v[100:103], v[210:213], v[186:189], v[100:103]
	v_mfma_f32_16x16x32_bf16 v[88:91], v[202:205], v[194:197], v[88:91]
	v_mfma_f32_16x16x32_bf16 v[84:87], v[210:213], v[194:197], v[84:87]
	v_mfma_f32_16x16x32_bf16 v[136:139], v[206:209], v[174:177], v[136:139]
	v_mfma_f32_16x16x32_bf16 v[132:135], v[214:217], v[174:177], v[132:135]
	v_mfma_f32_16x16x32_bf16 v[120:123], v[206:209], v[182:185], v[120:123]
	v_mfma_f32_16x16x32_bf16 v[116:119], v[214:217], v[182:185], v[116:119]
	v_mfma_f32_16x16x32_bf16 v[104:107], v[206:209], v[190:193], v[104:107]
	v_mfma_f32_16x16x32_bf16 v[100:103], v[214:217], v[190:193], v[100:103]
	v_mfma_f32_16x16x32_bf16 v[88:91], v[206:209], v[198:201], v[88:91]
	v_mfma_f32_16x16x32_bf16 v[84:87], v[214:217], v[198:201], v[84:87]
	s_barrier
	s_setprio 0
	s_mov_b32 m0, s34
	v_lshl_add_u64 v[166:167], v[218:219], 0, s[12:13]
	ds_read_b128 v[158:161], v165 offset:49152
	ds_read_b128 v[174:177], v165 offset:50176
	ds_read_b128 v[178:181], v165 offset:51200
	ds_read_b128 v[182:185], v165 offset:52224
	ds_read_b128 v[186:189], v165 offset:53248
	ds_read_b128 v[190:193], v165 offset:54272
	ds_read_b128 v[194:197], v165 offset:55296
	ds_read_b128 v[198:201], v165 offset:56320
	global_load_lds_dwordx4 v[166:167], off
	s_waitcnt vmcnt(10)
	s_setprio 1
	s_barrier
	s_waitcnt lgkmcnt(0)
	v_mfma_f32_16x16x32_bf16 v[64:67], v[68:71], v[158:161], v[64:67]
	v_mfma_f32_16x16x32_bf16 v[60:63], v[76:79], v[158:161], v[60:63]
	v_mfma_f32_16x16x32_bf16 v[48:51], v[68:71], v[178:181], v[48:51]
	v_mfma_f32_16x16x32_bf16 v[44:47], v[76:79], v[178:181], v[44:47]
	v_mfma_f32_16x16x32_bf16 v[32:35], v[68:71], v[186:189], v[32:35]
	v_mfma_f32_16x16x32_bf16 v[28:31], v[76:79], v[186:189], v[28:31]
	v_mfma_f32_16x16x32_bf16 v[14:17], v[68:71], v[194:197], v[14:17]
	v_mfma_f32_16x16x32_bf16 v[10:13], v[76:79], v[194:197], v[10:13]
	v_mfma_f32_16x16x32_bf16 v[64:67], v[72:75], v[174:177], v[64:67]
	v_mfma_f32_16x16x32_bf16 v[60:63], v[80:83], v[174:177], v[60:63]
	v_mfma_f32_16x16x32_bf16 v[48:51], v[72:75], v[182:185], v[48:51]
	v_mfma_f32_16x16x32_bf16 v[44:47], v[80:83], v[182:185], v[44:47]
	v_mfma_f32_16x16x32_bf16 v[32:35], v[72:75], v[190:193], v[32:35]
	v_mfma_f32_16x16x32_bf16 v[28:31], v[80:83], v[190:193], v[28:31]
	v_mfma_f32_16x16x32_bf16 v[14:17], v[72:75], v[198:201], v[14:17]
	v_mfma_f32_16x16x32_bf16 v[10:13], v[80:83], v[198:201], v[10:13]
	s_barrier
	s_setprio 0
	s_add_u32 s0, s26, 0x40080
	s_addc_u32 s1, s27, 0
	s_add_i32 s26, s28, s54
	s_mov_b32 m0, s26
	s_nop 0
	global_load_lds_dwordx4 v26, s[0:1]
	s_add_i32 m0, s26, 0x2000
	s_nop 0
	global_load_lds_dwordx4 v148, s[0:1]
	v_lshl_add_u64 v[166:167], v[220:221], 0, s[12:13]
	s_mov_b32 m0, s35
	s_nop 0
	global_load_lds_dwordx4 v[166:167], off
	v_add_u32_e32 v80, 0x10000, v163
	ds_read_b128 v[68:71], v80
	ds_read_b128 v[72:75], v80 offset:1024
	ds_read_b128 v[76:79], v80 offset:2048
	ds_read_b128 v[80:83], v80 offset:3072
	s_waitcnt vmcnt(8)
	s_setprio 1
	s_barrier
	v_mfma_f32_16x16x32_bf16 v[56:59], v[202:205], v[158:161], v[56:59]
	v_mfma_f32_16x16x32_bf16 v[52:55], v[210:213], v[158:161], v[52:55]
	v_mfma_f32_16x16x32_bf16 v[40:43], v[202:205], v[178:181], v[40:43]
	v_mfma_f32_16x16x32_bf16 v[36:39], v[210:213], v[178:181], v[36:39]
	v_mfma_f32_16x16x32_bf16 v[22:25], v[202:205], v[186:189], v[22:25]
	v_mfma_f32_16x16x32_bf16 v[18:21], v[210:213], v[186:189], v[18:21]
	v_mfma_f32_16x16x32_bf16 v[6:9], v[202:205], v[194:197], v[6:9]
	v_mfma_f32_16x16x32_bf16 v[2:5], v[210:213], v[194:197], v[2:5]
	v_mfma_f32_16x16x32_bf16 v[56:59], v[206:209], v[174:177], v[56:59]
	v_mfma_f32_16x16x32_bf16 v[52:55], v[214:217], v[174:177], v[52:55]
	v_mfma_f32_16x16x32_bf16 v[40:43], v[206:209], v[182:185], v[40:43]
	v_mfma_f32_16x16x32_bf16 v[36:39], v[214:217], v[182:185], v[36:39]
	v_mfma_f32_16x16x32_bf16 v[22:25], v[206:209], v[190:193], v[22:25]
	v_mfma_f32_16x16x32_bf16 v[18:21], v[214:217], v[190:193], v[18:21]
	v_mfma_f32_16x16x32_bf16 v[6:9], v[206:209], v[198:201], v[6:9]
	v_mfma_f32_16x16x32_bf16 v[2:5], v[214:217], v[198:201], v[2:5]
	s_barrier
	s_setprio 0
	s_add_i32 s82, s82, 2
	s_add_u32 s24, s24, 0x100
	s_addc_u32 s25, s25, 0
	s_add_u32 s73, s73, 0x100
	s_addc_u32 s81, s81, 0
	s_cmp_gt_u32 s82, 13
	s_cbranch_scc0 .LBB0_1048
	s_waitcnt lgkmcnt(0)
	v_readlane_b32 s82, v255, 51
	s_cmpk_gt_i32 s22, 0xff
	s_mov_b64 s[24:25], 0xb000
	v_readlane_b32 s83, v255, 52
	s_cbranch_scc1 .LBB0_1044
	s_ashr_i32 s0, s22, 5
	s_mul_hi_i32 s25, s0, 0x1600
	s_mul_i32 s24, s0, 0x1600
	s_branch .LBB0_1044

.LBB0_1122:
	s_add_u32 s26, s24, 0x100
	s_addc_u32 s27, s25, 0
	s_add_i32 s0, 0, 0x10000
	s_cmp_eq_u32 s72, 40
	s_cselect_b32 s31, s43, s27
	s_cselect_b32 s30, s42, s26
	s_cselect_b32 s29, s45, s69
	s_cselect_b32 s28, s44, s68
	s_add_i32 m0, s36, 0xc000
	ds_read_b128 v[162:165], v188
	ds_read_b128 v[172:175], v188 offset:1024
	ds_read_b128 v[176:179], v188 offset:2048
	ds_read_b128 v[180:183], v188 offset:3072
	ds_read_b128 v[190:193], v188 offset:4096
	ds_read_b128 v[194:197], v188 offset:5120
	ds_read_b128 v[198:201], v188 offset:6144
	ds_read_b128 v[202:205], v188 offset:7168
	global_load_lds_dwordx4 v150, s[24:25]
	s_mov_b64 s[100:101], s[24:25]
	s_waitcnt vmcnt(10) lgkmcnt(8)
	s_setprio 1
	s_barrier
	s_waitcnt lgkmcnt(0)
	v_mfma_f32_16x16x32_bf16 v[128:131], v[132:135], v[162:165], v[128:131]
	v_mfma_f32_16x16x32_bf16 v[124:127], v[154:157], v[162:165], v[124:127]
	v_mfma_f32_16x16x32_bf16 v[120:123], v[132:135], v[176:179], v[120:123]
	v_mfma_f32_16x16x32_bf16 v[116:119], v[154:157], v[176:179], v[116:119]
	v_mfma_f32_16x16x32_bf16 v[112:115], v[132:135], v[190:193], v[112:115]
	v_mfma_f32_16x16x32_bf16 v[108:111], v[154:157], v[190:193], v[108:111]
	v_mfma_f32_16x16x32_bf16 v[104:107], v[132:135], v[198:201], v[104:107]
	v_mfma_f32_16x16x32_bf16 v[100:103], v[154:157], v[198:201], v[100:103]
	v_mfma_f32_16x16x32_bf16 v[128:131], v[136:139], v[172:175], v[128:131]
	v_mfma_f32_16x16x32_bf16 v[124:127], v[158:161], v[172:175], v[124:127]
	v_mfma_f32_16x16x32_bf16 v[120:123], v[136:139], v[180:183], v[120:123]
	v_mfma_f32_16x16x32_bf16 v[116:119], v[158:161], v[180:183], v[116:119]
	v_mfma_f32_16x16x32_bf16 v[112:115], v[136:139], v[194:197], v[112:115]
	v_mfma_f32_16x16x32_bf16 v[108:111], v[158:161], v[194:197], v[108:111]
	v_mfma_f32_16x16x32_bf16 v[104:107], v[136:139], v[202:205], v[104:107]
	v_mfma_f32_16x16x32_bf16 v[100:103], v[158:161], v[202:205], v[100:103]
	s_barrier
	s_setprio 0
	s_add_i32 s24, 0, 0x14000
	v_add_u32_e32 v166, s24, v186
	s_add_i32 s0, s0, s17
	ds_read_b128 v[206:209], v166
	ds_read_b128 v[210:213], v166 offset:1024
	ds_read_b128 v[214:217], v166 offset:2048
	ds_read_b128 v[218:221], v166 offset:3072
	v_lshl_add_u64 v[166:167], s[28:29], 0, v[26:27]
	s_mov_b32 m0, s0
	v_lshl_add_u64 v[168:169], s[28:29], 0, v[144:145]
	global_load_lds_dwordx4 v[166:167], off
	s_add_i32 m0, s0, 0x2000
	s_nop 0
	global_load_lds_dwordx4 v[168:169], off
	v_lshl_add_u64 v[238:239], s[100:101], 0, v[152:153]
	s_add_i32 m0, s36, 0xe000
	s_nop 0
	global_load_lds_dwordx4 v[238:239], off
	s_waitcnt vmcnt(8)
	s_setprio 1
	s_barrier
	s_waitcnt lgkmcnt(0)
	v_mfma_f32_16x16x32_bf16 v[68:71], v[206:209], v[162:165], v[68:71]
	v_mfma_f32_16x16x32_bf16 v[60:63], v[214:217], v[162:165], v[60:63]
	v_mfma_f32_16x16x32_bf16 v[56:59], v[206:209], v[176:179], v[56:59]
	v_mfma_f32_16x16x32_bf16 v[52:55], v[214:217], v[176:179], v[52:55]
	v_mfma_f32_16x16x32_bf16 v[48:51], v[206:209], v[190:193], v[48:51]
	v_mfma_f32_16x16x32_bf16 v[44:47], v[214:217], v[190:193], v[44:47]
	v_mfma_f32_16x16x32_bf16 v[40:43], v[206:209], v[198:201], v[40:43]
	v_mfma_f32_16x16x32_bf16 v[36:39], v[214:217], v[198:201], v[36:39]
	v_mfma_f32_16x16x32_bf16 v[68:71], v[210:213], v[172:175], v[68:71]
	v_mfma_f32_16x16x32_bf16 v[60:63], v[218:221], v[172:175], v[60:63]
	v_mfma_f32_16x16x32_bf16 v[56:59], v[210:213], v[180:183], v[56:59]
	v_mfma_f32_16x16x32_bf16 v[52:55], v[218:221], v[180:183], v[52:55]
	v_mfma_f32_16x16x32_bf16 v[48:51], v[210:213], v[194:197], v[48:51]
	v_mfma_f32_16x16x32_bf16 v[44:47], v[218:221], v[194:197], v[44:47]
	v_mfma_f32_16x16x32_bf16 v[40:43], v[210:213], v[202:205], v[40:43]
	v_mfma_f32_16x16x32_bf16 v[36:39], v[218:221], v[202:205], v[36:39]
	s_barrier
	s_setprio 0
	s_mov_b32 m0, s36
	v_lshl_add_u64 v[184:185], s[30:31], 0, v[140:141]
	ds_read_b128 v[162:165], v188 offset:16384
	ds_read_b128 v[172:175], v188 offset:17408
	ds_read_b128 v[176:179], v188 offset:18432
	ds_read_b128 v[180:183], v188 offset:19456
	ds_read_b128 v[190:193], v188 offset:20480
	ds_read_b128 v[194:197], v188 offset:21504
	ds_read_b128 v[198:201], v188 offset:22528
	ds_read_b128 v[202:205], v188 offset:23552
	global_load_lds_dwordx4 v[184:185], off
	s_waitcnt vmcnt(10)
	s_setprio 1
	s_barrier
	s_waitcnt lgkmcnt(0)
	v_mfma_f32_16x16x32_bf16 v[96:99], v[132:135], v[162:165], v[96:99]
	v_mfma_f32_16x16x32_bf16 v[92:95], v[154:157], v[162:165], v[92:95]
	v_mfma_f32_16x16x32_bf16 v[88:91], v[132:135], v[176:179], v[88:91]
	v_mfma_f32_16x16x32_bf16 v[84:87], v[154:157], v[176:179], v[84:87]
	v_mfma_f32_16x16x32_bf16 v[80:83], v[132:135], v[190:193], v[80:83]
	v_mfma_f32_16x16x32_bf16 v[76:79], v[154:157], v[190:193], v[76:79]
	v_mfma_f32_16x16x32_bf16 v[72:75], v[132:135], v[198:201], v[72:75]
	v_mfma_f32_16x16x32_bf16 v[64:67], v[154:157], v[198:201], v[64:67]
	v_mfma_f32_16x16x32_bf16 v[96:99], v[136:139], v[172:175], v[96:99]
	v_mfma_f32_16x16x32_bf16 v[92:95], v[158:161], v[172:175], v[92:95]
	v_mfma_f32_16x16x32_bf16 v[88:91], v[136:139], v[180:183], v[88:91]
	v_mfma_f32_16x16x32_bf16 v[84:87], v[158:161], v[180:183], v[84:87]
	v_mfma_f32_16x16x32_bf16 v[80:83], v[136:139], v[194:197], v[80:83]
	v_mfma_f32_16x16x32_bf16 v[76:79], v[158:161], v[194:197], v[76:79]
	v_mfma_f32_16x16x32_bf16 v[72:75], v[136:139], v[202:205], v[72:75]
	v_mfma_f32_16x16x32_bf16 v[64:67], v[158:161], v[202:205], v[64:67]
	s_barrier
	s_setprio 0
	s_add_u32 s0, s28, 0xb0000
	s_addc_u32 s1, s29, 0
	s_add_i32 s24, s24, s17
	s_mov_b32 m0, s24
	s_nop 0
	global_load_lds_dwordx4 v26, s[0:1]
	s_add_i32 m0, s24, 0x2000
	s_nop 0
	global_load_lds_dwordx4 v144, s[0:1]
	v_lshl_add_u64 v[222:223], s[30:31], 0, v[142:143]
	s_mov_b32 m0, s37
	s_nop 0
	global_load_lds_dwordx4 v[222:223], off
	v_add_u32_e32 v158, 0x18000, v186
	ds_read_b128 v[132:135], v158
	ds_read_b128 v[136:139], v158 offset:1024
	ds_read_b128 v[154:157], v158 offset:2048
	ds_read_b128 v[158:161], v158 offset:3072
	s_waitcnt vmcnt(8)
	s_setprio 1
	s_barrier
	v_mfma_f32_16x16x32_bf16 v[32:35], v[206:209], v[162:165], v[32:35]
	v_mfma_f32_16x16x32_bf16 v[28:31], v[214:217], v[162:165], v[28:31]
	v_mfma_f32_16x16x32_bf16 v[22:25], v[206:209], v[176:179], v[22:25]
	v_mfma_f32_16x16x32_bf16 v[18:21], v[214:217], v[176:179], v[18:21]
	v_mfma_f32_16x16x32_bf16 v[14:17], v[206:209], v[190:193], v[14:17]
	v_mfma_f32_16x16x32_bf16 v[10:13], v[214:217], v[190:193], v[10:13]
	v_mfma_f32_16x16x32_bf16 v[6:9], v[206:209], v[198:201], v[6:9]
	v_mfma_f32_16x16x32_bf16 v[2:5], v[214:217], v[198:201], v[2:5]
	v_mfma_f32_16x16x32_bf16 v[32:35], v[210:213], v[172:175], v[32:35]
	v_mfma_f32_16x16x32_bf16 v[28:31], v[218:221], v[172:175], v[28:31]
	v_mfma_f32_16x16x32_bf16 v[22:25], v[210:213], v[180:183], v[22:25]
	v_mfma_f32_16x16x32_bf16 v[18:21], v[218:221], v[180:183], v[18:21]
	v_mfma_f32_16x16x32_bf16 v[14:17], v[210:213], v[194:197], v[14:17]
	v_mfma_f32_16x16x32_bf16 v[10:13], v[218:221], v[194:197], v[10:13]
	v_mfma_f32_16x16x32_bf16 v[6:9], v[210:213], v[202:205], v[6:9]
	v_mfma_f32_16x16x32_bf16 v[2:5], v[218:221], v[202:205], v[2:5]
	s_barrier
	s_setprio 0
	s_add_i32 s24, 0, 0x18000
	s_add_u32 s0, s30, 0xb0000
	s_addc_u32 s1, s31, 0
	s_mov_b32 m0, s52
	ds_read_b128 v[162:165], v188 offset:32768
	ds_read_b128 v[172:175], v188 offset:33792
	ds_read_b128 v[176:179], v188 offset:34816
	ds_read_b128 v[180:183], v188 offset:35840
	ds_read_b128 v[190:193], v188 offset:36864
	ds_read_b128 v[194:197], v188 offset:37888
	ds_read_b128 v[198:201], v188 offset:38912
	ds_read_b128 v[202:205], v188 offset:39936
	global_load_lds_dwordx4 v140, s[0:1]
	s_mov_b64 s[100:101], s[0:1]
	s_waitcnt vmcnt(10) lgkmcnt(8)
	s_setprio 1
	s_barrier
	s_waitcnt lgkmcnt(0)
	v_mfma_f32_16x16x32_bf16 v[128:131], v[132:135], v[162:165], v[128:131]
	v_mfma_f32_16x16x32_bf16 v[124:127], v[154:157], v[162:165], v[124:127]
	v_mfma_f32_16x16x32_bf16 v[120:123], v[132:135], v[176:179], v[120:123]
	v_mfma_f32_16x16x32_bf16 v[116:119], v[154:157], v[176:179], v[116:119]
	v_mfma_f32_16x16x32_bf16 v[112:115], v[132:135], v[190:193], v[112:115]
	v_mfma_f32_16x16x32_bf16 v[108:111], v[154:157], v[190:193], v[108:111]
	v_mfma_f32_16x16x32_bf16 v[104:107], v[132:135], v[198:201], v[104:107]
	v_mfma_f32_16x16x32_bf16 v[100:103], v[154:157], v[198:201], v[100:103]
	v_mfma_f32_16x16x32_bf16 v[128:131], v[136:139], v[172:175], v[128:131]
	v_mfma_f32_16x16x32_bf16 v[124:127], v[158:161], v[172:175], v[124:127]
	v_mfma_f32_16x16x32_bf16 v[120:123], v[136:139], v[180:183], v[120:123]
	v_mfma_f32_16x16x32_bf16 v[116:119], v[158:161], v[180:183], v[116:119]
	v_mfma_f32_16x16x32_bf16 v[112:115], v[136:139], v[194:197], v[112:115]
	v_mfma_f32_16x16x32_bf16 v[108:111], v[158:161], v[194:197], v[108:111]
	v_mfma_f32_16x16x32_bf16 v[104:107], v[136:139], v[202:205], v[104:107]
	v_mfma_f32_16x16x32_bf16 v[100:103], v[158:161], v[202:205], v[100:103]
	s_barrier
	s_setprio 0
	s_add_i32 s25, 0, 0x1c000
	s_add_i32 s0, s24, s17
	v_add_u32_e32 v189, s25, v186
	v_lshl_add_u64 v[166:167], v[166:167], 0, s[12:13]
	s_mov_b32 m0, s0
	ds_read_b128 v[206:209], v189
	ds_read_b128 v[210:213], v189 offset:1024
	ds_read_b128 v[214:217], v189 offset:2048
	ds_read_b128 v[218:221], v189 offset:3072
	global_load_lds_dwordx4 v[166:167], off
	v_lshl_add_u64 v[166:167], v[168:169], 0, s[12:13]
	s_add_i32 m0, s0, 0x2000
	s_nop 0
	global_load_lds_dwordx4 v[166:167], off
	s_mov_b32 m0, s54
	s_nop 0
	global_load_lds_dwordx4 v142, s[100:101]
	s_waitcnt vmcnt(8)
	s_setprio 1
	s_barrier
	s_waitcnt lgkmcnt(0)
	v_mfma_f32_16x16x32_bf16 v[68:71], v[206:209], v[162:165], v[68:71]
	v_mfma_f32_16x16x32_bf16 v[60:63], v[214:217], v[162:165], v[60:63]
	v_mfma_f32_16x16x32_bf16 v[56:59], v[206:209], v[176:179], v[56:59]
	v_mfma_f32_16x16x32_bf16 v[52:55], v[214:217], v[176:179], v[52:55]
	v_mfma_f32_16x16x32_bf16 v[48:51], v[206:209], v[190:193], v[48:51]
	v_mfma_f32_16x16x32_bf16 v[44:47], v[214:217], v[190:193], v[44:47]
	v_mfma_f32_16x16x32_bf16 v[40:43], v[206:209], v[198:201], v[40:43]
	v_mfma_f32_16x16x32_bf16 v[36:39], v[214:217], v[198:201], v[36:39]
	v_mfma_f32_16x16x32_bf16 v[68:71], v[210:213], v[172:175], v[68:71]
	v_mfma_f32_16x16x32_bf16 v[60:63], v[218:221], v[172:175], v[60:63]
	v_mfma_f32_16x16x32_bf16 v[56:59], v[210:213], v[180:183], v[56:59]
	v_mfma_f32_16x16x32_bf16 v[52:55], v[218:221], v[180:183], v[52:55]
	v_mfma_f32_16x16x32_bf16 v[48:51], v[210:213], v[194:197], v[48:51]
	v_mfma_f32_16x16x32_bf16 v[44:47], v[218:221], v[194:197], v[44:47]
	v_mfma_f32_16x16x32_bf16 v[40:43], v[210:213], v[202:205], v[40:43]
	v_mfma_f32_16x16x32_bf16 v[36:39], v[218:221], v[202:205], v[36:39]
	s_barrier
	s_setprio 0
	s_mov_b32 m0, s55
	v_lshl_add_u64 v[166:167], v[184:185], 0, s[12:13]
	ds_read_b128 v[162:165], v188 offset:49152
	ds_read_b128 v[172:175], v188 offset:50176
	ds_read_b128 v[176:179], v188 offset:51200
	ds_read_b128 v[180:183], v188 offset:52224
	ds_read_b128 v[190:193], v188 offset:53248
	ds_read_b128 v[194:197], v188 offset:54272
	ds_read_b128 v[198:201], v188 offset:55296
	ds_read_b128 v[202:205], v188 offset:56320
	global_load_lds_dwordx4 v[166:167], off
	s_waitcnt vmcnt(10)
	s_setprio 1
	s_barrier
	s_waitcnt lgkmcnt(0)
	v_mfma_f32_16x16x32_bf16 v[96:99], v[132:135], v[162:165], v[96:99]
	v_mfma_f32_16x16x32_bf16 v[92:95], v[154:157], v[162:165], v[92:95]
	v_mfma_f32_16x16x32_bf16 v[88:91], v[132:135], v[176:179], v[88:91]
	v_mfma_f32_16x16x32_bf16 v[84:87], v[154:157], v[176:179], v[84:87]
	v_mfma_f32_16x16x32_bf16 v[80:83], v[132:135], v[190:193], v[80:83]
	v_mfma_f32_16x16x32_bf16 v[76:79], v[154:157], v[190:193], v[76:79]
	v_mfma_f32_16x16x32_bf16 v[72:75], v[132:135], v[198:201], v[72:75]
	v_mfma_f32_16x16x32_bf16 v[64:67], v[154:157], v[198:201], v[64:67]
	v_mfma_f32_16x16x32_bf16 v[96:99], v[136:139], v[172:175], v[96:99]
	v_mfma_f32_16x16x32_bf16 v[92:95], v[158:161], v[172:175], v[92:95]
	v_mfma_f32_16x16x32_bf16 v[88:91], v[136:139], v[180:183], v[88:91]
	v_mfma_f32_16x16x32_bf16 v[84:87], v[158:161], v[180:183], v[84:87]
	v_mfma_f32_16x16x32_bf16 v[80:83], v[136:139], v[194:197], v[80:83]
	v_mfma_f32_16x16x32_bf16 v[76:79], v[158:161], v[194:197], v[76:79]
	v_mfma_f32_16x16x32_bf16 v[72:75], v[136:139], v[202:205], v[72:75]
	v_mfma_f32_16x16x32_bf16 v[64:67], v[158:161], v[202:205], v[64:67]
	s_barrier
	s_setprio 0
	s_add_u32 s0, s28, 0xb0080
	s_addc_u32 s1, s29, 0
	s_add_i32 s24, s25, s17
	s_mov_b32 m0, s24
	s_nop 0
	global_load_lds_dwordx4 v26, s[0:1]
	s_add_i32 m0, s24, 0x2000
	s_nop 0
	global_load_lds_dwordx4 v144, s[0:1]
	v_lshl_add_u64 v[166:167], v[222:223], 0, s[12:13]
	s_mov_b32 m0, s56
	s_nop 0
	global_load_lds_dwordx4 v[166:167], off
	v_add_u32_e32 v158, 0x10000, v186
	ds_read_b128 v[132:135], v158
	ds_read_b128 v[136:139], v158 offset:1024
	ds_read_b128 v[154:157], v158 offset:2048
	ds_read_b128 v[158:161], v158 offset:3072
	s_waitcnt vmcnt(8)
	s_setprio 1
	s_barrier
	v_mfma_f32_16x16x32_bf16 v[32:35], v[206:209], v[162:165], v[32:35]
	v_mfma_f32_16x16x32_bf16 v[28:31], v[214:217], v[162:165], v[28:31]
	v_mfma_f32_16x16x32_bf16 v[22:25], v[206:209], v[176:179], v[22:25]
	v_mfma_f32_16x16x32_bf16 v[18:21], v[214:217], v[176:179], v[18:21]
	v_mfma_f32_16x16x32_bf16 v[14:17], v[206:209], v[190:193], v[14:17]
	v_mfma_f32_16x16x32_bf16 v[10:13], v[214:217], v[190:193], v[10:13]
	v_mfma_f32_16x16x32_bf16 v[6:9], v[206:209], v[198:201], v[6:9]
	v_mfma_f32_16x16x32_bf16 v[2:5], v[214:217], v[198:201], v[2:5]
	v_mfma_f32_16x16x32_bf16 v[32:35], v[210:213], v[172:175], v[32:35]
	v_mfma_f32_16x16x32_bf16 v[28:31], v[218:221], v[172:175], v[28:31]
	v_mfma_f32_16x16x32_bf16 v[22:25], v[210:213], v[180:183], v[22:25]
	v_mfma_f32_16x16x32_bf16 v[18:21], v[218:221], v[180:183], v[18:21]
	v_mfma_f32_16x16x32_bf16 v[14:17], v[210:213], v[194:197], v[14:17]
	v_mfma_f32_16x16x32_bf16 v[10:13], v[218:221], v[194:197], v[10:13]
	v_mfma_f32_16x16x32_bf16 v[6:9], v[210:213], v[202:205], v[6:9]
	v_mfma_f32_16x16x32_bf16 v[2:5], v[218:221], v[202:205], v[2:5]
	s_barrier
	s_setprio 0
	s_add_i32 s72, s72, 2
	s_add_u32 s68, s68, 0x100
	s_addc_u32 s69, s69, 0
	s_cmp_gt_u32 s72, 41
	s_mov_b64 s[24:25], s[26:27]
	s_cbranch_scc0 .LBB0_1122
	s_waitcnt lgkmcnt(0)
	s_min_i32 s0, s22, 0x100
	s_ashr_i32 s26, s0, 5
	s_add_i32 s0, s22, 0xffffff00
	s_cmpk_lt_i32 s22, 0x100
	s_cselect_b32 s0, s22, s0
	s_cselect_b32 s25, 0, s51
	s_cselect_b32 s24, 0, s50
	s_ashr_i32 s1, s0, 31
	s_lshl_b64 s[0:1], s[0:1], 19
	s_add_u32 s24, s20, s24
	v_lshl_or_b32 v166, s23, 8, v187
	s_addc_u32 s25, s21, s25
	s_ashr_i32 s23, s22, 31
	v_lshl_add_u64 v[132:133], s[0:1], 0, v[146:147]
	s_lshl_b64 s[22:23], s[22:23], 10
	s_mul_hi_i32 s1, s26, 0x9000
	s_mul_i32 s26, s26, 0x9000
	s_add_u32 s0, s34, s26
	v_ashrrev_i32_e32 v167, 31, v166
	s_addc_u32 s1, s35, s1
	v_lshl_add_u64 v[154:155], v[166:167], 2, s[0:1]
	v_lshl_add_u64 v[168:169], v[132:133], 0, v[166:167]
	v_lshl_add_u64 v[176:177], v[132:133], 1, s[24:25]
	global_load_dwordx4 v[132:135], v[154:155], off offset:16
	global_load_dwordx4 v[136:139], v[154:155], off
	v_lshl_add_u64 v[182:183], v[168:169], 1, s[24:25]
	v_add_co_u32_e32 v184, vcc, s65, v182
	s_mov_b32 s0, 0x20000
	s_nop 0
	v_addc_co_u32_e32 v185, vcc, 0, v183, vcc
	v_add_co_u32_e32 v178, vcc, s0, v182
	s_mov_b32 s1, 0x30000
	s_nop 0
	v_addc_co_u32_e32 v179, vcc, 0, v183, vcc
	v_add_co_u32_e32 v180, vcc, s1, v182
	v_lshl_add_u64 v[176:177], v[166:167], 1, v[176:177]
	s_nop 0
	v_addc_co_u32_e32 v181, vcc, 0, v183, vcc
	s_mov_b32 s24, 0x80000
	s_mov_b32 s25, 0x90000
	s_waitcnt vmcnt(0)
	v_pk_mul_f32 v[164:165], v[134:135], 0.5 op_sel_hi:[1,0]
	v_pk_mul_f32 v[174:175], v[138:139], 0.5 op_sel_hi:[1,0]
	v_pk_mul_f32 v[172:173], v[136:137], 0.5 op_sel_hi:[1,0]
	v_pk_mul_f32 v[162:163], v[132:133], 0.5 op_sel_hi:[1,0]
	global_load_dwordx4 v[132:135], v[154:155], off offset:528
	global_load_dwordx4 v[136:139], v[154:155], off offset:512
	global_load_dwordx4 v[190:193], v[182:183], off offset:2048
	global_load_dwordx4 v[194:197], v[184:185], off offset:2048
	s_waitcnt vmcnt(0)
	v_pk_mul_f32 v[156:157], v[134:135], 0.5 op_sel_hi:[1,0]
	v_pk_mul_f32 v[160:161], v[138:139], 0.5 op_sel_hi:[1,0]
	v_pk_mul_f32 v[158:159], v[136:137], 0.5 op_sel_hi:[1,0]
	global_load_dwordx4 v[136:139], v[178:179], off offset:2048
	v_pk_mul_f32 v[154:155], v[132:133], 0.5 op_sel_hi:[1,0]
	global_load_dwordx4 v[132:135], v[180:181], off offset:2048
	v_lshlrev_b32_e32 v166, 16, v190
	v_and_b32_e32 v167, 0xffff0000, v190
	v_lshlrev_b32_e32 v168, 16, v191
	v_and_b32_e32 v169, 0xffff0000, v191
	v_lshlrev_b32_e32 v190, 16, v192
	v_and_b32_e32 v191, 0xffff0000, v192
	v_lshlrev_b32_e32 v192, 16, v193
	v_and_b32_e32 v193, 0xffff0000, v193
	v_pk_fma_f32 v[130:131], v[130:131], v[174:175], v[168:169]
	v_pk_fma_f32 v[128:129], v[128:129], v[172:173], v[166:167]
	v_pk_fma_f32 v[166:167], v[126:127], v[164:165], v[192:193]
	v_pk_fma_f32 v[126:127], v[124:125], v[162:163], v[190:191]
	v_lshlrev_b32_e32 v202, 16, v196
	v_and_b32_e32 v203, 0xffff0000, v196
	v_lshlrev_b32_e32 v204, 16, v197
	v_and_b32_e32 v205, 0xffff0000, v197
	v_cvt_pk_bf16_f32 v124, v128, v129
	v_cvt_pk_bf16_f32 v125, v130, v131
	v_cvt_pk_bf16_f32 v126, v126, v127
	v_cvt_pk_bf16_f32 v127, v166, v167
	v_lshlrev_b32_e32 v200, 16, v195
	v_and_b32_e32 v201, 0xffff0000, v195
	global_store_dwordx4 v[176:177], v[124:127], off offset:2048
	v_lshlrev_b32_e32 v193, 16, v124
	v_and_b32_e32 v196, 0xffff0000, v124
	v_lshlrev_b32_e32 v191, 16, v125
	v_and_b32_e32 v195, 0xffff0000, v125
	v_pk_fma_f32 v[124:125], v[118:119], v[164:165], v[204:205]
	v_pk_fma_f32 v[118:119], v[116:117], v[162:163], v[202:203]
	v_lshlrev_b32_e32 v198, 16, v194
	v_cvt_pk_bf16_f32 v118, v118, v119
	v_cvt_pk_bf16_f32 v119, v124, v125
	v_add_co_u32_e32 v124, vcc, s65, v176
	v_and_b32_e32 v199, 0xffff0000, v194
	s_nop 0
	v_addc_co_u32_e32 v125, vcc, 0, v177, vcc
	v_lshlrev_b32_e32 v190, 16, v126
	v_and_b32_e32 v194, 0xffff0000, v126
	v_add_co_u32_e32 v126, vcc, s24, v182
	v_lshlrev_b32_e32 v189, 16, v127
	v_and_b32_e32 v192, 0xffff0000, v127
	v_addc_co_u32_e32 v127, vcc, 0, v183, vcc
	v_add_co_u32_e32 v128, vcc, s25, v182
	v_pk_fma_f32 v[122:123], v[122:123], v[174:175], v[200:201]
	v_pk_fma_f32 v[120:121], v[120:121], v[172:173], v[198:199]
	v_addc_co_u32_e32 v129, vcc, 0, v183, vcc
	v_cvt_pk_bf16_f32 v116, v120, v121
	v_cvt_pk_bf16_f32 v117, v122, v123
	global_store_dwordx4 v[124:125], v[116:119], off offset:2048
	global_load_dwordx4 v[120:123], v[126:127], off offset:2048
	global_load_dwordx4 v[198:201], v[128:129], off offset:2048
	s_waitcnt vmcnt(0)
	v_lshlrev_b32_e32 v130, 16, v136
	v_and_b32_e32 v131, 0xffff0000, v136
	v_lshlrev_b32_e32 v166, 16, v138
	v_and_b32_e32 v167, 0xffff0000, v138
	v_lshlrev_b32_e32 v138, 16, v139
	v_and_b32_e32 v139, 0xffff0000, v139
	v_pk_fma_f32 v[112:113], v[112:113], v[172:173], v[130:131]
	v_pk_fma_f32 v[130:131], v[110:111], v[164:165], v[138:139]
	v_pk_fma_f32 v[110:111], v[108:109], v[162:163], v[166:167]
	v_lshlrev_b32_e32 v168, 16, v132
	v_cvt_pk_bf16_f32 v110, v110, v111
	v_cvt_pk_bf16_f32 v111, v130, v131
	v_add_co_u32_e32 v130, vcc, s0, v176
	v_and_b32_e32 v169, 0xffff0000, v132
	v_lshlrev_b32_e32 v132, 16, v133
	v_and_b32_e32 v133, 0xffff0000, v133
	v_addc_co_u32_e32 v131, vcc, 0, v177, vcc
	v_lshlrev_b32_e32 v136, 16, v137
	v_and_b32_e32 v137, 0xffff0000, v137
	v_lshlrev_b32_e32 v202, 16, v134
	v_and_b32_e32 v203, 0xffff0000, v134
	v_lshlrev_b32_e32 v134, 16, v135
	v_and_b32_e32 v135, 0xffff0000, v135
	v_pk_fma_f32 v[106:107], v[106:107], v[174:175], v[132:133]
	v_add_co_u32_e32 v132, vcc, s1, v176
	v_pk_fma_f32 v[114:115], v[114:115], v[174:175], v[136:137]
	v_cvt_pk_bf16_f32 v108, v112, v113
	v_pk_fma_f32 v[104:105], v[104:105], v[172:173], v[168:169]
	v_pk_fma_f32 v[112:113], v[102:103], v[164:165], v[134:135]
	v_pk_fma_f32 v[102:103], v[100:101], v[162:163], v[202:203]
	v_addc_co_u32_e32 v133, vcc, 0, v177, vcc
	v_cvt_pk_bf16_f32 v109, v114, v115
	v_cvt_pk_bf16_f32 v100, v104, v105
	v_cvt_pk_bf16_f32 v101, v106, v107
	v_cvt_pk_bf16_f32 v102, v102, v103
	v_cvt_pk_bf16_f32 v103, v112, v113
	v_add_co_u32_e32 v134, vcc, s76, v182
	global_store_dwordx4 v[130:131], v[108:111], off offset:2048
	global_store_dwordx4 v[132:133], v[100:103], off offset:2048
	v_addc_co_u32_e32 v135, vcc, 0, v183, vcc
	s_mov_b32 s0, 0xb0000
	global_load_dwordx4 v[112:115], v[134:135], off offset:2048
	v_add_co_u32_e32 v136, vcc, s0, v182
	v_lshlrev_b32_e32 v138, 16, v120
	s_nop 0
	v_addc_co_u32_e32 v137, vcc, 0, v183, vcc
	global_load_dwordx4 v[104:107], v[136:137], off offset:2048
	v_and_b32_e32 v139, 0xffff0000, v120
	v_lshlrev_b32_e32 v120, 16, v121
	v_and_b32_e32 v121, 0xffff0000, v121
	v_lshlrev_b32_e32 v166, 16, v122
	v_and_b32_e32 v167, 0xffff0000, v122
	v_lshlrev_b32_e32 v122, 16, v123
	v_and_b32_e32 v123, 0xffff0000, v123
	v_pk_fma_f32 v[96:97], v[96:97], v[172:173], v[138:139]
	v_lshlrev_b32_e32 v168, 16, v198
	v_and_b32_e32 v169, 0xffff0000, v198
	v_lshlrev_b32_e32 v198, 16, v199
	v_and_b32_e32 v199, 0xffff0000, v199
	v_pk_fma_f32 v[98:99], v[98:99], v[174:175], v[120:121]
	v_pk_fma_f32 v[120:121], v[94:95], v[164:165], v[122:123]
	v_pk_fma_f32 v[94:95], v[92:93], v[162:163], v[166:167]
	v_cvt_pk_bf16_f32 v92, v96, v97
	v_add_co_u32_e32 v96, vcc, s24, v176
	v_lshlrev_b32_e32 v202, 16, v200
	v_and_b32_e32 v203, 0xffff0000, v200
	v_lshlrev_b32_e32 v200, 16, v201
	v_and_b32_e32 v201, 0xffff0000, v201
	v_addc_co_u32_e32 v97, vcc, 0, v177, vcc
	v_pk_fma_f32 v[90:91], v[90:91], v[174:175], v[198:199]
	v_pk_fma_f32 v[88:89], v[88:89], v[172:173], v[168:169]
	v_cvt_pk_bf16_f32 v93, v98, v99
	v_pk_fma_f32 v[98:99], v[86:87], v[164:165], v[200:201]
	v_pk_fma_f32 v[86:87], v[84:85], v[162:163], v[202:203]
	v_cvt_pk_bf16_f32 v84, v88, v89
	v_cvt_pk_bf16_f32 v85, v90, v91
	v_add_co_u32_e32 v88, vcc, s25, v176
	v_cvt_pk_bf16_f32 v86, v86, v87
	v_cvt_pk_bf16_f32 v87, v98, v99
	v_addc_co_u32_e32 v89, vcc, 0, v177, vcc
	v_cvt_pk_bf16_f32 v94, v94, v95
	v_cvt_pk_bf16_f32 v95, v120, v121
	global_store_dwordx4 v[96:97], v[92:95], off offset:2048
	global_store_dwordx4 v[88:89], v[84:87], off offset:2048
	global_load_dwordx4 v[120:123], v[182:183], off offset:2304
	s_nop 0
	global_load_dwordx4 v[182:185], v[184:185], off offset:2304
	s_waitcnt vmcnt(0)
	v_lshlrev_b32_e32 v90, 16, v112
	v_and_b32_e32 v91, 0xffff0000, v112
	v_lshlrev_b32_e32 v98, 16, v113
	v_and_b32_e32 v99, 0xffff0000, v113
	v_lshlrev_b32_e32 v112, 16, v114
	v_and_b32_e32 v113, 0xffff0000, v114
	v_lshlrev_b32_e32 v114, 16, v115
	v_and_b32_e32 v115, 0xffff0000, v115
	v_pk_fma_f32 v[80:81], v[80:81], v[172:173], v[90:91]
	v_pk_fma_f32 v[90:91], v[78:79], v[164:165], v[114:115]
	v_pk_fma_f32 v[78:79], v[76:77], v[162:163], v[112:113]
	v_cvt_pk_bf16_f32 v76, v80, v81
	v_add_co_u32_e32 v80, vcc, s76, v176
	v_lshlrev_b32_e32 v138, 16, v104
	v_and_b32_e32 v139, 0xffff0000, v104
	v_lshlrev_b32_e32 v104, 16, v105
	v_and_b32_e32 v105, 0xffff0000, v105
	v_lshlrev_b32_e32 v166, 16, v106
	v_and_b32_e32 v167, 0xffff0000, v106
	v_lshlrev_b32_e32 v106, 16, v107
	v_and_b32_e32 v107, 0xffff0000, v107
	v_pk_fma_f32 v[82:83], v[82:83], v[174:175], v[98:99]
	v_addc_co_u32_e32 v81, vcc, 0, v177, vcc
	v_pk_fma_f32 v[72:73], v[72:73], v[172:173], v[138:139]
	v_cvt_pk_bf16_f32 v77, v82, v83
	v_pk_fma_f32 v[74:75], v[74:75], v[174:175], v[104:105]
	v_pk_fma_f32 v[82:83], v[66:67], v[164:165], v[106:107]
	v_pk_fma_f32 v[66:67], v[64:65], v[162:163], v[166:167]
	v_cvt_pk_bf16_f32 v64, v72, v73
	v_add_co_u32_e32 v72, vcc, s0, v176
	v_cvt_pk_bf16_f32 v78, v78, v79
	v_cvt_pk_bf16_f32 v79, v90, v91
	v_cvt_pk_bf16_f32 v65, v74, v75
	v_cvt_pk_bf16_f32 v66, v66, v67
	v_cvt_pk_bf16_f32 v67, v82, v83
	v_addc_co_u32_e32 v73, vcc, 0, v177, vcc
	global_store_dwordx4 v[80:81], v[76:79], off offset:2048
	global_store_dwordx4 v[72:73], v[64:67], off offset:2048
	global_load_dwordx4 v[104:107], v[178:179], off offset:2304
	global_load_dwordx4 v[112:115], v[180:181], off offset:2304
	v_lshlrev_b32_e32 v74, 16, v120
	v_and_b32_e32 v75, 0xffff0000, v120
	v_lshlrev_b32_e32 v82, 16, v121
	v_and_b32_e32 v83, 0xffff0000, v121
	v_lshlrev_b32_e32 v90, 16, v122
	v_and_b32_e32 v91, 0xffff0000, v122
	v_lshlrev_b32_e32 v98, 16, v123
	v_and_b32_e32 v99, 0xffff0000, v123
	v_pk_fma_f32 v[70:71], v[70:71], v[160:161], v[82:83]
	v_pk_fma_f32 v[68:69], v[68:69], v[158:159], v[74:75]
	v_pk_fma_f32 v[74:75], v[62:63], v[156:157], v[98:99]
	v_pk_fma_f32 v[62:63], v[60:61], v[154:155], v[90:91]
	v_lshlrev_b32_e32 v120, 16, v182
	v_and_b32_e32 v121, 0xffff0000, v182
	v_lshlrev_b32_e32 v122, 16, v183
	v_and_b32_e32 v123, 0xffff0000, v183
	v_lshlrev_b32_e32 v138, 16, v184
	v_and_b32_e32 v139, 0xffff0000, v184
	v_lshlrev_b32_e32 v162, 16, v185
	v_and_b32_e32 v163, 0xffff0000, v185
	v_cvt_pk_bf16_f32 v60, v68, v69
	v_cvt_pk_bf16_f32 v61, v70, v71
	v_cvt_pk_bf16_f32 v62, v62, v63
	v_cvt_pk_bf16_f32 v63, v74, v75
	global_store_dwordx4 v[176:177], v[60:63], off offset:2304
	v_lshlrev_b32_e32 v164, 16, v60
	v_and_b32_e32 v165, 0xffff0000, v60
	v_lshlrev_b32_e32 v166, 16, v61
	v_and_b32_e32 v167, 0xffff0000, v61
	v_pk_fma_f32 v[58:59], v[58:59], v[160:161], v[122:123]
	v_pk_fma_f32 v[56:57], v[56:57], v[158:159], v[120:121]
	v_pk_fma_f32 v[60:61], v[54:55], v[156:157], v[162:163]
	v_pk_fma_f32 v[54:55], v[52:53], v[154:155], v[138:139]
	v_cvt_pk_bf16_f32 v52, v56, v57
	v_cvt_pk_bf16_f32 v53, v58, v59
	v_cvt_pk_bf16_f32 v54, v54, v55
	v_cvt_pk_bf16_f32 v55, v60, v61
	global_store_dwordx4 v[124:125], v[52:55], off offset:2304
	v_lshlrev_b32_e32 v168, 16, v62
	v_and_b32_e32 v169, 0xffff0000, v62
	v_lshlrev_b32_e32 v172, 16, v63
	v_and_b32_e32 v173, 0xffff0000, v63
	global_load_dwordx4 v[56:59], v[126:127], off offset:2304
	global_load_dwordx4 v[60:63], v[128:129], off offset:2304
	s_waitcnt vmcnt(0)
	v_lshlrev_b32_e32 v68, 16, v104
	v_and_b32_e32 v69, 0xffff0000, v104
	v_lshlrev_b32_e32 v70, 16, v105
	v_and_b32_e32 v71, 0xffff0000, v105
	v_lshlrev_b32_e32 v74, 16, v106
	v_and_b32_e32 v75, 0xffff0000, v106
	v_lshlrev_b32_e32 v82, 16, v107
	v_and_b32_e32 v83, 0xffff0000, v107
	v_lshlrev_b32_e32 v90, 16, v112
	v_and_b32_e32 v91, 0xffff0000, v112
	v_lshlrev_b32_e32 v98, 16, v113
	v_and_b32_e32 v99, 0xffff0000, v113
	v_lshlrev_b32_e32 v104, 16, v114
	v_and_b32_e32 v105, 0xffff0000, v114
	v_lshlrev_b32_e32 v106, 16, v115
	v_and_b32_e32 v107, 0xffff0000, v115
	v_pk_fma_f32 v[48:49], v[48:49], v[158:159], v[68:69]
	v_pk_fma_f32 v[50:51], v[50:51], v[160:161], v[70:71]
	v_pk_fma_f32 v[68:69], v[46:47], v[156:157], v[82:83]
	v_pk_fma_f32 v[46:47], v[44:45], v[154:155], v[74:75]
	v_cvt_pk_bf16_f32 v44, v48, v49
	v_pk_fma_f32 v[42:43], v[42:43], v[160:161], v[98:99]
	v_pk_fma_f32 v[40:41], v[40:41], v[158:159], v[90:91]
	v_pk_fma_f32 v[48:49], v[38:39], v[156:157], v[106:107]
	v_pk_fma_f32 v[38:39], v[36:37], v[154:155], v[104:105]
	v_cvt_pk_bf16_f32 v45, v50, v51
	v_cvt_pk_bf16_f32 v46, v46, v47
	v_cvt_pk_bf16_f32 v47, v68, v69
	v_cvt_pk_bf16_f32 v36, v40, v41
	v_cvt_pk_bf16_f32 v37, v42, v43
	v_cvt_pk_bf16_f32 v38, v38, v39
	v_cvt_pk_bf16_f32 v39, v48, v49
	global_store_dwordx4 v[130:131], v[44:47], off offset:2304
	global_store_dwordx4 v[132:133], v[36:39], off offset:2304
	global_load_dwordx4 v[40:43], v[134:135], off offset:2304
	global_load_dwordx4 v[48:51], v[136:137], off offset:2304
	v_lshlrev_b32_e32 v68, 16, v56
	v_and_b32_e32 v69, 0xffff0000, v56
	v_lshlrev_b32_e32 v56, 16, v57
	v_and_b32_e32 v57, 0xffff0000, v57
	v_lshlrev_b32_e32 v70, 16, v58
	v_and_b32_e32 v71, 0xffff0000, v58
	v_lshlrev_b32_e32 v58, 16, v59
	v_and_b32_e32 v59, 0xffff0000, v59
	v_lshlrev_b32_e32 v74, 16, v60
	v_and_b32_e32 v75, 0xffff0000, v60
	v_lshlrev_b32_e32 v82, 16, v62
	v_and_b32_e32 v83, 0xffff0000, v62
	v_lshlrev_b32_e32 v62, 16, v63
	v_and_b32_e32 v63, 0xffff0000, v63
	v_pk_fma_f32 v[32:33], v[32:33], v[158:159], v[68:69]
	v_lshlrev_b32_e32 v60, 16, v61
	v_and_b32_e32 v61, 0xffff0000, v61
	v_pk_fma_f32 v[34:35], v[34:35], v[160:161], v[56:57]
	v_pk_fma_f32 v[56:57], v[30:31], v[156:157], v[58:59]
	v_pk_fma_f32 v[30:31], v[28:29], v[154:155], v[70:71]
	v_cvt_pk_bf16_f32 v28, v32, v33
	v_pk_fma_f32 v[22:23], v[22:23], v[158:159], v[74:75]
	v_pk_fma_f32 v[32:33], v[20:21], v[156:157], v[62:63]
	v_pk_fma_f32 v[20:21], v[18:19], v[154:155], v[82:83]
	v_cvt_pk_bf16_f32 v29, v34, v35
	v_pk_fma_f32 v[24:25], v[24:25], v[160:161], v[60:61]
	v_cvt_pk_bf16_f32 v18, v22, v23
	v_cvt_pk_bf16_f32 v20, v20, v21
	v_cvt_pk_bf16_f32 v21, v32, v33
	v_cvt_pk_bf16_f32 v19, v24, v25
	v_cvt_pk_bf16_f32 v30, v30, v31
	v_cvt_pk_bf16_f32 v31, v56, v57
	global_store_dwordx4 v[96:97], v[28:31], off offset:2304
	global_store_dwordx4 v[88:89], v[18:21], off offset:2304
	s_waitcnt vmcnt(0)
	v_lshlrev_b32_e32 v22, 16, v40
	v_and_b32_e32 v23, 0xffff0000, v40
	v_lshlrev_b32_e32 v32, 16, v42
	v_and_b32_e32 v33, 0xffff0000, v42
	v_lshlrev_b32_e32 v34, 16, v43
	v_and_b32_e32 v35, 0xffff0000, v43
	v_lshlrev_b32_e32 v42, 16, v49
	v_and_b32_e32 v43, 0xffff0000, v49
	v_lshlrev_b32_e32 v24, 16, v41
	v_and_b32_e32 v25, 0xffff0000, v41
	v_lshlrev_b32_e32 v40, 16, v48
	v_and_b32_e32 v41, 0xffff0000, v48
	v_lshlrev_b32_e32 v48, 16, v50
	v_and_b32_e32 v49, 0xffff0000, v50
	v_lshlrev_b32_e32 v50, 16, v51
	v_and_b32_e32 v51, 0xffff0000, v51
	v_pk_fma_f32 v[14:15], v[14:15], v[158:159], v[22:23]
	v_pk_fma_f32 v[8:9], v[8:9], v[160:161], v[42:43]
	v_pk_fma_f32 v[22:23], v[12:13], v[156:157], v[34:35]
	v_pk_fma_f32 v[12:13], v[10:11], v[154:155], v[32:33]
	v_cvt_pk_bf16_f32 v10, v14, v15
	v_pk_fma_f32 v[14:15], v[4:5], v[156:157], v[50:51]
	v_pk_fma_f32 v[4:5], v[2:3], v[154:155], v[48:49]
	v_cvt_pk_bf16_f32 v3, v8, v9
	v_and_b32_e32 v9, 64, v227
	v_xor_b32_e32 v8, 16, v227
	v_add_u32_e32 v9, 64, v9
	v_cvt_pk_bf16_f32 v4, v4, v5
	v_cvt_pk_bf16_f32 v5, v14, v15
	v_cmp_lt_i32_e32 vcc, v8, v9
	v_xor_b32_e32 v14, 32, v227
	v_mul_f32_e32 v15, v195, v195
	v_cndmask_b32_e32 v8, v227, v8, vcc
	v_cmp_lt_i32_e32 vcc, v14, v9
	v_pk_fma_f32 v[16:17], v[16:17], v[160:161], v[24:25]
	v_fmac_f32_e32 v15, v191, v191
	v_cndmask_b32_e32 v9, v227, v14, vcc
	v_mul_f32_e32 v14, v196, v196
	v_fmac_f32_e32 v14, v193, v193
	v_cvt_pk_bf16_f32 v11, v16, v17
	v_add_f32_e32 v14, v14, v15
	v_mul_f32_e32 v15, v194, v194
	v_mul_f32_e32 v16, v192, v192
	v_fmac_f32_e32 v15, v190, v190
	v_fmac_f32_e32 v16, v189, v189
	v_add_f32_e32 v15, v15, v16
	v_add_f32_e32 v14, v14, v15
	v_mul_f32_e32 v15, v165, v165
	v_mul_f32_e32 v16, v167, v167
	v_fmac_f32_e32 v15, v164, v164
	v_fmac_f32_e32 v16, v166, v166
	v_add_f32_e32 v15, v15, v16
	v_add_f32_e32 v14, v14, v15
	v_mul_f32_e32 v15, v169, v169
	v_mul_f32_e32 v16, v173, v173
	v_fmac_f32_e32 v15, v168, v168
	v_fmac_f32_e32 v16, v172, v172
	v_add_f32_e32 v15, v15, v16
	v_lshlrev_b32_e32 v8, 2, v8
	v_add_f32_e32 v14, v15, v14
	ds_bpermute_b32 v15, v8, v14
	v_lshlrev_b32_e32 v9, 2, v9
	v_pk_fma_f32 v[6:7], v[6:7], v[158:159], v[40:41]
	v_cvt_pk_bf16_f32 v12, v12, v13
	v_cvt_pk_bf16_f32 v13, v22, v23
	s_waitcnt lgkmcnt(0)
	v_add_f32_e32 v14, v14, v15
	ds_bpermute_b32 v15, v9, v14
	v_cvt_pk_bf16_f32 v2, v6, v7
	v_lshl_add_u64 v[6:7], v[148:149], 0, s[22:23]
	global_store_dwordx4 v[80:81], v[10:13], off offset:2304
	global_store_dwordx4 v[72:73], v[2:5], off offset:2304
	s_and_saveexec_b64 s[22:23], s[38:39]
	s_cbranch_execz .LBB0_1125
	s_waitcnt lgkmcnt(0)
	v_add_f32_e32 v14, v14, v15
	global_atomic_add_f32 v[6:7], v14, off

.LBB0_1156:
	s_add_u32 s28, s26, 0x100
	s_addc_u32 s29, s27, 0
	s_add_i32 s0, 0, 0x10000
	s_cmp_eq_u32 s81, 40
	s_cselect_b32 s35, s43, s29
	s_cselect_b32 s34, s42, s28
	s_cselect_b32 s31, s23, s45
	s_cselect_b32 s30, s22, s44
	s_add_i32 m0, s52, 0xc000
	ds_read_b128 v[172:175], v224
	ds_read_b128 v[176:179], v224 offset:1024
	ds_read_b128 v[180:183], v224 offset:2048
	ds_read_b128 v[184:187], v224 offset:3072
	ds_read_b128 v[188:191], v224 offset:4096
	ds_read_b128 v[192:195], v224 offset:5120
	ds_read_b128 v[196:199], v224 offset:6144
	ds_read_b128 v[200:203], v224 offset:7168
	global_load_lds_dwordx4 v152, s[26:27]
	s_mov_b64 s[100:101], s[26:27]
	s_waitcnt vmcnt(10) lgkmcnt(8)
	s_setprio 1
	s_barrier
	s_waitcnt lgkmcnt(0)
	v_mfma_f32_16x16x32_bf16 v[128:131], v[132:135], v[172:175], v[128:131]
	v_mfma_f32_16x16x32_bf16 v[124:127], v[156:159], v[172:175], v[124:127]
	v_mfma_f32_16x16x32_bf16 v[120:123], v[132:135], v[180:183], v[120:123]
	v_mfma_f32_16x16x32_bf16 v[116:119], v[156:159], v[180:183], v[116:119]
	v_mfma_f32_16x16x32_bf16 v[112:115], v[132:135], v[188:191], v[112:115]
	v_mfma_f32_16x16x32_bf16 v[108:111], v[156:159], v[188:191], v[108:111]
	v_mfma_f32_16x16x32_bf16 v[104:107], v[132:135], v[196:199], v[104:107]
	v_mfma_f32_16x16x32_bf16 v[100:103], v[156:159], v[196:199], v[100:103]
	v_mfma_f32_16x16x32_bf16 v[128:131], v[136:139], v[176:179], v[128:131]
	v_mfma_f32_16x16x32_bf16 v[124:127], v[160:163], v[176:179], v[124:127]
	v_mfma_f32_16x16x32_bf16 v[120:123], v[136:139], v[184:187], v[120:123]
	v_mfma_f32_16x16x32_bf16 v[116:119], v[160:163], v[184:187], v[116:119]
	v_mfma_f32_16x16x32_bf16 v[112:115], v[136:139], v[192:195], v[112:115]
	v_mfma_f32_16x16x32_bf16 v[108:111], v[160:163], v[192:195], v[108:111]
	v_mfma_f32_16x16x32_bf16 v[104:107], v[136:139], v[200:203], v[104:107]
	v_mfma_f32_16x16x32_bf16 v[100:103], v[160:163], v[200:203], v[100:103]
	s_barrier
	s_setprio 0
	s_add_i32 s26, 0, 0x14000
	v_add_u32_e32 v164, s26, v222
	s_add_i32 s0, s0, s17
	ds_read_b128 v[204:207], v164
	ds_read_b128 v[208:211], v164 offset:1024
	ds_read_b128 v[212:215], v164 offset:2048
	ds_read_b128 v[216:219], v164 offset:3072
	v_lshl_add_u64 v[164:165], s[30:31], 0, v[26:27]
	s_mov_b32 m0, s0
	v_lshl_add_u64 v[166:167], s[30:31], 0, v[144:145]
	global_load_lds_dwordx4 v[164:165], off
	s_add_i32 m0, s0, 0x2000
	s_nop 0
	global_load_lds_dwordx4 v[166:167], off
	v_lshl_add_u64 v[238:239], s[100:101], 0, v[154:155]
	s_add_i32 m0, s52, 0xe000
	s_nop 0
	global_load_lds_dwordx4 v[238:239], off
	s_waitcnt vmcnt(8)
	s_setprio 1
	s_barrier
	s_waitcnt lgkmcnt(0)
	v_mfma_f32_16x16x32_bf16 v[64:67], v[204:207], v[172:175], v[64:67]
	v_mfma_f32_16x16x32_bf16 v[60:63], v[212:215], v[172:175], v[60:63]
	v_mfma_f32_16x16x32_bf16 v[56:59], v[204:207], v[180:183], v[56:59]
	v_mfma_f32_16x16x32_bf16 v[52:55], v[212:215], v[180:183], v[52:55]
	v_mfma_f32_16x16x32_bf16 v[48:51], v[204:207], v[188:191], v[48:51]
	v_mfma_f32_16x16x32_bf16 v[44:47], v[212:215], v[188:191], v[44:47]
	v_mfma_f32_16x16x32_bf16 v[40:43], v[204:207], v[196:199], v[40:43]
	v_mfma_f32_16x16x32_bf16 v[36:39], v[212:215], v[196:199], v[36:39]
	v_mfma_f32_16x16x32_bf16 v[64:67], v[208:211], v[176:179], v[64:67]
	v_mfma_f32_16x16x32_bf16 v[60:63], v[216:219], v[176:179], v[60:63]
	v_mfma_f32_16x16x32_bf16 v[56:59], v[208:211], v[184:187], v[56:59]
	v_mfma_f32_16x16x32_bf16 v[52:55], v[216:219], v[184:187], v[52:55]
	v_mfma_f32_16x16x32_bf16 v[48:51], v[208:211], v[192:195], v[48:51]
	v_mfma_f32_16x16x32_bf16 v[44:47], v[216:219], v[192:195], v[44:47]
	v_mfma_f32_16x16x32_bf16 v[40:43], v[208:211], v[200:203], v[40:43]
	v_mfma_f32_16x16x32_bf16 v[36:39], v[216:219], v[200:203], v[36:39]
	s_barrier
	s_setprio 0
	s_mov_b32 m0, s52
	v_lshl_add_u64 v[168:169], s[34:35], 0, v[140:141]
	ds_read_b128 v[172:175], v224 offset:16384
	ds_read_b128 v[176:179], v224 offset:17408
	ds_read_b128 v[180:183], v224 offset:18432
	ds_read_b128 v[184:187], v224 offset:19456
	ds_read_b128 v[188:191], v224 offset:20480
	ds_read_b128 v[192:195], v224 offset:21504
	ds_read_b128 v[196:199], v224 offset:22528
	ds_read_b128 v[200:203], v224 offset:23552
	global_load_lds_dwordx4 v[168:169], off
	s_waitcnt vmcnt(10)
	s_setprio 1
	s_barrier
	s_waitcnt lgkmcnt(0)
	v_mfma_f32_16x16x32_bf16 v[96:99], v[132:135], v[172:175], v[96:99]
	v_mfma_f32_16x16x32_bf16 v[92:95], v[156:159], v[172:175], v[92:95]
	v_mfma_f32_16x16x32_bf16 v[88:91], v[132:135], v[180:183], v[88:91]
	v_mfma_f32_16x16x32_bf16 v[84:87], v[156:159], v[180:183], v[84:87]
	v_mfma_f32_16x16x32_bf16 v[80:83], v[132:135], v[188:191], v[80:83]
	v_mfma_f32_16x16x32_bf16 v[76:79], v[156:159], v[188:191], v[76:79]
	v_mfma_f32_16x16x32_bf16 v[72:75], v[132:135], v[196:199], v[72:75]
	v_mfma_f32_16x16x32_bf16 v[68:71], v[156:159], v[196:199], v[68:71]
	v_mfma_f32_16x16x32_bf16 v[96:99], v[136:139], v[176:179], v[96:99]
	v_mfma_f32_16x16x32_bf16 v[92:95], v[160:163], v[176:179], v[92:95]
	v_mfma_f32_16x16x32_bf16 v[88:91], v[136:139], v[184:187], v[88:91]
	v_mfma_f32_16x16x32_bf16 v[84:87], v[160:163], v[184:187], v[84:87]
	v_mfma_f32_16x16x32_bf16 v[80:83], v[136:139], v[192:195], v[80:83]
	v_mfma_f32_16x16x32_bf16 v[76:79], v[160:163], v[192:195], v[76:79]
	v_mfma_f32_16x16x32_bf16 v[72:75], v[136:139], v[200:203], v[72:75]
	v_mfma_f32_16x16x32_bf16 v[68:71], v[160:163], v[200:203], v[68:71]
	s_barrier
	s_setprio 0
	s_add_u32 s0, s30, 0xb0000
	s_addc_u32 s1, s31, 0
	s_add_i32 s26, s26, s17
	s_mov_b32 m0, s26
	s_nop 0
	global_load_lds_dwordx4 v26, s[0:1]
	s_add_i32 m0, s26, 0x2000
	s_nop 0
	global_load_lds_dwordx4 v144, s[0:1]
	v_lshl_add_u64 v[220:221], s[34:35], 0, v[142:143]
	s_mov_b32 m0, s54
	s_nop 0
	global_load_lds_dwordx4 v[220:221], off
	v_add_u32_e32 v160, 0x18000, v222
	ds_read_b128 v[132:135], v160
	ds_read_b128 v[136:139], v160 offset:1024
	ds_read_b128 v[156:159], v160 offset:2048
	ds_read_b128 v[160:163], v160 offset:3072
	s_waitcnt vmcnt(8)
	s_setprio 1
	s_barrier
	v_mfma_f32_16x16x32_bf16 v[32:35], v[204:207], v[172:175], v[32:35]
	v_mfma_f32_16x16x32_bf16 v[28:31], v[212:215], v[172:175], v[28:31]
	v_mfma_f32_16x16x32_bf16 v[22:25], v[204:207], v[180:183], v[22:25]
	v_mfma_f32_16x16x32_bf16 v[18:21], v[212:215], v[180:183], v[18:21]
	v_mfma_f32_16x16x32_bf16 v[14:17], v[204:207], v[188:191], v[14:17]
	v_mfma_f32_16x16x32_bf16 v[10:13], v[212:215], v[188:191], v[10:13]
	v_mfma_f32_16x16x32_bf16 v[6:9], v[204:207], v[196:199], v[6:9]
	v_mfma_f32_16x16x32_bf16 v[2:5], v[212:215], v[196:199], v[2:5]
	v_mfma_f32_16x16x32_bf16 v[32:35], v[208:211], v[176:179], v[32:35]
	v_mfma_f32_16x16x32_bf16 v[28:31], v[216:219], v[176:179], v[28:31]
	v_mfma_f32_16x16x32_bf16 v[22:25], v[208:211], v[184:187], v[22:25]
	v_mfma_f32_16x16x32_bf16 v[18:21], v[216:219], v[184:187], v[18:21]
	v_mfma_f32_16x16x32_bf16 v[14:17], v[208:211], v[192:195], v[14:17]
	v_mfma_f32_16x16x32_bf16 v[10:13], v[216:219], v[192:195], v[10:13]
	v_mfma_f32_16x16x32_bf16 v[6:9], v[208:211], v[200:203], v[6:9]
	v_mfma_f32_16x16x32_bf16 v[2:5], v[216:219], v[200:203], v[2:5]
	s_barrier
	s_setprio 0
	s_add_i32 s26, 0, 0x18000
	s_add_u32 s0, s34, 0xb0000
	s_addc_u32 s1, s35, 0
	s_mov_b32 m0, s55
	ds_read_b128 v[172:175], v224 offset:32768
	ds_read_b128 v[176:179], v224 offset:33792
	ds_read_b128 v[180:183], v224 offset:34816
	ds_read_b128 v[184:187], v224 offset:35840
	ds_read_b128 v[188:191], v224 offset:36864
	ds_read_b128 v[192:195], v224 offset:37888
	ds_read_b128 v[196:199], v224 offset:38912
	ds_read_b128 v[200:203], v224 offset:39936
	global_load_lds_dwordx4 v140, s[0:1]
	s_mov_b64 s[100:101], s[0:1]
	s_waitcnt vmcnt(10) lgkmcnt(8)
	s_setprio 1
	s_barrier
	s_waitcnt lgkmcnt(0)
	v_mfma_f32_16x16x32_bf16 v[128:131], v[132:135], v[172:175], v[128:131]
	v_mfma_f32_16x16x32_bf16 v[124:127], v[156:159], v[172:175], v[124:127]
	v_mfma_f32_16x16x32_bf16 v[120:123], v[132:135], v[180:183], v[120:123]
	v_mfma_f32_16x16x32_bf16 v[116:119], v[156:159], v[180:183], v[116:119]
	v_mfma_f32_16x16x32_bf16 v[112:115], v[132:135], v[188:191], v[112:115]
	v_mfma_f32_16x16x32_bf16 v[108:111], v[156:159], v[188:191], v[108:111]
	v_mfma_f32_16x16x32_bf16 v[104:107], v[132:135], v[196:199], v[104:107]
	v_mfma_f32_16x16x32_bf16 v[100:103], v[156:159], v[196:199], v[100:103]
	v_mfma_f32_16x16x32_bf16 v[128:131], v[136:139], v[176:179], v[128:131]
	v_mfma_f32_16x16x32_bf16 v[124:127], v[160:163], v[176:179], v[124:127]
	v_mfma_f32_16x16x32_bf16 v[120:123], v[136:139], v[184:187], v[120:123]
	v_mfma_f32_16x16x32_bf16 v[116:119], v[160:163], v[184:187], v[116:119]
	v_mfma_f32_16x16x32_bf16 v[112:115], v[136:139], v[192:195], v[112:115]
	v_mfma_f32_16x16x32_bf16 v[108:111], v[160:163], v[192:195], v[108:111]
	v_mfma_f32_16x16x32_bf16 v[104:107], v[136:139], v[200:203], v[104:107]
	v_mfma_f32_16x16x32_bf16 v[100:103], v[160:163], v[200:203], v[100:103]
	s_barrier
	s_setprio 0
	s_add_i32 s27, 0, 0x1c000
	s_add_i32 s0, s26, s17
	v_add_u32_e32 v216, s27, v222
	v_lshl_add_u64 v[164:165], v[164:165], 0, s[12:13]
	s_mov_b32 m0, s0
	ds_read_b128 v[204:207], v216
	ds_read_b128 v[208:211], v216 offset:1024
	ds_read_b128 v[212:215], v216 offset:2048
	ds_read_b128 v[216:219], v216 offset:3072
	global_load_lds_dwordx4 v[164:165], off
	v_lshl_add_u64 v[164:165], v[166:167], 0, s[12:13]
	s_add_i32 m0, s0, 0x2000
	s_nop 0
	global_load_lds_dwordx4 v[164:165], off
	s_mov_b32 m0, s56
	s_nop 0
	global_load_lds_dwordx4 v142, s[100:101]
	s_waitcnt vmcnt(8)
	s_setprio 1
	s_barrier
	s_waitcnt lgkmcnt(0)
	v_mfma_f32_16x16x32_bf16 v[64:67], v[204:207], v[172:175], v[64:67]
	v_mfma_f32_16x16x32_bf16 v[60:63], v[212:215], v[172:175], v[60:63]
	v_mfma_f32_16x16x32_bf16 v[56:59], v[204:207], v[180:183], v[56:59]
	v_mfma_f32_16x16x32_bf16 v[52:55], v[212:215], v[180:183], v[52:55]
	v_mfma_f32_16x16x32_bf16 v[48:51], v[204:207], v[188:191], v[48:51]
	v_mfma_f32_16x16x32_bf16 v[44:47], v[212:215], v[188:191], v[44:47]
	v_mfma_f32_16x16x32_bf16 v[40:43], v[204:207], v[196:199], v[40:43]
	v_mfma_f32_16x16x32_bf16 v[36:39], v[212:215], v[196:199], v[36:39]
	v_mfma_f32_16x16x32_bf16 v[64:67], v[208:211], v[176:179], v[64:67]
	v_mfma_f32_16x16x32_bf16 v[60:63], v[216:219], v[176:179], v[60:63]
	v_mfma_f32_16x16x32_bf16 v[56:59], v[208:211], v[184:187], v[56:59]
	v_mfma_f32_16x16x32_bf16 v[52:55], v[216:219], v[184:187], v[52:55]
	v_mfma_f32_16x16x32_bf16 v[48:51], v[208:211], v[192:195], v[48:51]
	v_mfma_f32_16x16x32_bf16 v[44:47], v[216:219], v[192:195], v[44:47]
	v_mfma_f32_16x16x32_bf16 v[40:43], v[208:211], v[200:203], v[40:43]
	v_mfma_f32_16x16x32_bf16 v[36:39], v[216:219], v[200:203], v[36:39]
	s_barrier
	s_setprio 0
	s_mov_b32 m0, s59
	v_lshl_add_u64 v[164:165], v[168:169], 0, s[12:13]
	ds_read_b128 v[172:175], v224 offset:49152
	ds_read_b128 v[176:179], v224 offset:50176
	ds_read_b128 v[180:183], v224 offset:51200
	ds_read_b128 v[184:187], v224 offset:52224
	ds_read_b128 v[188:191], v224 offset:53248
	ds_read_b128 v[192:195], v224 offset:54272
	ds_read_b128 v[196:199], v224 offset:55296
	ds_read_b128 v[200:203], v224 offset:56320
	global_load_lds_dwordx4 v[164:165], off
	s_waitcnt vmcnt(10)
	s_setprio 1
	s_barrier
	s_waitcnt lgkmcnt(0)
	v_mfma_f32_16x16x32_bf16 v[96:99], v[132:135], v[172:175], v[96:99]
	v_mfma_f32_16x16x32_bf16 v[92:95], v[156:159], v[172:175], v[92:95]
	v_mfma_f32_16x16x32_bf16 v[88:91], v[132:135], v[180:183], v[88:91]
	v_mfma_f32_16x16x32_bf16 v[84:87], v[156:159], v[180:183], v[84:87]
	v_mfma_f32_16x16x32_bf16 v[80:83], v[132:135], v[188:191], v[80:83]
	v_mfma_f32_16x16x32_bf16 v[76:79], v[156:159], v[188:191], v[76:79]
	v_mfma_f32_16x16x32_bf16 v[72:75], v[132:135], v[196:199], v[72:75]
	v_mfma_f32_16x16x32_bf16 v[68:71], v[156:159], v[196:199], v[68:71]
	v_mfma_f32_16x16x32_bf16 v[96:99], v[136:139], v[176:179], v[96:99]
	v_mfma_f32_16x16x32_bf16 v[92:95], v[160:163], v[176:179], v[92:95]
	v_mfma_f32_16x16x32_bf16 v[88:91], v[136:139], v[184:187], v[88:91]
	v_mfma_f32_16x16x32_bf16 v[84:87], v[160:163], v[184:187], v[84:87]
	v_mfma_f32_16x16x32_bf16 v[80:83], v[136:139], v[192:195], v[80:83]
	v_mfma_f32_16x16x32_bf16 v[76:79], v[160:163], v[192:195], v[76:79]
	v_mfma_f32_16x16x32_bf16 v[72:75], v[136:139], v[200:203], v[72:75]
	v_mfma_f32_16x16x32_bf16 v[68:71], v[160:163], v[200:203], v[68:71]
	s_barrier
	s_setprio 0
	s_add_u32 s0, s30, 0xb0080
	s_addc_u32 s1, s31, 0
	s_add_i32 s26, s27, s17
	s_mov_b32 m0, s26
	s_nop 0
	global_load_lds_dwordx4 v26, s[0:1]
	s_add_i32 m0, s26, 0x2000
	s_nop 0
	global_load_lds_dwordx4 v144, s[0:1]
	v_lshl_add_u64 v[164:165], v[220:221], 0, s[12:13]
	s_mov_b32 m0, s68
	s_nop 0
	global_load_lds_dwordx4 v[164:165], off
	v_add_u32_e32 v160, 0x10000, v222
	ds_read_b128 v[132:135], v160
	ds_read_b128 v[136:139], v160 offset:1024
	ds_read_b128 v[156:159], v160 offset:2048
	ds_read_b128 v[160:163], v160 offset:3072
	s_waitcnt vmcnt(8)
	s_setprio 1
	s_barrier
	v_mfma_f32_16x16x32_bf16 v[32:35], v[204:207], v[172:175], v[32:35]
	v_mfma_f32_16x16x32_bf16 v[28:31], v[212:215], v[172:175], v[28:31]
	v_mfma_f32_16x16x32_bf16 v[22:25], v[204:207], v[180:183], v[22:25]
	v_mfma_f32_16x16x32_bf16 v[18:21], v[212:215], v[180:183], v[18:21]
	v_mfma_f32_16x16x32_bf16 v[14:17], v[204:207], v[188:191], v[14:17]
	v_mfma_f32_16x16x32_bf16 v[10:13], v[212:215], v[188:191], v[10:13]
	v_mfma_f32_16x16x32_bf16 v[6:9], v[204:207], v[196:199], v[6:9]
	v_mfma_f32_16x16x32_bf16 v[2:5], v[212:215], v[196:199], v[2:5]
	v_mfma_f32_16x16x32_bf16 v[32:35], v[208:211], v[176:179], v[32:35]
	v_mfma_f32_16x16x32_bf16 v[28:31], v[216:219], v[176:179], v[28:31]
	v_mfma_f32_16x16x32_bf16 v[22:25], v[208:211], v[184:187], v[22:25]
	v_mfma_f32_16x16x32_bf16 v[18:21], v[216:219], v[184:187], v[18:21]
	v_mfma_f32_16x16x32_bf16 v[14:17], v[208:211], v[192:195], v[14:17]
	v_mfma_f32_16x16x32_bf16 v[10:13], v[216:219], v[192:195], v[10:13]
	v_mfma_f32_16x16x32_bf16 v[6:9], v[208:211], v[200:203], v[6:9]
	v_mfma_f32_16x16x32_bf16 v[2:5], v[216:219], v[200:203], v[2:5]
	s_barrier
	s_setprio 0
	s_add_i32 s81, s81, 2
	s_add_u32 s44, s44, 0x100
	s_addc_u32 s45, s45, 0
	s_cmp_gt_u32 s81, 41
	s_mov_b64 s[26:27], s[28:29]
	s_cbranch_scc0 .LBB0_1156
	s_waitcnt lgkmcnt(0)
	s_min_i32 s0, s24, 0x100
	s_ashr_i32 s0, s0, 5
	s_ashr_i32 s1, s0, 31
	s_add_i32 s26, s24, 0xffffff00
	s_cmpk_lt_i32 s24, 0x100
	s_cselect_b32 s26, s24, s26
	s_cselect_b32 s28, 0, s51
	s_cselect_b32 s29, 0, s50
	s_ashr_i32 s27, s26, 31
	s_lshl_b64 s[26:27], s[26:27], 19
	v_lshl_add_u64 v[132:133], s[26:27], 0, v[146:147]
	s_add_u32 s26, s20, s29
	v_lshl_or_b32 v166, s25, 8, v223
	s_addc_u32 s27, s21, s28
	s_ashr_i32 s25, s24, 31
	s_lshl_b64 s[28:29], s[24:25], 19
	v_lshl_add_u64 v[178:179], v[148:149], 0, s[28:29]
	s_lshl_b64 s[24:25], s[24:25], 10
	s_mul_i32 s28, s0, 0x9000
	v_ashrrev_i32_e32 v167, 31, v166
	s_mul_hi_i32 s29, s0, 0x9000
	s_add_u32 s28, s36, s28
	s_addc_u32 s29, s37, s29
	v_lshlrev_b64 v[180:181], 2, v[166:167]
	v_lshl_add_u64 v[156:157], s[28:29], 0, v[180:181]
	v_lshl_add_u64 v[168:169], v[132:133], 0, v[166:167]
	v_lshl_add_u64 v[182:183], v[132:133], 1, s[26:27]
	global_load_dwordx4 v[132:135], v[156:157], off offset:16
	global_load_dwordx4 v[136:139], v[156:157], off
	s_lshl_b64 s[0:1], s[0:1], 12
	s_add_u32 s28, s57, s0
	s_addc_u32 s29, s58, s1
	v_lshl_add_u64 v[180:181], s[28:29], 0, v[180:181]
	v_lshl_add_u64 v[196:197], v[168:169], 1, s[26:27]
	v_add_co_u32_e32 v210, vcc, s65, v196
	s_mov_b32 s1, 0x20000
	s_nop 0
	v_addc_co_u32_e32 v211, vcc, 0, v197, vcc
	v_add_co_u32_e32 v184, vcc, s1, v196
	s_mov_b32 s26, 0x30000
	s_nop 0
	v_addc_co_u32_e32 v185, vcc, 0, v197, vcc
	v_add_co_u32_e32 v188, vcc, s26, v196
	v_lshlrev_b64 v[166:167], 1, v[166:167]
	s_nop 0
	v_addc_co_u32_e32 v189, vcc, 0, v197, vcc
	v_lshl_add_u64 v[178:179], v[178:179], 0, v[166:167]
	v_lshl_add_u64 v[182:183], v[182:183], 0, v[166:167]
	s_mov_b32 s0, 0x8000
	s_mov_b32 s27, 0x80000
	s_mov_b32 s28, 0x90000
	s_waitcnt vmcnt(0)
	v_pk_mul_f32 v[172:173], v[134:135], 0.5 op_sel_hi:[1,0]
	v_pk_mul_f32 v[176:177], v[138:139], 0.5 op_sel_hi:[1,0]
	v_pk_mul_f32 v[174:175], v[136:137], 0.5 op_sel_hi:[1,0]
	v_pk_mul_f32 v[164:165], v[132:133], 0.5 op_sel_hi:[1,0]
	global_load_dwordx4 v[132:135], v[156:157], off offset:528
	global_load_dwordx4 v[136:139], v[156:157], off offset:512
	s_waitcnt vmcnt(0)
	v_pk_mul_f32 v[158:159], v[134:135], 0.5 op_sel_hi:[1,0]
	v_pk_mul_f32 v[162:163], v[138:139], 0.5 op_sel_hi:[1,0]
	v_pk_mul_f32 v[160:161], v[136:137], 0.5 op_sel_hi:[1,0]
	v_pk_mul_f32 v[156:157], v[132:133], 0.5 op_sel_hi:[1,0]
	global_load_dwordx4 v[132:135], v[180:181], off offset:16
	global_load_dwordx4 v[136:139], v[180:181], off
	global_load_dwordx4 v[190:193], v[196:197], off offset:2048
	global_load_dwordx4 v[198:201], v[210:211], off offset:2048
	global_load_dwordx4 v[202:205], v[184:185], off offset:2048
	global_load_dwordx4 v[206:209], v[188:189], off offset:2048
	s_waitcnt vmcnt(0)
	v_lshlrev_b32_e32 v166, 16, v190
	v_and_b32_e32 v167, 0xffff0000, v190
	v_lshlrev_b32_e32 v168, 16, v191
	v_and_b32_e32 v169, 0xffff0000, v191
	v_lshlrev_b32_e32 v186, 16, v192
	v_and_b32_e32 v187, 0xffff0000, v192
	v_lshlrev_b32_e32 v190, 16, v193
	v_and_b32_e32 v191, 0xffff0000, v193
	v_pk_fma_f32 v[130:131], v[130:131], v[176:177], v[168:169]
	v_pk_fma_f32 v[128:129], v[128:129], v[174:175], v[166:167]
	v_pk_fma_f32 v[126:127], v[126:127], v[172:173], v[190:191]
	v_pk_fma_f32 v[124:125], v[124:125], v[164:165], v[186:187]
	v_cvt_pk_bf16_f32 v190, v128, v129
	v_cvt_pk_bf16_f32 v191, v130, v131
	v_cvt_pk_bf16_f32 v192, v124, v125
	v_cvt_pk_bf16_f32 v193, v126, v127
	v_lshlrev_b32_e32 v130, 16, v190
	v_and_b32_e32 v131, 0xffff0000, v190
	v_lshlrev_b32_e32 v128, 16, v191
	v_and_b32_e32 v129, 0xffff0000, v191
	v_lshlrev_b32_e32 v126, 16, v192
	v_and_b32_e32 v127, 0xffff0000, v192
	v_lshlrev_b32_e32 v124, 16, v193
	v_and_b32_e32 v125, 0xffff0000, v193
	v_lshlrev_b32_e32 v212, 16, v200
	v_and_b32_e32 v213, 0xffff0000, v200
	v_lshlrev_b32_e32 v200, 16, v201
	v_and_b32_e32 v201, 0xffff0000, v201
	global_store_dwordx4 v[182:183], v[190:193], off offset:2048
	v_pk_mul_f32 v[166:167], v[138:139], v[128:129]
	v_pk_mul_f32 v[168:169], v[136:137], v[130:131]
	v_pk_mul_f32 v[186:187], v[134:135], v[124:125]
	v_pk_mul_f32 v[192:193], v[132:133], v[126:127]
	v_lshlrev_b32_e32 v194, 16, v198
	v_and_b32_e32 v195, 0xffff0000, v198
	v_lshlrev_b32_e32 v198, 16, v199
	v_and_b32_e32 v199, 0xffff0000, v199
	v_cvt_pk_bf16_f32 v190, v168, v169
	v_cvt_pk_bf16_f32 v191, v166, v167
	v_cvt_pk_bf16_f32 v192, v192, v193
	v_cvt_pk_bf16_f32 v193, v186, v187
	v_pk_fma_f32 v[118:119], v[118:119], v[172:173], v[200:201]
	v_pk_fma_f32 v[116:117], v[116:117], v[164:165], v[212:213]
	global_store_dwordx4 v[178:179], v[190:193], off
	v_pk_fma_f32 v[122:123], v[122:123], v[176:177], v[198:199]
	v_pk_fma_f32 v[120:121], v[120:121], v[174:175], v[194:195]
	v_cvt_pk_bf16_f32 v192, v116, v117
	v_cvt_pk_bf16_f32 v193, v118, v119
	v_add_co_u32_e32 v186, vcc, s65, v182
	v_cvt_pk_bf16_f32 v190, v120, v121
	v_cvt_pk_bf16_f32 v191, v122, v123
	v_addc_co_u32_e32 v187, vcc, 0, v183, vcc
	v_lshlrev_b32_e32 v118, 16, v192
	v_and_b32_e32 v119, 0xffff0000, v192
	v_lshlrev_b32_e32 v116, 16, v193
	v_and_b32_e32 v117, 0xffff0000, v193
	global_store_dwordx4 v[186:187], v[190:193], off offset:2048
	v_lshlrev_b32_e32 v122, 16, v190
	v_and_b32_e32 v123, 0xffff0000, v190
	v_lshlrev_b32_e32 v120, 16, v191
	v_and_b32_e32 v121, 0xffff0000, v191
	v_pk_mul_f32 v[190:191], v[134:135], v[116:117]
	v_pk_mul_f32 v[194:195], v[132:133], v[118:119]
	v_pk_mul_f32 v[166:167], v[138:139], v[120:121]
	v_pk_mul_f32 v[168:169], v[136:137], v[122:123]
	v_cvt_pk_bf16_f32 v194, v194, v195
	v_cvt_pk_bf16_f32 v195, v190, v191
	v_add_co_u32_e32 v190, vcc, s0, v178
	v_cvt_pk_bf16_f32 v192, v168, v169
	v_cvt_pk_bf16_f32 v193, v166, v167
	v_addc_co_u32_e32 v191, vcc, 0, v179, vcc
	global_store_dwordx4 v[190:191], v[192:195], off
	v_lshlrev_b32_e32 v198, 16, v204
	v_and_b32_e32 v199, 0xffff0000, v204
	v_add_co_u32_e32 v192, vcc, s27, v196
	v_lshlrev_b32_e32 v200, 16, v205
	s_nop 0
	v_addc_co_u32_e32 v193, vcc, 0, v197, vcc
	v_add_co_u32_e32 v194, vcc, s28, v196
	v_and_b32_e32 v201, 0xffff0000, v205
	global_load_dwordx4 v[212:215], v[192:193], off offset:2048
	v_addc_co_u32_e32 v195, vcc, 0, v197, vcc
	v_lshlrev_b32_e32 v166, 16, v202
	v_and_b32_e32 v167, 0xffff0000, v202
	v_lshlrev_b32_e32 v168, 16, v203
	v_and_b32_e32 v169, 0xffff0000, v203
	v_pk_fma_f32 v[110:111], v[110:111], v[172:173], v[200:201]
	v_pk_fma_f32 v[108:109], v[108:109], v[164:165], v[198:199]
	v_pk_fma_f32 v[114:115], v[114:115], v[176:177], v[168:169]
	v_pk_fma_f32 v[112:113], v[112:113], v[174:175], v[166:167]
	v_cvt_pk_bf16_f32 v202, v108, v109
	v_cvt_pk_bf16_f32 v203, v110, v111
	v_add_co_u32_e32 v198, vcc, s1, v182
	global_load_dwordx4 v[216:219], v[194:195], off offset:2048
	v_cvt_pk_bf16_f32 v200, v112, v113
	v_cvt_pk_bf16_f32 v201, v114, v115
	v_addc_co_u32_e32 v199, vcc, 0, v183, vcc
	v_lshlrev_b32_e32 v110, 16, v202
	v_and_b32_e32 v111, 0xffff0000, v202
	v_lshlrev_b32_e32 v108, 16, v203
	v_and_b32_e32 v109, 0xffff0000, v203
	global_store_dwordx4 v[198:199], v[200:203], off offset:2048
	v_lshlrev_b32_e32 v114, 16, v200
	v_and_b32_e32 v115, 0xffff0000, v200
	v_lshlrev_b32_e32 v112, 16, v201
	v_and_b32_e32 v113, 0xffff0000, v201
	v_pk_mul_f32 v[200:201], v[134:135], v[108:109]
	v_pk_mul_f32 v[204:205], v[132:133], v[110:111]
	v_lshlrev_b32_e32 v234, 16, v208
	v_and_b32_e32 v235, 0xffff0000, v208
	v_lshlrev_b32_e32 v208, 16, v209
	v_and_b32_e32 v209, 0xffff0000, v209
	v_pk_mul_f32 v[166:167], v[138:139], v[112:113]
	v_pk_mul_f32 v[168:169], v[136:137], v[114:115]
	v_cvt_pk_bf16_f32 v204, v204, v205
	v_cvt_pk_bf16_f32 v205, v200, v201
	v_add_co_u32_e32 v200, vcc, s65, v178
	v_lshlrev_b32_e32 v220, 16, v206
	v_and_b32_e32 v221, 0xffff0000, v206
	v_lshlrev_b32_e32 v206, 16, v207
	v_and_b32_e32 v207, 0xffff0000, v207
	v_cvt_pk_bf16_f32 v202, v168, v169
	v_cvt_pk_bf16_f32 v203, v166, v167
	v_addc_co_u32_e32 v201, vcc, 0, v179, vcc
	v_pk_fma_f32 v[102:103], v[102:103], v[172:173], v[208:209]
	v_pk_fma_f32 v[100:101], v[100:101], v[164:165], v[234:235]
	global_store_dwordx4 v[200:201], v[202:205], off
	v_pk_fma_f32 v[106:107], v[106:107], v[176:177], v[206:207]
	v_pk_fma_f32 v[104:105], v[104:105], v[174:175], v[220:221]
	v_cvt_pk_bf16_f32 v206, v100, v101
	v_cvt_pk_bf16_f32 v207, v102, v103
	v_add_co_u32_e32 v202, vcc, s26, v182
	v_cvt_pk_bf16_f32 v204, v104, v105
	v_cvt_pk_bf16_f32 v205, v106, v107
	v_addc_co_u32_e32 v203, vcc, 0, v183, vcc
	v_lshlrev_b32_e32 v102, 16, v206
	v_and_b32_e32 v103, 0xffff0000, v206
	v_lshlrev_b32_e32 v100, 16, v207
	v_and_b32_e32 v101, 0xffff0000, v207
	global_store_dwordx4 v[202:203], v[204:207], off offset:2048
	v_lshlrev_b32_e32 v106, 16, v204
	v_and_b32_e32 v107, 0xffff0000, v204
	v_lshlrev_b32_e32 v104, 16, v205
	v_and_b32_e32 v105, 0xffff0000, v205
	v_pk_mul_f32 v[204:205], v[134:135], v[100:101]
	v_pk_mul_f32 v[208:209], v[132:133], v[102:103]
	s_mov_b32 s0, 0x18000
	v_pk_mul_f32 v[166:167], v[138:139], v[104:105]
	v_pk_mul_f32 v[168:169], v[136:137], v[106:107]
	v_cvt_pk_bf16_f32 v208, v208, v209
	v_cvt_pk_bf16_f32 v209, v204, v205
	v_add_co_u32_e32 v204, vcc, s0, v178
	v_cvt_pk_bf16_f32 v206, v168, v169
	v_cvt_pk_bf16_f32 v207, v166, v167
	v_addc_co_u32_e32 v205, vcc, 0, v179, vcc
	global_store_dwordx4 v[204:205], v[206:209], off
	s_mov_b32 s0, 0xb0000
	s_waitcnt vmcnt(0)
	v_lshlrev_b32_e32 v166, 16, v212
	v_add_co_u32_e32 v206, vcc, s76, v196
	v_and_b32_e32 v167, 0xffff0000, v212
	s_nop 0
	v_addc_co_u32_e32 v207, vcc, 0, v197, vcc
	global_load_dwordx4 v[238:241], v[206:207], off offset:2048
	v_add_co_u32_e32 v208, vcc, s0, v196
	v_lshlrev_b32_e32 v168, 16, v213
	s_nop 0
	v_addc_co_u32_e32 v209, vcc, 0, v197, vcc
	global_load_dwordx4 v[242:245], v[208:209], off offset:2048
	v_and_b32_e32 v169, 0xffff0000, v213
	v_lshlrev_b32_e32 v212, 16, v214
	v_and_b32_e32 v213, 0xffff0000, v214
	v_lshlrev_b32_e32 v214, 16, v215
	v_and_b32_e32 v215, 0xffff0000, v215
	v_pk_fma_f32 v[94:95], v[94:95], v[172:173], v[214:215]
	v_pk_fma_f32 v[92:93], v[92:93], v[164:165], v[212:213]
	v_lshlrev_b32_e32 v220, 16, v216
	v_and_b32_e32 v221, 0xffff0000, v216
	v_lshlrev_b32_e32 v234, 16, v217
	v_and_b32_e32 v235, 0xffff0000, v217
	v_pk_fma_f32 v[98:99], v[98:99], v[176:177], v[168:169]
	v_pk_fma_f32 v[96:97], v[96:97], v[174:175], v[166:167]
	v_cvt_pk_bf16_f32 v216, v92, v93
	v_cvt_pk_bf16_f32 v217, v94, v95
	v_add_co_u32_e32 v212, vcc, s27, v182
	v_cvt_pk_bf16_f32 v214, v96, v97
	v_cvt_pk_bf16_f32 v215, v98, v99
	v_addc_co_u32_e32 v213, vcc, 0, v183, vcc
	v_lshlrev_b32_e32 v94, 16, v216
	v_and_b32_e32 v95, 0xffff0000, v216
	v_lshlrev_b32_e32 v92, 16, v217
	v_and_b32_e32 v93, 0xffff0000, v217
	v_lshlrev_b32_e32 v246, 16, v218
	v_and_b32_e32 v247, 0xffff0000, v218
	v_lshlrev_b32_e32 v248, 16, v219
	v_and_b32_e32 v249, 0xffff0000, v219
	global_store_dwordx4 v[212:213], v[214:217], off offset:2048
	v_lshlrev_b32_e32 v98, 16, v214
	v_and_b32_e32 v99, 0xffff0000, v214
	v_lshlrev_b32_e32 v96, 16, v215
	v_and_b32_e32 v97, 0xffff0000, v215
	v_pk_mul_f32 v[214:215], v[134:135], v[92:93]
	v_pk_mul_f32 v[218:219], v[132:133], v[94:95]
	s_mov_b32 s1, 0x40000
	v_pk_mul_f32 v[166:167], v[138:139], v[96:97]
	v_pk_mul_f32 v[168:169], v[136:137], v[98:99]
	v_cvt_pk_bf16_f32 v218, v218, v219
	v_cvt_pk_bf16_f32 v219, v214, v215
	v_add_co_u32_e32 v214, vcc, s1, v178
	v_cvt_pk_bf16_f32 v216, v168, v169
	v_cvt_pk_bf16_f32 v217, v166, v167
	v_addc_co_u32_e32 v215, vcc, 0, v179, vcc
	v_pk_fma_f32 v[86:87], v[86:87], v[172:173], v[248:249]
	global_store_dwordx4 v[214:215], v[216:219], off
	v_pk_fma_f32 v[90:91], v[90:91], v[176:177], v[234:235]
	v_pk_fma_f32 v[88:89], v[88:89], v[174:175], v[220:221]
	v_pk_fma_f32 v[84:85], v[84:85], v[164:165], v[246:247]
	v_cvt_pk_bf16_f32 v221, v86, v87
	v_add_co_u32_e32 v216, vcc, s28, v182
	v_cvt_pk_bf16_f32 v218, v88, v89
	v_cvt_pk_bf16_f32 v219, v90, v91
	v_cvt_pk_bf16_f32 v220, v84, v85
	v_addc_co_u32_e32 v217, vcc, 0, v183, vcc
	v_lshlrev_b32_e32 v84, 16, v221
	v_and_b32_e32 v85, 0xffff0000, v221
	global_store_dwordx4 v[216:217], v[218:221], off offset:2048
	v_lshlrev_b32_e32 v90, 16, v218
	v_and_b32_e32 v91, 0xffff0000, v218
	v_lshlrev_b32_e32 v88, 16, v219
	v_and_b32_e32 v89, 0xffff0000, v219
	v_lshlrev_b32_e32 v86, 16, v220
	v_and_b32_e32 v87, 0xffff0000, v220
	v_pk_mul_f32 v[218:219], v[134:135], v[84:85]
	s_mov_b32 s1, 0x48000
	v_pk_mul_f32 v[166:167], v[138:139], v[88:89]
	v_pk_mul_f32 v[168:169], v[136:137], v[90:91]
	v_pk_mul_f32 v[220:221], v[132:133], v[86:87]
	v_cvt_pk_bf16_f32 v249, v218, v219
	v_add_co_u32_e32 v218, vcc, s1, v178
	v_cvt_pk_bf16_f32 v246, v168, v169
	v_cvt_pk_bf16_f32 v247, v166, v167
	v_cvt_pk_bf16_f32 v248, v220, v221
	v_addc_co_u32_e32 v219, vcc, 0, v179, vcc
	global_store_dwordx4 v[218:219], v[246:249], off
	global_load_dwordx4 v[246:249], v[196:197], off offset:2304
	s_nop 0
	global_load_dwordx4 v[250:253], v[210:211], off offset:2304
	s_waitcnt vmcnt(0)
	v_lshlrev_b32_e32 v196, 16, v240
	v_and_b32_e32 v197, 0xffff0000, v240
	v_lshlrev_b32_e32 v210, 16, v241
	v_and_b32_e32 v211, 0xffff0000, v241
	v_lshlrev_b32_e32 v166, 16, v238
	v_and_b32_e32 v167, 0xffff0000, v238
	v_lshlrev_b32_e32 v168, 16, v239
	v_and_b32_e32 v169, 0xffff0000, v239
	v_pk_fma_f32 v[78:79], v[78:79], v[172:173], v[210:211]
	v_pk_fma_f32 v[76:77], v[76:77], v[164:165], v[196:197]
	v_pk_fma_f32 v[82:83], v[82:83], v[176:177], v[168:169]
	v_pk_fma_f32 v[80:81], v[80:81], v[174:175], v[166:167]
	v_cvt_pk_bf16_f32 v240, v76, v77
	v_cvt_pk_bf16_f32 v241, v78, v79
	v_add_co_u32_e32 v196, vcc, s76, v182
	v_cvt_pk_bf16_f32 v238, v80, v81
	v_cvt_pk_bf16_f32 v239, v82, v83
	v_addc_co_u32_e32 v197, vcc, 0, v183, vcc
	v_lshlrev_b32_e32 v78, 16, v240
	v_and_b32_e32 v79, 0xffff0000, v240
	v_lshlrev_b32_e32 v76, 16, v241
	v_and_b32_e32 v77, 0xffff0000, v241
	global_store_dwordx4 v[196:197], v[238:241], off offset:2048
	v_lshlrev_b32_e32 v80, 16, v239
	v_and_b32_e32 v81, 0xffff0000, v239
	v_pk_mul_f32 v[210:211], v[134:135], v[76:77]
	v_pk_mul_f32 v[240:241], v[132:133], v[78:79]
	v_lshlrev_b32_e32 v220, 16, v242
	v_and_b32_e32 v221, 0xffff0000, v242
	v_lshlrev_b32_e32 v234, 16, v243
	v_and_b32_e32 v235, 0xffff0000, v243
	v_lshlrev_b32_e32 v242, 16, v244
	v_and_b32_e32 v243, 0xffff0000, v244
	v_lshlrev_b32_e32 v244, 16, v245
	v_and_b32_e32 v245, 0xffff0000, v245
	v_pk_mul_f32 v[166:167], v[138:139], v[80:81]
	v_cvt_pk_bf16_f32 v240, v240, v241
	v_cvt_pk_bf16_f32 v241, v210, v211
	v_add_co_u32_e32 v210, vcc, s77, v178
	v_lshlrev_b32_e32 v82, 16, v238
	v_and_b32_e32 v83, 0xffff0000, v238
	v_cvt_pk_bf16_f32 v239, v166, v167
	v_addc_co_u32_e32 v211, vcc, 0, v179, vcc
	v_pk_fma_f32 v[74:75], v[74:75], v[176:177], v[234:235]
	v_pk_fma_f32 v[72:73], v[72:73], v[174:175], v[220:221]
	v_pk_fma_f32 v[166:167], v[70:71], v[172:173], v[244:245]
	v_pk_fma_f32 v[70:71], v[68:69], v[164:165], v[242:243]
	v_pk_mul_f32 v[168:169], v[136:137], v[82:83]
	v_cvt_pk_bf16_f32 v68, v72, v73
	v_cvt_pk_bf16_f32 v69, v74, v75
	v_cvt_pk_bf16_f32 v70, v70, v71
	v_cvt_pk_bf16_f32 v71, v166, v167
	v_add_co_u32_e32 v220, vcc, s0, v182
	v_cvt_pk_bf16_f32 v238, v168, v169
	s_nop 0
	v_addc_co_u32_e32 v221, vcc, 0, v183, vcc
	v_lshlrev_b32_e32 v176, 16, v68
	v_and_b32_e32 v177, 0xffff0000, v68
	v_lshlrev_b32_e32 v174, 16, v69
	v_and_b32_e32 v175, 0xffff0000, v69
	v_lshlrev_b32_e32 v172, 16, v70
	v_and_b32_e32 v173, 0xffff0000, v70
	v_lshlrev_b32_e32 v164, 16, v71
	v_and_b32_e32 v165, 0xffff0000, v71
	s_mov_b32 s0, 0x58000
	global_store_dwordx4 v[210:211], v[238:241], off
	global_store_dwordx4 v[220:221], v[68:71], off offset:2048
	v_pk_mul_f32 v[72:73], v[134:135], v[164:165]
	v_pk_mul_f32 v[74:75], v[132:133], v[172:173]
	v_pk_mul_f32 v[70:71], v[138:139], v[174:175]
	v_pk_mul_f32 v[68:69], v[136:137], v[176:177]
	v_add_co_u32_e32 v132, vcc, s0, v178
	v_cvt_pk_bf16_f32 v68, v68, v69
	v_cvt_pk_bf16_f32 v69, v70, v71
	v_cvt_pk_bf16_f32 v70, v74, v75
	v_cvt_pk_bf16_f32 v71, v72, v73
	v_addc_co_u32_e32 v133, vcc, 0, v179, vcc
	global_store_dwordx4 v[132:133], v[68:71], off
	global_load_dwordx4 v[134:137], v[184:185], off offset:2304
	global_load_dwordx4 v[238:241], v[188:189], off offset:2304
	s_nop 0
	global_load_dwordx4 v[68:71], v[180:181], off offset:528
	global_load_dwordx4 v[72:75], v[180:181], off offset:512
	v_lshlrev_b32_e32 v138, 16, v246
	v_and_b32_e32 v139, 0xffff0000, v246
	v_lshlrev_b32_e32 v166, 16, v247
	v_and_b32_e32 v167, 0xffff0000, v247
	v_lshlrev_b32_e32 v168, 16, v248
	v_and_b32_e32 v169, 0xffff0000, v248
	v_lshlrev_b32_e32 v180, 16, v249
	v_and_b32_e32 v181, 0xffff0000, v249
	v_pk_fma_f32 v[66:67], v[66:67], v[162:163], v[166:167]
	v_pk_fma_f32 v[64:65], v[64:65], v[160:161], v[138:139]
	v_pk_fma_f32 v[62:63], v[62:63], v[158:159], v[180:181]
	v_pk_fma_f32 v[60:61], v[60:61], v[156:157], v[168:169]
	v_cvt_pk_bf16_f32 v242, v64, v65
	v_cvt_pk_bf16_f32 v243, v66, v67
	v_cvt_pk_bf16_f32 v244, v60, v61
	v_cvt_pk_bf16_f32 v245, v62, v63
	v_lshlrev_b32_e32 v66, 16, v242
	v_and_b32_e32 v67, 0xffff0000, v242
	v_lshlrev_b32_e32 v64, 16, v243
	v_and_b32_e32 v65, 0xffff0000, v243
	v_lshlrev_b32_e32 v62, 16, v244
	v_and_b32_e32 v63, 0xffff0000, v244
	v_lshlrev_b32_e32 v60, 16, v245
	v_and_b32_e32 v61, 0xffff0000, v245
	v_lshlrev_b32_e32 v184, 16, v250
	v_and_b32_e32 v185, 0xffff0000, v250
	v_lshlrev_b32_e32 v188, 16, v251
	v_and_b32_e32 v189, 0xffff0000, v251
	v_lshlrev_b32_e32 v234, 16, v252
	v_and_b32_e32 v235, 0xffff0000, v252
	v_lshlrev_b32_e32 v246, 16, v253
	v_and_b32_e32 v247, 0xffff0000, v253
	global_store_dwordx4 v[182:183], v[242:245], off offset:2304
	v_pk_fma_f32 v[58:59], v[58:59], v[162:163], v[188:189]
	v_pk_fma_f32 v[56:57], v[56:57], v[160:161], v[184:185]
	v_pk_fma_f32 v[54:55], v[54:55], v[158:159], v[246:247]
	v_pk_fma_f32 v[52:53], v[52:53], v[156:157], v[234:235]
	s_waitcnt vmcnt(0)
	v_lshlrev_b32_e32 v188, 16, v240
	v_pk_mul_f32 v[168:169], v[70:71], v[60:61]
	v_pk_mul_f32 v[138:139], v[74:75], v[64:65]
	v_pk_mul_f32 v[166:167], v[72:73], v[66:67]
	v_pk_mul_f32 v[182:183], v[68:69], v[62:63]
	v_cvt_pk_bf16_f32 v180, v166, v167
	v_cvt_pk_bf16_f32 v181, v138, v139
	v_cvt_pk_bf16_f32 v182, v182, v183
	v_cvt_pk_bf16_f32 v183, v168, v169
	global_store_dwordx4 v[178:179], v[180:183], off offset:256
	v_cvt_pk_bf16_f32 v178, v56, v57
	v_cvt_pk_bf16_f32 v179, v58, v59
	v_cvt_pk_bf16_f32 v180, v52, v53
	v_cvt_pk_bf16_f32 v181, v54, v55
	v_lshlrev_b32_e32 v58, 16, v178
	v_and_b32_e32 v59, 0xffff0000, v178
	v_lshlrev_b32_e32 v56, 16, v179
	v_and_b32_e32 v57, 0xffff0000, v179
	v_lshlrev_b32_e32 v54, 16, v180
	v_and_b32_e32 v55, 0xffff0000, v180
	v_lshlrev_b32_e32 v52, 16, v181
	v_and_b32_e32 v53, 0xffff0000, v181
	global_store_dwordx4 v[186:187], v[178:181], off offset:2304
	v_pk_mul_f32 v[138:139], v[74:75], v[56:57]
	v_pk_mul_f32 v[166:167], v[72:73], v[58:59]
	v_pk_mul_f32 v[168:169], v[70:71], v[52:53]
	v_pk_mul_f32 v[180:181], v[68:69], v[54:55]
	v_cvt_pk_bf16_f32 v178, v166, v167
	v_cvt_pk_bf16_f32 v179, v138, v139
	v_cvt_pk_bf16_f32 v180, v180, v181
	v_cvt_pk_bf16_f32 v181, v168, v169
	v_lshlrev_b32_e32 v138, 16, v134
	v_and_b32_e32 v139, 0xffff0000, v134
	v_lshlrev_b32_e32 v134, 16, v135
	v_and_b32_e32 v135, 0xffff0000, v135
	v_lshlrev_b32_e32 v166, 16, v136
	v_and_b32_e32 v167, 0xffff0000, v136
	v_lshlrev_b32_e32 v136, 16, v137
	v_and_b32_e32 v137, 0xffff0000, v137
	global_store_dwordx4 v[190:191], v[178:181], off offset:256
	v_pk_fma_f32 v[50:51], v[50:51], v[162:163], v[134:135]
	v_pk_fma_f32 v[48:49], v[48:49], v[160:161], v[138:139]
	v_pk_fma_f32 v[46:47], v[46:47], v[158:159], v[136:137]
	v_pk_fma_f32 v[44:45], v[44:45], v[156:157], v[166:167]
	global_load_dwordx4 v[178:181], v[192:193], off offset:2304
	global_load_dwordx4 v[182:185], v[194:195], off offset:2304
	v_cvt_pk_bf16_f32 v134, v48, v49
	v_cvt_pk_bf16_f32 v135, v50, v51
	v_cvt_pk_bf16_f32 v136, v44, v45
	v_cvt_pk_bf16_f32 v137, v46, v47
	v_lshlrev_b32_e32 v50, 16, v134
	v_and_b32_e32 v51, 0xffff0000, v134
	v_lshlrev_b32_e32 v48, 16, v135
	v_and_b32_e32 v49, 0xffff0000, v135
	v_lshlrev_b32_e32 v46, 16, v136
	v_and_b32_e32 v47, 0xffff0000, v136
	v_lshlrev_b32_e32 v44, 16, v137
	v_and_b32_e32 v45, 0xffff0000, v137
	v_lshlrev_b32_e32 v168, 16, v238
	v_and_b32_e32 v169, 0xffff0000, v238
	v_lshlrev_b32_e32 v186, 16, v239
	v_and_b32_e32 v187, 0xffff0000, v239
	v_and_b32_e32 v189, 0xffff0000, v240
	v_lshlrev_b32_e32 v190, 16, v241
	v_and_b32_e32 v191, 0xffff0000, v241
	global_store_dwordx4 v[198:199], v[134:137], off offset:2304
	v_pk_mul_f32 v[138:139], v[70:71], v[44:45]
	v_pk_mul_f32 v[166:167], v[68:69], v[46:47]
	v_pk_mul_f32 v[136:137], v[74:75], v[48:49]
	v_pk_mul_f32 v[134:135], v[72:73], v[50:51]
	v_pk_fma_f32 v[42:43], v[42:43], v[162:163], v[186:187]
	v_cvt_pk_bf16_f32 v134, v134, v135
	v_cvt_pk_bf16_f32 v135, v136, v137
	v_cvt_pk_bf16_f32 v136, v166, v167
	v_cvt_pk_bf16_f32 v137, v138, v139
	v_pk_fma_f32 v[40:41], v[40:41], v[160:161], v[168:169]
	v_pk_fma_f32 v[38:39], v[38:39], v[158:159], v[190:191]
	v_pk_fma_f32 v[36:37], v[36:37], v[156:157], v[188:189]
	global_store_dwordx4 v[200:201], v[134:137], off offset:256
	v_mul_f32_e32 v67, v67, v67
	v_mul_f32_e32 v65, v65, v65
	v_cvt_pk_bf16_f32 v134, v40, v41
	v_cvt_pk_bf16_f32 v135, v42, v43
	v_cvt_pk_bf16_f32 v136, v36, v37
	v_cvt_pk_bf16_f32 v137, v38, v39
	v_lshlrev_b32_e32 v42, 16, v134
	v_and_b32_e32 v43, 0xffff0000, v134
	v_lshlrev_b32_e32 v40, 16, v135
	v_and_b32_e32 v41, 0xffff0000, v135
	v_lshlrev_b32_e32 v38, 16, v136
	v_and_b32_e32 v39, 0xffff0000, v136
	v_lshlrev_b32_e32 v36, 16, v137
	v_and_b32_e32 v37, 0xffff0000, v137
	global_store_dwordx4 v[202:203], v[134:137], off offset:2304
	v_pk_mul_f32 v[138:139], v[70:71], v[36:37]
	v_pk_mul_f32 v[166:167], v[68:69], v[38:39]
	v_pk_mul_f32 v[136:137], v[74:75], v[40:41]
	v_pk_mul_f32 v[134:135], v[72:73], v[42:43]
	v_fmac_f32_e32 v67, v66, v66
	v_cvt_pk_bf16_f32 v134, v134, v135
	v_cvt_pk_bf16_f32 v135, v136, v137
	v_cvt_pk_bf16_f32 v136, v166, v167
	v_cvt_pk_bf16_f32 v137, v138, v139
	global_store_dwordx4 v[204:205], v[134:137], off offset:256
	global_load_dwordx4 v[134:137], v[206:207], off offset:2304
	s_nop 0
	global_load_dwordx4 v[186:189], v[208:209], off offset:2304
	v_fmac_f32_e32 v65, v64, v64
	v_mul_f32_e32 v63, v63, v63
	v_mul_f32_e32 v61, v61, v61
	v_add_f32_e32 v64, v67, v65
	v_fmac_f32_e32 v63, v62, v62
	v_fmac_f32_e32 v61, v60, v60
	v_add_f32_e32 v60, v63, v61
	s_waitcnt vmcnt(0)
	v_lshlrev_b32_e32 v138, 16, v178
	v_and_b32_e32 v139, 0xffff0000, v178
	v_lshlrev_b32_e32 v166, 16, v179
	v_and_b32_e32 v167, 0xffff0000, v179
	v_lshlrev_b32_e32 v168, 16, v180
	v_and_b32_e32 v169, 0xffff0000, v180
	v_lshlrev_b32_e32 v178, 16, v181
	v_and_b32_e32 v179, 0xffff0000, v181
	v_pk_fma_f32 v[34:35], v[34:35], v[162:163], v[166:167]
	v_pk_fma_f32 v[32:33], v[32:33], v[160:161], v[138:139]
	v_pk_fma_f32 v[30:31], v[30:31], v[158:159], v[178:179]
	v_pk_fma_f32 v[28:29], v[28:29], v[156:157], v[168:169]
	v_cvt_pk_bf16_f32 v178, v32, v33
	v_cvt_pk_bf16_f32 v179, v34, v35
	v_cvt_pk_bf16_f32 v180, v28, v29
	v_cvt_pk_bf16_f32 v181, v30, v31
	v_lshlrev_b32_e32 v34, 16, v178
	v_and_b32_e32 v35, 0xffff0000, v178
	v_lshlrev_b32_e32 v32, 16, v179
	v_and_b32_e32 v33, 0xffff0000, v179
	v_lshlrev_b32_e32 v30, 16, v180
	v_and_b32_e32 v31, 0xffff0000, v180
	v_lshlrev_b32_e32 v28, 16, v181
	v_and_b32_e32 v29, 0xffff0000, v181
	v_lshlrev_b32_e32 v190, 16, v182
	v_and_b32_e32 v191, 0xffff0000, v182
	v_lshlrev_b32_e32 v182, 16, v183
	v_and_b32_e32 v183, 0xffff0000, v183
	global_store_dwordx4 v[212:213], v[178:181], off offset:2304
	v_pk_mul_f32 v[138:139], v[74:75], v[32:33]
	v_pk_mul_f32 v[166:167], v[72:73], v[34:35]
	v_pk_mul_f32 v[168:169], v[70:71], v[28:29]
	v_pk_mul_f32 v[180:181], v[68:69], v[30:31]
	v_cvt_pk_bf16_f32 v178, v166, v167
	v_cvt_pk_bf16_f32 v179, v138, v139
	v_cvt_pk_bf16_f32 v180, v180, v181
	v_cvt_pk_bf16_f32 v181, v168, v169
	v_pk_fma_f32 v[24:25], v[24:25], v[162:163], v[182:183]
	v_pk_fma_f32 v[22:23], v[22:23], v[160:161], v[190:191]
	v_lshlrev_b32_e32 v192, 16, v184
	v_and_b32_e32 v193, 0xffff0000, v184
	v_lshlrev_b32_e32 v184, 16, v185
	v_and_b32_e32 v185, 0xffff0000, v185
	global_store_dwordx4 v[214:215], v[178:181], off offset:256
	v_pk_fma_f32 v[20:21], v[20:21], v[158:159], v[184:185]
	v_pk_fma_f32 v[18:19], v[18:19], v[156:157], v[192:193]
	v_cvt_pk_bf16_f32 v178, v22, v23
	v_cvt_pk_bf16_f32 v179, v24, v25
	v_lshlrev_b32_e32 v24, 16, v178
	v_and_b32_e32 v25, 0xffff0000, v178
	v_lshlrev_b32_e32 v22, 16, v179
	v_and_b32_e32 v23, 0xffff0000, v179
	v_cvt_pk_bf16_f32 v180, v18, v19
	v_cvt_pk_bf16_f32 v181, v20, v21
	v_pk_mul_f32 v[138:139], v[74:75], v[22:23]
	v_pk_mul_f32 v[166:167], v[72:73], v[24:25]
	global_store_dwordx4 v[216:217], v[178:181], off offset:2304
	v_lshlrev_b32_e32 v20, 16, v180
	v_and_b32_e32 v21, 0xffff0000, v180
	v_cvt_pk_bf16_f32 v178, v166, v167
	v_cvt_pk_bf16_f32 v179, v138, v139
	v_lshlrev_b32_e32 v138, 16, v134
	v_and_b32_e32 v139, 0xffff0000, v134
	v_lshlrev_b32_e32 v134, 16, v135
	v_and_b32_e32 v135, 0xffff0000, v135
	v_lshlrev_b32_e32 v166, 16, v136
	v_and_b32_e32 v167, 0xffff0000, v136
	v_lshlrev_b32_e32 v136, 16, v137
	v_and_b32_e32 v137, 0xffff0000, v137
	v_lshlrev_b32_e32 v18, 16, v181
	v_and_b32_e32 v19, 0xffff0000, v181
	v_pk_fma_f32 v[16:17], v[16:17], v[162:163], v[134:135]
	v_pk_fma_f32 v[14:15], v[14:15], v[160:161], v[138:139]
	v_pk_fma_f32 v[12:13], v[12:13], v[158:159], v[136:137]
	v_pk_fma_f32 v[10:11], v[10:11], v[156:157], v[166:167]
	v_pk_mul_f32 v[168:169], v[70:71], v[18:19]
	v_pk_mul_f32 v[180:181], v[68:69], v[20:21]
	v_cvt_pk_bf16_f32 v134, v14, v15
	v_cvt_pk_bf16_f32 v135, v16, v17
	v_cvt_pk_bf16_f32 v136, v10, v11
	v_cvt_pk_bf16_f32 v137, v12, v13
	v_cvt_pk_bf16_f32 v180, v180, v181
	v_cvt_pk_bf16_f32 v181, v168, v169
	v_lshlrev_b32_e32 v16, 16, v134
	v_and_b32_e32 v17, 0xffff0000, v134
	v_lshlrev_b32_e32 v14, 16, v135
	v_and_b32_e32 v15, 0xffff0000, v135
	v_lshlrev_b32_e32 v12, 16, v136
	v_and_b32_e32 v13, 0xffff0000, v136
	v_lshlrev_b32_e32 v10, 16, v137
	v_and_b32_e32 v11, 0xffff0000, v137
	global_store_dwordx4 v[218:219], v[178:181], off offset:256
	v_lshlrev_b32_e32 v168, 16, v186
	v_and_b32_e32 v169, 0xffff0000, v186
	v_lshlrev_b32_e32 v178, 16, v187
	v_and_b32_e32 v179, 0xffff0000, v187
	v_lshlrev_b32_e32 v180, 16, v188
	v_and_b32_e32 v181, 0xffff0000, v188
	v_lshlrev_b32_e32 v182, 16, v189
	v_and_b32_e32 v183, 0xffff0000, v189
	global_store_dwordx4 v[196:197], v[134:137], off offset:2304
	v_pk_mul_f32 v[138:139], v[70:71], v[10:11]
	v_pk_mul_f32 v[166:167], v[68:69], v[12:13]
	v_pk_mul_f32 v[136:137], v[74:75], v[14:15]
	v_pk_mul_f32 v[134:135], v[72:73], v[16:17]
	v_pk_fma_f32 v[8:9], v[8:9], v[162:163], v[178:179]
	v_cvt_pk_bf16_f32 v134, v134, v135
	v_cvt_pk_bf16_f32 v135, v136, v137
	v_cvt_pk_bf16_f32 v136, v166, v167
	v_cvt_pk_bf16_f32 v137, v138, v139
	v_pk_fma_f32 v[6:7], v[6:7], v[160:161], v[168:169]
	v_pk_fma_f32 v[4:5], v[4:5], v[158:159], v[182:183]
	v_pk_fma_f32 v[2:3], v[2:3], v[156:157], v[180:181]
	global_store_dwordx4 v[210:211], v[134:137], off offset:256
	s_nop 1
	v_cvt_pk_bf16_f32 v134, v6, v7
	v_cvt_pk_bf16_f32 v135, v8, v9
	v_cvt_pk_bf16_f32 v136, v2, v3
	v_cvt_pk_bf16_f32 v137, v4, v5
	v_lshlrev_b32_e32 v8, 16, v134
	v_and_b32_e32 v9, 0xffff0000, v134
	v_lshlrev_b32_e32 v6, 16, v135
	v_and_b32_e32 v7, 0xffff0000, v135
	v_lshlrev_b32_e32 v4, 16, v136
	v_and_b32_e32 v5, 0xffff0000, v136
	v_lshlrev_b32_e32 v2, 16, v137
	v_and_b32_e32 v3, 0xffff0000, v137
	global_store_dwordx4 v[220:221], v[134:137], off offset:2304
	v_pk_mul_f32 v[74:75], v[74:75], v[6:7]
	v_pk_mul_f32 v[72:73], v[72:73], v[8:9]
	v_pk_mul_f32 v[134:135], v[70:71], v[2:3]
	v_pk_mul_f32 v[70:71], v[68:69], v[4:5]
	v_cvt_pk_bf16_f32 v68, v72, v73
	v_cvt_pk_bf16_f32 v69, v74, v75
	v_cvt_pk_bf16_f32 v70, v70, v71
	v_cvt_pk_bf16_f32 v71, v134, v135
	global_store_dwordx4 v[132:133], v[68:71], off offset:256
	v_xor_b32_e32 v72, 32, v227
	v_mul_f32_e32 v73, v129, v129
	v_and_b32_e32 v71, 64, v227
	v_xor_b32_e32 v70, 16, v227
	v_add_u32_e32 v71, 64, v71
	v_cmp_lt_i32_e32 vcc, v70, v71
	v_fmac_f32_e32 v73, v128, v128
	v_mul_f32_e32 v74, v125, v125
	v_cndmask_b32_e32 v70, v227, v70, vcc
	v_cmp_lt_i32_e32 vcc, v72, v71
	v_fmac_f32_e32 v74, v124, v124
	v_lshlrev_b32_e32 v70, 2, v70
	v_cndmask_b32_e32 v71, v227, v72, vcc
	v_mul_f32_e32 v72, v131, v131
	v_fmac_f32_e32 v72, v130, v130
	v_add_f32_e32 v72, v72, v73
	v_mul_f32_e32 v73, v127, v127
	v_fmac_f32_e32 v73, v126, v126
	v_add_f32_e32 v73, v73, v74
	v_add_f32_e32 v72, v72, v73
	v_add_f32_e32 v64, v72, v64
	v_add_f32_e32 v60, v60, v64
	ds_bpermute_b32 v61, v70, v60
	v_lshlrev_b32_e32 v71, 2, v71
	v_lshl_add_u64 v[68:69], v[150:151], 0, s[24:25]
	s_waitcnt lgkmcnt(0)
	v_add_f32_e32 v60, v60, v61
	ds_bpermute_b32 v61, v71, v60
	s_and_saveexec_b64 s[24:25], s[38:39]
	s_cbranch_execz .LBB0_1159
	s_waitcnt lgkmcnt(0)
	v_add_f32_e32 v60, v60, v61
	global_atomic_add_f32 v[68:69], v60, off

	.amdhsa_kernel _Z4mega4Args
		.amdhsa_group_segment_fixed_size 0
		.amdhsa_private_segment_fixed_size 0
		.amdhsa_kernarg_size 432
		.amdhsa_user_sgpr_count 2
		.amdhsa_user_sgpr_dispatch_ptr 0
		.amdhsa_user_sgpr_queue_ptr 0
		.amdhsa_user_sgpr_kernarg_segment_ptr 1
		.amdhsa_user_sgpr_dispatch_id 0
		.amdhsa_user_sgpr_kernarg_preload_length 0
		.amdhsa_user_sgpr_kernarg_preload_offset 0
		.amdhsa_user_sgpr_private_segment_size 0
		.amdhsa_uses_dynamic_stack 0
		.amdhsa_enable_private_segment 0
		.amdhsa_system_sgpr_workgroup_id_x 1
		.amdhsa_system_sgpr_workgroup_id_y 0
		.amdhsa_system_sgpr_workgroup_id_z 0
		.amdhsa_system_sgpr_workgroup_info 0
		.amdhsa_system_vgpr_workitem_id 0
		.amdhsa_next_free_vgpr 256
		.amdhsa_next_free_sgpr 102
		.amdhsa_accum_offset 256
		.amdhsa_reserve_vcc 1
		.amdhsa_float_round_mode_32 0
		.amdhsa_float_round_mode_16_64 0
		.amdhsa_float_denorm_mode_32 3
		.amdhsa_float_denorm_mode_16_64 3
		.amdhsa_dx10_clamp 1
		.amdhsa_ieee_mode 1
		.amdhsa_fp16_overflow 0
		.amdhsa_tg_split 0
		.amdhsa_exception_fp_ieee_invalid_op 0
		.amdhsa_exception_fp_denorm_src 0
		.amdhsa_exception_fp_ieee_div_zero 0
		.amdhsa_exception_fp_ieee_overflow 0
		.amdhsa_exception_fp_ieee_underflow 0
		.amdhsa_exception_fp_ieee_inexact 0
		.amdhsa_exception_int_div_zero 0
	.end_amdhsa_kernel

amdhsa.kernels:
  - .agpr_count:     0
    .args:
      - .offset:         0
        .size:           176
        .value_kind:     by_value
      - .offset:         176
        .size:           4
        .value_kind:     hidden_block_count_x
      - .offset:         180
        .size:           4
        .value_kind:     hidden_block_count_y
      - .offset:         184
        .size:           4
        .value_kind:     hidden_block_count_z
      - .offset:         188
        .size:           2
        .value_kind:     hidden_group_size_x
      - .offset:         190
        .size:           2
        .value_kind:     hidden_group_size_y
      - .offset:         192
        .size:           2
        .value_kind:     hidden_group_size_z
      - .offset:         194
        .size:           2
        .value_kind:     hidden_remainder_x
      - .offset:         196
        .size:           2
        .value_kind:     hidden_remainder_y
      - .offset:         198
        .size:           2
        .value_kind:     hidden_remainder_z
      - .offset:         216
        .size:           8
        .value_kind:     hidden_global_offset_x
      - .offset:         224
        .size:           8
        .value_kind:     hidden_global_offset_y
      - .offset:         232
        .size:           8
        .value_kind:     hidden_global_offset_z
      - .offset:         240
        .size:           2
        .value_kind:     hidden_grid_dims
      - .offset:         296
        .size:           4
        .value_kind:     hidden_dynamic_lds_size
    .group_segment_fixed_size: 0
    .kernarg_segment_align: 8
    .kernarg_segment_size: 432
    .language:       OpenCL C
    .language_version:
      - 2
      - 0
    .max_flat_workgroup_size: 512
    .name:           _Z4mega4Args
    .private_segment_fixed_size: 0
    .sgpr_count:     108
    .sgpr_spill_count: 134
    .symbol:         _Z4mega4Args.kd
    .uniform_work_group_size: 1
    .uses_dynamic_stack: false
    .vgpr_count:     256
    .vgpr_spill_count: 0
    .wavefront_size: 64
